# pre-MFMA lgkmcnt(0) waits moved ahead of their s_barrier (stricter, saves an issue slot after barrier release)
# baseline (speedup 1.0000x reference)
.LBB0_86:
	v_mov_b64_e32 v[0:1], 0x800
	s_ashr_i32 s7, s6, 31
	v_cmp_lt_i64_e32 vcc, s[8:9], v[0:1]
	s_lshl_b64 s[8:9], s[6:7], 20
	s_add_u32 s8, s23, s8
	s_addc_u32 s9, s24, s9
	s_and_b64 s[10:11], vcc, exec
	s_cselect_b32 s7, s9, s15
	s_cselect_b32 s38, s8, s14
	s_ashr_i32 s5, s4, 31
	s_lshl_b64 s[10:11], s[4:5], 20
	s_add_u32 s10, s25, s10
	s_addc_u32 s11, s26, s11
	s_and_b64 s[18:19], vcc, exec
	s_cselect_b32 s5, s11, s17
	s_cselect_b32 s39, s10, s16
	s_add_u32 s14, s14, 0x80080
	s_addc_u32 s15, s15, 0
	s_add_u32 s40, s16, 0x100
	s_addc_u32 s41, s17, 0
	s_mov_b32 s42, -2
	s_mov_b64 s[48:49], 0x80
	v_add_u32_e32 v220, 0x10000, v183
	s_add_u32 s16, s14, 0xfff80080
	s_addc_u32 s17, s15, -1
	s_add_i32 s43, 0, 0x10000
	ds_read_b128 v[128:131], v220 offset:0
	ds_read_b128 v[132:135], v220 offset:1024
	ds_read_b128 v[136:139], v220 offset:2048
	ds_read_b128 v[140:143], v220 offset:3072
	s_cmp_eq_u32 s42, 28
	s_cselect_b32 s19, s7, s17
	s_cselect_b32 s18, s38, s16
	s_cselect_b32 s17, s5, s41
	s_cselect_b32 s16, s39, s40
	s_add_i32 m0, s28, 0xc000
	ds_read_b128 v[144:147], v185
	ds_read_b128 v[148:151], v185 offset:1024
	ds_read_b128 v[152:155], v185 offset:2048
	ds_read_b128 v[156:159], v185 offset:3072
	ds_read_b128 v[170:173], v185 offset:4096
	ds_read_b128 v[174:177], v185 offset:5120
	ds_read_b128 v[178:181], v185 offset:6144
	ds_read_b128 v[186:189], v185 offset:7168
	global_load_lds_dwordx4 v166, s[14:15]
	s_add_i32 m0, s28, 0xe000
	s_nop 0
	global_load_lds_dwordx4 v168, s[14:15]
	s_waitcnt lgkmcnt(8)
	s_waitcnt lgkmcnt(0)
	s_barrier
	v_mfma_f32_16x16x32_bf16 v[124:127], v[128:131], v[144:147], 0
	v_mfma_f32_16x16x32_bf16 v[120:123], v[136:139], v[144:147], 0
	v_mfma_f32_16x16x32_bf16 v[108:111], v[128:131], v[152:155], 0
	v_mfma_f32_16x16x32_bf16 v[104:107], v[136:139], v[152:155], 0
	v_mfma_f32_16x16x32_bf16 v[92:95], v[128:131], v[170:173], 0
	v_mfma_f32_16x16x32_bf16 v[88:91], v[136:139], v[170:173], 0
	v_mfma_f32_16x16x32_bf16 v[76:79], v[128:131], v[178:181], 0
	v_mfma_f32_16x16x32_bf16 v[72:75], v[136:139], v[178:181], 0
	v_mfma_f32_16x16x32_bf16 v[124:127], v[132:135], v[148:151], v[124:127]
	v_mfma_f32_16x16x32_bf16 v[120:123], v[140:143], v[148:151], v[120:123]
	v_mfma_f32_16x16x32_bf16 v[108:111], v[132:135], v[156:159], v[108:111]
	v_mfma_f32_16x16x32_bf16 v[104:107], v[140:143], v[156:159], v[104:107]
	v_mfma_f32_16x16x32_bf16 v[92:95], v[132:135], v[174:177], v[92:95]
	v_mfma_f32_16x16x32_bf16 v[88:91], v[140:143], v[174:177], v[88:91]
	v_mfma_f32_16x16x32_bf16 v[76:79], v[132:135], v[186:189], v[76:79]
	v_mfma_f32_16x16x32_bf16 v[72:75], v[140:143], v[186:189], v[72:75]
	s_barrier
	s_add_i32 s46, 0, 0x14000
	s_add_i32 s43, s43, s27
	ds_read_b128 v[196:199], v220 offset:16384
	ds_read_b128 v[204:207], v220 offset:17408
	ds_read_b128 v[208:211], v220 offset:18432
	ds_read_b128 v[214:217], v220 offset:19456
	s_mov_b32 m0, s43
	s_nop 0
	global_load_lds_dwordx4 v192, s[16:17]
	s_add_i32 m0, s43, 0x2000
	s_nop 0
	global_load_lds_dwordx4 v164, s[16:17]
	s_waitcnt lgkmcnt(0)
	s_barrier
	v_mfma_f32_16x16x32_bf16 v[116:119], v[196:199], v[144:147], 0
	v_mfma_f32_16x16x32_bf16 v[112:115], v[208:211], v[144:147], 0
	v_mfma_f32_16x16x32_bf16 v[100:103], v[196:199], v[152:155], 0
	v_mfma_f32_16x16x32_bf16 v[96:99], v[208:211], v[152:155], 0
	v_mfma_f32_16x16x32_bf16 v[84:87], v[196:199], v[170:173], 0
	v_mfma_f32_16x16x32_bf16 v[80:83], v[208:211], v[170:173], 0
	v_mfma_f32_16x16x32_bf16 v[68:71], v[196:199], v[178:181], 0
	v_mfma_f32_16x16x32_bf16 v[64:67], v[208:211], v[178:181], 0
	v_mfma_f32_16x16x32_bf16 v[116:119], v[204:207], v[148:151], v[116:119]
	v_mfma_f32_16x16x32_bf16 v[112:115], v[214:217], v[148:151], v[112:115]
	v_mfma_f32_16x16x32_bf16 v[100:103], v[204:207], v[156:159], v[100:103]
	v_mfma_f32_16x16x32_bf16 v[96:99], v[214:217], v[156:159], v[96:99]
	v_mfma_f32_16x16x32_bf16 v[84:87], v[204:207], v[174:177], v[84:87]
	v_mfma_f32_16x16x32_bf16 v[80:83], v[214:217], v[174:177], v[80:83]
	v_mfma_f32_16x16x32_bf16 v[68:71], v[204:207], v[186:189], v[68:71]
	v_mfma_f32_16x16x32_bf16 v[64:67], v[214:217], v[186:189], v[64:67]
	s_mov_b32 m0, s28
	s_add_u32 s48, s18, 0x80
	s_addc_u32 s49, s19, 0
	s_barrier
	ds_read_b128 v[144:147], v185 offset:16384
	ds_read_b128 v[148:151], v185 offset:17408
	ds_read_b128 v[152:155], v185 offset:18432
	ds_read_b128 v[156:159], v185 offset:19456
	ds_read_b128 v[170:173], v185 offset:20480
	ds_read_b128 v[174:177], v185 offset:21504
	ds_read_b128 v[178:181], v185 offset:22528
	ds_read_b128 v[186:189], v185 offset:23552
	global_load_lds_dwordx4 v160, s[18:19]
	s_mov_b32 m0, s29
	s_nop 0
	global_load_lds_dwordx4 v162, s[18:19]
	s_waitcnt lgkmcnt(0)
	s_barrier
	v_mfma_f32_16x16x32_bf16 v[60:63], v[128:131], v[144:147], 0
	v_mfma_f32_16x16x32_bf16 v[56:59], v[136:139], v[144:147], 0
	v_mfma_f32_16x16x32_bf16 v[44:47], v[128:131], v[152:155], 0
	v_mfma_f32_16x16x32_bf16 v[40:43], v[136:139], v[152:155], 0
	v_mfma_f32_16x16x32_bf16 v[28:31], v[128:131], v[170:173], 0
	v_mfma_f32_16x16x32_bf16 v[24:27], v[136:139], v[170:173], 0
	v_mfma_f32_16x16x32_bf16 v[12:15], v[128:131], v[178:181], 0
	v_mfma_f32_16x16x32_bf16 v[8:11], v[136:139], v[178:181], 0
	v_mfma_f32_16x16x32_bf16 v[60:63], v[132:135], v[148:151], v[60:63]
	v_mfma_f32_16x16x32_bf16 v[56:59], v[140:143], v[148:151], v[56:59]
	v_mfma_f32_16x16x32_bf16 v[44:47], v[132:135], v[156:159], v[44:47]
	v_mfma_f32_16x16x32_bf16 v[40:43], v[140:143], v[156:159], v[40:43]
	v_mfma_f32_16x16x32_bf16 v[28:31], v[132:135], v[174:177], v[28:31]
	v_mfma_f32_16x16x32_bf16 v[24:27], v[140:143], v[174:177], v[24:27]
	v_mfma_f32_16x16x32_bf16 v[12:15], v[132:135], v[186:189], v[12:15]
	v_mfma_f32_16x16x32_bf16 v[8:11], v[140:143], v[186:189], v[8:11]
	s_barrier
	s_add_u32 s44, s16, 0x80000
	s_addc_u32 s45, s17, 0
	s_add_i32 s43, s46, s27
	s_mov_b32 m0, s43
	s_nop 0
	global_load_lds_dwordx4 v192, s[44:45]
	s_add_i32 m0, s43, 0x2000
	s_nop 0
	global_load_lds_dwordx4 v164, s[44:45]
	s_waitcnt vmcnt(6)
	s_barrier
	v_mfma_f32_16x16x32_bf16 v[52:55], v[196:199], v[144:147], 0
	v_mfma_f32_16x16x32_bf16 v[48:51], v[208:211], v[144:147], 0
	v_mfma_f32_16x16x32_bf16 v[36:39], v[196:199], v[152:155], 0
	v_mfma_f32_16x16x32_bf16 v[32:35], v[208:211], v[152:155], 0
	v_mfma_f32_16x16x32_bf16 v[20:23], v[196:199], v[170:173], 0
	v_mfma_f32_16x16x32_bf16 v[16:19], v[208:211], v[170:173], 0
	v_mfma_f32_16x16x32_bf16 v[4:7], v[196:199], v[178:181], 0
	v_mfma_f32_16x16x32_bf16 v[0:3], v[208:211], v[178:181], 0
	v_mfma_f32_16x16x32_bf16 v[52:55], v[204:207], v[148:151], v[52:55]
	v_mfma_f32_16x16x32_bf16 v[48:51], v[214:217], v[148:151], v[48:51]
	v_mfma_f32_16x16x32_bf16 v[36:39], v[204:207], v[156:159], v[36:39]
	v_mfma_f32_16x16x32_bf16 v[32:35], v[214:217], v[156:159], v[32:35]
	v_mfma_f32_16x16x32_bf16 v[20:23], v[204:207], v[174:177], v[20:23]
	v_mfma_f32_16x16x32_bf16 v[16:19], v[214:217], v[174:177], v[16:19]
	v_mfma_f32_16x16x32_bf16 v[4:7], v[204:207], v[186:189], v[4:7]
	v_mfma_f32_16x16x32_bf16 v[0:3], v[214:217], v[186:189], v[0:3]
	s_add_i32 s43, 0, 0x18000
	s_barrier
	ds_read_b128 v[128:131], v220 offset:32768
	ds_read_b128 v[132:135], v220 offset:33792
	ds_read_b128 v[136:139], v220 offset:34816
	ds_read_b128 v[140:143], v220 offset:35840
	s_add_u32 s18, s18, 0x80000
	s_addc_u32 s19, s19, 0
	s_mov_b32 m0, s30
	ds_read_b128 v[144:147], v185 offset:32768
	ds_read_b128 v[148:151], v185 offset:33792
	ds_read_b128 v[152:155], v185 offset:34816
	ds_read_b128 v[156:159], v185 offset:35840
	ds_read_b128 v[170:173], v185 offset:36864
	ds_read_b128 v[174:177], v185 offset:37888
	ds_read_b128 v[178:181], v185 offset:38912
	ds_read_b128 v[186:189], v185 offset:39936
	global_load_lds_dwordx4 v160, s[18:19]
	s_mov_b32 m0, s31
	s_nop 0
	global_load_lds_dwordx4 v162, s[18:19]
	s_waitcnt lgkmcnt(8)
	s_waitcnt lgkmcnt(0)
	s_barrier
	v_mfma_f32_16x16x32_bf16 v[124:127], v[128:131], v[144:147], v[124:127]
	v_mfma_f32_16x16x32_bf16 v[120:123], v[136:139], v[144:147], v[120:123]
	v_mfma_f32_16x16x32_bf16 v[108:111], v[128:131], v[152:155], v[108:111]
	v_mfma_f32_16x16x32_bf16 v[104:107], v[136:139], v[152:155], v[104:107]
	v_mfma_f32_16x16x32_bf16 v[92:95], v[128:131], v[170:173], v[92:95]
	v_mfma_f32_16x16x32_bf16 v[88:91], v[136:139], v[170:173], v[88:91]
	v_mfma_f32_16x16x32_bf16 v[76:79], v[128:131], v[178:181], v[76:79]
	v_mfma_f32_16x16x32_bf16 v[72:75], v[136:139], v[178:181], v[72:75]
	v_mfma_f32_16x16x32_bf16 v[124:127], v[132:135], v[148:151], v[124:127]
	v_mfma_f32_16x16x32_bf16 v[120:123], v[140:143], v[148:151], v[120:123]
	v_mfma_f32_16x16x32_bf16 v[108:111], v[132:135], v[156:159], v[108:111]
	v_mfma_f32_16x16x32_bf16 v[104:107], v[140:143], v[156:159], v[104:107]
	v_mfma_f32_16x16x32_bf16 v[92:95], v[132:135], v[174:177], v[92:95]
	v_mfma_f32_16x16x32_bf16 v[88:91], v[140:143], v[174:177], v[88:91]
	v_mfma_f32_16x16x32_bf16 v[76:79], v[132:135], v[186:189], v[76:79]
	v_mfma_f32_16x16x32_bf16 v[72:75], v[140:143], v[186:189], v[72:75]
	s_barrier
	s_add_i32 s18, 0, 0x1c000
	s_add_i32 s19, s43, s27
	s_add_i32 m0, s19, 0xffffff80
	ds_read_b128 v[196:199], v220 offset:49152
	ds_read_b128 v[204:207], v220 offset:50176
	ds_read_b128 v[208:211], v220 offset:51200
	ds_read_b128 v[214:217], v220 offset:52224
	global_load_lds_dwordx4 v192, s[16:17] offset:128
	s_add_i32 m0, s19, 0x1f80
	s_nop 0
	global_load_lds_dwordx4 v164, s[16:17] offset:128
	s_waitcnt lgkmcnt(0)
	s_barrier
	v_mfma_f32_16x16x32_bf16 v[116:119], v[196:199], v[144:147], v[116:119]
	v_mfma_f32_16x16x32_bf16 v[112:115], v[208:211], v[144:147], v[112:115]
	v_mfma_f32_16x16x32_bf16 v[100:103], v[196:199], v[152:155], v[100:103]
	v_mfma_f32_16x16x32_bf16 v[96:99], v[208:211], v[152:155], v[96:99]
	v_mfma_f32_16x16x32_bf16 v[84:87], v[196:199], v[170:173], v[84:87]
	v_mfma_f32_16x16x32_bf16 v[80:83], v[208:211], v[170:173], v[80:83]
	v_mfma_f32_16x16x32_bf16 v[68:71], v[196:199], v[178:181], v[68:71]
	v_mfma_f32_16x16x32_bf16 v[64:67], v[208:211], v[178:181], v[64:67]
	v_mfma_f32_16x16x32_bf16 v[116:119], v[204:207], v[148:151], v[116:119]
	v_mfma_f32_16x16x32_bf16 v[112:115], v[214:217], v[148:151], v[112:115]
	v_mfma_f32_16x16x32_bf16 v[100:103], v[204:207], v[156:159], v[100:103]
	v_mfma_f32_16x16x32_bf16 v[96:99], v[214:217], v[156:159], v[96:99]
	v_mfma_f32_16x16x32_bf16 v[84:87], v[204:207], v[174:177], v[84:87]
	v_mfma_f32_16x16x32_bf16 v[80:83], v[214:217], v[174:177], v[80:83]
	v_mfma_f32_16x16x32_bf16 v[68:71], v[204:207], v[186:189], v[68:71]
	v_mfma_f32_16x16x32_bf16 v[64:67], v[214:217], v[186:189], v[64:67]
	s_mov_b32 m0, s35
	s_barrier
	ds_read_b128 v[144:147], v185 offset:49152
	ds_read_b128 v[148:151], v185 offset:50176
	ds_read_b128 v[152:155], v185 offset:51200
	ds_read_b128 v[156:159], v185 offset:52224
	ds_read_b128 v[170:173], v185 offset:53248
	ds_read_b128 v[174:177], v185 offset:54272
	ds_read_b128 v[178:181], v185 offset:55296
	ds_read_b128 v[186:189], v185 offset:56320
	global_load_lds_dwordx4 v160, s[48:49]
	s_mov_b32 m0, s36
	s_nop 0
	global_load_lds_dwordx4 v162, s[48:49]
	s_waitcnt lgkmcnt(0)
	s_barrier
	v_mfma_f32_16x16x32_bf16 v[60:63], v[128:131], v[144:147], v[60:63]
	v_mfma_f32_16x16x32_bf16 v[56:59], v[136:139], v[144:147], v[56:59]
	v_mfma_f32_16x16x32_bf16 v[44:47], v[128:131], v[152:155], v[44:47]
	v_mfma_f32_16x16x32_bf16 v[40:43], v[136:139], v[152:155], v[40:43]
	v_mfma_f32_16x16x32_bf16 v[28:31], v[128:131], v[170:173], v[28:31]
	v_mfma_f32_16x16x32_bf16 v[24:27], v[136:139], v[170:173], v[24:27]
	v_mfma_f32_16x16x32_bf16 v[12:15], v[128:131], v[178:181], v[12:15]
	v_mfma_f32_16x16x32_bf16 v[8:11], v[136:139], v[178:181], v[8:11]
	v_mfma_f32_16x16x32_bf16 v[60:63], v[132:135], v[148:151], v[60:63]
	v_mfma_f32_16x16x32_bf16 v[56:59], v[140:143], v[148:151], v[56:59]
	v_mfma_f32_16x16x32_bf16 v[44:47], v[132:135], v[156:159], v[44:47]
	v_mfma_f32_16x16x32_bf16 v[40:43], v[140:143], v[156:159], v[40:43]
	v_mfma_f32_16x16x32_bf16 v[28:31], v[132:135], v[174:177], v[28:31]
	v_mfma_f32_16x16x32_bf16 v[24:27], v[140:143], v[174:177], v[24:27]
	v_mfma_f32_16x16x32_bf16 v[12:15], v[132:135], v[186:189], v[12:15]
	v_mfma_f32_16x16x32_bf16 v[8:11], v[140:143], v[186:189], v[8:11]
	s_barrier
	s_add_u32 s16, s16, 0x80080
	s_addc_u32 s17, s17, 0
	s_add_i32 s18, s18, s27
	s_mov_b32 m0, s18
	s_nop 0
	global_load_lds_dwordx4 v192, s[16:17]
	s_add_i32 m0, s18, 0x2000
	s_nop 0
	global_load_lds_dwordx4 v164, s[16:17]
	s_waitcnt vmcnt(6)
	s_barrier
	v_mfma_f32_16x16x32_bf16 v[52:55], v[196:199], v[144:147], v[52:55]
	v_mfma_f32_16x16x32_bf16 v[48:51], v[208:211], v[144:147], v[48:51]
	v_mfma_f32_16x16x32_bf16 v[36:39], v[196:199], v[152:155], v[36:39]
	v_mfma_f32_16x16x32_bf16 v[32:35], v[208:211], v[152:155], v[32:35]
	v_mfma_f32_16x16x32_bf16 v[20:23], v[196:199], v[170:173], v[20:23]
	v_mfma_f32_16x16x32_bf16 v[16:19], v[208:211], v[170:173], v[16:19]
	v_mfma_f32_16x16x32_bf16 v[4:7], v[196:199], v[178:181], v[4:7]
	v_mfma_f32_16x16x32_bf16 v[0:3], v[208:211], v[178:181], v[0:3]
	v_mfma_f32_16x16x32_bf16 v[52:55], v[204:207], v[148:151], v[52:55]
	v_mfma_f32_16x16x32_bf16 v[48:51], v[214:217], v[148:151], v[48:51]
	v_mfma_f32_16x16x32_bf16 v[36:39], v[204:207], v[156:159], v[36:39]
	v_mfma_f32_16x16x32_bf16 v[32:35], v[214:217], v[156:159], v[32:35]
	v_mfma_f32_16x16x32_bf16 v[20:23], v[204:207], v[174:177], v[20:23]
	v_mfma_f32_16x16x32_bf16 v[16:19], v[214:217], v[174:177], v[16:19]
	v_mfma_f32_16x16x32_bf16 v[4:7], v[204:207], v[186:189], v[4:7]
	v_mfma_f32_16x16x32_bf16 v[0:3], v[214:217], v[186:189], v[0:3]
	s_add_i32 s42, s42, 2
	s_add_u32 s14, s14, 0x100
	s_addc_u32 s15, s15, 0
	s_add_u32 s40, s40, 0x100
	s_addc_u32 s41, s41, 0
	s_cmp_gt_u32 s42, 29
	s_barrier
.LBB0_87:
	s_add_u32 s16, s14, 0xfff80080
	s_addc_u32 s17, s15, -1
	s_add_i32 s43, 0, 0x10000
	ds_read_b128 v[128:131], v220 offset:0
	ds_read_b128 v[132:135], v220 offset:1024
	ds_read_b128 v[136:139], v220 offset:2048
	ds_read_b128 v[140:143], v220 offset:3072
	s_cmp_eq_u32 s42, 28
	s_cselect_b32 s19, s7, s17
	s_cselect_b32 s18, s38, s16
	s_cselect_b32 s17, s5, s41
	s_cselect_b32 s16, s39, s40
	s_add_i32 m0, s28, 0xc000
	ds_read_b128 v[144:147], v185
	ds_read_b128 v[148:151], v185 offset:1024
	ds_read_b128 v[152:155], v185 offset:2048
	ds_read_b128 v[156:159], v185 offset:3072
	ds_read_b128 v[170:173], v185 offset:4096
	ds_read_b128 v[174:177], v185 offset:5120
	ds_read_b128 v[178:181], v185 offset:6144
	ds_read_b128 v[186:189], v185 offset:7168
	global_load_lds_dwordx4 v166, s[14:15]
	s_add_i32 m0, s28, 0xe000
	s_nop 0
	global_load_lds_dwordx4 v168, s[14:15]
	s_waitcnt lgkmcnt(8)
	s_waitcnt lgkmcnt(0)
	s_barrier
	v_mfma_f32_16x16x32_bf16 v[124:127], v[128:131], v[144:147], v[124:127]
	v_mfma_f32_16x16x32_bf16 v[120:123], v[136:139], v[144:147], v[120:123]
	v_mfma_f32_16x16x32_bf16 v[108:111], v[128:131], v[152:155], v[108:111]
	v_mfma_f32_16x16x32_bf16 v[104:107], v[136:139], v[152:155], v[104:107]
	v_mfma_f32_16x16x32_bf16 v[92:95], v[128:131], v[170:173], v[92:95]
	v_mfma_f32_16x16x32_bf16 v[88:91], v[136:139], v[170:173], v[88:91]
	v_mfma_f32_16x16x32_bf16 v[76:79], v[128:131], v[178:181], v[76:79]
	v_mfma_f32_16x16x32_bf16 v[72:75], v[136:139], v[178:181], v[72:75]
	v_mfma_f32_16x16x32_bf16 v[124:127], v[132:135], v[148:151], v[124:127]
	v_mfma_f32_16x16x32_bf16 v[120:123], v[140:143], v[148:151], v[120:123]
	v_mfma_f32_16x16x32_bf16 v[108:111], v[132:135], v[156:159], v[108:111]
	v_mfma_f32_16x16x32_bf16 v[104:107], v[140:143], v[156:159], v[104:107]
	v_mfma_f32_16x16x32_bf16 v[92:95], v[132:135], v[174:177], v[92:95]
	v_mfma_f32_16x16x32_bf16 v[88:91], v[140:143], v[174:177], v[88:91]
	v_mfma_f32_16x16x32_bf16 v[76:79], v[132:135], v[186:189], v[76:79]
	v_mfma_f32_16x16x32_bf16 v[72:75], v[140:143], v[186:189], v[72:75]
	s_barrier
	s_add_i32 s46, 0, 0x14000
	s_add_i32 s43, s43, s27
	ds_read_b128 v[196:199], v220 offset:16384
	ds_read_b128 v[204:207], v220 offset:17408
	ds_read_b128 v[208:211], v220 offset:18432
	ds_read_b128 v[214:217], v220 offset:19456
	s_mov_b32 m0, s43
	s_nop 0
	global_load_lds_dwordx4 v192, s[16:17]
	s_add_i32 m0, s43, 0x2000
	s_nop 0
	global_load_lds_dwordx4 v164, s[16:17]
	s_waitcnt lgkmcnt(0)
	s_barrier
	v_mfma_f32_16x16x32_bf16 v[116:119], v[196:199], v[144:147], v[116:119]
	v_mfma_f32_16x16x32_bf16 v[112:115], v[208:211], v[144:147], v[112:115]
	v_mfma_f32_16x16x32_bf16 v[100:103], v[196:199], v[152:155], v[100:103]
	v_mfma_f32_16x16x32_bf16 v[96:99], v[208:211], v[152:155], v[96:99]
	v_mfma_f32_16x16x32_bf16 v[84:87], v[196:199], v[170:173], v[84:87]
	v_mfma_f32_16x16x32_bf16 v[80:83], v[208:211], v[170:173], v[80:83]
	v_mfma_f32_16x16x32_bf16 v[68:71], v[196:199], v[178:181], v[68:71]
	v_mfma_f32_16x16x32_bf16 v[64:67], v[208:211], v[178:181], v[64:67]
	v_mfma_f32_16x16x32_bf16 v[116:119], v[204:207], v[148:151], v[116:119]
	v_mfma_f32_16x16x32_bf16 v[112:115], v[214:217], v[148:151], v[112:115]
	v_mfma_f32_16x16x32_bf16 v[100:103], v[204:207], v[156:159], v[100:103]
	v_mfma_f32_16x16x32_bf16 v[96:99], v[214:217], v[156:159], v[96:99]
	v_mfma_f32_16x16x32_bf16 v[84:87], v[204:207], v[174:177], v[84:87]
	v_mfma_f32_16x16x32_bf16 v[80:83], v[214:217], v[174:177], v[80:83]
	v_mfma_f32_16x16x32_bf16 v[68:71], v[204:207], v[186:189], v[68:71]
	v_mfma_f32_16x16x32_bf16 v[64:67], v[214:217], v[186:189], v[64:67]
	s_mov_b32 m0, s28
	s_add_u32 s48, s18, 0x80
	s_addc_u32 s49, s19, 0
	s_barrier
	ds_read_b128 v[144:147], v185 offset:16384
	ds_read_b128 v[148:151], v185 offset:17408
	ds_read_b128 v[152:155], v185 offset:18432
	ds_read_b128 v[156:159], v185 offset:19456
	ds_read_b128 v[170:173], v185 offset:20480
	ds_read_b128 v[174:177], v185 offset:21504
	ds_read_b128 v[178:181], v185 offset:22528
	ds_read_b128 v[186:189], v185 offset:23552
	global_load_lds_dwordx4 v160, s[18:19]
	s_mov_b32 m0, s29
	s_nop 0
	global_load_lds_dwordx4 v162, s[18:19]
	s_waitcnt lgkmcnt(0)
	s_barrier
	v_mfma_f32_16x16x32_bf16 v[60:63], v[128:131], v[144:147], v[60:63]
	v_mfma_f32_16x16x32_bf16 v[56:59], v[136:139], v[144:147], v[56:59]
	v_mfma_f32_16x16x32_bf16 v[44:47], v[128:131], v[152:155], v[44:47]
	v_mfma_f32_16x16x32_bf16 v[40:43], v[136:139], v[152:155], v[40:43]
	v_mfma_f32_16x16x32_bf16 v[28:31], v[128:131], v[170:173], v[28:31]
	v_mfma_f32_16x16x32_bf16 v[24:27], v[136:139], v[170:173], v[24:27]
	v_mfma_f32_16x16x32_bf16 v[12:15], v[128:131], v[178:181], v[12:15]
	v_mfma_f32_16x16x32_bf16 v[8:11], v[136:139], v[178:181], v[8:11]
	v_mfma_f32_16x16x32_bf16 v[60:63], v[132:135], v[148:151], v[60:63]
	v_mfma_f32_16x16x32_bf16 v[56:59], v[140:143], v[148:151], v[56:59]
	v_mfma_f32_16x16x32_bf16 v[44:47], v[132:135], v[156:159], v[44:47]
	v_mfma_f32_16x16x32_bf16 v[40:43], v[140:143], v[156:159], v[40:43]
	v_mfma_f32_16x16x32_bf16 v[28:31], v[132:135], v[174:177], v[28:31]
	v_mfma_f32_16x16x32_bf16 v[24:27], v[140:143], v[174:177], v[24:27]
	v_mfma_f32_16x16x32_bf16 v[12:15], v[132:135], v[186:189], v[12:15]
	v_mfma_f32_16x16x32_bf16 v[8:11], v[140:143], v[186:189], v[8:11]
	s_barrier
	s_add_u32 s44, s16, 0x80000
	s_addc_u32 s45, s17, 0
	s_add_i32 s43, s46, s27
	s_mov_b32 m0, s43
	s_nop 0
	global_load_lds_dwordx4 v192, s[44:45]
	s_add_i32 m0, s43, 0x2000
	s_nop 0
	global_load_lds_dwordx4 v164, s[44:45]
	s_waitcnt vmcnt(6)
	s_barrier
	v_mfma_f32_16x16x32_bf16 v[52:55], v[196:199], v[144:147], v[52:55]
	v_mfma_f32_16x16x32_bf16 v[48:51], v[208:211], v[144:147], v[48:51]
	v_mfma_f32_16x16x32_bf16 v[36:39], v[196:199], v[152:155], v[36:39]
	v_mfma_f32_16x16x32_bf16 v[32:35], v[208:211], v[152:155], v[32:35]
	v_mfma_f32_16x16x32_bf16 v[20:23], v[196:199], v[170:173], v[20:23]
	v_mfma_f32_16x16x32_bf16 v[16:19], v[208:211], v[170:173], v[16:19]
	v_mfma_f32_16x16x32_bf16 v[4:7], v[196:199], v[178:181], v[4:7]
	v_mfma_f32_16x16x32_bf16 v[0:3], v[208:211], v[178:181], v[0:3]
	v_mfma_f32_16x16x32_bf16 v[52:55], v[204:207], v[148:151], v[52:55]
	v_mfma_f32_16x16x32_bf16 v[48:51], v[214:217], v[148:151], v[48:51]
	v_mfma_f32_16x16x32_bf16 v[36:39], v[204:207], v[156:159], v[36:39]
	v_mfma_f32_16x16x32_bf16 v[32:35], v[214:217], v[156:159], v[32:35]
	v_mfma_f32_16x16x32_bf16 v[20:23], v[204:207], v[174:177], v[20:23]
	v_mfma_f32_16x16x32_bf16 v[16:19], v[214:217], v[174:177], v[16:19]
	v_mfma_f32_16x16x32_bf16 v[4:7], v[204:207], v[186:189], v[4:7]
	v_mfma_f32_16x16x32_bf16 v[0:3], v[214:217], v[186:189], v[0:3]
	s_add_i32 s43, 0, 0x18000
	s_barrier
	ds_read_b128 v[128:131], v220 offset:32768
	ds_read_b128 v[132:135], v220 offset:33792
	ds_read_b128 v[136:139], v220 offset:34816
	ds_read_b128 v[140:143], v220 offset:35840
	s_add_u32 s18, s18, 0x80000
	s_addc_u32 s19, s19, 0
	s_mov_b32 m0, s30
	ds_read_b128 v[144:147], v185 offset:32768
	ds_read_b128 v[148:151], v185 offset:33792
	ds_read_b128 v[152:155], v185 offset:34816
	ds_read_b128 v[156:159], v185 offset:35840
	ds_read_b128 v[170:173], v185 offset:36864
	ds_read_b128 v[174:177], v185 offset:37888
	ds_read_b128 v[178:181], v185 offset:38912
	ds_read_b128 v[186:189], v185 offset:39936
	global_load_lds_dwordx4 v160, s[18:19]
	s_mov_b32 m0, s31
	s_nop 0
	global_load_lds_dwordx4 v162, s[18:19]
	s_waitcnt lgkmcnt(8)
	s_waitcnt lgkmcnt(0)
	s_barrier
	v_mfma_f32_16x16x32_bf16 v[124:127], v[128:131], v[144:147], v[124:127]
	v_mfma_f32_16x16x32_bf16 v[120:123], v[136:139], v[144:147], v[120:123]
	v_mfma_f32_16x16x32_bf16 v[108:111], v[128:131], v[152:155], v[108:111]
	v_mfma_f32_16x16x32_bf16 v[104:107], v[136:139], v[152:155], v[104:107]
	v_mfma_f32_16x16x32_bf16 v[92:95], v[128:131], v[170:173], v[92:95]
	v_mfma_f32_16x16x32_bf16 v[88:91], v[136:139], v[170:173], v[88:91]
	v_mfma_f32_16x16x32_bf16 v[76:79], v[128:131], v[178:181], v[76:79]
	v_mfma_f32_16x16x32_bf16 v[72:75], v[136:139], v[178:181], v[72:75]
	v_mfma_f32_16x16x32_bf16 v[124:127], v[132:135], v[148:151], v[124:127]
	v_mfma_f32_16x16x32_bf16 v[120:123], v[140:143], v[148:151], v[120:123]
	v_mfma_f32_16x16x32_bf16 v[108:111], v[132:135], v[156:159], v[108:111]
	v_mfma_f32_16x16x32_bf16 v[104:107], v[140:143], v[156:159], v[104:107]
	v_mfma_f32_16x16x32_bf16 v[92:95], v[132:135], v[174:177], v[92:95]
	v_mfma_f32_16x16x32_bf16 v[88:91], v[140:143], v[174:177], v[88:91]
	v_mfma_f32_16x16x32_bf16 v[76:79], v[132:135], v[186:189], v[76:79]
	v_mfma_f32_16x16x32_bf16 v[72:75], v[140:143], v[186:189], v[72:75]
	s_barrier
	s_add_i32 s18, 0, 0x1c000
	s_add_i32 s19, s43, s27
	s_add_i32 m0, s19, 0xffffff80
	ds_read_b128 v[196:199], v220 offset:49152
	ds_read_b128 v[204:207], v220 offset:50176
	ds_read_b128 v[208:211], v220 offset:51200
	ds_read_b128 v[214:217], v220 offset:52224
	global_load_lds_dwordx4 v192, s[16:17] offset:128
	s_add_i32 m0, s19, 0x1f80
	s_nop 0
	global_load_lds_dwordx4 v164, s[16:17] offset:128
	s_waitcnt lgkmcnt(0)
	s_barrier
	v_mfma_f32_16x16x32_bf16 v[116:119], v[196:199], v[144:147], v[116:119]
	v_mfma_f32_16x16x32_bf16 v[112:115], v[208:211], v[144:147], v[112:115]
	v_mfma_f32_16x16x32_bf16 v[100:103], v[196:199], v[152:155], v[100:103]
	v_mfma_f32_16x16x32_bf16 v[96:99], v[208:211], v[152:155], v[96:99]
	v_mfma_f32_16x16x32_bf16 v[84:87], v[196:199], v[170:173], v[84:87]
	v_mfma_f32_16x16x32_bf16 v[80:83], v[208:211], v[170:173], v[80:83]
	v_mfma_f32_16x16x32_bf16 v[68:71], v[196:199], v[178:181], v[68:71]
	v_mfma_f32_16x16x32_bf16 v[64:67], v[208:211], v[178:181], v[64:67]
	v_mfma_f32_16x16x32_bf16 v[116:119], v[204:207], v[148:151], v[116:119]
	v_mfma_f32_16x16x32_bf16 v[112:115], v[214:217], v[148:151], v[112:115]
	v_mfma_f32_16x16x32_bf16 v[100:103], v[204:207], v[156:159], v[100:103]
	v_mfma_f32_16x16x32_bf16 v[96:99], v[214:217], v[156:159], v[96:99]
	v_mfma_f32_16x16x32_bf16 v[84:87], v[204:207], v[174:177], v[84:87]
	v_mfma_f32_16x16x32_bf16 v[80:83], v[214:217], v[174:177], v[80:83]
	v_mfma_f32_16x16x32_bf16 v[68:71], v[204:207], v[186:189], v[68:71]
	v_mfma_f32_16x16x32_bf16 v[64:67], v[214:217], v[186:189], v[64:67]
	s_mov_b32 m0, s35
	s_barrier
	ds_read_b128 v[144:147], v185 offset:49152
	ds_read_b128 v[148:151], v185 offset:50176
	ds_read_b128 v[152:155], v185 offset:51200
	ds_read_b128 v[156:159], v185 offset:52224
	ds_read_b128 v[170:173], v185 offset:53248
	ds_read_b128 v[174:177], v185 offset:54272
	ds_read_b128 v[178:181], v185 offset:55296
	ds_read_b128 v[186:189], v185 offset:56320
	global_load_lds_dwordx4 v160, s[48:49]
	s_mov_b32 m0, s36
	s_nop 0
	global_load_lds_dwordx4 v162, s[48:49]
	s_waitcnt lgkmcnt(0)
	s_barrier
	v_mfma_f32_16x16x32_bf16 v[60:63], v[128:131], v[144:147], v[60:63]
	v_mfma_f32_16x16x32_bf16 v[56:59], v[136:139], v[144:147], v[56:59]
	v_mfma_f32_16x16x32_bf16 v[44:47], v[128:131], v[152:155], v[44:47]
	v_mfma_f32_16x16x32_bf16 v[40:43], v[136:139], v[152:155], v[40:43]
	v_mfma_f32_16x16x32_bf16 v[28:31], v[128:131], v[170:173], v[28:31]
	v_mfma_f32_16x16x32_bf16 v[24:27], v[136:139], v[170:173], v[24:27]
	v_mfma_f32_16x16x32_bf16 v[12:15], v[128:131], v[178:181], v[12:15]
	v_mfma_f32_16x16x32_bf16 v[8:11], v[136:139], v[178:181], v[8:11]
	v_mfma_f32_16x16x32_bf16 v[60:63], v[132:135], v[148:151], v[60:63]
	v_mfma_f32_16x16x32_bf16 v[56:59], v[140:143], v[148:151], v[56:59]
	v_mfma_f32_16x16x32_bf16 v[44:47], v[132:135], v[156:159], v[44:47]
	v_mfma_f32_16x16x32_bf16 v[40:43], v[140:143], v[156:159], v[40:43]
	v_mfma_f32_16x16x32_bf16 v[28:31], v[132:135], v[174:177], v[28:31]
	v_mfma_f32_16x16x32_bf16 v[24:27], v[140:143], v[174:177], v[24:27]
	v_mfma_f32_16x16x32_bf16 v[12:15], v[132:135], v[186:189], v[12:15]
	v_mfma_f32_16x16x32_bf16 v[8:11], v[140:143], v[186:189], v[8:11]
	s_barrier
	s_add_u32 s16, s16, 0x80080
	s_addc_u32 s17, s17, 0
	s_add_i32 s18, s18, s27
	s_mov_b32 m0, s18
	s_nop 0
	global_load_lds_dwordx4 v192, s[16:17]
	s_add_i32 m0, s18, 0x2000
	s_nop 0
	global_load_lds_dwordx4 v164, s[16:17]
	s_waitcnt vmcnt(6)
	s_barrier
	v_mfma_f32_16x16x32_bf16 v[52:55], v[196:199], v[144:147], v[52:55]
	v_mfma_f32_16x16x32_bf16 v[48:51], v[208:211], v[144:147], v[48:51]
	v_mfma_f32_16x16x32_bf16 v[36:39], v[196:199], v[152:155], v[36:39]
	v_mfma_f32_16x16x32_bf16 v[32:35], v[208:211], v[152:155], v[32:35]
	v_mfma_f32_16x16x32_bf16 v[20:23], v[196:199], v[170:173], v[20:23]
	v_mfma_f32_16x16x32_bf16 v[16:19], v[208:211], v[170:173], v[16:19]
	v_mfma_f32_16x16x32_bf16 v[4:7], v[196:199], v[178:181], v[4:7]
	v_mfma_f32_16x16x32_bf16 v[0:3], v[208:211], v[178:181], v[0:3]
	v_mfma_f32_16x16x32_bf16 v[52:55], v[204:207], v[148:151], v[52:55]
	v_mfma_f32_16x16x32_bf16 v[48:51], v[214:217], v[148:151], v[48:51]
	v_mfma_f32_16x16x32_bf16 v[36:39], v[204:207], v[156:159], v[36:39]
	v_mfma_f32_16x16x32_bf16 v[32:35], v[214:217], v[156:159], v[32:35]
	v_mfma_f32_16x16x32_bf16 v[20:23], v[204:207], v[174:177], v[20:23]
	v_mfma_f32_16x16x32_bf16 v[16:19], v[214:217], v[174:177], v[16:19]
	v_mfma_f32_16x16x32_bf16 v[4:7], v[204:207], v[186:189], v[4:7]
	v_mfma_f32_16x16x32_bf16 v[0:3], v[214:217], v[186:189], v[0:3]
	s_add_i32 s42, s42, 2
	s_add_u32 s14, s14, 0x100
	s_addc_u32 s15, s15, 0
	s_add_u32 s40, s40, 0x100
	s_addc_u32 s41, s41, 0
	s_cmp_gt_u32 s42, 29
	s_barrier
	s_cbranch_scc0 .LBB0_87
	v_lshl_or_b32 v128, s13, 8, v184
	v_lshl_add_u32 v172, s12, 8, v182
	v_ashrrev_i32_e32 v129, 31, v128
	v_lshlrev_b64 v[170:171], 1, v[128:129]
	v_ashrrev_i32_e32 v173, 31, v172
	v_lshl_add_u64 v[174:175], s[2:3], 0, v[170:171]
	v_lshlrev_b64 v[128:129], 13, v[172:173]
	v_lshl_add_u64 v[130:131], v[174:175], 0, v[128:129]
	global_load_dwordx4 v[186:189], v[130:131], off
	global_load_dwordx4 v[196:199], v[130:131], off offset:256
	s_lshl_b32 s5, s13, 1
	v_mul_f32_e32 v133, 0xbfb8aa3b, v124
	v_mul_f32_e32 v135, 0xbfb8aa3b, v125
	v_mul_f32_e32 v137, 0xbfb8aa3b, v126
	v_mul_f32_e32 v138, 0xbfb8aa3b, v127
	v_mul_f32_e32 v139, 0xbfb8aa3b, v120
	v_mul_f32_e32 v140, 0xbfb8aa3b, v121
	s_and_b32 s12, s5, -4
	v_or_b32_e32 v132, 16, v172
	v_or_b32_e32 v136, 48, v172
	v_exp_f32_e32 v148, v133
	v_exp_f32_e32 v149, v135
	v_exp_f32_e32 v150, v137
	v_exp_f32_e32 v151, v138
	v_exp_f32_e32 v204, v139
	v_exp_f32_e32 v205, v140
	s_ashr_i32 s13, s12, 31
	v_or_b32_e32 v134, 32, v172
	v_ashrrev_i32_e32 v133, 31, v132
	v_ashrrev_i32_e32 v137, 31, v136
	s_lshl_b64 s[12:13], s[12:13], 2
	v_mul_f32_e32 v141, 0xbfb8aa3b, v122
	v_ashrrev_i32_e32 v135, 31, v134
	v_lshlrev_b64 v[180:181], 13, v[132:133]
	v_lshlrev_b64 v[176:177], 13, v[136:137]
	s_add_u32 s12, s33, s12
	v_exp_f32_e32 v212, v141
	v_lshlrev_b64 v[138:139], 7, v[172:173]
	v_lshlrev_b64 v[140:141], 7, v[132:133]
	v_lshlrev_b64 v[142:143], 7, v[134:135]
	v_lshlrev_b64 v[178:179], 13, v[134:135]
	v_lshlrev_b64 v[144:145], 7, v[136:137]
	v_lshl_add_u64 v[128:129], s[2:3], 0, v[128:129]
	v_lshl_add_u64 v[130:131], v[174:175], 0, v[180:181]
	v_lshl_add_u64 v[136:137], v[174:175], 0, v[176:177]
	s_addc_u32 s13, s34, s13
	v_lshl_add_u64 v[146:147], v[174:175], 0, v[178:179]
	v_lshl_add_u64 v[190:191], v[128:129], 0, v[170:171]
	global_load_dwordx4 v[156:159], v[130:131], off
	global_load_dwordx4 v[152:155], v[130:131], off offset:256
	global_load_dwordx4 v[132:135], v[136:137], off
	s_nop 0
	global_load_dwordx4 v[128:131], v[136:137], off offset:256
	v_add_f32_e32 v148, 1.0, v148
	v_add_f32_e32 v149, 1.0, v149
	v_add_f32_e32 v150, 1.0, v150
	v_add_f32_e32 v151, 1.0, v151
	v_add_f32_e32 v173, 1.0, v204
	v_add_f32_e32 v204, 1.0, v205
	v_lshl_add_u64 v[136:137], s[12:13], 0, v[138:139]
	v_lshl_add_u64 v[138:139], s[12:13], 0, v[140:141]
	v_lshl_add_u64 v[140:141], s[12:13], 0, v[142:143]
	v_lshl_add_u64 v[144:145], s[12:13], 0, v[144:145]
	v_rcp_f32_e32 v214, v148
	v_rcp_f32_e32 v215, v149
	v_rcp_f32_e32 v216, v150
	v_rcp_f32_e32 v217, v151
	v_rcp_f32_e32 v218, v204
	global_load_dwordx4 v[204:207], v[136:137], off
	global_load_dwordx4 v[208:211], v[138:139], off
	s_nop 0
	global_load_dwordx4 v[136:139], v[140:141], off
	global_load_dwordx4 v[148:151], v[146:147], off
	s_nop 0
	global_load_dwordx4 v[140:143], v[146:147], off offset:256
	s_nop 0
	global_load_dwordx4 v[144:147], v[144:145], off
	v_rcp_f32_e32 v173, v173
	v_mul_f32_e32 v124, v124, v214
	v_mul_f32_e32 v125, v125, v215
	v_mul_f32_e32 v127, v127, v217
	v_mul_f32_e32 v120, v120, v173
	v_mul_f32_e32 v121, v121, v218
	s_mov_b32 s14, 0x358637bd
	s_mov_b32 s5, 0x800000
	v_mul_f32_e32 v126, v126, v216
	s_mov_b64 s[16:17], s[10:11]
	s_mov_b32 s11, 0xc000
	s_waitcnt vmcnt(0)
	v_lshlrev_b32_e32 v173, 16, v186
	v_and_b32_e32 v186, 0xffff0000, v186
	v_lshlrev_b32_e32 v214, 16, v187
	v_and_b32_e32 v187, 0xffff0000, v187
	v_mul_f32_e32 v125, v125, v186
	v_mul_f32_e32 v127, v127, v187
	v_add_f32_e32 v186, 1.0, v212
	v_mul_f32_e32 v187, 0xbfb8aa3b, v123
	v_rcp_f32_e32 v186, v186
	v_exp_f32_e32 v187, v187
	v_mul_f32_e32 v124, v124, v173
	v_and_b32_e32 v173, 0xffff0000, v188
	v_mul_f32_e32 v122, v122, v186
	v_add_f32_e32 v186, 1.0, v187
	v_mul_f32_e32 v187, 0xbfb8aa3b, v116
	v_rcp_f32_e32 v186, v186
	v_exp_f32_e32 v187, v187
	v_mul_f32_e32 v121, v121, v173
	v_lshlrev_b32_e32 v173, 16, v189
	v_mul_f32_e32 v123, v123, v186
	v_add_f32_e32 v186, 1.0, v187
	v_mul_f32_e32 v187, 0xbfb8aa3b, v117
	v_rcp_f32_e32 v186, v186
	v_exp_f32_e32 v187, v187
	v_mul_f32_e32 v122, v122, v173
	v_and_b32_e32 v173, 0xffff0000, v189
	v_mul_f32_e32 v116, v116, v186
	v_add_f32_e32 v186, 1.0, v187
	v_mul_f32_e32 v187, 0xbfb8aa3b, v118
	v_rcp_f32_e32 v186, v186
	v_exp_f32_e32 v187, v187
	v_mul_f32_e32 v123, v123, v173
	v_lshlrev_b32_e32 v173, 16, v196
	v_mul_f32_e32 v173, v116, v173
	v_mul_f32_e32 v116, v117, v186
	v_add_f32_e32 v186, 1.0, v187
	v_mul_f32_e32 v187, 0xbfb8aa3b, v119
	v_rcp_f32_e32 v186, v186
	v_exp_f32_e32 v187, v187
	v_and_b32_e32 v117, 0xffff0000, v196
	v_lshlrev_b32_e32 v215, 16, v188
	v_mul_f32_e32 v188, v116, v117
	v_mul_f32_e32 v116, v118, v186
	v_add_f32_e32 v118, 1.0, v187
	v_rcp_f32_e32 v118, v118
	v_mul_f32_e32 v186, 0xbfb8aa3b, v112
	v_exp_f32_e32 v186, v186
	v_lshlrev_b32_e32 v117, 16, v197
	v_mul_f32_e32 v187, v116, v117
	v_mul_f32_e32 v116, v119, v118
	v_mul_f32_e32 v119, 0xbfb8aa3b, v113
	v_add_f32_e32 v118, 1.0, v186
	v_exp_f32_e32 v119, v119
	v_rcp_f32_e32 v118, v118
	v_and_b32_e32 v117, 0xffff0000, v197
	v_mul_f32_e32 v186, v116, v117
	v_add_f32_e32 v117, 1.0, v119
	v_mul_f32_e32 v112, v112, v118
	v_rcp_f32_e32 v117, v117
	v_mul_f32_e32 v118, 0xbfb8aa3b, v114
	v_exp_f32_e32 v118, v118
	v_lshlrev_b32_e32 v116, 16, v198
	v_mul_f32_e32 v189, v112, v116
	v_mul_f32_e32 v112, v113, v117
	v_and_b32_e32 v113, 0xffff0000, v198
	v_add_f32_e32 v116, 1.0, v118
	v_mul_f32_e32 v196, v112, v113
	v_mul_f32_e32 v112, 0xbfb8aa3b, v115
	v_rcp_f32_e32 v116, v116
	v_exp_f32_e32 v112, v112
	v_mov_b32_e32 v117, v206
	v_mov_b32_e32 v206, v211
	v_mul_f32_e32 v113, v114, v116
	v_lshlrev_b32_e32 v114, 16, v199
	v_add_f32_e32 v112, 1.0, v112
	v_mul_f32_e32 v197, v113, v114
	v_rcp_f32_e32 v114, v112
	v_mov_b32_e32 v112, v208
	v_mov_b32_e32 v113, v204
	v_mov_b32_e32 v204, v209
	v_pk_add_f32 v[112:113], v[112:113], v[204:205]
	v_mov_b32_e32 v116, v210
	v_pk_add_f32 v[112:113], v[116:117], v[112:113]
	v_mul_f32_e32 v114, v115, v114
	v_pk_add_f32 v[116:117], v[206:207], v[112:113]
	v_mov_b64_e32 v[112:113], s[14:15]
	s_mov_b32 s14, 0x3b000000
	v_pk_fma_f32 v[118:119], v[116:117], s[14:15], v[112:113] op_sel_hi:[1,0,0]
	v_and_b32_e32 v115, 0xffff0000, v199
	v_mul_f32_e32 v116, 0x4b800000, v119
	v_cmp_gt_f32_e32 vcc, s5, v119
	v_mul_f32_e32 v126, v126, v214
	v_mul_f32_e32 v120, v120, v215
	v_cndmask_b32_e32 v116, v119, v116, vcc
	v_rsq_f32_e32 v116, v116
	v_mul_f32_e32 v119, v114, v115
	v_mul_f32_e32 v114, 0x45800000, v116
	v_cndmask_b32_e32 v198, v116, v114, vcc
	v_mul_f32_e32 v114, v124, v198
	v_mul_f32_e32 v115, v125, v198
	v_cvt_pk_bf16_f32 v114, v114, v115
	v_mul_f32_e32 v115, v126, v198
	v_mul_f32_e32 v116, v127, v198
	v_cvt_pk_bf16_f32 v115, v115, v116
	v_mul_f32_e32 v116, v120, v198
	v_mul_f32_e32 v117, v121, v198
	v_cvt_pk_bf16_f32 v116, v116, v117
	v_mul_f32_e32 v117, v122, v198
	v_mul_f32_e32 v120, v123, v198
	v_cvt_pk_bf16_f32 v117, v117, v120
	global_store_dwordx4 v[190:191], v[114:117], off
	v_mul_f32_e32 v119, v119, v198
	v_cmp_gt_f32_e32 vcc, s5, v118
	v_mul_f32_e32 v114, v173, v198
	v_mul_f32_e32 v115, v188, v198
	v_cvt_pk_bf16_f32 v114, v114, v115
	v_mul_f32_e32 v115, v187, v198
	v_mul_f32_e32 v116, v186, v198
	v_cvt_pk_bf16_f32 v115, v115, v116
	v_mul_f32_e32 v116, v189, v198
	v_mul_f32_e32 v117, v196, v198
	v_cvt_pk_bf16_f32 v116, v116, v117
	v_mul_f32_e32 v117, v197, v198
	v_cvt_pk_bf16_f32 v117, v117, v119
	v_mul_f32_e32 v119, 0x4b800000, v118
	v_cndmask_b32_e32 v118, v118, v119, vcc
	global_store_dwordx4 v[190:191], v[114:117], off offset:256
	v_rsq_f32_e32 v118, v118
	v_mul_f32_e32 v123, 0xbfb8aa3b, v61
	v_mul_f32_e32 v114, 0xbfb8aa3b, v108
	v_exp_f32_e32 v116, v114
	v_mul_f32_e32 v114, 0x45800000, v118
	v_cndmask_b32_e32 v117, v118, v114, vcc
	v_mul_f32_e32 v118, 0xbfb8aa3b, v109
	v_add_f32_e32 v116, 1.0, v116
	v_rcp_f32_e32 v116, v116
	v_exp_f32_e32 v118, v118
	v_lshl_add_u64 v[114:115], s[2:3], 0, v[180:181]
	v_lshl_add_u64 v[114:115], v[114:115], 0, v[170:171]
	v_mul_f32_e32 v108, v108, v116
	v_lshlrev_b32_e32 v116, 16, v156
	v_mul_f32_e32 v108, v108, v116
	v_add_f32_e32 v116, 1.0, v118
	v_rcp_f32_e32 v116, v116
	v_mul_f32_e32 v118, 0xbfb8aa3b, v110
	v_exp_f32_e32 v118, v118
	v_mul_f32_e32 v108, v108, v117
	v_mul_f32_e32 v109, v109, v116
	v_and_b32_e32 v116, 0xffff0000, v156
	v_mul_f32_e32 v109, v109, v116
	v_add_f32_e32 v116, 1.0, v118
	v_mul_f32_e32 v118, 0xbfb8aa3b, v111
	v_rcp_f32_e32 v116, v116
	v_exp_f32_e32 v118, v118
	v_mul_f32_e32 v109, v109, v117
	v_cvt_pk_bf16_f32 v108, v108, v109
	v_mul_f32_e32 v109, v110, v116
	v_add_f32_e32 v110, 1.0, v118
	v_rcp_f32_e32 v110, v110
	v_lshlrev_b32_e32 v116, 16, v157
	v_mul_f32_e32 v109, v109, v116
	v_and_b32_e32 v116, 0xffff0000, v157
	v_mul_f32_e32 v110, v111, v110
	v_mul_f32_e32 v111, 0xbfb8aa3b, v104
	v_exp_f32_e32 v111, v111
	v_mul_f32_e32 v110, v110, v116
	v_mul_f32_e32 v109, v109, v117
	v_mul_f32_e32 v110, v110, v117
	v_add_f32_e32 v111, 1.0, v111
	v_cvt_pk_bf16_f32 v109, v109, v110
	v_mul_f32_e32 v110, 0xbfb8aa3b, v105
	v_rcp_f32_e32 v111, v111
	v_exp_f32_e32 v110, v110
	v_exp_f32_e32 v123, v123
	v_mul_f32_e32 v124, 0xbfb8aa3b, v62
	v_mul_f32_e32 v104, v104, v111
	v_lshlrev_b32_e32 v111, 16, v158
	v_add_f32_e32 v110, 1.0, v110
	v_mul_f32_e32 v104, v104, v111
	v_rcp_f32_e32 v110, v110
	v_mul_f32_e32 v111, 0xbfb8aa3b, v106
	v_exp_f32_e32 v111, v111
	v_mul_f32_e32 v104, v104, v117
	v_mul_f32_e32 v105, v105, v110
	v_and_b32_e32 v110, 0xffff0000, v158
	v_mul_f32_e32 v105, v105, v110
	v_add_f32_e32 v110, 1.0, v111
	v_rcp_f32_e32 v111, v110
	v_mul_f32_e32 v110, 0xbfb8aa3b, v107
	v_exp_f32_e32 v116, v110
	v_mul_f32_e32 v105, v105, v117
	v_cvt_pk_bf16_f32 v110, v104, v105
	v_mul_f32_e32 v104, v106, v111
	v_add_f32_e32 v105, 1.0, v116
	v_rcp_f32_e32 v105, v105
	v_lshlrev_b32_e32 v106, 16, v159
	v_mul_f32_e32 v104, v104, v106
	v_and_b32_e32 v106, 0xffff0000, v159
	v_mul_f32_e32 v105, v107, v105
	v_mul_f32_e32 v107, 0xbfb8aa3b, v100
	v_exp_f32_e32 v107, v107
	v_mul_f32_e32 v104, v104, v117
	v_mul_f32_e32 v105, v105, v106
	v_mul_f32_e32 v105, v105, v117
	v_cvt_pk_bf16_f32 v111, v104, v105
	v_add_f32_e32 v104, 1.0, v107
	v_rcp_f32_e32 v104, v104
	v_mul_f32_e32 v105, 0xbfb8aa3b, v101
	v_exp_f32_e32 v105, v105
	global_store_dwordx4 v[114:115], v[108:111], off
	v_mul_f32_e32 v100, v100, v104
	v_lshlrev_b32_e32 v104, 16, v152
	v_mul_f32_e32 v100, v100, v104
	v_add_f32_e32 v104, 1.0, v105
	v_rcp_f32_e32 v104, v104
	v_mul_f32_e32 v105, 0xbfb8aa3b, v102
	v_exp_f32_e32 v105, v105
	v_mul_f32_e32 v100, v100, v117
	v_mul_f32_e32 v101, v101, v104
	v_and_b32_e32 v104, 0xffff0000, v152
	v_mul_f32_e32 v101, v101, v104
	v_add_f32_e32 v104, 1.0, v105
	v_mul_f32_e32 v105, 0xbfb8aa3b, v103
	v_rcp_f32_e32 v104, v104
	v_exp_f32_e32 v105, v105
	v_mul_f32_e32 v101, v101, v117
	v_cvt_pk_bf16_f32 v100, v100, v101
	v_mul_f32_e32 v101, v102, v104
	v_add_f32_e32 v102, 1.0, v105
	v_rcp_f32_e32 v102, v102
	v_lshlrev_b32_e32 v104, 16, v153
	v_mul_f32_e32 v101, v101, v104
	v_and_b32_e32 v104, 0xffff0000, v153
	v_mul_f32_e32 v102, v103, v102
	v_mul_f32_e32 v103, 0xbfb8aa3b, v96
	v_exp_f32_e32 v103, v103
	v_mul_f32_e32 v102, v102, v104
	v_mul_f32_e32 v101, v101, v117
	v_mul_f32_e32 v102, v102, v117
	v_add_f32_e32 v103, 1.0, v103
	v_cvt_pk_bf16_f32 v101, v101, v102
	v_mul_f32_e32 v102, 0xbfb8aa3b, v97
	v_rcp_f32_e32 v103, v103
	v_exp_f32_e32 v102, v102
	v_add_f32_e32 v123, 1.0, v123
	v_rcp_f32_e32 v123, v123
	v_mul_f32_e32 v96, v96, v103
	v_lshlrev_b32_e32 v103, 16, v154
	v_add_f32_e32 v102, 1.0, v102
	v_mul_f32_e32 v96, v96, v103
	v_rcp_f32_e32 v102, v102
	v_mul_f32_e32 v103, 0xbfb8aa3b, v98
	v_exp_f32_e32 v103, v103
	v_mul_f32_e32 v96, v96, v117
	v_mul_f32_e32 v97, v97, v102
	v_and_b32_e32 v102, 0xffff0000, v154
	v_mul_f32_e32 v97, v97, v102
	v_add_f32_e32 v102, 1.0, v103
	v_rcp_f32_e32 v103, v102
	v_mul_f32_e32 v102, 0xbfb8aa3b, v99
	v_exp_f32_e32 v104, v102
	v_mul_f32_e32 v97, v97, v117
	v_cvt_pk_bf16_f32 v102, v96, v97
	v_mul_f32_e32 v96, v98, v103
	v_add_f32_e32 v97, 1.0, v104
	v_rcp_f32_e32 v97, v97
	v_lshlrev_b32_e32 v98, 16, v155
	v_mul_f32_e32 v96, v96, v98
	v_and_b32_e32 v98, 0xffff0000, v155
	v_mul_f32_e32 v97, v99, v97
	v_mul_f32_e32 v99, 0xbfb8aa3b, v93
	v_exp_f32_e32 v99, v99
	v_mul_f32_e32 v97, v97, v98
	v_mul_f32_e32 v96, v96, v117
	v_mul_f32_e32 v97, v97, v117
	v_cvt_pk_bf16_f32 v103, v96, v97
	global_store_dwordx4 v[114:115], v[100:103], off offset:256
	v_add_f32_e32 v99, 1.0, v99
	v_rcp_f32_e32 v99, v99
	v_mul_f32_e32 v100, 0xbfb8aa3b, v94
	v_exp_f32_e32 v100, v100
	v_mul_f32_e32 v98, 0xbfb8aa3b, v92
	v_mul_f32_e32 v93, v93, v99
	v_exp_f32_e32 v98, v98
	v_add_f32_e32 v99, 1.0, v100
	v_mul_f32_e32 v100, 0xbfb8aa3b, v95
	v_rcp_f32_e32 v99, v99
	v_exp_f32_e32 v100, v100
	v_add_f32_e32 v98, 1.0, v98
	v_rcp_f32_e32 v98, v98
	v_mul_f32_e32 v94, v94, v99
	v_add_f32_e32 v99, 1.0, v100
	v_mul_f32_e32 v100, 0xbfb8aa3b, v88
	v_rcp_f32_e32 v99, v99
	v_exp_f32_e32 v100, v100
	v_mul_f32_e32 v92, v92, v98
	v_lshlrev_b32_e32 v98, 16, v148
	v_mul_f32_e32 v95, v95, v99
	v_add_f32_e32 v99, 1.0, v100
	v_mul_f32_e32 v100, 0xbfb8aa3b, v89
	v_rcp_f32_e32 v99, v99
	v_exp_f32_e32 v100, v100
	v_mul_f32_e32 v92, v92, v98
	v_and_b32_e32 v98, 0xffff0000, v148
	v_mul_f32_e32 v88, v88, v99
	v_add_f32_e32 v99, 1.0, v100
	v_mul_f32_e32 v100, 0xbfb8aa3b, v90
	v_rcp_f32_e32 v99, v99
	v_exp_f32_e32 v100, v100
	v_mul_f32_e32 v93, v93, v98
	v_lshlrev_b32_e32 v98, 16, v149
	v_mul_f32_e32 v89, v89, v99
	v_add_f32_e32 v99, 1.0, v100
	v_mul_f32_e32 v100, 0xbfb8aa3b, v91
	v_rcp_f32_e32 v99, v99
	v_exp_f32_e32 v100, v100
	v_mul_f32_e32 v94, v94, v98
	v_and_b32_e32 v98, 0xffff0000, v149
	v_mul_f32_e32 v90, v90, v99
	v_add_f32_e32 v99, 1.0, v100
	v_mul_f32_e32 v100, 0xbfb8aa3b, v84
	v_rcp_f32_e32 v99, v99
	v_exp_f32_e32 v100, v100
	v_mul_f32_e32 v95, v95, v98
	v_lshlrev_b32_e32 v98, 16, v150
	v_mul_f32_e32 v91, v91, v99
	v_add_f32_e32 v99, 1.0, v100
	v_mul_f32_e32 v100, 0xbfb8aa3b, v85
	v_rcp_f32_e32 v99, v99
	v_exp_f32_e32 v100, v100
	v_mul_f32_e32 v88, v88, v98
	v_and_b32_e32 v98, 0xffff0000, v150
	v_mul_f32_e32 v84, v84, v99
	v_add_f32_e32 v99, 1.0, v100
	v_mul_f32_e32 v100, 0xbfb8aa3b, v86
	v_rcp_f32_e32 v99, v99
	v_exp_f32_e32 v100, v100
	v_mul_f32_e32 v89, v89, v98
	v_lshlrev_b32_e32 v98, 16, v151
	v_mul_f32_e32 v90, v90, v98
	v_and_b32_e32 v98, 0xffff0000, v151
	v_mul_f32_e32 v91, v91, v98
	v_lshlrev_b32_e32 v98, 16, v140
	v_mul_f32_e32 v98, v84, v98
	v_mul_f32_e32 v84, v85, v99
	v_add_f32_e32 v99, 1.0, v100
	v_mul_f32_e32 v100, 0xbfb8aa3b, v87
	v_rcp_f32_e32 v99, v99
	v_exp_f32_e32 v100, v100
	v_and_b32_e32 v85, 0xffff0000, v140
	v_mul_f32_e32 v101, v84, v85
	v_mul_f32_e32 v84, v86, v99
	v_add_f32_e32 v86, 1.0, v100
	v_rcp_f32_e32 v86, v86
	v_mul_f32_e32 v99, 0xbfb8aa3b, v80
	v_exp_f32_e32 v99, v99
	v_lshlrev_b32_e32 v85, 16, v141
	v_mul_f32_e32 v100, v84, v85
	v_mul_f32_e32 v84, v87, v86
	v_mul_f32_e32 v87, 0xbfb8aa3b, v81
	v_add_f32_e32 v86, 1.0, v99
	v_exp_f32_e32 v87, v87
	v_rcp_f32_e32 v86, v86
	v_and_b32_e32 v85, 0xffff0000, v141
	v_mul_f32_e32 v99, v84, v85
	v_add_f32_e32 v85, 1.0, v87
	v_mul_f32_e32 v80, v80, v86
	v_rcp_f32_e32 v85, v85
	v_mul_f32_e32 v86, 0xbfb8aa3b, v82
	v_exp_f32_e32 v86, v86
	v_lshlrev_b32_e32 v84, 16, v142
	v_mul_f32_e32 v87, v80, v84
	v_mul_f32_e32 v80, v81, v85
	v_and_b32_e32 v81, 0xffff0000, v142
	v_add_f32_e32 v84, 1.0, v86
	v_mul_f32_e32 v86, v80, v81
	v_mul_f32_e32 v80, 0xbfb8aa3b, v83
	v_rcp_f32_e32 v84, v84
	v_exp_f32_e32 v80, v80
	v_mov_b32_e32 v85, v138
	v_mov_b32_e32 v138, v147
	v_mul_f32_e32 v81, v82, v84
	v_lshlrev_b32_e32 v82, 16, v143
	v_add_f32_e32 v80, 1.0, v80
	v_mul_f32_e32 v102, v81, v82
	v_rcp_f32_e32 v82, v80
	v_mov_b32_e32 v80, v144
	v_mov_b32_e32 v81, v136
	v_mov_b32_e32 v136, v145
	v_pk_add_f32 v[80:81], v[80:81], v[136:137]
	v_mov_b32_e32 v84, v146
	v_pk_add_f32 v[80:81], v[84:85], v[80:81]
	v_lshl_add_u64 v[96:97], s[2:3], 0, v[178:179]
	v_pk_add_f32 v[80:81], v[138:139], v[80:81]
	v_lshl_add_u64 v[96:97], v[96:97], 0, v[170:171]
	v_pk_fma_f32 v[84:85], v[80:81], s[14:15], v[112:113] op_sel_hi:[1,0,0]
	v_mul_f32_e32 v81, v83, v82
	v_mul_f32_e32 v80, 0x4b800000, v85
	v_cmp_gt_f32_e32 vcc, s5, v85
	v_and_b32_e32 v82, 0xffff0000, v143
	v_exp_f32_e32 v124, v124
	v_cndmask_b32_e32 v80, v85, v80, vcc
	v_rsq_f32_e32 v80, v80
	v_mul_f32_e32 v85, v81, v82
	v_mul_f32_e32 v61, v61, v123
	v_mul_f32_e32 v123, 0xbfb8aa3b, v63
	v_mul_f32_e32 v81, 0x45800000, v80
	v_cndmask_b32_e32 v103, v80, v81, vcc
	v_mul_f32_e32 v80, v92, v103
	v_mul_f32_e32 v81, v93, v103
	v_cvt_pk_bf16_f32 v80, v80, v81
	v_mul_f32_e32 v81, v94, v103
	v_mul_f32_e32 v82, v95, v103
	v_cvt_pk_bf16_f32 v81, v81, v82
	v_mul_f32_e32 v82, v88, v103
	v_mul_f32_e32 v83, v89, v103
	v_cvt_pk_bf16_f32 v82, v82, v83
	v_mul_f32_e32 v83, v90, v103
	v_mul_f32_e32 v88, v91, v103
	v_cvt_pk_bf16_f32 v83, v83, v88
	global_store_dwordx4 v[96:97], v[80:83], off
	v_mul_f32_e32 v85, v85, v103
	v_cmp_gt_f32_e32 vcc, s5, v84
	v_mul_f32_e32 v80, v98, v103
	v_mul_f32_e32 v81, v101, v103
	v_cvt_pk_bf16_f32 v80, v80, v81
	v_mul_f32_e32 v81, v100, v103
	v_mul_f32_e32 v82, v99, v103
	v_cvt_pk_bf16_f32 v81, v81, v82
	v_mul_f32_e32 v82, v87, v103
	v_mul_f32_e32 v83, v86, v103
	v_cvt_pk_bf16_f32 v82, v82, v83
	v_mul_f32_e32 v83, v102, v103
	v_cvt_pk_bf16_f32 v83, v83, v85
	v_mul_f32_e32 v85, 0x4b800000, v84
	v_cndmask_b32_e32 v84, v84, v85, vcc
	global_store_dwordx4 v[96:97], v[80:83], off offset:256
	v_rsq_f32_e32 v84, v84
	v_exp_f32_e32 v123, v123
	v_mul_f32_e32 v80, 0xbfb8aa3b, v76
	v_exp_f32_e32 v82, v80
	v_mul_f32_e32 v80, 0x45800000, v84
	v_cndmask_b32_e32 v83, v84, v80, vcc
	v_mul_f32_e32 v84, 0xbfb8aa3b, v77
	v_add_f32_e32 v82, 1.0, v82
	v_rcp_f32_e32 v82, v82
	v_exp_f32_e32 v84, v84
	v_lshl_add_u64 v[80:81], s[2:3], 0, v[176:177]
	v_lshl_add_u64 v[80:81], v[80:81], 0, v[170:171]
	v_mul_f32_e32 v76, v76, v82
	v_lshlrev_b32_e32 v82, 16, v132
	v_mul_f32_e32 v76, v76, v82
	v_add_f32_e32 v82, 1.0, v84
	v_rcp_f32_e32 v82, v82
	v_mul_f32_e32 v84, 0xbfb8aa3b, v78
	v_exp_f32_e32 v84, v84
	v_mul_f32_e32 v76, v76, v83
	v_mul_f32_e32 v77, v77, v82
	v_and_b32_e32 v82, 0xffff0000, v132
	v_mul_f32_e32 v77, v77, v82
	v_add_f32_e32 v82, 1.0, v84
	v_mul_f32_e32 v84, 0xbfb8aa3b, v79
	v_rcp_f32_e32 v82, v82
	v_exp_f32_e32 v84, v84
	v_mul_f32_e32 v77, v77, v83
	v_cvt_pk_bf16_f32 v76, v76, v77
	v_mul_f32_e32 v77, v78, v82
	v_add_f32_e32 v78, 1.0, v84
	v_rcp_f32_e32 v78, v78
	v_lshlrev_b32_e32 v82, 16, v133
	v_mul_f32_e32 v77, v77, v82
	v_and_b32_e32 v82, 0xffff0000, v133
	v_mul_f32_e32 v78, v79, v78
	v_mul_f32_e32 v79, 0xbfb8aa3b, v72
	v_exp_f32_e32 v79, v79
	v_mul_f32_e32 v78, v78, v82
	v_mul_f32_e32 v77, v77, v83
	v_mul_f32_e32 v78, v78, v83
	v_add_f32_e32 v79, 1.0, v79
	v_cvt_pk_bf16_f32 v77, v77, v78
	v_mul_f32_e32 v78, 0xbfb8aa3b, v73
	v_rcp_f32_e32 v79, v79
	v_exp_f32_e32 v78, v78
	v_mul_f32_e32 v72, v72, v79
	v_lshlrev_b32_e32 v79, 16, v134
	v_add_f32_e32 v78, 1.0, v78
	v_mul_f32_e32 v72, v72, v79
	v_rcp_f32_e32 v78, v78
	v_mul_f32_e32 v79, 0xbfb8aa3b, v74
	v_exp_f32_e32 v79, v79
	v_mul_f32_e32 v72, v72, v83
	v_mul_f32_e32 v73, v73, v78
	v_and_b32_e32 v78, 0xffff0000, v134
	v_mul_f32_e32 v73, v73, v78
	v_add_f32_e32 v78, 1.0, v79
	v_rcp_f32_e32 v79, v78
	v_mul_f32_e32 v78, 0xbfb8aa3b, v75
	v_exp_f32_e32 v82, v78
	v_mul_f32_e32 v73, v73, v83
	v_cvt_pk_bf16_f32 v78, v72, v73
	v_mul_f32_e32 v72, v74, v79
	v_add_f32_e32 v73, 1.0, v82
	v_rcp_f32_e32 v73, v73
	v_lshlrev_b32_e32 v74, 16, v135
	v_mul_f32_e32 v72, v72, v74
	v_and_b32_e32 v74, 0xffff0000, v135
	v_mul_f32_e32 v73, v75, v73
	v_mul_f32_e32 v75, 0xbfb8aa3b, v68
	v_exp_f32_e32 v75, v75
	v_mul_f32_e32 v72, v72, v83
	v_mul_f32_e32 v73, v73, v74
	v_mul_f32_e32 v73, v73, v83
	v_cvt_pk_bf16_f32 v79, v72, v73
	v_add_f32_e32 v72, 1.0, v75
	v_rcp_f32_e32 v72, v72
	v_mul_f32_e32 v73, 0xbfb8aa3b, v69
	v_exp_f32_e32 v73, v73
	global_store_dwordx4 v[80:81], v[76:79], off
	v_mul_f32_e32 v68, v68, v72
	v_lshlrev_b32_e32 v72, 16, v128
	v_mul_f32_e32 v68, v68, v72
	v_add_f32_e32 v72, 1.0, v73
	v_rcp_f32_e32 v72, v72
	v_mul_f32_e32 v73, 0xbfb8aa3b, v70
	v_exp_f32_e32 v73, v73
	v_mul_f32_e32 v68, v68, v83
	v_mul_f32_e32 v69, v69, v72
	v_and_b32_e32 v72, 0xffff0000, v128
	v_mul_f32_e32 v69, v69, v72
	v_add_f32_e32 v72, 1.0, v73
	v_mul_f32_e32 v73, 0xbfb8aa3b, v71
	v_rcp_f32_e32 v72, v72
	v_exp_f32_e32 v73, v73
	v_mul_f32_e32 v69, v69, v83
	v_cvt_pk_bf16_f32 v68, v68, v69
	v_mul_f32_e32 v69, v70, v72
	v_add_f32_e32 v70, 1.0, v73
	v_rcp_f32_e32 v70, v70
	v_lshlrev_b32_e32 v72, 16, v129
	v_mul_f32_e32 v69, v69, v72
	v_and_b32_e32 v72, 0xffff0000, v129
	v_mul_f32_e32 v70, v71, v70
	v_mul_f32_e32 v71, 0xbfb8aa3b, v64
	v_exp_f32_e32 v71, v71
	v_mul_f32_e32 v70, v70, v72
	v_mul_f32_e32 v69, v69, v83
	v_mul_f32_e32 v70, v70, v83
	v_add_f32_e32 v71, 1.0, v71
	v_cvt_pk_bf16_f32 v69, v69, v70
	v_mul_f32_e32 v70, 0xbfb8aa3b, v65
	v_rcp_f32_e32 v71, v71
	v_exp_f32_e32 v70, v70
	v_mul_f32_e32 v64, v64, v71
	v_lshlrev_b32_e32 v71, 16, v130
	v_add_f32_e32 v70, 1.0, v70
	v_mul_f32_e32 v64, v64, v71
	v_rcp_f32_e32 v70, v70
	v_mul_f32_e32 v71, 0xbfb8aa3b, v66
	v_exp_f32_e32 v71, v71
	v_mul_f32_e32 v64, v64, v83
	v_mul_f32_e32 v65, v65, v70
	v_and_b32_e32 v70, 0xffff0000, v130
	v_mul_f32_e32 v65, v65, v70
	v_add_f32_e32 v70, 1.0, v71
	v_rcp_f32_e32 v71, v70
	v_mul_f32_e32 v70, 0xbfb8aa3b, v67
	v_exp_f32_e32 v72, v70
	v_mul_f32_e32 v65, v65, v83
	v_cvt_pk_bf16_f32 v70, v64, v65
	v_mul_f32_e32 v64, v66, v71
	v_add_f32_e32 v65, 1.0, v72
	v_rcp_f32_e32 v65, v65
	v_lshlrev_b32_e32 v66, 16, v131
	v_mul_f32_e32 v64, v64, v66
	v_and_b32_e32 v66, 0xffff0000, v131
	v_mul_f32_e32 v65, v67, v65
	v_mul_f32_e32 v64, v64, v83
	v_mul_f32_e32 v65, v65, v66
	v_mul_f32_e32 v65, v65, v83
	v_cvt_pk_bf16_f32 v71, v64, v65
	v_add_u32_e32 v64, 0x80, v172
	v_ashrrev_i32_e32 v65, 31, v64
	v_lshlrev_b64 v[110:111], 13, v[64:65]
	v_lshl_add_u64 v[66:67], v[174:175], 0, v[110:111]
	global_load_dwordx4 v[102:105], v[66:67], off
	v_lshlrev_b64 v[64:65], 7, v[64:65]
	global_store_dwordx4 v[80:81], v[68:71], off offset:256
	v_lshl_add_u64 v[64:65], s[12:13], 0, v[64:65]
	global_load_dwordx4 v[106:109], v[64:65], off
	v_add_u32_e32 v64, 0x90, v172
	v_ashrrev_i32_e32 v65, 31, v64
	v_lshlrev_b64 v[68:69], 7, v[64:65]
	v_lshl_add_u64 v[68:69], s[12:13], 0, v[68:69]
	global_load_dwordx4 v[114:117], v[66:67], off offset:256
	global_load_dwordx4 v[118:121], v[68:69], off
	v_lshlrev_b64 v[100:101], 13, v[64:65]
	v_lshl_add_u64 v[64:65], v[174:175], 0, v[100:101]
	global_load_dwordx4 v[92:95], v[64:65], off
	global_load_dwordx4 v[88:91], v[64:65], off offset:256
	v_add_u32_e32 v64, 0xa0, v172
	v_ashrrev_i32_e32 v65, 31, v64
	v_lshlrev_b64 v[66:67], 7, v[64:65]
	v_lshl_add_u64 v[66:67], s[12:13], 0, v[66:67]
	v_lshlrev_b64 v[98:99], 13, v[64:65]
	v_lshl_add_u64 v[64:65], v[174:175], 0, v[98:99]
	global_load_dwordx4 v[72:75], v[66:67], off
	global_load_dwordx4 v[84:87], v[64:65], off
	v_add_u32_e32 v66, 0xb0, v172
	v_ashrrev_i32_e32 v67, 31, v66
	v_lshlrev_b64 v[68:69], 7, v[66:67]
	v_lshlrev_b64 v[96:97], 13, v[66:67]
	v_mul_f32_e32 v66, 0xbfb8aa3b, v60
	v_exp_f32_e32 v122, v66
	v_lshl_add_u64 v[68:69], s[12:13], 0, v[68:69]
	global_load_dwordx4 v[76:79], v[64:65], off offset:256
	global_load_dwordx4 v[80:83], v[68:69], off
	v_lshl_add_u64 v[64:65], v[174:175], 0, v[96:97]
	v_add_f32_e32 v122, 1.0, v122
	v_rcp_f32_e32 v122, v122
	global_load_dwordx4 v[68:71], v[64:65], off
	s_nop 0
	global_load_dwordx4 v[64:67], v[64:65], off offset:256
	v_lshl_add_u64 v[110:111], s[2:3], 0, v[110:111]
	v_lshl_add_u64 v[110:111], v[110:111], 0, v[170:171]
	v_mul_f32_e32 v60, v60, v122
	s_mov_b32 s13, s4
	s_mov_b32 s12, s6
	s_waitcnt vmcnt(0)
	v_lshlrev_b32_e32 v122, 16, v102
	v_mul_f32_e32 v60, v60, v122
	v_add_f32_e32 v122, 1.0, v124
	v_rcp_f32_e32 v122, v122
	v_and_b32_e32 v102, 0xffff0000, v102
	v_mul_f32_e32 v61, v61, v102
	v_lshlrev_b32_e32 v102, 16, v103
	v_mul_f32_e32 v62, v62, v122
	v_add_f32_e32 v122, 1.0, v123
	v_mul_f32_e32 v123, 0xbfb8aa3b, v56
	v_rcp_f32_e32 v122, v122
	v_exp_f32_e32 v123, v123
	v_mul_f32_e32 v62, v62, v102
	v_and_b32_e32 v102, 0xffff0000, v103
	v_mul_f32_e32 v63, v63, v122
	v_add_f32_e32 v103, 1.0, v123
	v_mul_f32_e32 v122, 0xbfb8aa3b, v57
	v_rcp_f32_e32 v103, v103
	v_exp_f32_e32 v122, v122
	v_mul_f32_e32 v63, v63, v102
	v_lshlrev_b32_e32 v102, 16, v104
	v_mul_f32_e32 v56, v56, v103
	v_add_f32_e32 v103, 1.0, v122
	v_mul_f32_e32 v122, 0xbfb8aa3b, v58
	v_rcp_f32_e32 v103, v103
	v_exp_f32_e32 v122, v122
	v_mul_f32_e32 v56, v56, v102
	v_and_b32_e32 v102, 0xffff0000, v104
	v_mul_f32_e32 v57, v57, v103
	v_add_f32_e32 v103, 1.0, v122
	v_mul_f32_e32 v104, 0xbfb8aa3b, v59
	v_rcp_f32_e32 v103, v103
	v_exp_f32_e32 v104, v104
	v_mul_f32_e32 v57, v57, v102
	v_lshlrev_b32_e32 v102, 16, v105
	v_mul_f32_e32 v58, v58, v103
	v_add_f32_e32 v103, 1.0, v104
	v_mul_f32_e32 v104, 0xbfb8aa3b, v52
	v_rcp_f32_e32 v103, v103
	v_exp_f32_e32 v104, v104
	v_mul_f32_e32 v58, v58, v102
	v_and_b32_e32 v102, 0xffff0000, v105
	v_mul_f32_e32 v59, v59, v103
	v_add_f32_e32 v103, 1.0, v104
	v_mul_f32_e32 v104, 0xbfb8aa3b, v53
	v_rcp_f32_e32 v103, v103
	v_exp_f32_e32 v104, v104
	v_mul_f32_e32 v59, v59, v102
	v_lshlrev_b32_e32 v102, 16, v114
	v_mul_f32_e32 v52, v52, v103
	v_add_f32_e32 v103, 1.0, v104
	v_mul_f32_e32 v104, 0xbfb8aa3b, v54
	v_rcp_f32_e32 v103, v103
	v_exp_f32_e32 v104, v104
	v_mul_f32_e32 v102, v52, v102
	v_mul_f32_e32 v52, v53, v103
	v_add_f32_e32 v103, 1.0, v104
	v_mul_f32_e32 v104, 0xbfb8aa3b, v55
	v_rcp_f32_e32 v103, v103
	v_exp_f32_e32 v104, v104
	v_and_b32_e32 v53, 0xffff0000, v114
	v_mul_f32_e32 v105, v52, v53
	v_mul_f32_e32 v52, v54, v103
	v_add_f32_e32 v54, 1.0, v104
	v_rcp_f32_e32 v54, v54
	v_mul_f32_e32 v103, 0xbfb8aa3b, v48
	v_exp_f32_e32 v103, v103
	v_lshlrev_b32_e32 v53, 16, v115
	v_mul_f32_e32 v104, v52, v53
	v_mul_f32_e32 v52, v55, v54
	v_mul_f32_e32 v55, 0xbfb8aa3b, v49
	v_add_f32_e32 v54, 1.0, v103
	v_exp_f32_e32 v55, v55
	v_rcp_f32_e32 v54, v54
	v_and_b32_e32 v53, 0xffff0000, v115
	v_mul_f32_e32 v103, v52, v53
	v_add_f32_e32 v53, 1.0, v55
	v_mul_f32_e32 v48, v48, v54
	v_rcp_f32_e32 v53, v53
	v_mul_f32_e32 v54, 0xbfb8aa3b, v50
	v_exp_f32_e32 v54, v54
	v_lshlrev_b32_e32 v52, 16, v116
	v_mul_f32_e32 v55, v48, v52
	v_mul_f32_e32 v48, v49, v53
	v_and_b32_e32 v49, 0xffff0000, v116
	v_add_f32_e32 v52, 1.0, v54
	v_mul_f32_e32 v54, v48, v49
	v_mul_f32_e32 v48, 0xbfb8aa3b, v51
	v_rcp_f32_e32 v52, v52
	v_exp_f32_e32 v48, v48
	v_mov_b32_e32 v53, v108
	v_mov_b32_e32 v108, v121
	v_mul_f32_e32 v49, v50, v52
	v_lshlrev_b32_e32 v50, 16, v117
	v_add_f32_e32 v48, 1.0, v48
	v_mul_f32_e32 v114, v49, v50
	v_rcp_f32_e32 v50, v48
	v_mov_b32_e32 v48, v118
	v_mov_b32_e32 v49, v106
	v_mov_b32_e32 v106, v119
	v_pk_add_f32 v[48:49], v[48:49], v[106:107]
	v_mov_b32_e32 v52, v120
	v_pk_add_f32 v[48:49], v[52:53], v[48:49]
	s_nop 0
	v_pk_add_f32 v[48:49], v[108:109], v[48:49]
	s_nop 0
	v_pk_fma_f32 v[52:53], v[48:49], s[14:15], v[112:113] op_sel_hi:[1,0,0]
	v_mul_f32_e32 v49, v51, v50
	v_mul_f32_e32 v48, 0x4b800000, v53
	v_cmp_gt_f32_e32 vcc, s5, v53
	v_and_b32_e32 v50, 0xffff0000, v117
	s_nop 0
	v_cndmask_b32_e32 v48, v53, v48, vcc
	v_rsq_f32_e32 v48, v48
	v_mul_f32_e32 v53, v49, v50
	v_mul_f32_e32 v49, 0x45800000, v48
	v_cndmask_b32_e32 v106, v48, v49, vcc
	v_mul_f32_e32 v48, v60, v106
	v_mul_f32_e32 v49, v61, v106
	v_cvt_pk_bf16_f32 v48, v48, v49
	v_mul_f32_e32 v49, v62, v106
	v_mul_f32_e32 v50, v63, v106
	v_cvt_pk_bf16_f32 v49, v49, v50
	v_mul_f32_e32 v50, v56, v106
	v_mul_f32_e32 v51, v57, v106
	v_cvt_pk_bf16_f32 v50, v50, v51
	v_mul_f32_e32 v51, v58, v106
	v_mul_f32_e32 v56, v59, v106
	v_cvt_pk_bf16_f32 v51, v51, v56
	global_store_dwordx4 v[110:111], v[48:51], off
	v_mul_f32_e32 v53, v53, v106
	v_cmp_gt_f32_e32 vcc, s5, v52
	v_mul_f32_e32 v48, v102, v106
	v_mul_f32_e32 v49, v105, v106
	v_cvt_pk_bf16_f32 v48, v48, v49
	v_mul_f32_e32 v49, v104, v106
	v_mul_f32_e32 v50, v103, v106
	v_cvt_pk_bf16_f32 v49, v49, v50
	v_mul_f32_e32 v50, v55, v106
	v_mul_f32_e32 v51, v54, v106
	v_cvt_pk_bf16_f32 v50, v50, v51
	v_mul_f32_e32 v51, v114, v106
	v_cvt_pk_bf16_f32 v51, v51, v53
	v_mul_f32_e32 v53, 0x4b800000, v52
	v_cndmask_b32_e32 v52, v52, v53, vcc
	global_store_dwordx4 v[110:111], v[48:51], off offset:256
	v_rsq_f32_e32 v52, v52
	s_nop 0
	v_mul_f32_e32 v48, 0xbfb8aa3b, v44
	v_exp_f32_e32 v50, v48
	v_mul_f32_e32 v48, 0x45800000, v52
	v_cndmask_b32_e32 v51, v52, v48, vcc
	v_mul_f32_e32 v52, 0xbfb8aa3b, v45
	v_add_f32_e32 v50, 1.0, v50
	v_rcp_f32_e32 v50, v50
	v_exp_f32_e32 v52, v52
	v_lshl_add_u64 v[48:49], s[2:3], 0, v[100:101]
	v_lshl_add_u64 v[48:49], v[48:49], 0, v[170:171]
	v_mul_f32_e32 v44, v44, v50
	v_lshlrev_b32_e32 v50, 16, v92
	v_mul_f32_e32 v44, v44, v50
	v_add_f32_e32 v50, 1.0, v52
	v_rcp_f32_e32 v50, v50
	v_mul_f32_e32 v52, 0xbfb8aa3b, v46
	v_exp_f32_e32 v52, v52
	v_mul_f32_e32 v44, v44, v51
	v_mul_f32_e32 v45, v45, v50
	v_and_b32_e32 v50, 0xffff0000, v92
	v_mul_f32_e32 v45, v45, v50
	v_add_f32_e32 v50, 1.0, v52
	v_mul_f32_e32 v52, 0xbfb8aa3b, v47
	v_rcp_f32_e32 v50, v50
	v_exp_f32_e32 v52, v52
	v_mul_f32_e32 v45, v45, v51
	v_cvt_pk_bf16_f32 v44, v44, v45
	v_mul_f32_e32 v45, v46, v50
	v_add_f32_e32 v46, 1.0, v52
	v_rcp_f32_e32 v46, v46
	v_lshlrev_b32_e32 v50, 16, v93
	v_mul_f32_e32 v45, v45, v50
	v_and_b32_e32 v50, 0xffff0000, v93
	v_mul_f32_e32 v46, v47, v46
	v_mul_f32_e32 v47, 0xbfb8aa3b, v40
	v_exp_f32_e32 v47, v47
	v_mul_f32_e32 v46, v46, v50
	v_mul_f32_e32 v45, v45, v51
	v_mul_f32_e32 v46, v46, v51
	v_add_f32_e32 v47, 1.0, v47
	v_cvt_pk_bf16_f32 v45, v45, v46
	v_mul_f32_e32 v46, 0xbfb8aa3b, v41
	v_rcp_f32_e32 v47, v47
	v_exp_f32_e32 v46, v46
	v_mul_f32_e32 v40, v40, v47
	v_lshlrev_b32_e32 v47, 16, v94
	v_add_f32_e32 v46, 1.0, v46
	v_mul_f32_e32 v40, v40, v47
	v_rcp_f32_e32 v46, v46
	v_mul_f32_e32 v47, 0xbfb8aa3b, v42
	v_exp_f32_e32 v47, v47
	v_mul_f32_e32 v40, v40, v51
	v_mul_f32_e32 v41, v41, v46
	v_and_b32_e32 v46, 0xffff0000, v94
	v_mul_f32_e32 v41, v41, v46
	v_add_f32_e32 v46, 1.0, v47
	v_rcp_f32_e32 v47, v46
	v_mul_f32_e32 v46, 0xbfb8aa3b, v43
	v_exp_f32_e32 v50, v46
	v_mul_f32_e32 v41, v41, v51
	v_cvt_pk_bf16_f32 v46, v40, v41
	v_mul_f32_e32 v40, v42, v47
	v_add_f32_e32 v41, 1.0, v50
	v_rcp_f32_e32 v41, v41
	v_lshlrev_b32_e32 v42, 16, v95
	v_mul_f32_e32 v40, v40, v42
	v_and_b32_e32 v42, 0xffff0000, v95
	v_mul_f32_e32 v41, v43, v41
	v_mul_f32_e32 v43, 0xbfb8aa3b, v36
	v_exp_f32_e32 v43, v43
	v_mul_f32_e32 v40, v40, v51
	v_mul_f32_e32 v41, v41, v42
	v_mul_f32_e32 v41, v41, v51
	v_cvt_pk_bf16_f32 v47, v40, v41
	v_add_f32_e32 v40, 1.0, v43
	v_rcp_f32_e32 v40, v40
	v_mul_f32_e32 v41, 0xbfb8aa3b, v37
	v_exp_f32_e32 v41, v41
	global_store_dwordx4 v[48:49], v[44:47], off
	v_mul_f32_e32 v36, v36, v40
	v_lshlrev_b32_e32 v40, 16, v88
	v_mul_f32_e32 v36, v36, v40
	v_add_f32_e32 v40, 1.0, v41
	v_rcp_f32_e32 v40, v40
	v_mul_f32_e32 v41, 0xbfb8aa3b, v38
	v_exp_f32_e32 v41, v41
	v_mul_f32_e32 v36, v36, v51
	v_mul_f32_e32 v37, v37, v40
	v_and_b32_e32 v40, 0xffff0000, v88
	v_mul_f32_e32 v37, v37, v40
	v_add_f32_e32 v40, 1.0, v41
	v_mul_f32_e32 v41, 0xbfb8aa3b, v39
	v_rcp_f32_e32 v40, v40
	v_exp_f32_e32 v41, v41
	v_mul_f32_e32 v37, v37, v51
	v_cvt_pk_bf16_f32 v36, v36, v37
	v_mul_f32_e32 v37, v38, v40
	v_add_f32_e32 v38, 1.0, v41
	v_rcp_f32_e32 v38, v38
	v_lshlrev_b32_e32 v40, 16, v89
	v_mul_f32_e32 v37, v37, v40
	v_and_b32_e32 v40, 0xffff0000, v89
	v_mul_f32_e32 v38, v39, v38
	v_mul_f32_e32 v39, 0xbfb8aa3b, v32
	v_exp_f32_e32 v39, v39
	v_mul_f32_e32 v38, v38, v40
	v_mul_f32_e32 v37, v37, v51
	v_mul_f32_e32 v38, v38, v51
	v_add_f32_e32 v39, 1.0, v39
	v_cvt_pk_bf16_f32 v37, v37, v38
	v_mul_f32_e32 v38, 0xbfb8aa3b, v33
	v_rcp_f32_e32 v39, v39
	v_exp_f32_e32 v38, v38
	v_mul_f32_e32 v32, v32, v39
	v_lshlrev_b32_e32 v39, 16, v90
	v_add_f32_e32 v38, 1.0, v38
	v_mul_f32_e32 v32, v32, v39
	v_rcp_f32_e32 v38, v38
	v_mul_f32_e32 v39, 0xbfb8aa3b, v34
	v_exp_f32_e32 v39, v39
	v_mul_f32_e32 v32, v32, v51
	v_mul_f32_e32 v33, v33, v38
	v_and_b32_e32 v38, 0xffff0000, v90
	v_mul_f32_e32 v33, v33, v38
	v_add_f32_e32 v38, 1.0, v39
	v_rcp_f32_e32 v39, v38
	v_mul_f32_e32 v38, 0xbfb8aa3b, v35
	v_exp_f32_e32 v40, v38
	v_mul_f32_e32 v33, v33, v51
	v_cvt_pk_bf16_f32 v38, v32, v33
	v_mul_f32_e32 v32, v34, v39
	v_add_f32_e32 v33, 1.0, v40
	v_rcp_f32_e32 v33, v33
	v_lshlrev_b32_e32 v34, 16, v91
	v_mul_f32_e32 v32, v32, v34
	v_and_b32_e32 v34, 0xffff0000, v91
	v_mul_f32_e32 v33, v35, v33
	v_mul_f32_e32 v35, 0xbfb8aa3b, v29
	v_exp_f32_e32 v35, v35
	v_mul_f32_e32 v33, v33, v34
	v_mul_f32_e32 v32, v32, v51
	v_mul_f32_e32 v33, v33, v51
	v_cvt_pk_bf16_f32 v39, v32, v33
	global_store_dwordx4 v[48:49], v[36:39], off offset:256
	v_add_f32_e32 v35, 1.0, v35
	v_rcp_f32_e32 v35, v35
	v_mul_f32_e32 v36, 0xbfb8aa3b, v30
	v_exp_f32_e32 v36, v36
	v_mul_f32_e32 v34, 0xbfb8aa3b, v28
	v_mul_f32_e32 v29, v29, v35
	v_exp_f32_e32 v34, v34
	v_add_f32_e32 v35, 1.0, v36
	v_mul_f32_e32 v36, 0xbfb8aa3b, v31
	v_rcp_f32_e32 v35, v35
	v_exp_f32_e32 v36, v36
	v_add_f32_e32 v34, 1.0, v34
	v_rcp_f32_e32 v34, v34
	v_mul_f32_e32 v30, v30, v35
	v_add_f32_e32 v35, 1.0, v36
	v_mul_f32_e32 v36, 0xbfb8aa3b, v24
	v_rcp_f32_e32 v35, v35
	v_exp_f32_e32 v36, v36
	v_mul_f32_e32 v28, v28, v34
	v_lshlrev_b32_e32 v34, 16, v84
	v_mul_f32_e32 v31, v31, v35
	v_add_f32_e32 v35, 1.0, v36
	v_mul_f32_e32 v36, 0xbfb8aa3b, v25
	v_rcp_f32_e32 v35, v35
	v_exp_f32_e32 v36, v36
	v_mul_f32_e32 v28, v28, v34
	v_and_b32_e32 v34, 0xffff0000, v84
	v_mul_f32_e32 v24, v24, v35
	v_add_f32_e32 v35, 1.0, v36
	v_mul_f32_e32 v36, 0xbfb8aa3b, v26
	v_rcp_f32_e32 v35, v35
	v_exp_f32_e32 v36, v36
	v_mul_f32_e32 v29, v29, v34
	v_lshlrev_b32_e32 v34, 16, v85
	v_mul_f32_e32 v25, v25, v35
	v_add_f32_e32 v35, 1.0, v36
	v_mul_f32_e32 v36, 0xbfb8aa3b, v27
	v_rcp_f32_e32 v35, v35
	v_exp_f32_e32 v36, v36
	v_mul_f32_e32 v30, v30, v34
	v_and_b32_e32 v34, 0xffff0000, v85
	v_mul_f32_e32 v26, v26, v35
	v_add_f32_e32 v35, 1.0, v36
	v_mul_f32_e32 v36, 0xbfb8aa3b, v20
	v_rcp_f32_e32 v35, v35
	v_exp_f32_e32 v36, v36
	v_mul_f32_e32 v31, v31, v34
	v_lshlrev_b32_e32 v34, 16, v86
	v_mul_f32_e32 v27, v27, v35
	v_add_f32_e32 v35, 1.0, v36
	v_mul_f32_e32 v36, 0xbfb8aa3b, v21
	v_rcp_f32_e32 v35, v35
	v_exp_f32_e32 v36, v36
	v_mul_f32_e32 v24, v24, v34
	v_and_b32_e32 v34, 0xffff0000, v86
	v_mul_f32_e32 v20, v20, v35
	v_add_f32_e32 v35, 1.0, v36
	v_mul_f32_e32 v36, 0xbfb8aa3b, v22
	v_rcp_f32_e32 v35, v35
	v_exp_f32_e32 v36, v36
	v_mul_f32_e32 v25, v25, v34
	v_lshlrev_b32_e32 v34, 16, v87
	v_mul_f32_e32 v26, v26, v34
	v_and_b32_e32 v34, 0xffff0000, v87
	v_mul_f32_e32 v27, v27, v34
	v_lshlrev_b32_e32 v34, 16, v76
	v_mul_f32_e32 v34, v20, v34
	v_mul_f32_e32 v20, v21, v35
	v_add_f32_e32 v35, 1.0, v36
	v_mul_f32_e32 v36, 0xbfb8aa3b, v23
	v_rcp_f32_e32 v35, v35
	v_exp_f32_e32 v36, v36
	v_and_b32_e32 v21, 0xffff0000, v76
	v_mul_f32_e32 v37, v20, v21
	v_mul_f32_e32 v20, v22, v35
	v_add_f32_e32 v22, 1.0, v36
	v_rcp_f32_e32 v22, v22
	v_mul_f32_e32 v35, 0xbfb8aa3b, v16
	v_exp_f32_e32 v35, v35
	v_lshlrev_b32_e32 v21, 16, v77
	v_mul_f32_e32 v36, v20, v21
	v_mul_f32_e32 v20, v23, v22
	v_mul_f32_e32 v23, 0xbfb8aa3b, v17
	v_add_f32_e32 v22, 1.0, v35
	v_exp_f32_e32 v23, v23
	v_rcp_f32_e32 v22, v22
	v_and_b32_e32 v21, 0xffff0000, v77
	v_mul_f32_e32 v35, v20, v21
	v_add_f32_e32 v21, 1.0, v23
	v_mul_f32_e32 v16, v16, v22
	v_rcp_f32_e32 v21, v21
	v_mul_f32_e32 v22, 0xbfb8aa3b, v18
	v_exp_f32_e32 v22, v22
	v_lshlrev_b32_e32 v20, 16, v78
	v_mul_f32_e32 v23, v16, v20
	v_mul_f32_e32 v16, v17, v21
	v_and_b32_e32 v17, 0xffff0000, v78
	v_add_f32_e32 v20, 1.0, v22
	v_mul_f32_e32 v22, v16, v17
	v_mul_f32_e32 v16, 0xbfb8aa3b, v19
	v_rcp_f32_e32 v20, v20
	v_exp_f32_e32 v16, v16
	v_mov_b32_e32 v21, v74
	v_mov_b32_e32 v74, v83
	v_mul_f32_e32 v17, v18, v20
	v_lshlrev_b32_e32 v18, 16, v79
	v_add_f32_e32 v16, 1.0, v16
	v_mul_f32_e32 v38, v17, v18
	v_rcp_f32_e32 v18, v16
	v_mov_b32_e32 v16, v80
	v_mov_b32_e32 v17, v72
	v_mov_b32_e32 v72, v81
	v_pk_add_f32 v[16:17], v[16:17], v[72:73]
	v_mov_b32_e32 v20, v82
	v_pk_add_f32 v[16:17], v[20:21], v[16:17]
	v_lshl_add_u64 v[32:33], s[2:3], 0, v[98:99]
	v_pk_add_f32 v[16:17], v[74:75], v[16:17]
	v_lshl_add_u64 v[32:33], v[32:33], 0, v[170:171]
	v_pk_fma_f32 v[20:21], v[16:17], s[14:15], v[112:113] op_sel_hi:[1,0,0]
	v_mul_f32_e32 v17, v19, v18
	v_mul_f32_e32 v16, 0x4b800000, v21
	v_cmp_gt_f32_e32 vcc, s5, v21
	v_and_b32_e32 v18, 0xffff0000, v79
	s_mov_b64 s[14:15], s[8:9]
	v_cndmask_b32_e32 v16, v21, v16, vcc
	v_rsq_f32_e32 v16, v16
	v_mul_f32_e32 v21, v17, v18
	v_mul_f32_e32 v17, 0x45800000, v16
	v_cndmask_b32_e32 v39, v16, v17, vcc
	v_mul_f32_e32 v16, v28, v39
	v_mul_f32_e32 v17, v29, v39
	v_cvt_pk_bf16_f32 v16, v16, v17
	v_mul_f32_e32 v17, v30, v39
	v_mul_f32_e32 v18, v31, v39
	v_cvt_pk_bf16_f32 v17, v17, v18
	v_mul_f32_e32 v18, v24, v39
	v_mul_f32_e32 v19, v25, v39
	v_cvt_pk_bf16_f32 v18, v18, v19
	v_mul_f32_e32 v19, v26, v39
	v_mul_f32_e32 v24, v27, v39
	v_cvt_pk_bf16_f32 v19, v19, v24
	global_store_dwordx4 v[32:33], v[16:19], off
	v_mul_f32_e32 v21, v21, v39
	v_cmp_gt_f32_e32 vcc, s5, v20
	v_mul_f32_e32 v16, v34, v39
	v_mul_f32_e32 v17, v37, v39
	v_cvt_pk_bf16_f32 v16, v16, v17
	v_mul_f32_e32 v17, v36, v39
	v_mul_f32_e32 v18, v35, v39
	v_cvt_pk_bf16_f32 v17, v17, v18
	v_mul_f32_e32 v18, v23, v39
	v_mul_f32_e32 v19, v22, v39
	v_cvt_pk_bf16_f32 v18, v18, v19
	v_mul_f32_e32 v19, v38, v39
	v_cvt_pk_bf16_f32 v19, v19, v21
	v_mul_f32_e32 v21, 0x4b800000, v20
	v_cndmask_b32_e32 v20, v20, v21, vcc
	global_store_dwordx4 v[32:33], v[16:19], off offset:256
	v_rsq_f32_e32 v20, v20
	s_nop 0
	v_mul_f32_e32 v16, 0xbfb8aa3b, v12
	v_exp_f32_e32 v18, v16
	v_mul_f32_e32 v16, 0x45800000, v20
	v_cndmask_b32_e32 v19, v20, v16, vcc
	v_mul_f32_e32 v20, 0xbfb8aa3b, v13
	v_add_f32_e32 v18, 1.0, v18
	v_rcp_f32_e32 v18, v18
	v_exp_f32_e32 v20, v20
	v_lshl_add_u64 v[16:17], s[2:3], 0, v[96:97]
	v_lshl_add_u64 v[16:17], v[16:17], 0, v[170:171]
	v_mul_f32_e32 v12, v12, v18
	v_lshlrev_b32_e32 v18, 16, v68
	v_mul_f32_e32 v12, v12, v18
	v_add_f32_e32 v18, 1.0, v20
	v_rcp_f32_e32 v18, v18
	v_mul_f32_e32 v20, 0xbfb8aa3b, v14
	v_exp_f32_e32 v20, v20
	v_mul_f32_e32 v12, v12, v19
	v_mul_f32_e32 v13, v13, v18
	v_and_b32_e32 v18, 0xffff0000, v68
	v_mul_f32_e32 v13, v13, v18
	v_add_f32_e32 v18, 1.0, v20
	v_mul_f32_e32 v20, 0xbfb8aa3b, v15
	v_rcp_f32_e32 v18, v18
	v_exp_f32_e32 v20, v20
	v_mul_f32_e32 v13, v13, v19
	v_cvt_pk_bf16_f32 v12, v12, v13
	v_mul_f32_e32 v13, v14, v18
	v_add_f32_e32 v14, 1.0, v20
	v_rcp_f32_e32 v14, v14
	v_lshlrev_b32_e32 v18, 16, v69
	v_mul_f32_e32 v13, v13, v18
	v_and_b32_e32 v18, 0xffff0000, v69
	v_mul_f32_e32 v14, v15, v14
	v_mul_f32_e32 v15, 0xbfb8aa3b, v8
	v_exp_f32_e32 v15, v15
	v_mul_f32_e32 v14, v14, v18
	v_mul_f32_e32 v13, v13, v19
	v_mul_f32_e32 v14, v14, v19
	v_add_f32_e32 v15, 1.0, v15
	v_cvt_pk_bf16_f32 v13, v13, v14
	v_mul_f32_e32 v14, 0xbfb8aa3b, v9
	v_rcp_f32_e32 v15, v15
	v_exp_f32_e32 v14, v14
	s_and_b64 vcc, exec, s[0:1]
	v_mul_f32_e32 v8, v8, v15
	v_lshlrev_b32_e32 v15, 16, v70
	v_add_f32_e32 v14, 1.0, v14
	v_mul_f32_e32 v8, v8, v15
	v_rcp_f32_e32 v14, v14
	v_mul_f32_e32 v15, 0xbfb8aa3b, v10
	v_exp_f32_e32 v15, v15
	v_mul_f32_e32 v8, v8, v19
	v_mul_f32_e32 v9, v9, v14
	v_and_b32_e32 v14, 0xffff0000, v70
	v_mul_f32_e32 v9, v9, v14
	v_add_f32_e32 v14, 1.0, v15
	v_rcp_f32_e32 v15, v14
	v_mul_f32_e32 v14, 0xbfb8aa3b, v11
	v_exp_f32_e32 v18, v14
	v_mul_f32_e32 v9, v9, v19
	v_cvt_pk_bf16_f32 v14, v8, v9
	v_mul_f32_e32 v8, v10, v15
	v_add_f32_e32 v9, 1.0, v18
	v_rcp_f32_e32 v9, v9
	v_lshlrev_b32_e32 v10, 16, v71
	v_mul_f32_e32 v8, v8, v10
	v_and_b32_e32 v10, 0xffff0000, v71
	v_mul_f32_e32 v9, v11, v9
	v_mul_f32_e32 v11, 0xbfb8aa3b, v4
	v_exp_f32_e32 v11, v11
	v_mul_f32_e32 v8, v8, v19
	v_mul_f32_e32 v9, v9, v10
	v_mul_f32_e32 v9, v9, v19
	v_cvt_pk_bf16_f32 v15, v8, v9
	v_add_f32_e32 v8, 1.0, v11
	v_rcp_f32_e32 v8, v8
	v_mul_f32_e32 v9, 0xbfb8aa3b, v5
	v_exp_f32_e32 v9, v9
	global_store_dwordx4 v[16:17], v[12:15], off
	v_mul_f32_e32 v4, v4, v8
	v_lshlrev_b32_e32 v8, 16, v64
	v_mul_f32_e32 v4, v4, v8
	v_add_f32_e32 v8, 1.0, v9
	v_rcp_f32_e32 v8, v8
	v_mul_f32_e32 v9, 0xbfb8aa3b, v6
	v_exp_f32_e32 v9, v9
	v_mul_f32_e32 v4, v4, v19
	v_mul_f32_e32 v5, v5, v8
	v_and_b32_e32 v8, 0xffff0000, v64
	v_mul_f32_e32 v5, v5, v8
	v_add_f32_e32 v8, 1.0, v9
	v_mul_f32_e32 v9, 0xbfb8aa3b, v7
	v_rcp_f32_e32 v8, v8
	v_exp_f32_e32 v9, v9
	v_mul_f32_e32 v5, v5, v19
	v_cvt_pk_bf16_f32 v4, v4, v5
	v_mul_f32_e32 v5, v6, v8
	v_add_f32_e32 v6, 1.0, v9
	v_rcp_f32_e32 v6, v6
	v_lshlrev_b32_e32 v8, 16, v65
	v_mul_f32_e32 v5, v5, v8
	v_and_b32_e32 v8, 0xffff0000, v65
	v_mul_f32_e32 v6, v7, v6
	v_mul_f32_e32 v7, 0xbfb8aa3b, v0
	v_exp_f32_e32 v7, v7
	v_mul_f32_e32 v6, v6, v8
	v_mul_f32_e32 v5, v5, v19
	v_mul_f32_e32 v6, v6, v19
	v_add_f32_e32 v7, 1.0, v7
	v_cvt_pk_bf16_f32 v5, v5, v6
	v_mul_f32_e32 v6, 0xbfb8aa3b, v1
	v_rcp_f32_e32 v7, v7
	v_exp_f32_e32 v6, v6
	v_mul_f32_e32 v0, v0, v7
	v_lshlrev_b32_e32 v7, 16, v66
	v_add_f32_e32 v6, 1.0, v6
	v_mul_f32_e32 v0, v0, v7
	v_rcp_f32_e32 v6, v6
	v_mul_f32_e32 v7, 0xbfb8aa3b, v2
	v_exp_f32_e32 v7, v7
	v_mul_f32_e32 v0, v0, v19
	v_mul_f32_e32 v1, v1, v6
	v_and_b32_e32 v6, 0xffff0000, v66
	v_mul_f32_e32 v1, v1, v6
	v_add_f32_e32 v6, 1.0, v7
	v_rcp_f32_e32 v7, v6
	v_mul_f32_e32 v6, 0xbfb8aa3b, v3
	v_exp_f32_e32 v8, v6
	v_mul_f32_e32 v1, v1, v19
	v_cvt_pk_bf16_f32 v6, v0, v1
	v_mul_f32_e32 v0, v2, v7
	v_add_f32_e32 v1, 1.0, v8
	v_rcp_f32_e32 v1, v1
	v_lshlrev_b32_e32 v2, 16, v67
	v_mul_f32_e32 v0, v0, v2
	v_and_b32_e32 v2, 0xffff0000, v67
	v_mul_f32_e32 v1, v3, v1
	v_mul_f32_e32 v1, v1, v2
	v_mul_f32_e32 v0, v0, v19
	v_mul_f32_e32 v1, v1, v19
	v_cvt_pk_bf16_f32 v7, v0, v1
	global_store_dwordx4 v[16:17], v[4:7], off offset:256
	s_cbranch_vccz .LBB0_80
	s_waitcnt vmcnt(0)
	s_cmpk_gt_u32 s21, 0xff
	s_cbranch_scc1 .LBB0_91
	s_barrier

.LBB0_199:
	v_mov_b64_e32 v[0:1], 0x1000
	s_ashr_i32 s9, s8, 31
	v_cmp_lt_i64_e32 vcc, s[10:11], v[0:1]
	s_lshl_b64 s[10:11], s[8:9], 20
	s_add_u32 s10, s23, s10
	s_addc_u32 s11, s24, s11
	s_and_b64 s[12:13], vcc, exec
	s_cselect_b32 s5, s11, s15
	s_cselect_b32 s9, s10, s14
	s_ashr_i32 s7, s6, 31
	s_lshl_b64 s[12:13], s[6:7], 20
	s_add_u32 s12, s25, s12
	s_addc_u32 s13, s26, s13
	s_and_b64 s[18:19], vcc, exec
	s_cselect_b32 s7, s13, s17
	s_cselect_b32 s37, s12, s16
	s_add_u32 s14, s14, 0x80080
	s_addc_u32 s15, s15, 0
	s_add_u32 s38, s16, 0x100
	s_addc_u32 s39, s17, 0
	s_mov_b32 s40, -2
	s_mov_b64 s[48:49], 0x80
	v_add_u32_e32 v222, 0x10000, v238
	s_add_u32 s16, s14, 0xfff80080
	s_addc_u32 s17, s15, -1
	s_add_i32 s41, 0, 0x10000
	ds_read_b128 v[128:131], v222 offset:0
	ds_read_b128 v[132:135], v222 offset:1024
	ds_read_b128 v[136:139], v222 offset:2048
	ds_read_b128 v[140:143], v222 offset:3072
	s_cmp_eq_u32 s40, 28
	s_cselect_b32 s19, s5, s17
	s_cselect_b32 s18, s9, s16
	s_cselect_b32 s17, s7, s39
	s_cselect_b32 s16, s37, s38
	s_add_i32 m0, s28, 0xc000
	ds_read_b128 v[144:147], v240
	ds_read_b128 v[148:151], v240 offset:1024
	ds_read_b128 v[152:155], v240 offset:2048
	ds_read_b128 v[156:159], v240 offset:3072
	ds_read_b128 v[160:163], v240 offset:4096
	ds_read_b128 v[164:167], v240 offset:5120
	ds_read_b128 v[168:171], v240 offset:6144
	ds_read_b128 v[172:175], v240 offset:7168
	global_load_lds_dwordx4 v218, s[14:15]
	s_add_i32 m0, s28, 0xe000
	s_nop 0
	global_load_lds_dwordx4 v220, s[14:15]
	s_waitcnt lgkmcnt(8)
	s_waitcnt lgkmcnt(0)
	s_barrier
	v_mfma_f32_16x16x32_bf16 v[124:127], v[128:131], v[144:147], 0
	v_mfma_f32_16x16x32_bf16 v[120:123], v[136:139], v[144:147], 0
	v_mfma_f32_16x16x32_bf16 v[116:119], v[128:131], v[152:155], 0
	v_mfma_f32_16x16x32_bf16 v[108:111], v[136:139], v[152:155], 0
	v_mfma_f32_16x16x32_bf16 v[100:103], v[128:131], v[160:163], 0
	v_mfma_f32_16x16x32_bf16 v[92:95], v[136:139], v[160:163], 0
	v_mfma_f32_16x16x32_bf16 v[84:87], v[128:131], v[168:171], 0
	v_mfma_f32_16x16x32_bf16 v[76:79], v[136:139], v[168:171], 0
	v_mfma_f32_16x16x32_bf16 v[124:127], v[132:135], v[148:151], v[124:127]
	v_mfma_f32_16x16x32_bf16 v[120:123], v[140:143], v[148:151], v[120:123]
	v_mfma_f32_16x16x32_bf16 v[116:119], v[132:135], v[156:159], v[116:119]
	v_mfma_f32_16x16x32_bf16 v[108:111], v[140:143], v[156:159], v[108:111]
	v_mfma_f32_16x16x32_bf16 v[100:103], v[132:135], v[164:167], v[100:103]
	v_mfma_f32_16x16x32_bf16 v[92:95], v[140:143], v[164:167], v[92:95]
	v_mfma_f32_16x16x32_bf16 v[84:87], v[132:135], v[172:175], v[84:87]
	v_mfma_f32_16x16x32_bf16 v[76:79], v[140:143], v[172:175], v[76:79]
	s_barrier
	s_add_i32 s44, 0, 0x14000
	s_add_i32 s41, s41, s27
	s_mov_b32 m0, s41
	ds_read_b128 v[176:179], v222 offset:16384
	ds_read_b128 v[180:183], v222 offset:17408
	ds_read_b128 v[184:187], v222 offset:18432
	ds_read_b128 v[188:191], v222 offset:19456
	global_load_lds_dwordx4 v206, s[16:17]
	s_add_i32 m0, s41, 0x2000
	s_nop 0
	global_load_lds_dwordx4 v210, s[16:17]
	s_waitcnt lgkmcnt(0)
	s_barrier
	v_mfma_f32_16x16x32_bf16 v[112:115], v[176:179], v[144:147], 0
	v_mfma_f32_16x16x32_bf16 v[104:107], v[184:187], v[144:147], 0
	v_mfma_f32_16x16x32_bf16 v[96:99], v[176:179], v[152:155], 0
	v_mfma_f32_16x16x32_bf16 v[88:91], v[184:187], v[152:155], 0
	v_mfma_f32_16x16x32_bf16 v[80:83], v[176:179], v[160:163], 0
	v_mfma_f32_16x16x32_bf16 v[72:75], v[184:187], v[160:163], 0
	v_mfma_f32_16x16x32_bf16 v[68:71], v[176:179], v[168:171], 0
	v_mfma_f32_16x16x32_bf16 v[64:67], v[184:187], v[168:171], 0
	v_mfma_f32_16x16x32_bf16 v[112:115], v[180:183], v[148:151], v[112:115]
	v_mfma_f32_16x16x32_bf16 v[104:107], v[188:191], v[148:151], v[104:107]
	v_mfma_f32_16x16x32_bf16 v[96:99], v[180:183], v[156:159], v[96:99]
	v_mfma_f32_16x16x32_bf16 v[88:91], v[188:191], v[156:159], v[88:91]
	v_mfma_f32_16x16x32_bf16 v[80:83], v[180:183], v[164:167], v[80:83]
	v_mfma_f32_16x16x32_bf16 v[72:75], v[188:191], v[164:167], v[72:75]
	v_mfma_f32_16x16x32_bf16 v[68:71], v[180:183], v[172:175], v[68:71]
	v_mfma_f32_16x16x32_bf16 v[64:67], v[188:191], v[172:175], v[64:67]
	s_mov_b32 m0, s28
	s_add_u32 s48, s18, 0x80
	s_addc_u32 s49, s19, 0
	s_barrier
	ds_read_b128 v[144:147], v240 offset:16384
	ds_read_b128 v[148:151], v240 offset:17408
	ds_read_b128 v[152:155], v240 offset:18432
	ds_read_b128 v[156:159], v240 offset:19456
	ds_read_b128 v[160:163], v240 offset:20480
	ds_read_b128 v[164:167], v240 offset:21504
	ds_read_b128 v[168:171], v240 offset:22528
	ds_read_b128 v[172:175], v240 offset:23552
	global_load_lds_dwordx4 v204, s[18:19]
	s_mov_b32 m0, s29
	s_nop 0
	global_load_lds_dwordx4 v208, s[18:19]
	s_waitcnt lgkmcnt(0)
	s_barrier
	v_mfma_f32_16x16x32_bf16 v[60:63], v[128:131], v[144:147], 0
	v_mfma_f32_16x16x32_bf16 v[56:59], v[136:139], v[144:147], 0
	v_mfma_f32_16x16x32_bf16 v[52:55], v[128:131], v[152:155], 0
	v_mfma_f32_16x16x32_bf16 v[44:47], v[136:139], v[152:155], 0
	v_mfma_f32_16x16x32_bf16 v[36:39], v[128:131], v[160:163], 0
	v_mfma_f32_16x16x32_bf16 v[28:31], v[136:139], v[160:163], 0
	v_mfma_f32_16x16x32_bf16 v[20:23], v[128:131], v[168:171], 0
	v_mfma_f32_16x16x32_bf16 v[12:15], v[136:139], v[168:171], 0
	v_mfma_f32_16x16x32_bf16 v[60:63], v[132:135], v[148:151], v[60:63]
	v_mfma_f32_16x16x32_bf16 v[56:59], v[140:143], v[148:151], v[56:59]
	v_mfma_f32_16x16x32_bf16 v[52:55], v[132:135], v[156:159], v[52:55]
	v_mfma_f32_16x16x32_bf16 v[44:47], v[140:143], v[156:159], v[44:47]
	v_mfma_f32_16x16x32_bf16 v[36:39], v[132:135], v[164:167], v[36:39]
	v_mfma_f32_16x16x32_bf16 v[28:31], v[140:143], v[164:167], v[28:31]
	v_mfma_f32_16x16x32_bf16 v[20:23], v[132:135], v[172:175], v[20:23]
	v_mfma_f32_16x16x32_bf16 v[12:15], v[140:143], v[172:175], v[12:15]
	s_barrier
	s_add_u32 s42, s16, 0x80000
	s_addc_u32 s43, s17, 0
	s_add_i32 s41, s44, s27
	s_mov_b32 m0, s41
	s_nop 0
	global_load_lds_dwordx4 v206, s[42:43]
	s_add_i32 m0, s41, 0x2000
	s_nop 0
	global_load_lds_dwordx4 v210, s[42:43]
	s_waitcnt vmcnt(6)
	s_barrier
	v_mfma_f32_16x16x32_bf16 v[48:51], v[176:179], v[144:147], 0
	v_mfma_f32_16x16x32_bf16 v[40:43], v[184:187], v[144:147], 0
	v_mfma_f32_16x16x32_bf16 v[32:35], v[176:179], v[152:155], 0
	v_mfma_f32_16x16x32_bf16 v[24:27], v[184:187], v[152:155], 0
	v_mfma_f32_16x16x32_bf16 v[16:19], v[176:179], v[160:163], 0
	v_mfma_f32_16x16x32_bf16 v[8:11], v[184:187], v[160:163], 0
	v_mfma_f32_16x16x32_bf16 v[4:7], v[176:179], v[168:171], 0
	v_mfma_f32_16x16x32_bf16 v[0:3], v[184:187], v[168:171], 0
	v_mfma_f32_16x16x32_bf16 v[48:51], v[180:183], v[148:151], v[48:51]
	v_mfma_f32_16x16x32_bf16 v[40:43], v[188:191], v[148:151], v[40:43]
	v_mfma_f32_16x16x32_bf16 v[32:35], v[180:183], v[156:159], v[32:35]
	v_mfma_f32_16x16x32_bf16 v[24:27], v[188:191], v[156:159], v[24:27]
	v_mfma_f32_16x16x32_bf16 v[16:19], v[180:183], v[164:167], v[16:19]
	v_mfma_f32_16x16x32_bf16 v[8:11], v[188:191], v[164:167], v[8:11]
	v_mfma_f32_16x16x32_bf16 v[4:7], v[180:183], v[172:175], v[4:7]
	v_mfma_f32_16x16x32_bf16 v[0:3], v[188:191], v[172:175], v[0:3]
	s_add_i32 s41, 0, 0x18000
	s_barrier
	ds_read_b128 v[128:131], v222 offset:32768
	ds_read_b128 v[132:135], v222 offset:33792
	ds_read_b128 v[136:139], v222 offset:34816
	ds_read_b128 v[140:143], v222 offset:35840
	s_add_u32 s18, s18, 0x80000
	s_addc_u32 s19, s19, 0
	s_mov_b32 m0, s30
	ds_read_b128 v[144:147], v240 offset:32768
	ds_read_b128 v[148:151], v240 offset:33792
	ds_read_b128 v[152:155], v240 offset:34816
	ds_read_b128 v[156:159], v240 offset:35840
	ds_read_b128 v[160:163], v240 offset:36864
	ds_read_b128 v[164:167], v240 offset:37888
	ds_read_b128 v[168:171], v240 offset:38912
	ds_read_b128 v[172:175], v240 offset:39936
	global_load_lds_dwordx4 v204, s[18:19]
	s_mov_b32 m0, s31
	s_nop 0
	global_load_lds_dwordx4 v208, s[18:19]
	s_waitcnt lgkmcnt(8)
	s_waitcnt lgkmcnt(0)
	s_barrier
	v_mfma_f32_16x16x32_bf16 v[124:127], v[128:131], v[144:147], v[124:127]
	v_mfma_f32_16x16x32_bf16 v[120:123], v[136:139], v[144:147], v[120:123]
	v_mfma_f32_16x16x32_bf16 v[116:119], v[128:131], v[152:155], v[116:119]
	v_mfma_f32_16x16x32_bf16 v[108:111], v[136:139], v[152:155], v[108:111]
	v_mfma_f32_16x16x32_bf16 v[100:103], v[128:131], v[160:163], v[100:103]
	v_mfma_f32_16x16x32_bf16 v[92:95], v[136:139], v[160:163], v[92:95]
	v_mfma_f32_16x16x32_bf16 v[84:87], v[128:131], v[168:171], v[84:87]
	v_mfma_f32_16x16x32_bf16 v[76:79], v[136:139], v[168:171], v[76:79]
	v_mfma_f32_16x16x32_bf16 v[124:127], v[132:135], v[148:151], v[124:127]
	v_mfma_f32_16x16x32_bf16 v[120:123], v[140:143], v[148:151], v[120:123]
	v_mfma_f32_16x16x32_bf16 v[116:119], v[132:135], v[156:159], v[116:119]
	v_mfma_f32_16x16x32_bf16 v[108:111], v[140:143], v[156:159], v[108:111]
	v_mfma_f32_16x16x32_bf16 v[100:103], v[132:135], v[164:167], v[100:103]
	v_mfma_f32_16x16x32_bf16 v[92:95], v[140:143], v[164:167], v[92:95]
	v_mfma_f32_16x16x32_bf16 v[84:87], v[132:135], v[172:175], v[84:87]
	v_mfma_f32_16x16x32_bf16 v[76:79], v[140:143], v[172:175], v[76:79]
	s_barrier
	s_add_i32 s18, 0, 0x1c000
	s_add_i32 s19, s41, s27
	s_add_i32 m0, s19, 0xffffff80
	ds_read_b128 v[176:179], v222 offset:49152
	ds_read_b128 v[180:183], v222 offset:50176
	ds_read_b128 v[184:187], v222 offset:51200
	ds_read_b128 v[188:191], v222 offset:52224
	global_load_lds_dwordx4 v206, s[16:17] offset:128
	s_add_i32 m0, s19, 0x1f80
	s_nop 0
	global_load_lds_dwordx4 v210, s[16:17] offset:128
	s_waitcnt lgkmcnt(0)
	s_barrier
	v_mfma_f32_16x16x32_bf16 v[112:115], v[176:179], v[144:147], v[112:115]
	v_mfma_f32_16x16x32_bf16 v[104:107], v[184:187], v[144:147], v[104:107]
	v_mfma_f32_16x16x32_bf16 v[96:99], v[176:179], v[152:155], v[96:99]
	v_mfma_f32_16x16x32_bf16 v[88:91], v[184:187], v[152:155], v[88:91]
	v_mfma_f32_16x16x32_bf16 v[80:83], v[176:179], v[160:163], v[80:83]
	v_mfma_f32_16x16x32_bf16 v[72:75], v[184:187], v[160:163], v[72:75]
	v_mfma_f32_16x16x32_bf16 v[68:71], v[176:179], v[168:171], v[68:71]
	v_mfma_f32_16x16x32_bf16 v[64:67], v[184:187], v[168:171], v[64:67]
	v_mfma_f32_16x16x32_bf16 v[112:115], v[180:183], v[148:151], v[112:115]
	v_mfma_f32_16x16x32_bf16 v[104:107], v[188:191], v[148:151], v[104:107]
	v_mfma_f32_16x16x32_bf16 v[96:99], v[180:183], v[156:159], v[96:99]
	v_mfma_f32_16x16x32_bf16 v[88:91], v[188:191], v[156:159], v[88:91]
	v_mfma_f32_16x16x32_bf16 v[80:83], v[180:183], v[164:167], v[80:83]
	v_mfma_f32_16x16x32_bf16 v[72:75], v[188:191], v[164:167], v[72:75]
	v_mfma_f32_16x16x32_bf16 v[68:71], v[180:183], v[172:175], v[68:71]
	v_mfma_f32_16x16x32_bf16 v[64:67], v[188:191], v[172:175], v[64:67]
	s_mov_b32 m0, s33
	s_barrier
	ds_read_b128 v[144:147], v240 offset:49152
	ds_read_b128 v[148:151], v240 offset:50176
	ds_read_b128 v[152:155], v240 offset:51200
	ds_read_b128 v[156:159], v240 offset:52224
	ds_read_b128 v[160:163], v240 offset:53248
	ds_read_b128 v[164:167], v240 offset:54272
	ds_read_b128 v[168:171], v240 offset:55296
	ds_read_b128 v[172:175], v240 offset:56320
	global_load_lds_dwordx4 v204, s[48:49]
	s_mov_b32 m0, s34
	s_nop 0
	global_load_lds_dwordx4 v208, s[48:49]
	s_waitcnt lgkmcnt(0)
	s_barrier
	v_mfma_f32_16x16x32_bf16 v[60:63], v[128:131], v[144:147], v[60:63]
	v_mfma_f32_16x16x32_bf16 v[56:59], v[136:139], v[144:147], v[56:59]
	v_mfma_f32_16x16x32_bf16 v[52:55], v[128:131], v[152:155], v[52:55]
	v_mfma_f32_16x16x32_bf16 v[44:47], v[136:139], v[152:155], v[44:47]
	v_mfma_f32_16x16x32_bf16 v[36:39], v[128:131], v[160:163], v[36:39]
	v_mfma_f32_16x16x32_bf16 v[28:31], v[136:139], v[160:163], v[28:31]
	v_mfma_f32_16x16x32_bf16 v[20:23], v[128:131], v[168:171], v[20:23]
	v_mfma_f32_16x16x32_bf16 v[12:15], v[136:139], v[168:171], v[12:15]
	v_mfma_f32_16x16x32_bf16 v[60:63], v[132:135], v[148:151], v[60:63]
	v_mfma_f32_16x16x32_bf16 v[56:59], v[140:143], v[148:151], v[56:59]
	v_mfma_f32_16x16x32_bf16 v[52:55], v[132:135], v[156:159], v[52:55]
	v_mfma_f32_16x16x32_bf16 v[44:47], v[140:143], v[156:159], v[44:47]
	v_mfma_f32_16x16x32_bf16 v[36:39], v[132:135], v[164:167], v[36:39]
	v_mfma_f32_16x16x32_bf16 v[28:31], v[140:143], v[164:167], v[28:31]
	v_mfma_f32_16x16x32_bf16 v[20:23], v[132:135], v[172:175], v[20:23]
	v_mfma_f32_16x16x32_bf16 v[12:15], v[140:143], v[172:175], v[12:15]
	s_barrier
	s_add_u32 s16, s16, 0x80080
	s_addc_u32 s17, s17, 0
	s_add_i32 s18, s18, s27
	s_mov_b32 m0, s18
	s_nop 0
	global_load_lds_dwordx4 v206, s[16:17]
	s_add_i32 m0, s18, 0x2000
	s_nop 0
	global_load_lds_dwordx4 v210, s[16:17]
	s_waitcnt vmcnt(6)
	s_barrier
	v_mfma_f32_16x16x32_bf16 v[48:51], v[176:179], v[144:147], v[48:51]
	v_mfma_f32_16x16x32_bf16 v[40:43], v[184:187], v[144:147], v[40:43]
	v_mfma_f32_16x16x32_bf16 v[32:35], v[176:179], v[152:155], v[32:35]
	v_mfma_f32_16x16x32_bf16 v[24:27], v[184:187], v[152:155], v[24:27]
	v_mfma_f32_16x16x32_bf16 v[16:19], v[176:179], v[160:163], v[16:19]
	v_mfma_f32_16x16x32_bf16 v[8:11], v[184:187], v[160:163], v[8:11]
	v_mfma_f32_16x16x32_bf16 v[4:7], v[176:179], v[168:171], v[4:7]
	v_mfma_f32_16x16x32_bf16 v[0:3], v[184:187], v[168:171], v[0:3]
	v_mfma_f32_16x16x32_bf16 v[48:51], v[180:183], v[148:151], v[48:51]
	v_mfma_f32_16x16x32_bf16 v[40:43], v[188:191], v[148:151], v[40:43]
	v_mfma_f32_16x16x32_bf16 v[32:35], v[180:183], v[156:159], v[32:35]
	v_mfma_f32_16x16x32_bf16 v[24:27], v[188:191], v[156:159], v[24:27]
	v_mfma_f32_16x16x32_bf16 v[16:19], v[180:183], v[164:167], v[16:19]
	v_mfma_f32_16x16x32_bf16 v[8:11], v[188:191], v[164:167], v[8:11]
	v_mfma_f32_16x16x32_bf16 v[4:7], v[180:183], v[172:175], v[4:7]
	v_mfma_f32_16x16x32_bf16 v[0:3], v[188:191], v[172:175], v[0:3]
	s_add_i32 s40, s40, 2
	s_add_u32 s14, s14, 0x100
	s_addc_u32 s15, s15, 0
	s_add_u32 s38, s38, 0x100
	s_addc_u32 s39, s39, 0
	s_cmp_gt_u32 s40, 29
	s_barrier
.LBB0_200:
	s_add_u32 s16, s14, 0xfff80080
	s_addc_u32 s17, s15, -1
	s_add_i32 s41, 0, 0x10000
	ds_read_b128 v[128:131], v222 offset:0
	ds_read_b128 v[132:135], v222 offset:1024
	ds_read_b128 v[136:139], v222 offset:2048
	ds_read_b128 v[140:143], v222 offset:3072
	s_cmp_eq_u32 s40, 28
	s_cselect_b32 s19, s5, s17
	s_cselect_b32 s18, s9, s16
	s_cselect_b32 s17, s7, s39
	s_cselect_b32 s16, s37, s38
	s_add_i32 m0, s28, 0xc000
	ds_read_b128 v[144:147], v240
	ds_read_b128 v[148:151], v240 offset:1024
	ds_read_b128 v[152:155], v240 offset:2048
	ds_read_b128 v[156:159], v240 offset:3072
	ds_read_b128 v[160:163], v240 offset:4096
	ds_read_b128 v[164:167], v240 offset:5120
	ds_read_b128 v[168:171], v240 offset:6144
	ds_read_b128 v[172:175], v240 offset:7168
	global_load_lds_dwordx4 v218, s[14:15]
	s_add_i32 m0, s28, 0xe000
	s_nop 0
	global_load_lds_dwordx4 v220, s[14:15]
	s_waitcnt lgkmcnt(8)
	s_waitcnt lgkmcnt(0)
	s_barrier
	v_mfma_f32_16x16x32_bf16 v[124:127], v[128:131], v[144:147], v[124:127]
	v_mfma_f32_16x16x32_bf16 v[120:123], v[136:139], v[144:147], v[120:123]
	v_mfma_f32_16x16x32_bf16 v[116:119], v[128:131], v[152:155], v[116:119]
	v_mfma_f32_16x16x32_bf16 v[108:111], v[136:139], v[152:155], v[108:111]
	v_mfma_f32_16x16x32_bf16 v[100:103], v[128:131], v[160:163], v[100:103]
	v_mfma_f32_16x16x32_bf16 v[92:95], v[136:139], v[160:163], v[92:95]
	v_mfma_f32_16x16x32_bf16 v[84:87], v[128:131], v[168:171], v[84:87]
	v_mfma_f32_16x16x32_bf16 v[76:79], v[136:139], v[168:171], v[76:79]
	v_mfma_f32_16x16x32_bf16 v[124:127], v[132:135], v[148:151], v[124:127]
	v_mfma_f32_16x16x32_bf16 v[120:123], v[140:143], v[148:151], v[120:123]
	v_mfma_f32_16x16x32_bf16 v[116:119], v[132:135], v[156:159], v[116:119]
	v_mfma_f32_16x16x32_bf16 v[108:111], v[140:143], v[156:159], v[108:111]
	v_mfma_f32_16x16x32_bf16 v[100:103], v[132:135], v[164:167], v[100:103]
	v_mfma_f32_16x16x32_bf16 v[92:95], v[140:143], v[164:167], v[92:95]
	v_mfma_f32_16x16x32_bf16 v[84:87], v[132:135], v[172:175], v[84:87]
	v_mfma_f32_16x16x32_bf16 v[76:79], v[140:143], v[172:175], v[76:79]
	s_barrier
	s_add_i32 s44, 0, 0x14000
	s_add_i32 s41, s41, s27
	s_mov_b32 m0, s41
	ds_read_b128 v[176:179], v222 offset:16384
	ds_read_b128 v[180:183], v222 offset:17408
	ds_read_b128 v[184:187], v222 offset:18432
	ds_read_b128 v[188:191], v222 offset:19456
	global_load_lds_dwordx4 v206, s[16:17]
	s_add_i32 m0, s41, 0x2000
	s_nop 0
	global_load_lds_dwordx4 v210, s[16:17]
	s_waitcnt lgkmcnt(0)
	s_barrier
	v_mfma_f32_16x16x32_bf16 v[112:115], v[176:179], v[144:147], v[112:115]
	v_mfma_f32_16x16x32_bf16 v[104:107], v[184:187], v[144:147], v[104:107]
	v_mfma_f32_16x16x32_bf16 v[96:99], v[176:179], v[152:155], v[96:99]
	v_mfma_f32_16x16x32_bf16 v[88:91], v[184:187], v[152:155], v[88:91]
	v_mfma_f32_16x16x32_bf16 v[80:83], v[176:179], v[160:163], v[80:83]
	v_mfma_f32_16x16x32_bf16 v[72:75], v[184:187], v[160:163], v[72:75]
	v_mfma_f32_16x16x32_bf16 v[68:71], v[176:179], v[168:171], v[68:71]
	v_mfma_f32_16x16x32_bf16 v[64:67], v[184:187], v[168:171], v[64:67]
	v_mfma_f32_16x16x32_bf16 v[112:115], v[180:183], v[148:151], v[112:115]
	v_mfma_f32_16x16x32_bf16 v[104:107], v[188:191], v[148:151], v[104:107]
	v_mfma_f32_16x16x32_bf16 v[96:99], v[180:183], v[156:159], v[96:99]
	v_mfma_f32_16x16x32_bf16 v[88:91], v[188:191], v[156:159], v[88:91]
	v_mfma_f32_16x16x32_bf16 v[80:83], v[180:183], v[164:167], v[80:83]
	v_mfma_f32_16x16x32_bf16 v[72:75], v[188:191], v[164:167], v[72:75]
	v_mfma_f32_16x16x32_bf16 v[68:71], v[180:183], v[172:175], v[68:71]
	v_mfma_f32_16x16x32_bf16 v[64:67], v[188:191], v[172:175], v[64:67]
	s_mov_b32 m0, s28
	s_add_u32 s48, s18, 0x80
	s_addc_u32 s49, s19, 0
	s_barrier
	ds_read_b128 v[144:147], v240 offset:16384
	ds_read_b128 v[148:151], v240 offset:17408
	ds_read_b128 v[152:155], v240 offset:18432
	ds_read_b128 v[156:159], v240 offset:19456
	ds_read_b128 v[160:163], v240 offset:20480
	ds_read_b128 v[164:167], v240 offset:21504
	ds_read_b128 v[168:171], v240 offset:22528
	ds_read_b128 v[172:175], v240 offset:23552
	global_load_lds_dwordx4 v204, s[18:19]
	s_mov_b32 m0, s29
	s_nop 0
	global_load_lds_dwordx4 v208, s[18:19]
	s_waitcnt lgkmcnt(0)
	s_barrier
	v_mfma_f32_16x16x32_bf16 v[60:63], v[128:131], v[144:147], v[60:63]
	v_mfma_f32_16x16x32_bf16 v[56:59], v[136:139], v[144:147], v[56:59]
	v_mfma_f32_16x16x32_bf16 v[52:55], v[128:131], v[152:155], v[52:55]
	v_mfma_f32_16x16x32_bf16 v[44:47], v[136:139], v[152:155], v[44:47]
	v_mfma_f32_16x16x32_bf16 v[36:39], v[128:131], v[160:163], v[36:39]
	v_mfma_f32_16x16x32_bf16 v[28:31], v[136:139], v[160:163], v[28:31]
	v_mfma_f32_16x16x32_bf16 v[20:23], v[128:131], v[168:171], v[20:23]
	v_mfma_f32_16x16x32_bf16 v[12:15], v[136:139], v[168:171], v[12:15]
	v_mfma_f32_16x16x32_bf16 v[60:63], v[132:135], v[148:151], v[60:63]
	v_mfma_f32_16x16x32_bf16 v[56:59], v[140:143], v[148:151], v[56:59]
	v_mfma_f32_16x16x32_bf16 v[52:55], v[132:135], v[156:159], v[52:55]
	v_mfma_f32_16x16x32_bf16 v[44:47], v[140:143], v[156:159], v[44:47]
	v_mfma_f32_16x16x32_bf16 v[36:39], v[132:135], v[164:167], v[36:39]
	v_mfma_f32_16x16x32_bf16 v[28:31], v[140:143], v[164:167], v[28:31]
	v_mfma_f32_16x16x32_bf16 v[20:23], v[132:135], v[172:175], v[20:23]
	v_mfma_f32_16x16x32_bf16 v[12:15], v[140:143], v[172:175], v[12:15]
	s_barrier
	s_add_u32 s42, s16, 0x80000
	s_addc_u32 s43, s17, 0
	s_add_i32 s41, s44, s27
	s_mov_b32 m0, s41
	s_nop 0
	global_load_lds_dwordx4 v206, s[42:43]
	s_add_i32 m0, s41, 0x2000
	s_nop 0
	global_load_lds_dwordx4 v210, s[42:43]
	s_waitcnt vmcnt(6)
	s_barrier
	v_mfma_f32_16x16x32_bf16 v[48:51], v[176:179], v[144:147], v[48:51]
	v_mfma_f32_16x16x32_bf16 v[40:43], v[184:187], v[144:147], v[40:43]
	v_mfma_f32_16x16x32_bf16 v[32:35], v[176:179], v[152:155], v[32:35]
	v_mfma_f32_16x16x32_bf16 v[24:27], v[184:187], v[152:155], v[24:27]
	v_mfma_f32_16x16x32_bf16 v[16:19], v[176:179], v[160:163], v[16:19]
	v_mfma_f32_16x16x32_bf16 v[8:11], v[184:187], v[160:163], v[8:11]
	v_mfma_f32_16x16x32_bf16 v[4:7], v[176:179], v[168:171], v[4:7]
	v_mfma_f32_16x16x32_bf16 v[0:3], v[184:187], v[168:171], v[0:3]
	v_mfma_f32_16x16x32_bf16 v[48:51], v[180:183], v[148:151], v[48:51]
	v_mfma_f32_16x16x32_bf16 v[40:43], v[188:191], v[148:151], v[40:43]
	v_mfma_f32_16x16x32_bf16 v[32:35], v[180:183], v[156:159], v[32:35]
	v_mfma_f32_16x16x32_bf16 v[24:27], v[188:191], v[156:159], v[24:27]
	v_mfma_f32_16x16x32_bf16 v[16:19], v[180:183], v[164:167], v[16:19]
	v_mfma_f32_16x16x32_bf16 v[8:11], v[188:191], v[164:167], v[8:11]
	v_mfma_f32_16x16x32_bf16 v[4:7], v[180:183], v[172:175], v[4:7]
	v_mfma_f32_16x16x32_bf16 v[0:3], v[188:191], v[172:175], v[0:3]
	s_add_i32 s41, 0, 0x18000
	s_barrier
	ds_read_b128 v[128:131], v222 offset:32768
	ds_read_b128 v[132:135], v222 offset:33792
	ds_read_b128 v[136:139], v222 offset:34816
	ds_read_b128 v[140:143], v222 offset:35840
	s_add_u32 s18, s18, 0x80000
	s_addc_u32 s19, s19, 0
	s_mov_b32 m0, s30
	ds_read_b128 v[144:147], v240 offset:32768
	ds_read_b128 v[148:151], v240 offset:33792
	ds_read_b128 v[152:155], v240 offset:34816
	ds_read_b128 v[156:159], v240 offset:35840
	ds_read_b128 v[160:163], v240 offset:36864
	ds_read_b128 v[164:167], v240 offset:37888
	ds_read_b128 v[168:171], v240 offset:38912
	ds_read_b128 v[172:175], v240 offset:39936
	global_load_lds_dwordx4 v204, s[18:19]
	s_mov_b32 m0, s31
	s_nop 0
	global_load_lds_dwordx4 v208, s[18:19]
	s_waitcnt lgkmcnt(8)
	s_waitcnt lgkmcnt(0)
	s_barrier
	v_mfma_f32_16x16x32_bf16 v[124:127], v[128:131], v[144:147], v[124:127]
	v_mfma_f32_16x16x32_bf16 v[120:123], v[136:139], v[144:147], v[120:123]
	v_mfma_f32_16x16x32_bf16 v[116:119], v[128:131], v[152:155], v[116:119]
	v_mfma_f32_16x16x32_bf16 v[108:111], v[136:139], v[152:155], v[108:111]
	v_mfma_f32_16x16x32_bf16 v[100:103], v[128:131], v[160:163], v[100:103]
	v_mfma_f32_16x16x32_bf16 v[92:95], v[136:139], v[160:163], v[92:95]
	v_mfma_f32_16x16x32_bf16 v[84:87], v[128:131], v[168:171], v[84:87]
	v_mfma_f32_16x16x32_bf16 v[76:79], v[136:139], v[168:171], v[76:79]
	v_mfma_f32_16x16x32_bf16 v[124:127], v[132:135], v[148:151], v[124:127]
	v_mfma_f32_16x16x32_bf16 v[120:123], v[140:143], v[148:151], v[120:123]
	v_mfma_f32_16x16x32_bf16 v[116:119], v[132:135], v[156:159], v[116:119]
	v_mfma_f32_16x16x32_bf16 v[108:111], v[140:143], v[156:159], v[108:111]
	v_mfma_f32_16x16x32_bf16 v[100:103], v[132:135], v[164:167], v[100:103]
	v_mfma_f32_16x16x32_bf16 v[92:95], v[140:143], v[164:167], v[92:95]
	v_mfma_f32_16x16x32_bf16 v[84:87], v[132:135], v[172:175], v[84:87]
	v_mfma_f32_16x16x32_bf16 v[76:79], v[140:143], v[172:175], v[76:79]
	s_barrier
	s_add_i32 s18, 0, 0x1c000
	s_add_i32 s19, s41, s27
	s_add_i32 m0, s19, 0xffffff80
	ds_read_b128 v[176:179], v222 offset:49152
	ds_read_b128 v[180:183], v222 offset:50176
	ds_read_b128 v[184:187], v222 offset:51200
	ds_read_b128 v[188:191], v222 offset:52224
	global_load_lds_dwordx4 v206, s[16:17] offset:128
	s_add_i32 m0, s19, 0x1f80
	s_nop 0
	global_load_lds_dwordx4 v210, s[16:17] offset:128
	s_waitcnt lgkmcnt(0)
	s_barrier
	v_mfma_f32_16x16x32_bf16 v[112:115], v[176:179], v[144:147], v[112:115]
	v_mfma_f32_16x16x32_bf16 v[104:107], v[184:187], v[144:147], v[104:107]
	v_mfma_f32_16x16x32_bf16 v[96:99], v[176:179], v[152:155], v[96:99]
	v_mfma_f32_16x16x32_bf16 v[88:91], v[184:187], v[152:155], v[88:91]
	v_mfma_f32_16x16x32_bf16 v[80:83], v[176:179], v[160:163], v[80:83]
	v_mfma_f32_16x16x32_bf16 v[72:75], v[184:187], v[160:163], v[72:75]
	v_mfma_f32_16x16x32_bf16 v[68:71], v[176:179], v[168:171], v[68:71]
	v_mfma_f32_16x16x32_bf16 v[64:67], v[184:187], v[168:171], v[64:67]
	v_mfma_f32_16x16x32_bf16 v[112:115], v[180:183], v[148:151], v[112:115]
	v_mfma_f32_16x16x32_bf16 v[104:107], v[188:191], v[148:151], v[104:107]
	v_mfma_f32_16x16x32_bf16 v[96:99], v[180:183], v[156:159], v[96:99]
	v_mfma_f32_16x16x32_bf16 v[88:91], v[188:191], v[156:159], v[88:91]
	v_mfma_f32_16x16x32_bf16 v[80:83], v[180:183], v[164:167], v[80:83]
	v_mfma_f32_16x16x32_bf16 v[72:75], v[188:191], v[164:167], v[72:75]
	v_mfma_f32_16x16x32_bf16 v[68:71], v[180:183], v[172:175], v[68:71]
	v_mfma_f32_16x16x32_bf16 v[64:67], v[188:191], v[172:175], v[64:67]
	s_mov_b32 m0, s33
	s_barrier
	ds_read_b128 v[144:147], v240 offset:49152
	ds_read_b128 v[148:151], v240 offset:50176
	ds_read_b128 v[152:155], v240 offset:51200
	ds_read_b128 v[156:159], v240 offset:52224
	ds_read_b128 v[160:163], v240 offset:53248
	ds_read_b128 v[164:167], v240 offset:54272
	ds_read_b128 v[168:171], v240 offset:55296
	ds_read_b128 v[172:175], v240 offset:56320
	global_load_lds_dwordx4 v204, s[48:49]
	s_mov_b32 m0, s34
	s_nop 0
	global_load_lds_dwordx4 v208, s[48:49]
	s_waitcnt lgkmcnt(0)
	s_barrier
	v_mfma_f32_16x16x32_bf16 v[60:63], v[128:131], v[144:147], v[60:63]
	v_mfma_f32_16x16x32_bf16 v[56:59], v[136:139], v[144:147], v[56:59]
	v_mfma_f32_16x16x32_bf16 v[52:55], v[128:131], v[152:155], v[52:55]
	v_mfma_f32_16x16x32_bf16 v[44:47], v[136:139], v[152:155], v[44:47]
	v_mfma_f32_16x16x32_bf16 v[36:39], v[128:131], v[160:163], v[36:39]
	v_mfma_f32_16x16x32_bf16 v[28:31], v[136:139], v[160:163], v[28:31]
	v_mfma_f32_16x16x32_bf16 v[20:23], v[128:131], v[168:171], v[20:23]
	v_mfma_f32_16x16x32_bf16 v[12:15], v[136:139], v[168:171], v[12:15]
	v_mfma_f32_16x16x32_bf16 v[60:63], v[132:135], v[148:151], v[60:63]
	v_mfma_f32_16x16x32_bf16 v[56:59], v[140:143], v[148:151], v[56:59]
	v_mfma_f32_16x16x32_bf16 v[52:55], v[132:135], v[156:159], v[52:55]
	v_mfma_f32_16x16x32_bf16 v[44:47], v[140:143], v[156:159], v[44:47]
	v_mfma_f32_16x16x32_bf16 v[36:39], v[132:135], v[164:167], v[36:39]
	v_mfma_f32_16x16x32_bf16 v[28:31], v[140:143], v[164:167], v[28:31]
	v_mfma_f32_16x16x32_bf16 v[20:23], v[132:135], v[172:175], v[20:23]
	v_mfma_f32_16x16x32_bf16 v[12:15], v[140:143], v[172:175], v[12:15]
	s_barrier
	s_add_u32 s16, s16, 0x80080
	s_addc_u32 s17, s17, 0
	s_add_i32 s18, s18, s27
	s_mov_b32 m0, s18
	s_nop 0
	global_load_lds_dwordx4 v206, s[16:17]
	s_add_i32 m0, s18, 0x2000
	s_nop 0
	global_load_lds_dwordx4 v210, s[16:17]
	s_waitcnt vmcnt(6)
	s_barrier
	v_mfma_f32_16x16x32_bf16 v[48:51], v[176:179], v[144:147], v[48:51]
	v_mfma_f32_16x16x32_bf16 v[40:43], v[184:187], v[144:147], v[40:43]
	v_mfma_f32_16x16x32_bf16 v[32:35], v[176:179], v[152:155], v[32:35]
	v_mfma_f32_16x16x32_bf16 v[24:27], v[184:187], v[152:155], v[24:27]
	v_mfma_f32_16x16x32_bf16 v[16:19], v[176:179], v[160:163], v[16:19]
	v_mfma_f32_16x16x32_bf16 v[8:11], v[184:187], v[160:163], v[8:11]
	v_mfma_f32_16x16x32_bf16 v[4:7], v[176:179], v[168:171], v[4:7]
	v_mfma_f32_16x16x32_bf16 v[0:3], v[184:187], v[168:171], v[0:3]
	v_mfma_f32_16x16x32_bf16 v[48:51], v[180:183], v[148:151], v[48:51]
	v_mfma_f32_16x16x32_bf16 v[40:43], v[188:191], v[148:151], v[40:43]
	v_mfma_f32_16x16x32_bf16 v[32:35], v[180:183], v[156:159], v[32:35]
	v_mfma_f32_16x16x32_bf16 v[24:27], v[188:191], v[156:159], v[24:27]
	v_mfma_f32_16x16x32_bf16 v[16:19], v[180:183], v[164:167], v[16:19]
	v_mfma_f32_16x16x32_bf16 v[8:11], v[188:191], v[164:167], v[8:11]
	v_mfma_f32_16x16x32_bf16 v[4:7], v[180:183], v[172:175], v[4:7]
	v_mfma_f32_16x16x32_bf16 v[0:3], v[188:191], v[172:175], v[0:3]
	s_add_i32 s40, s40, 2
	s_add_u32 s14, s14, 0x100
	s_addc_u32 s15, s15, 0
	s_add_u32 s38, s38, 0x100
	s_addc_u32 s39, s39, 0
	s_cmp_gt_u32 s40, 29
	s_barrier
	s_cbranch_scc0 .LBB0_200
	v_lshl_add_u32 v228, s4, 8, v237
	v_or_b32_e32 v226, 16, v228
	s_mov_b64 s[4:5], -1
	s_cmp_lt_i32 s36, 16
	v_ashrrev_i32_e32 v229, 31, v228
	v_lshlrev_b32_e32 v192, 1, v212
	v_ashrrev_i32_e32 v227, 31, v226
	v_or_b32_e32 v224, 32, v228
	v_or_b32_e32 v222, 48, v228
	s_cbranch_scc0 .LBB0_203
	s_and_b32 s7, s36, 7
	s_cmp_gt_i32 s36, 7
	s_cselect_b64 vcc, -1, 0
	s_and_b64 s[4:5], vcc, exec
	s_mov_b32 s4, 0x15000000
	s_cselect_b32 s4, s4, 0xd000000
	s_add_u32 s4, s50, s4
	s_addc_u32 s5, s51, 0
	s_lshl_b32 s9, s7, 9
	s_add_u32 s4, s4, s9
	v_cvt_f32_ubyte0_e32 v128, s7
	s_addc_u32 s5, s5, 0
	v_sub_f32_e32 v128, 0xc0a00000, v128
	s_mov_b32 s7, 0xc2fc0000
	v_lshl_add_u64 v[230:231], s[4:5], 0, v[192:193]
	v_cmp_gt_f32_e64 s[4:5], s7, v128
	v_ashrrev_i32_e32 v225, 31, v224
	s_nop 0
	v_cndmask_b32_e64 v129, 0, v234, s[4:5]
	v_add_f32_e32 v128, v128, v129
	v_exp_f32_e32 v128, v128
	s_and_b64 s[4:5], s[4:5], exec
	s_cselect_b32 s4, 0xffffffc0, 0
	v_mov_b32_e32 v129, v193
	v_ldexp_f32 v128, v128, s4
	v_sub_f32_e32 v128, 1.0, v128
	v_log_f32_e32 v241, v128
	v_lshlrev_b32_e32 v128, 9, v228
	v_and_b32_e32 v128, 0x1f9e00, v128
	v_lshl_add_u64 v[130:131], v[214:215], 0, v[128:129]
	v_lshl_add_u64 v[132:133], v[216:217], 0, v[128:129]
	global_load_dwordx4 v[180:183], v[130:131], off offset:16
	global_load_dwordx4 v[188:191], v[130:131], off
	global_load_dwordx4 v[176:179], v[132:133], off offset:16
	global_load_dwordx4 v[184:187], v[132:133], off
	v_or_b32_e32 v130, 0x2000, v128
	v_mov_b32_e32 v131, v193
	v_lshl_add_u64 v[132:133], v[214:215], 0, v[130:131]
	v_lshl_add_u64 v[130:131], v[216:217], 0, v[130:131]
	global_load_dwordx4 v[164:167], v[132:133], off offset:16
	global_load_dwordx4 v[172:175], v[132:133], off
	global_load_dwordx4 v[160:163], v[130:131], off offset:16
	global_load_dwordx4 v[168:171], v[130:131], off
	v_mul_f32_e64 v196, v241, -v239
	v_cmp_gt_f32_e64 s[4:5], s7, v196
	v_or_b32_e32 v130, 0x4000, v128
	v_mov_b32_e32 v131, v193
	v_cndmask_b32_e64 v196, 0, v234, s[4:5]
	v_fma_f32 v196, v241, -v239, v196
	v_exp_f32_e32 v196, v196
	v_cndmask_b32_e64 v197, 0, v235, s[4:5]
	v_lshl_add_u64 v[132:133], v[214:215], 0, v[130:131]
	v_lshl_add_u64 v[130:131], v[216:217], 0, v[130:131]
	v_ldexp_f32 v196, v196, v197
	v_mul_f32_e32 v196, 0x3d800000, v196
	v_cndmask_b32_e32 v242, 1.0, v196, vcc
	v_mov_b32_e32 v196, v124
	v_mov_b32_e32 v197, v112
	global_load_dwordx4 v[148:151], v[132:133], off offset:16
	global_load_dwordx4 v[156:159], v[132:133], off
	global_load_dwordx4 v[144:147], v[130:131], off offset:16
	global_load_dwordx4 v[152:155], v[130:131], off
	v_or_b32_e32 v128, 0x6000, v128
	v_lshl_add_u64 v[130:131], v[214:215], 0, v[128:129]
	v_lshl_add_u64 v[136:137], v[216:217], 0, v[128:129]
	global_load_dwordx4 v[132:135], v[130:131], off offset:16
	global_load_dwordx4 v[140:143], v[130:131], off
	s_nop 0
	global_load_dwordx4 v[128:131], v[136:137], off offset:16
	s_nop 0
	global_load_dwordx4 v[136:139], v[136:137], off
	s_movk_i32 s4, 0x5f
	s_waitcnt vmcnt(0)
	v_mov_b32_e32 v198, v188
	v_mov_b32_e32 v199, v184
	v_pk_mul_f32 v[196:197], v[196:197], v[198:199]
	s_nop 0
	v_sub_f32_e32 v184, v196, v197
	v_mov_b32_e32 v196, v112
	v_mov_b32_e32 v197, v124
	v_pk_mul_f32 v[196:197], v[196:197], v[198:199]
	v_mul_f32_e32 v223, v242, v184
	v_add_f32_e32 v184, v196, v197
	v_mul_f32_e32 v198, v242, v184
	v_mov_b32_e32 v196, v125
	v_mov_b32_e32 v197, v113
	v_mov_b32_e32 v184, v189
	v_pk_mul_f32 v[188:189], v[196:197], v[184:185]
	s_nop 0
	v_sub_f32_e32 v188, v188, v189
	v_mul_f32_e32 v196, v242, v188
	v_mov_b32_e32 v188, v113
	v_mov_b32_e32 v189, v125
	v_pk_mul_f32 v[184:185], v[188:189], v[184:185]
	v_mov_b32_e32 v188, v190
	v_add_f32_e32 v184, v184, v185
	v_mul_f32_e32 v197, v242, v184
	v_mov_b32_e32 v184, v126
	v_mov_b32_e32 v185, v114
	v_mov_b32_e32 v189, v186
	v_pk_mul_f32 v[184:185], v[184:185], v[188:189]
	v_mov_b32_e32 v186, v191
	v_sub_f32_e32 v184, v184, v185
	v_mul_f32_e32 v190, v242, v184
	v_mov_b32_e32 v184, v114
	v_mov_b32_e32 v185, v126
	v_pk_mul_f32 v[184:185], v[184:185], v[188:189]
	s_nop 0
	v_add_f32_e32 v184, v184, v185
	v_mul_f32_e32 v188, v242, v184
	v_mov_b32_e32 v184, v127
	v_mov_b32_e32 v185, v115
	v_pk_mul_f32 v[184:185], v[184:185], v[186:187]
	s_nop 0
	v_sub_f32_e32 v184, v184, v185
	v_mul_f32_e32 v189, v242, v184
	v_mov_b32_e32 v184, v115
	v_mov_b32_e32 v185, v127
	v_pk_mul_f32 v[184:185], v[184:185], v[186:187]
	v_mov_b32_e32 v186, v180
	v_add_f32_e32 v184, v184, v185
	v_mul_f32_e32 v191, v242, v184
	v_mov_b32_e32 v184, v120
	v_mov_b32_e32 v185, v104
	v_mov_b32_e32 v187, v176
	v_pk_mul_f32 v[184:185], v[184:185], v[186:187]
	s_nop 0
	v_sub_f32_e32 v176, v184, v185
	v_mov_b32_e32 v184, v104
	v_mov_b32_e32 v185, v120
	v_pk_mul_f32 v[184:185], v[184:185], v[186:187]
	v_mul_f32_e32 v199, v242, v176
	v_add_f32_e32 v176, v184, v185
	v_mul_f32_e32 v186, v242, v176
	v_mov_b32_e32 v184, v121
	v_mov_b32_e32 v185, v105
	v_mov_b32_e32 v176, v181
	v_pk_mul_f32 v[180:181], v[184:185], v[176:177]
	s_nop 0
	v_sub_f32_e32 v180, v180, v181
	v_mul_f32_e32 v184, v242, v180
	v_mov_b32_e32 v180, v105
	v_mov_b32_e32 v181, v121
	v_pk_mul_f32 v[176:177], v[180:181], v[176:177]
	v_mov_b32_e32 v180, v182
	v_add_f32_e32 v176, v176, v177
	v_mul_f32_e32 v185, v242, v176
	v_mov_b32_e32 v176, v122
	v_mov_b32_e32 v177, v106
	v_mov_b32_e32 v181, v178
	v_pk_mul_f32 v[176:177], v[176:177], v[180:181]
	v_mov_b32_e32 v178, v183
	v_sub_f32_e32 v176, v176, v177
	v_mul_f32_e32 v182, v242, v176
	v_mov_b32_e32 v176, v106
	v_mov_b32_e32 v177, v122
	v_pk_mul_f32 v[176:177], v[176:177], v[180:181]
	s_nop 0
	v_add_f32_e32 v176, v176, v177
	v_mul_f32_e32 v187, v242, v176
	v_mov_b32_e32 v176, v123
	v_mov_b32_e32 v177, v107
	v_pk_mul_f32 v[176:177], v[176:177], v[178:179]
	s_nop 0
	v_sub_f32_e32 v176, v176, v177
	v_mul_f32_e32 v181, v242, v176
	v_mov_b32_e32 v176, v107
	v_mov_b32_e32 v177, v123
	v_pk_mul_f32 v[176:177], v[176:177], v[178:179]
	v_cvt_pk_bf16_f32 v178, v223, v196
	v_cvt_pk_bf16_f32 v179, v190, v189
	v_cvt_pk_bf16_f32 v180, v199, v184
	v_cvt_pk_bf16_f32 v181, v182, v181
	v_cvt_pk_bf16_f32 v182, v198, v197
	s_nop 0
	v_add_f32_e32 v176, v176, v177
	v_mul_f32_e32 v176, v242, v176
	v_cvt_pk_bf16_f32 v183, v188, v191
	v_cvt_pk_bf16_f32 v184, v186, v185
	v_cvt_pk_bf16_f32 v185, v187, v176
	v_lshlrev_b64 v[176:177], 12, v[228:229]
	v_lshl_add_u64 v[176:177], v[230:231], 0, v[176:177]
	global_store_dwordx4 v[176:177], v[178:181], off
	global_store_dwordx4 v[176:177], v[182:185], off offset:256
	v_ashrrev_i32_e32 v223, 31, v222
	v_bitop3_b32 v178, v228, s4, 16 bitop3:0xc8
	v_add_u32_e32 v178, 1, v178
	v_cvt_f32_ubyte0_e32 v178, v178
	v_mul_f32_e64 v179, v241, -v178
	v_cmp_gt_f32_e64 s[4:5], s7, v179
	v_mov_b32_e32 v181, v168
	v_mov_b32_e32 v190, v60
	v_cndmask_b32_e64 v180, 0, v234, s[4:5]
	v_fma_f32 v178, v241, -v178, v180
	v_exp_f32_e32 v178, v178
	v_cndmask_b32_e64 v179, 0, v235, s[4:5]
	v_mov_b32_e32 v180, v172
	s_movk_i32 s4, 0x6f
	v_ldexp_f32 v178, v178, v179
	v_mul_f32_e32 v178, 0x3d800000, v178
	v_cndmask_b32_e32 v182, 1.0, v178, vcc
	v_mov_b32_e32 v178, v116
	v_mov_b32_e32 v179, v96
	v_pk_mul_f32 v[178:179], v[178:179], v[180:181]
	v_mov_b32_e32 v191, v48
	v_sub_f32_e32 v168, v178, v179
	v_mov_b32_e32 v178, v96
	v_mov_b32_e32 v179, v116
	v_pk_mul_f32 v[178:179], v[178:179], v[180:181]
	v_mul_f32_e32 v183, v182, v168
	v_add_f32_e32 v168, v178, v179
	v_mul_f32_e32 v180, v182, v168
	v_mov_b32_e32 v178, v117
	v_mov_b32_e32 v179, v97
	v_mov_b32_e32 v168, v173
	v_pk_mul_f32 v[172:173], v[178:179], v[168:169]
	s_nop 0
	v_sub_f32_e32 v172, v172, v173
	v_mul_f32_e32 v178, v182, v172
	v_mov_b32_e32 v172, v97
	v_mov_b32_e32 v173, v117
	v_pk_mul_f32 v[168:169], v[172:173], v[168:169]
	v_mov_b32_e32 v172, v174
	v_add_f32_e32 v168, v168, v169
	v_mul_f32_e32 v179, v182, v168
	v_mov_b32_e32 v168, v118
	v_mov_b32_e32 v169, v98
	v_mov_b32_e32 v173, v170
	v_pk_mul_f32 v[168:169], v[168:169], v[172:173]
	v_mov_b32_e32 v170, v175
	v_sub_f32_e32 v168, v168, v169
	v_mul_f32_e32 v174, v182, v168
	v_mov_b32_e32 v168, v98
	v_mov_b32_e32 v169, v118
	v_pk_mul_f32 v[168:169], v[168:169], v[172:173]
	s_nop 0
	v_add_f32_e32 v168, v168, v169
	v_mul_f32_e32 v172, v182, v168
	v_mov_b32_e32 v168, v119
	v_mov_b32_e32 v169, v99
	v_pk_mul_f32 v[168:169], v[168:169], v[170:171]
	s_nop 0
	v_sub_f32_e32 v168, v168, v169
	v_mul_f32_e32 v173, v182, v168
	v_mov_b32_e32 v168, v99
	v_mov_b32_e32 v169, v119
	v_pk_mul_f32 v[168:169], v[168:169], v[170:171]
	v_mov_b32_e32 v170, v164
	v_add_f32_e32 v168, v168, v169
	v_mul_f32_e32 v175, v182, v168
	v_mov_b32_e32 v168, v108
	v_mov_b32_e32 v169, v88
	v_mov_b32_e32 v171, v160
	v_pk_mul_f32 v[168:169], v[168:169], v[170:171]
	s_nop 0
	v_sub_f32_e32 v160, v168, v169
	v_mov_b32_e32 v168, v88
	v_mov_b32_e32 v169, v108
	v_pk_mul_f32 v[168:169], v[168:169], v[170:171]
	v_mul_f32_e32 v181, v182, v160
	v_add_f32_e32 v160, v168, v169
	v_mul_f32_e32 v170, v182, v160
	v_mov_b32_e32 v168, v109
	v_mov_b32_e32 v169, v89
	v_mov_b32_e32 v160, v165
	v_pk_mul_f32 v[164:165], v[168:169], v[160:161]
	s_nop 0
	v_sub_f32_e32 v164, v164, v165
	v_mul_f32_e32 v168, v182, v164
	v_mov_b32_e32 v164, v89
	v_mov_b32_e32 v165, v109
	v_pk_mul_f32 v[160:161], v[164:165], v[160:161]
	v_mov_b32_e32 v164, v166
	v_add_f32_e32 v160, v160, v161
	v_mul_f32_e32 v169, v182, v160
	v_mov_b32_e32 v160, v110
	v_mov_b32_e32 v161, v90
	v_mov_b32_e32 v165, v162
	v_pk_mul_f32 v[160:161], v[160:161], v[164:165]
	v_mov_b32_e32 v162, v167
	v_sub_f32_e32 v160, v160, v161
	v_mul_f32_e32 v166, v182, v160
	v_mov_b32_e32 v160, v90
	v_mov_b32_e32 v161, v110
	v_pk_mul_f32 v[160:161], v[160:161], v[164:165]
	s_nop 0
	v_add_f32_e32 v160, v160, v161
	v_mul_f32_e32 v171, v182, v160
	v_mov_b32_e32 v160, v111
	v_mov_b32_e32 v161, v91
	v_pk_mul_f32 v[160:161], v[160:161], v[162:163]
	s_nop 0
	v_sub_f32_e32 v160, v160, v161
	v_mul_f32_e32 v164, v182, v160
	v_mov_b32_e32 v160, v91
	v_mov_b32_e32 v161, v111
	v_pk_mul_f32 v[160:161], v[160:161], v[162:163]
	s_nop 0
	v_add_f32_e32 v160, v160, v161
	v_mul_f32_e32 v167, v182, v160
	v_cvt_pk_bf16_f32 v160, v183, v178
	v_cvt_pk_bf16_f32 v161, v174, v173
	v_cvt_pk_bf16_f32 v162, v181, v168
	v_cvt_pk_bf16_f32 v163, v166, v164
	v_cvt_pk_bf16_f32 v164, v180, v179
	v_cvt_pk_bf16_f32 v165, v172, v175
	v_cvt_pk_bf16_f32 v166, v170, v169
	v_lshlrev_b64 v[168:169], 12, v[226:227]
	v_lshl_add_u64 v[168:169], v[230:231], 0, v[168:169]
	v_cvt_pk_bf16_f32 v167, v171, v167
	global_store_dwordx4 v[168:169], v[160:163], off
	global_store_dwordx4 v[168:169], v[164:167], off offset:256
	s_nop 0
	v_bitop3_b32 v160, v228, s4, 32 bitop3:0xc8
	v_add_u32_e32 v160, 1, v160
	v_cvt_f32_ubyte0_e32 v160, v160
	v_mul_f32_e64 v161, v241, -v160
	v_cmp_gt_f32_e64 s[4:5], s7, v161
	v_mov_b32_e32 v163, v152
	s_nop 0
	v_cndmask_b32_e64 v162, 0, v234, s[4:5]
	v_fma_f32 v160, v241, -v160, v162
	v_exp_f32_e32 v160, v160
	v_cndmask_b32_e64 v161, 0, v235, s[4:5]
	v_mov_b32_e32 v162, v156
	s_movk_i32 s4, 0x7f
	v_ldexp_f32 v160, v160, v161
	v_mul_f32_e32 v160, 0x3d800000, v160
	v_cndmask_b32_e32 v164, 1.0, v160, vcc
	v_mov_b32_e32 v160, v100
	v_mov_b32_e32 v161, v80
	v_pk_mul_f32 v[160:161], v[160:161], v[162:163]
	s_nop 0
	v_sub_f32_e32 v152, v160, v161
	v_mov_b32_e32 v160, v80
	v_mov_b32_e32 v161, v100
	v_pk_mul_f32 v[160:161], v[160:161], v[162:163]
	v_mul_f32_e32 v165, v164, v152
	v_add_f32_e32 v152, v160, v161
	v_mul_f32_e32 v162, v164, v152
	v_mov_b32_e32 v160, v101
	v_mov_b32_e32 v161, v81
	v_mov_b32_e32 v152, v157
	v_pk_mul_f32 v[156:157], v[160:161], v[152:153]
	s_nop 0
	v_sub_f32_e32 v156, v156, v157
	v_mul_f32_e32 v160, v164, v156
	v_mov_b32_e32 v156, v81
	v_mov_b32_e32 v157, v101
	v_pk_mul_f32 v[152:153], v[156:157], v[152:153]
	v_mov_b32_e32 v156, v158
	v_add_f32_e32 v152, v152, v153
	v_mul_f32_e32 v161, v164, v152
	v_mov_b32_e32 v152, v102
	v_mov_b32_e32 v153, v82
	v_mov_b32_e32 v157, v154
	v_pk_mul_f32 v[152:153], v[152:153], v[156:157]
	v_mov_b32_e32 v154, v159
	v_sub_f32_e32 v152, v152, v153
	v_mul_f32_e32 v158, v164, v152
	v_mov_b32_e32 v152, v82
	v_mov_b32_e32 v153, v102
	v_pk_mul_f32 v[152:153], v[152:153], v[156:157]
	s_nop 0
	v_add_f32_e32 v152, v152, v153
	v_mul_f32_e32 v156, v164, v152
	v_mov_b32_e32 v152, v103
	v_mov_b32_e32 v153, v83
	v_pk_mul_f32 v[152:153], v[152:153], v[154:155]
	s_nop 0
	v_sub_f32_e32 v152, v152, v153
	v_mul_f32_e32 v157, v164, v152
	v_mov_b32_e32 v152, v83
	v_mov_b32_e32 v153, v103
	v_pk_mul_f32 v[152:153], v[152:153], v[154:155]
	v_mov_b32_e32 v154, v148
	v_add_f32_e32 v152, v152, v153
	v_mul_f32_e32 v159, v164, v152
	v_mov_b32_e32 v152, v92
	v_mov_b32_e32 v153, v72
	v_mov_b32_e32 v155, v144
	v_pk_mul_f32 v[152:153], v[152:153], v[154:155]
	s_nop 0
	v_sub_f32_e32 v144, v152, v153
	v_mov_b32_e32 v152, v72
	v_mov_b32_e32 v153, v92
	v_pk_mul_f32 v[152:153], v[152:153], v[154:155]
	v_mul_f32_e32 v163, v164, v144
	v_add_f32_e32 v144, v152, v153
	v_mul_f32_e32 v154, v164, v144
	v_mov_b32_e32 v152, v93
	v_mov_b32_e32 v153, v73
	v_mov_b32_e32 v144, v149
	v_pk_mul_f32 v[148:149], v[152:153], v[144:145]
	s_nop 0
	v_sub_f32_e32 v148, v148, v149
	v_mul_f32_e32 v152, v164, v148
	v_mov_b32_e32 v148, v73
	v_mov_b32_e32 v149, v93
	v_pk_mul_f32 v[144:145], v[148:149], v[144:145]
	v_mov_b32_e32 v148, v150
	v_add_f32_e32 v144, v144, v145
	v_mul_f32_e32 v153, v164, v144
	v_mov_b32_e32 v144, v94
	v_mov_b32_e32 v145, v74
	v_mov_b32_e32 v149, v146
	v_pk_mul_f32 v[144:145], v[144:145], v[148:149]
	v_mov_b32_e32 v146, v151
	v_sub_f32_e32 v144, v144, v145
	v_mul_f32_e32 v150, v164, v144
	v_mov_b32_e32 v144, v74
	v_mov_b32_e32 v145, v94
	v_pk_mul_f32 v[144:145], v[144:145], v[148:149]
	s_nop 0
	v_add_f32_e32 v144, v144, v145
	v_mul_f32_e32 v155, v164, v144
	v_mov_b32_e32 v144, v95
	v_mov_b32_e32 v145, v75
	v_pk_mul_f32 v[144:145], v[144:145], v[146:147]
	s_nop 0
	v_sub_f32_e32 v144, v144, v145
	v_mul_f32_e32 v148, v164, v144
	v_mov_b32_e32 v144, v75
	v_mov_b32_e32 v145, v95
	v_pk_mul_f32 v[144:145], v[144:145], v[146:147]
	s_nop 0
	v_add_f32_e32 v144, v144, v145
	v_mul_f32_e32 v151, v164, v144
	v_cvt_pk_bf16_f32 v144, v165, v160
	v_cvt_pk_bf16_f32 v145, v158, v157
	v_cvt_pk_bf16_f32 v146, v163, v152
	v_cvt_pk_bf16_f32 v147, v150, v148
	v_cvt_pk_bf16_f32 v148, v162, v161
	v_cvt_pk_bf16_f32 v149, v156, v159
	v_cvt_pk_bf16_f32 v150, v154, v153
	v_lshlrev_b64 v[152:153], 12, v[224:225]
	v_lshl_add_u64 v[152:153], v[230:231], 0, v[152:153]
	v_cvt_pk_bf16_f32 v151, v155, v151
	global_store_dwordx4 v[152:153], v[144:147], off
	global_store_dwordx4 v[152:153], v[148:151], off offset:256
	s_nop 0
	v_bitop3_b32 v144, v228, s4, 48 bitop3:0xc8
	v_add_u32_e32 v144, 1, v144
	v_cvt_f32_ubyte0_e32 v144, v144
	v_mul_f32_e64 v145, v241, -v144
	v_cmp_gt_f32_e64 s[4:5], s7, v145
	v_mov_b32_e32 v147, v136
	s_nop 0
	v_cndmask_b32_e64 v146, 0, v234, s[4:5]
	v_fma_f32 v144, v241, -v144, v146
	v_exp_f32_e32 v144, v144
	v_cndmask_b32_e64 v145, 0, v235, s[4:5]
	v_mov_b32_e32 v146, v140
	s_mov_b64 s[4:5], 0x80000
	v_ldexp_f32 v144, v144, v145
	v_mul_f32_e32 v144, 0x3d800000, v144
	v_cndmask_b32_e32 v148, 1.0, v144, vcc
	v_mov_b32_e32 v144, v84
	v_mov_b32_e32 v145, v68
	v_pk_mul_f32 v[144:145], v[144:145], v[146:147]
	s_nop 0
	v_sub_f32_e32 v136, v144, v145
	v_mov_b32_e32 v144, v68
	v_mov_b32_e32 v145, v84
	v_pk_mul_f32 v[144:145], v[144:145], v[146:147]
	v_mul_f32_e32 v149, v148, v136
	v_add_f32_e32 v136, v144, v145
	v_mul_f32_e32 v146, v148, v136
	v_mov_b32_e32 v144, v85
	v_mov_b32_e32 v145, v69
	v_mov_b32_e32 v136, v141
	v_pk_mul_f32 v[140:141], v[144:145], v[136:137]
	s_nop 0
	v_sub_f32_e32 v140, v140, v141
	v_mul_f32_e32 v144, v148, v140
	v_mov_b32_e32 v140, v69
	v_mov_b32_e32 v141, v85
	v_pk_mul_f32 v[136:137], v[140:141], v[136:137]
	v_mov_b32_e32 v140, v142
	v_add_f32_e32 v136, v136, v137
	v_mul_f32_e32 v145, v148, v136
	v_mov_b32_e32 v136, v86
	v_mov_b32_e32 v137, v70
	v_mov_b32_e32 v141, v138
	v_pk_mul_f32 v[136:137], v[136:137], v[140:141]
	v_mov_b32_e32 v138, v143
	v_sub_f32_e32 v136, v136, v137
	v_mul_f32_e32 v142, v148, v136
	v_mov_b32_e32 v136, v70
	v_mov_b32_e32 v137, v86
	v_pk_mul_f32 v[136:137], v[136:137], v[140:141]
	s_nop 0
	v_add_f32_e32 v136, v136, v137
	v_mul_f32_e32 v140, v148, v136
	v_mov_b32_e32 v136, v87
	v_mov_b32_e32 v137, v71
	v_pk_mul_f32 v[136:137], v[136:137], v[138:139]
	s_nop 0
	v_sub_f32_e32 v136, v136, v137
	v_mul_f32_e32 v141, v148, v136
	v_mov_b32_e32 v136, v71
	v_mov_b32_e32 v137, v87
	v_pk_mul_f32 v[136:137], v[136:137], v[138:139]
	v_mov_b32_e32 v138, v132
	v_add_f32_e32 v136, v136, v137
	v_mul_f32_e32 v143, v148, v136
	v_mov_b32_e32 v136, v76
	v_mov_b32_e32 v137, v64
	v_mov_b32_e32 v139, v128
	v_pk_mul_f32 v[136:137], v[136:137], v[138:139]
	s_nop 0
	v_sub_f32_e32 v128, v136, v137
	v_mov_b32_e32 v136, v64
	v_mov_b32_e32 v137, v76
	v_pk_mul_f32 v[136:137], v[136:137], v[138:139]
	v_mul_f32_e32 v147, v148, v128
	v_add_f32_e32 v128, v136, v137
	v_mul_f32_e32 v138, v148, v128
	v_mov_b32_e32 v136, v77
	v_mov_b32_e32 v137, v65
	v_mov_b32_e32 v128, v133
	v_pk_mul_f32 v[132:133], v[136:137], v[128:129]
	s_nop 0
	v_sub_f32_e32 v132, v132, v133
	v_mul_f32_e32 v136, v148, v132
	v_mov_b32_e32 v132, v65
	v_mov_b32_e32 v133, v77
	v_pk_mul_f32 v[128:129], v[132:133], v[128:129]
	v_mov_b32_e32 v132, v134
	v_add_f32_e32 v128, v128, v129
	v_mul_f32_e32 v137, v148, v128
	v_mov_b32_e32 v128, v78
	v_mov_b32_e32 v129, v66
	v_mov_b32_e32 v133, v130
	v_pk_mul_f32 v[128:129], v[128:129], v[132:133]
	v_mov_b32_e32 v130, v135
	v_sub_f32_e32 v128, v128, v129
	v_mul_f32_e32 v134, v148, v128
	v_mov_b32_e32 v128, v66
	v_mov_b32_e32 v129, v78
	v_pk_mul_f32 v[128:129], v[128:129], v[132:133]
	s_nop 0
	v_add_f32_e32 v128, v128, v129
	v_mul_f32_e32 v139, v148, v128
	v_mov_b32_e32 v128, v79
	v_mov_b32_e32 v129, v67
	v_pk_mul_f32 v[128:129], v[128:129], v[130:131]
	s_nop 0
	v_sub_f32_e32 v128, v128, v129
	v_mul_f32_e32 v132, v148, v128
	v_mov_b32_e32 v128, v67
	v_mov_b32_e32 v129, v79
	v_pk_mul_f32 v[128:129], v[128:129], v[130:131]
	s_nop 0
	v_add_f32_e32 v128, v128, v129
	v_mul_f32_e32 v135, v148, v128
	v_cvt_pk_bf16_f32 v128, v149, v144
	v_cvt_pk_bf16_f32 v129, v142, v141
	v_cvt_pk_bf16_f32 v130, v147, v136
	v_cvt_pk_bf16_f32 v131, v134, v132
	v_cvt_pk_bf16_f32 v132, v146, v145
	v_cvt_pk_bf16_f32 v133, v140, v143
	v_cvt_pk_bf16_f32 v134, v138, v137
	v_lshlrev_b64 v[136:137], 12, v[222:223]
	v_lshl_add_u64 v[136:137], v[230:231], 0, v[136:137]
	v_cvt_pk_bf16_f32 v135, v139, v135
	global_store_dwordx4 v[136:137], v[128:131], off
	global_store_dwordx4 v[136:137], v[132:135], off offset:256
	s_nop 0
	v_mov_b32_e32 v128, 0x4000
	v_lshl_add_u32 v128, v228, 7, v128
	v_and_b32_e32 v128, 0x7e780, v128
	v_lshlrev_b32_e32 v128, 2, v128
	v_mov_b32_e32 v129, v193
	v_lshl_add_u64 v[130:131], v[214:215], 0, v[128:129]
	v_lshl_add_u64 v[132:133], v[216:217], 0, v[128:129]
	global_load_dwordx4 v[168:171], v[130:131], off offset:16
	global_load_dwordx4 v[172:175], v[130:131], off
	global_load_dwordx4 v[178:181], v[132:133], off offset:16
	global_load_dwordx4 v[182:185], v[132:133], off
	v_or_b32_e32 v130, 0x2000, v128
	v_mov_b32_e32 v131, v193
	v_lshl_add_u64 v[132:133], v[214:215], 0, v[130:131]
	v_lshl_add_u64 v[130:131], v[216:217], 0, v[130:131]
	global_load_dwordx4 v[164:167], v[132:133], off offset:16
	global_load_dwordx4 v[186:189], v[132:133], off
	global_load_dwordx4 v[160:163], v[130:131], off offset:16
	global_load_dwordx4 v[196:199], v[130:131], off
	v_or_b32_e32 v130, 0x4000, v128
	v_mov_b32_e32 v131, v193
	v_lshl_add_u64 v[132:133], v[214:215], 0, v[130:131]
	v_lshl_add_u64 v[130:131], v[216:217], 0, v[130:131]
	global_load_dwordx4 v[148:151], v[132:133], off offset:16
	global_load_dwordx4 v[156:159], v[132:133], off
	global_load_dwordx4 v[144:147], v[130:131], off offset:16
	global_load_dwordx4 v[152:155], v[130:131], off
	v_or_b32_e32 v128, 0x6000, v128
	v_lshl_add_u64 v[130:131], v[214:215], 0, v[128:129]
	v_lshl_add_u64 v[136:137], v[216:217], 0, v[128:129]
	global_load_dwordx4 v[132:135], v[130:131], off offset:16
	global_load_dwordx4 v[140:143], v[130:131], off
	s_nop 0
	global_load_dwordx4 v[128:131], v[136:137], off offset:16
	s_nop 0
	global_load_dwordx4 v[136:139], v[136:137], off
	s_waitcnt vmcnt(0)
	v_mov_b32_e32 v244, v172
	v_mov_b32_e32 v245, v182
	v_pk_mul_f32 v[190:191], v[190:191], v[244:245]
	v_mov_b32_e32 v182, v173
	v_sub_f32_e32 v172, v190, v191
	v_mov_b32_e32 v190, v48
	v_mov_b32_e32 v191, v60
	v_pk_mul_f32 v[190:191], v[190:191], v[244:245]
	v_mul_f32_e32 v223, v242, v172
	v_add_f32_e32 v172, v190, v191
	v_mov_b32_e32 v190, v61
	v_mov_b32_e32 v191, v49
	v_mul_f32_e32 v225, v242, v172
	v_pk_mul_f32 v[172:173], v[190:191], v[182:183]
	s_nop 0
	v_sub_f32_e32 v172, v172, v173
	v_mul_f32_e32 v190, v242, v172
	v_mov_b32_e32 v172, v49
	v_mov_b32_e32 v173, v61
	v_pk_mul_f32 v[172:173], v[172:173], v[182:183]
	v_mov_b32_e32 v182, v174
	v_add_f32_e32 v172, v172, v173
	v_mul_f32_e32 v191, v242, v172
	v_mov_b32_e32 v172, v62
	v_mov_b32_e32 v173, v50
	v_mov_b32_e32 v183, v184
	v_pk_mul_f32 v[172:173], v[172:173], v[182:183]
	v_mov_b32_e32 v184, v175
	v_sub_f32_e32 v172, v172, v173
	v_mul_f32_e32 v243, v242, v172
	v_mov_b32_e32 v172, v50
	v_mov_b32_e32 v173, v62
	v_pk_mul_f32 v[172:173], v[172:173], v[182:183]
	v_mov_b32_e32 v174, v168
	v_add_f32_e32 v172, v172, v173
	v_mul_f32_e32 v182, v242, v172
	v_mov_b32_e32 v172, v63
	v_mov_b32_e32 v173, v51
	v_pk_mul_f32 v[172:173], v[172:173], v[184:185]
	v_mov_b32_e32 v175, v178
	v_sub_f32_e32 v172, v172, v173
	v_mul_f32_e32 v183, v242, v172
	v_mov_b32_e32 v172, v51
	v_mov_b32_e32 v173, v63
	v_pk_mul_f32 v[172:173], v[172:173], v[184:185]
	v_mov_b32_e32 v178, v169
	v_add_f32_e32 v172, v172, v173
	v_mul_f32_e32 v184, v242, v172
	v_mov_b32_e32 v172, v56
	v_mov_b32_e32 v173, v40
	v_pk_mul_f32 v[172:173], v[172:173], v[174:175]
	s_nop 0
	v_sub_f32_e32 v168, v172, v173
	v_mov_b32_e32 v172, v40
	v_mov_b32_e32 v173, v56
	v_pk_mul_f32 v[172:173], v[172:173], v[174:175]
	v_mul_f32_e32 v185, v242, v168
	v_add_f32_e32 v168, v172, v173
	v_mov_b32_e32 v172, v57
	v_mov_b32_e32 v173, v41
	v_mul_f32_e32 v174, v242, v168
	v_pk_mul_f32 v[168:169], v[172:173], v[178:179]
	v_mov_b32_e32 v172, v170
	v_sub_f32_e32 v168, v168, v169
	v_mul_f32_e32 v175, v242, v168
	v_mov_b32_e32 v168, v41
	v_mov_b32_e32 v169, v57
	v_pk_mul_f32 v[168:169], v[168:169], v[178:179]
	v_mov_b32_e32 v173, v180
	v_add_f32_e32 v168, v168, v169
	v_mul_f32_e32 v178, v242, v168
	v_mov_b32_e32 v168, v58
	v_mov_b32_e32 v169, v42
	v_pk_mul_f32 v[168:169], v[168:169], v[172:173]
	v_mov_b32_e32 v180, v171
	v_sub_f32_e32 v168, v168, v169
	v_mul_f32_e32 v179, v242, v168
	v_mov_b32_e32 v168, v42
	v_mov_b32_e32 v169, v58
	v_pk_mul_f32 v[168:169], v[168:169], v[172:173]
	s_nop 0
	v_add_f32_e32 v168, v168, v169
	v_mul_f32_e32 v244, v242, v168
	v_mov_b32_e32 v168, v59
	v_mov_b32_e32 v169, v43
	v_pk_mul_f32 v[168:169], v[168:169], v[180:181]
	s_nop 0
	v_sub_f32_e32 v168, v168, v169
	v_mul_f32_e32 v171, v242, v168
	v_mov_b32_e32 v168, v43
	v_mov_b32_e32 v169, v59
	v_pk_mul_f32 v[168:169], v[168:169], v[180:181]
	s_nop 0
	v_add_f32_e32 v168, v168, v169
	v_mul_f32_e32 v180, v242, v168
	v_cvt_pk_bf16_f32 v168, v223, v190
	v_cvt_pk_bf16_f32 v169, v243, v183
	v_cvt_pk_bf16_f32 v170, v185, v175
	v_cvt_pk_bf16_f32 v171, v179, v171
	v_cvt_pk_bf16_f32 v172, v225, v191
	v_cvt_pk_bf16_f32 v173, v182, v184
	v_cvt_pk_bf16_f32 v174, v174, v178
	v_lshl_add_u64 v[178:179], v[176:177], 0, s[4:5]
	s_mov_b32 s4, 0x80000
	v_add_co_u32_e64 v176, s[4:5], s4, v176
	v_cvt_pk_bf16_f32 v175, v244, v180
	s_nop 1
	v_addc_co_u32_e64 v177, s[4:5], 0, v177, s[4:5]
	global_store_dwordx4 v[176:177], v[168:171], off
	global_store_dwordx4 v[178:179], v[172:175], off offset:256
	s_nop 0
	v_add_u32_e32 v168, 0x90, v228
	v_and_b32_e32 v169, 0x5f, v168
	v_add_u32_e32 v169, 1, v169
	v_cvt_f32_ubyte0_e32 v169, v169
	v_mul_f32_e64 v170, v241, -v169
	v_cmp_gt_f32_e64 s[4:5], s7, v170
	v_mov_b32_e32 v171, v32
	v_mov_b32_e32 v172, v186
	v_cndmask_b32_e64 v170, 0, v234, s[4:5]
	v_fma_f32 v169, v241, -v169, v170
	v_exp_f32_e32 v169, v169
	v_cndmask_b32_e64 v170, 0, v235, s[4:5]
	v_mov_b32_e32 v173, v196
	v_mov_b32_e32 v196, v187
	v_ldexp_f32 v169, v169, v170
	v_mov_b32_e32 v170, v52
	v_mul_f32_e32 v169, 0x3d800000, v169
	v_pk_mul_f32 v[170:171], v[170:171], v[172:173]
	v_cndmask_b32_e32 v169, 1.0, v169, vcc
	v_sub_f32_e32 v170, v170, v171
	v_mul_f32_e32 v174, v169, v170
	v_mov_b32_e32 v170, v32
	v_mov_b32_e32 v171, v52
	v_pk_mul_f32 v[170:171], v[170:171], v[172:173]
	v_mov_b32_e32 v172, v188
	v_add_f32_e32 v170, v170, v171
	v_mul_f32_e32 v175, v169, v170
	v_mov_b32_e32 v170, v53
	v_mov_b32_e32 v171, v33
	v_pk_mul_f32 v[170:171], v[170:171], v[196:197]
	v_mov_b32_e32 v173, v198
	v_sub_f32_e32 v170, v170, v171
	v_mul_f32_e32 v176, v169, v170
	v_mov_b32_e32 v170, v33
	v_mov_b32_e32 v171, v53
	v_pk_mul_f32 v[170:171], v[170:171], v[196:197]
	v_mov_b32_e32 v198, v189
	v_add_f32_e32 v170, v170, v171
	v_mul_f32_e32 v177, v169, v170
	v_mov_b32_e32 v170, v54
	v_mov_b32_e32 v171, v34
	v_pk_mul_f32 v[170:171], v[170:171], v[172:173]
	s_nop 0
	v_sub_f32_e32 v170, v170, v171
	v_mul_f32_e32 v178, v169, v170
	v_mov_b32_e32 v170, v34
	v_mov_b32_e32 v171, v54
	v_pk_mul_f32 v[170:171], v[170:171], v[172:173]
	v_mov_b32_e32 v172, v164
	v_add_f32_e32 v170, v170, v171
	v_mul_f32_e32 v179, v169, v170
	v_mov_b32_e32 v170, v55
	v_mov_b32_e32 v171, v35
	v_pk_mul_f32 v[170:171], v[170:171], v[198:199]
	v_mov_b32_e32 v173, v160
	v_sub_f32_e32 v170, v170, v171
	v_mul_f32_e32 v180, v169, v170
	v_mov_b32_e32 v170, v35
	v_mov_b32_e32 v171, v55
	v_pk_mul_f32 v[170:171], v[170:171], v[198:199]
	s_nop 0
	v_add_f32_e32 v170, v170, v171
	v_mul_f32_e32 v181, v169, v170
	v_mov_b32_e32 v170, v44
	v_mov_b32_e32 v171, v24
	v_pk_mul_f32 v[170:171], v[170:171], v[172:173]
	s_nop 0
	v_sub_f32_e32 v160, v170, v171
	v_mov_b32_e32 v170, v24
	v_mov_b32_e32 v171, v44
	v_pk_mul_f32 v[170:171], v[170:171], v[172:173]
	v_mul_f32_e32 v182, v169, v160
	v_add_f32_e32 v160, v170, v171
	v_mul_f32_e32 v172, v169, v160
	v_mov_b32_e32 v170, v45
	v_mov_b32_e32 v171, v25
	v_mov_b32_e32 v160, v165
	v_pk_mul_f32 v[164:165], v[170:171], v[160:161]
	s_nop 0
	v_sub_f32_e32 v164, v164, v165
	v_mul_f32_e32 v170, v169, v164
	v_mov_b32_e32 v164, v25
	v_mov_b32_e32 v165, v45
	v_pk_mul_f32 v[160:161], v[164:165], v[160:161]
	v_mov_b32_e32 v164, v166
	v_add_f32_e32 v160, v160, v161
	v_mul_f32_e32 v171, v169, v160
	v_mov_b32_e32 v160, v46
	v_mov_b32_e32 v161, v26
	v_mov_b32_e32 v165, v162
	v_pk_mul_f32 v[160:161], v[160:161], v[164:165]
	v_mov_b32_e32 v162, v167
	v_sub_f32_e32 v160, v160, v161
	v_mul_f32_e32 v166, v169, v160
	v_mov_b32_e32 v160, v26
	v_mov_b32_e32 v161, v46
	v_pk_mul_f32 v[160:161], v[160:161], v[164:165]
	s_nop 0
	v_add_f32_e32 v160, v160, v161
	v_mul_f32_e32 v173, v169, v160
	v_mov_b32_e32 v160, v47
	v_mov_b32_e32 v161, v27
	v_pk_mul_f32 v[160:161], v[160:161], v[162:163]
	s_nop 0
	v_sub_f32_e32 v160, v160, v161
	v_mul_f32_e32 v164, v169, v160
	v_mov_b32_e32 v160, v27
	v_mov_b32_e32 v161, v47
	v_pk_mul_f32 v[160:161], v[160:161], v[162:163]
	s_nop 0
	v_add_f32_e32 v160, v160, v161
	v_mul_f32_e32 v167, v169, v160
	v_ashrrev_i32_e32 v169, 31, v168
	v_lshlrev_b64 v[168:169], 12, v[168:169]
	v_cvt_pk_bf16_f32 v160, v174, v176
	v_cvt_pk_bf16_f32 v161, v178, v180
	v_cvt_pk_bf16_f32 v162, v182, v170
	v_cvt_pk_bf16_f32 v163, v166, v164
	v_lshl_add_u64 v[168:169], v[230:231], 0, v[168:169]
	v_cvt_pk_bf16_f32 v164, v175, v177
	v_cvt_pk_bf16_f32 v165, v179, v181
	v_cvt_pk_bf16_f32 v166, v172, v171
	v_cvt_pk_bf16_f32 v167, v173, v167
	global_store_dwordx4 v[168:169], v[160:163], off
	global_store_dwordx4 v[168:169], v[164:167], off offset:256
	s_nop 0
	v_add_u32_e32 v160, 0xa0, v228
	v_and_b32_e32 v161, 0x6f, v160
	v_add_u32_e32 v161, 1, v161
	v_cvt_f32_ubyte0_e32 v161, v161
	v_mul_f32_e64 v162, v241, -v161
	v_cmp_gt_f32_e64 s[4:5], s7, v162
	v_mov_b32_e32 v163, v16
	v_mov_b32_e32 v164, v156
	v_cndmask_b32_e64 v162, 0, v234, s[4:5]
	v_fma_f32 v161, v241, -v161, v162
	v_exp_f32_e32 v161, v161
	v_cndmask_b32_e64 v162, 0, v235, s[4:5]
	v_mov_b32_e32 v165, v152
	v_ldexp_f32 v161, v161, v162
	v_mov_b32_e32 v162, v36
	v_pk_mul_f32 v[162:163], v[162:163], v[164:165]
	v_mul_f32_e32 v161, 0x3d800000, v161
	v_sub_f32_e32 v152, v162, v163
	v_mov_b32_e32 v162, v16
	v_mov_b32_e32 v163, v36
	v_cndmask_b32_e32 v161, 1.0, v161, vcc
	v_pk_mul_f32 v[162:163], v[162:163], v[164:165]
	v_mul_f32_e32 v166, v161, v152
	v_add_f32_e32 v152, v162, v163
	v_mul_f32_e32 v164, v161, v152
	v_mov_b32_e32 v162, v37
	v_mov_b32_e32 v163, v17
	v_mov_b32_e32 v152, v157
	v_pk_mul_f32 v[156:157], v[162:163], v[152:153]
	s_nop 0
	v_sub_f32_e32 v156, v156, v157
	v_mul_f32_e32 v162, v161, v156
	v_mov_b32_e32 v156, v17
	v_mov_b32_e32 v157, v37
	v_pk_mul_f32 v[152:153], v[156:157], v[152:153]
	v_mov_b32_e32 v156, v158
	v_add_f32_e32 v152, v152, v153
	v_mul_f32_e32 v163, v161, v152
	v_mov_b32_e32 v152, v38
	v_mov_b32_e32 v153, v18
	v_mov_b32_e32 v157, v154
	v_pk_mul_f32 v[152:153], v[152:153], v[156:157]
	v_mov_b32_e32 v154, v159
	v_sub_f32_e32 v152, v152, v153
	v_mul_f32_e32 v158, v161, v152
	v_mov_b32_e32 v152, v18
	v_mov_b32_e32 v153, v38
	v_pk_mul_f32 v[152:153], v[152:153], v[156:157]
	s_nop 0
	v_add_f32_e32 v152, v152, v153
	v_mul_f32_e32 v156, v161, v152
	v_mov_b32_e32 v152, v39
	v_mov_b32_e32 v153, v19
	v_pk_mul_f32 v[152:153], v[152:153], v[154:155]
	s_nop 0
	v_sub_f32_e32 v152, v152, v153
	v_mul_f32_e32 v157, v161, v152
	v_mov_b32_e32 v152, v19
	v_mov_b32_e32 v153, v39
	v_pk_mul_f32 v[152:153], v[152:153], v[154:155]
	v_mov_b32_e32 v154, v148
	v_add_f32_e32 v152, v152, v153
	v_mul_f32_e32 v159, v161, v152
	v_mov_b32_e32 v152, v28
	v_mov_b32_e32 v153, v8
	v_mov_b32_e32 v155, v144
	v_pk_mul_f32 v[152:153], v[152:153], v[154:155]
	s_nop 0
	v_sub_f32_e32 v144, v152, v153
	v_mov_b32_e32 v152, v8
	v_mov_b32_e32 v153, v28
	v_pk_mul_f32 v[152:153], v[152:153], v[154:155]
	v_mul_f32_e32 v165, v161, v144
	v_add_f32_e32 v144, v152, v153
	v_mul_f32_e32 v154, v161, v144
	v_mov_b32_e32 v152, v29
	v_mov_b32_e32 v153, v9
	v_mov_b32_e32 v144, v149
	v_pk_mul_f32 v[148:149], v[152:153], v[144:145]
	s_nop 0
	v_sub_f32_e32 v148, v148, v149
	v_mul_f32_e32 v152, v161, v148
	v_mov_b32_e32 v148, v9
	v_mov_b32_e32 v149, v29
	v_pk_mul_f32 v[144:145], v[148:149], v[144:145]
	v_mov_b32_e32 v148, v150
	v_add_f32_e32 v144, v144, v145
	v_mul_f32_e32 v153, v161, v144
	v_mov_b32_e32 v144, v30
	v_mov_b32_e32 v145, v10
	v_mov_b32_e32 v149, v146
	v_pk_mul_f32 v[144:145], v[144:145], v[148:149]
	v_mov_b32_e32 v146, v151
	v_sub_f32_e32 v144, v144, v145
	v_mul_f32_e32 v150, v161, v144
	v_mov_b32_e32 v144, v10
	v_mov_b32_e32 v145, v30
	v_pk_mul_f32 v[144:145], v[144:145], v[148:149]
	s_nop 0
	v_add_f32_e32 v144, v144, v145
	v_mul_f32_e32 v155, v161, v144
	v_mov_b32_e32 v144, v31
	v_mov_b32_e32 v145, v11
	v_pk_mul_f32 v[144:145], v[144:145], v[146:147]
	s_nop 0
	v_sub_f32_e32 v144, v144, v145
	v_mul_f32_e32 v148, v161, v144
	v_mov_b32_e32 v144, v11
	v_mov_b32_e32 v145, v31
	v_pk_mul_f32 v[144:145], v[144:145], v[146:147]
	s_nop 0
	v_add_f32_e32 v144, v144, v145
	v_mul_f32_e32 v151, v161, v144
	v_ashrrev_i32_e32 v161, 31, v160
	v_cvt_pk_bf16_f32 v144, v166, v162
	v_cvt_pk_bf16_f32 v145, v158, v157
	v_cvt_pk_bf16_f32 v146, v165, v152
	v_cvt_pk_bf16_f32 v147, v150, v148
	v_cvt_pk_bf16_f32 v148, v164, v163
	v_cvt_pk_bf16_f32 v149, v156, v159
	v_cvt_pk_bf16_f32 v150, v154, v153
	v_lshlrev_b64 v[152:153], 12, v[160:161]
	v_lshl_add_u64 v[152:153], v[230:231], 0, v[152:153]
	v_cvt_pk_bf16_f32 v151, v155, v151
	global_store_dwordx4 v[152:153], v[144:147], off
	global_store_dwordx4 v[152:153], v[148:151], off offset:256
	s_nop 0
	v_add_u32_e32 v144, 0xb0, v228
	v_and_b32_e32 v145, 0x7f, v144
	v_add_u32_e32 v145, 1, v145
	v_cvt_f32_ubyte0_e32 v145, v145
	v_mul_f32_e64 v146, v241, -v145
	v_cmp_gt_f32_e64 s[4:5], s7, v146
	v_mov_b32_e32 v147, v4
	v_mov_b32_e32 v148, v140
	v_cndmask_b32_e64 v146, 0, v234, s[4:5]
	v_fma_f32 v145, v241, -v145, v146
	v_exp_f32_e32 v145, v145
	v_cndmask_b32_e64 v146, 0, v235, s[4:5]
	v_mov_b32_e32 v149, v136
	s_mov_b64 s[4:5], 0
	v_ldexp_f32 v145, v145, v146
	v_mov_b32_e32 v146, v20
	v_pk_mul_f32 v[146:147], v[146:147], v[148:149]
	v_mul_f32_e32 v145, 0x3d800000, v145
	v_sub_f32_e32 v136, v146, v147
	v_mov_b32_e32 v146, v4
	v_mov_b32_e32 v147, v20
	v_cndmask_b32_e32 v145, 1.0, v145, vcc
	v_pk_mul_f32 v[146:147], v[146:147], v[148:149]
	v_mul_f32_e32 v150, v145, v136
	v_add_f32_e32 v136, v146, v147
	v_mul_f32_e32 v148, v145, v136
	v_mov_b32_e32 v146, v21
	v_mov_b32_e32 v147, v5
	v_mov_b32_e32 v136, v141
	v_pk_mul_f32 v[140:141], v[146:147], v[136:137]
	s_nop 0
	v_sub_f32_e32 v140, v140, v141
	v_mul_f32_e32 v146, v145, v140
	v_mov_b32_e32 v140, v5
	v_mov_b32_e32 v141, v21
	v_pk_mul_f32 v[136:137], v[140:141], v[136:137]
	v_mov_b32_e32 v140, v142
	v_add_f32_e32 v136, v136, v137
	v_mul_f32_e32 v147, v145, v136
	v_mov_b32_e32 v136, v22
	v_mov_b32_e32 v137, v6
	v_mov_b32_e32 v141, v138
	v_pk_mul_f32 v[136:137], v[136:137], v[140:141]
	v_mov_b32_e32 v138, v143
	v_sub_f32_e32 v136, v136, v137
	v_mul_f32_e32 v142, v145, v136
	v_mov_b32_e32 v136, v6
	v_mov_b32_e32 v137, v22
	v_pk_mul_f32 v[136:137], v[136:137], v[140:141]
	s_nop 0
	v_add_f32_e32 v136, v136, v137
	v_mul_f32_e32 v140, v145, v136
	v_mov_b32_e32 v136, v23
	v_mov_b32_e32 v137, v7
	v_pk_mul_f32 v[136:137], v[136:137], v[138:139]
	s_nop 0
	v_sub_f32_e32 v136, v136, v137
	v_mul_f32_e32 v141, v145, v136
	v_mov_b32_e32 v136, v7
	v_mov_b32_e32 v137, v23
	v_pk_mul_f32 v[136:137], v[136:137], v[138:139]
	v_mov_b32_e32 v138, v132
	v_add_f32_e32 v136, v136, v137
	v_mul_f32_e32 v143, v145, v136
	v_mov_b32_e32 v136, v12
	v_mov_b32_e32 v137, v0
	v_mov_b32_e32 v139, v128
	v_pk_mul_f32 v[136:137], v[136:137], v[138:139]
	s_nop 0
	v_sub_f32_e32 v128, v136, v137
	v_mov_b32_e32 v136, v0
	v_mov_b32_e32 v137, v12
	v_pk_mul_f32 v[136:137], v[136:137], v[138:139]
	v_mul_f32_e32 v149, v145, v128
	v_add_f32_e32 v128, v136, v137
	v_mul_f32_e32 v138, v145, v128
	v_mov_b32_e32 v136, v13
	v_mov_b32_e32 v137, v1
	v_mov_b32_e32 v128, v133
	v_pk_mul_f32 v[132:133], v[136:137], v[128:129]
	s_nop 0
	v_sub_f32_e32 v132, v132, v133
	v_mul_f32_e32 v136, v145, v132
	v_mov_b32_e32 v132, v1
	v_mov_b32_e32 v133, v13
	v_pk_mul_f32 v[128:129], v[132:133], v[128:129]
	v_mov_b32_e32 v132, v134
	v_add_f32_e32 v128, v128, v129
	v_mul_f32_e32 v139, v145, v128
	v_mov_b32_e32 v128, v14
	v_mov_b32_e32 v129, v2
	v_mov_b32_e32 v133, v130
	v_pk_mul_f32 v[128:129], v[128:129], v[132:133]
	v_mov_b32_e32 v130, v135
	v_sub_f32_e32 v128, v128, v129
	v_mul_f32_e32 v137, v145, v128
	v_mov_b32_e32 v128, v2
	v_mov_b32_e32 v129, v14
	v_pk_mul_f32 v[128:129], v[128:129], v[132:133]
	v_cvt_pk_bf16_f32 v134, v150, v146
	v_cvt_pk_bf16_f32 v135, v142, v141
	v_cvt_pk_bf16_f32 v136, v149, v136
	s_nop 0
	v_add_f32_e32 v128, v128, v129
	v_mul_f32_e32 v132, v145, v128
	v_mov_b32_e32 v128, v15
	v_mov_b32_e32 v129, v3
	v_pk_mul_f32 v[128:129], v[128:129], v[130:131]
	s_nop 0
	v_sub_f32_e32 v128, v128, v129
	v_mul_f32_e32 v133, v145, v128
	v_mov_b32_e32 v128, v3
	v_mov_b32_e32 v129, v15
	v_pk_mul_f32 v[128:129], v[128:129], v[130:131]
	v_cvt_pk_bf16_f32 v137, v137, v133
	s_nop 0
	v_add_f32_e32 v128, v128, v129
	v_mul_f32_e32 v131, v145, v128
	v_ashrrev_i32_e32 v145, 31, v144
	v_cvt_pk_bf16_f32 v128, v148, v147
	v_cvt_pk_bf16_f32 v129, v140, v143
	v_cvt_pk_bf16_f32 v130, v138, v139
	v_cvt_pk_bf16_f32 v131, v132, v131
	v_lshlrev_b64 v[132:133], 12, v[144:145]
	v_lshl_add_u64 v[132:133], v[230:231], 0, v[132:133]
	global_store_dwordx4 v[132:133], v[134:137], off

.LBB0_216:
	v_mov_b64_e32 v[0:1], 0x1600
	s_ashr_i32 s7, s6, 31
	v_cmp_lt_i64_e32 vcc, s[8:9], v[0:1]
	s_lshl_b64 s[8:9], s[6:7], 20
	s_add_u32 s8, s22, s8
	s_addc_u32 s9, s23, s9
	s_and_b64 s[10:11], vcc, exec
	s_cselect_b32 s7, s9, s15
	s_cselect_b32 s36, s8, s14
	s_ashr_i32 s5, s4, 31
	s_lshl_b64 s[10:11], s[4:5], 20
	s_add_u32 s10, s24, s10
	s_addc_u32 s11, s25, s11
	s_and_b64 s[18:19], vcc, exec
	s_cselect_b32 s5, s11, s17
	s_cselect_b32 s37, s10, s16
	s_add_u32 s14, s14, 0x80080
	s_addc_u32 s15, s15, 0
	s_add_u32 s38, s16, 0x100
	s_addc_u32 s39, s17, 0
	s_mov_b32 s40, -2
	s_mov_b64 s[48:49], 0x80
	v_add_u32_e32 v220, 0x10000, v141
	s_add_u32 s16, s14, 0xfff80080
	s_addc_u32 s17, s15, -1
	s_add_i32 s41, 0, 0x10000
	ds_read_b128 v[144:147], v220 offset:0
	ds_read_b128 v[148:151], v220 offset:1024
	ds_read_b128 v[152:155], v220 offset:2048
	ds_read_b128 v[156:159], v220 offset:3072
	s_cmp_eq_u32 s40, 28
	s_cselect_b32 s19, s7, s17
	s_cselect_b32 s18, s36, s16
	s_cselect_b32 s17, s5, s39
	s_cselect_b32 s16, s37, s38
	s_add_i32 m0, s13, 0xc000
	ds_read_b128 v[160:163], v143
	ds_read_b128 v[164:167], v143 offset:1024
	ds_read_b128 v[168:171], v143 offset:2048
	ds_read_b128 v[172:175], v143 offset:3072
	ds_read_b128 v[176:179], v143 offset:4096
	ds_read_b128 v[180:183], v143 offset:5120
	ds_read_b128 v[184:187], v143 offset:6144
	ds_read_b128 v[188:191], v143 offset:7168
	global_load_lds_dwordx4 v134, s[14:15]
	s_add_i32 m0, s13, 0xe000
	s_nop 0
	global_load_lds_dwordx4 v136, s[14:15]
	s_waitcnt lgkmcnt(8)
	s_waitcnt lgkmcnt(0)
	s_barrier
	v_mfma_f32_16x16x32_bf16 v[124:127], v[144:147], v[160:163], 0
	v_mfma_f32_16x16x32_bf16 v[116:119], v[152:155], v[160:163], 0
	v_mfma_f32_16x16x32_bf16 v[108:111], v[144:147], v[168:171], 0
	v_mfma_f32_16x16x32_bf16 v[100:103], v[152:155], v[168:171], 0
	v_mfma_f32_16x16x32_bf16 v[92:95], v[144:147], v[176:179], 0
	v_mfma_f32_16x16x32_bf16 v[84:87], v[152:155], v[176:179], 0
	v_mfma_f32_16x16x32_bf16 v[76:79], v[144:147], v[184:187], 0
	v_mfma_f32_16x16x32_bf16 v[68:71], v[152:155], v[184:187], 0
	v_mfma_f32_16x16x32_bf16 v[124:127], v[148:151], v[164:167], v[124:127]
	v_mfma_f32_16x16x32_bf16 v[116:119], v[156:159], v[164:167], v[116:119]
	v_mfma_f32_16x16x32_bf16 v[108:111], v[148:151], v[172:175], v[108:111]
	v_mfma_f32_16x16x32_bf16 v[100:103], v[156:159], v[172:175], v[100:103]
	v_mfma_f32_16x16x32_bf16 v[92:95], v[148:151], v[180:183], v[92:95]
	v_mfma_f32_16x16x32_bf16 v[84:87], v[156:159], v[180:183], v[84:87]
	v_mfma_f32_16x16x32_bf16 v[76:79], v[148:151], v[188:191], v[76:79]
	v_mfma_f32_16x16x32_bf16 v[68:71], v[156:159], v[188:191], v[68:71]
	s_barrier
	s_add_i32 s44, 0, 0x14000
	s_add_i32 s41, s41, s26
	ds_read_b128 v[196:199], v220 offset:16384
	ds_read_b128 v[204:207], v220 offset:17408
	ds_read_b128 v[208:211], v220 offset:18432
	ds_read_b128 v[214:217], v220 offset:19456
	s_mov_b32 m0, s41
	s_nop 0
	global_load_lds_dwordx4 v192, s[16:17]
	s_add_i32 m0, s41, 0x2000
	s_nop 0
	global_load_lds_dwordx4 v128, s[16:17]
	s_waitcnt lgkmcnt(0)
	s_barrier
	v_mfma_f32_16x16x32_bf16 v[120:123], v[196:199], v[160:163], 0
	v_mfma_f32_16x16x32_bf16 v[112:115], v[208:211], v[160:163], 0
	v_mfma_f32_16x16x32_bf16 v[104:107], v[196:199], v[168:171], 0
	v_mfma_f32_16x16x32_bf16 v[96:99], v[208:211], v[168:171], 0
	v_mfma_f32_16x16x32_bf16 v[88:91], v[196:199], v[176:179], 0
	v_mfma_f32_16x16x32_bf16 v[80:83], v[208:211], v[176:179], 0
	v_mfma_f32_16x16x32_bf16 v[72:75], v[196:199], v[184:187], 0
	v_mfma_f32_16x16x32_bf16 v[64:67], v[208:211], v[184:187], 0
	v_mfma_f32_16x16x32_bf16 v[120:123], v[204:207], v[164:167], v[120:123]
	v_mfma_f32_16x16x32_bf16 v[112:115], v[214:217], v[164:167], v[112:115]
	v_mfma_f32_16x16x32_bf16 v[104:107], v[204:207], v[172:175], v[104:107]
	v_mfma_f32_16x16x32_bf16 v[96:99], v[214:217], v[172:175], v[96:99]
	v_mfma_f32_16x16x32_bf16 v[88:91], v[204:207], v[180:183], v[88:91]
	v_mfma_f32_16x16x32_bf16 v[80:83], v[214:217], v[180:183], v[80:83]
	v_mfma_f32_16x16x32_bf16 v[72:75], v[204:207], v[188:191], v[72:75]
	v_mfma_f32_16x16x32_bf16 v[64:67], v[214:217], v[188:191], v[64:67]
	s_mov_b32 m0, s13
	s_add_u32 s48, s18, 0x80
	s_addc_u32 s49, s19, 0
	s_barrier
	ds_read_b128 v[160:163], v143 offset:16384
	ds_read_b128 v[164:167], v143 offset:17408
	ds_read_b128 v[168:171], v143 offset:18432
	ds_read_b128 v[172:175], v143 offset:19456
	ds_read_b128 v[176:179], v143 offset:20480
	ds_read_b128 v[180:183], v143 offset:21504
	ds_read_b128 v[184:187], v143 offset:22528
	ds_read_b128 v[188:191], v143 offset:23552
	global_load_lds_dwordx4 v132, s[18:19]
	s_mov_b32 m0, s28
	s_nop 0
	global_load_lds_dwordx4 v130, s[18:19]
	s_waitcnt lgkmcnt(0)
	s_barrier
	v_mfma_f32_16x16x32_bf16 v[60:63], v[144:147], v[160:163], 0
	v_mfma_f32_16x16x32_bf16 v[52:55], v[152:155], v[160:163], 0
	v_mfma_f32_16x16x32_bf16 v[44:47], v[144:147], v[168:171], 0
	v_mfma_f32_16x16x32_bf16 v[36:39], v[152:155], v[168:171], 0
	v_mfma_f32_16x16x32_bf16 v[28:31], v[144:147], v[176:179], 0
	v_mfma_f32_16x16x32_bf16 v[20:23], v[152:155], v[176:179], 0
	v_mfma_f32_16x16x32_bf16 v[12:15], v[144:147], v[184:187], 0
	v_mfma_f32_16x16x32_bf16 v[4:7], v[152:155], v[184:187], 0
	v_mfma_f32_16x16x32_bf16 v[60:63], v[148:151], v[164:167], v[60:63]
	v_mfma_f32_16x16x32_bf16 v[52:55], v[156:159], v[164:167], v[52:55]
	v_mfma_f32_16x16x32_bf16 v[44:47], v[148:151], v[172:175], v[44:47]
	v_mfma_f32_16x16x32_bf16 v[36:39], v[156:159], v[172:175], v[36:39]
	v_mfma_f32_16x16x32_bf16 v[28:31], v[148:151], v[180:183], v[28:31]
	v_mfma_f32_16x16x32_bf16 v[20:23], v[156:159], v[180:183], v[20:23]
	v_mfma_f32_16x16x32_bf16 v[12:15], v[148:151], v[188:191], v[12:15]
	v_mfma_f32_16x16x32_bf16 v[4:7], v[156:159], v[188:191], v[4:7]
	s_barrier
	s_add_u32 s42, s16, 0x80000
	s_addc_u32 s43, s17, 0
	s_add_i32 s41, s44, s26
	s_mov_b32 m0, s41
	s_nop 0
	global_load_lds_dwordx4 v192, s[42:43]
	s_add_i32 m0, s41, 0x2000
	s_nop 0
	global_load_lds_dwordx4 v128, s[42:43]
	s_waitcnt vmcnt(6)
	s_barrier
	v_mfma_f32_16x16x32_bf16 v[56:59], v[196:199], v[160:163], 0
	v_mfma_f32_16x16x32_bf16 v[48:51], v[208:211], v[160:163], 0
	v_mfma_f32_16x16x32_bf16 v[40:43], v[196:199], v[168:171], 0
	v_mfma_f32_16x16x32_bf16 v[32:35], v[208:211], v[168:171], 0
	v_mfma_f32_16x16x32_bf16 v[24:27], v[196:199], v[176:179], 0
	v_mfma_f32_16x16x32_bf16 v[16:19], v[208:211], v[176:179], 0
	v_mfma_f32_16x16x32_bf16 v[8:11], v[196:199], v[184:187], 0
	v_mfma_f32_16x16x32_bf16 v[0:3], v[208:211], v[184:187], 0
	v_mfma_f32_16x16x32_bf16 v[56:59], v[204:207], v[164:167], v[56:59]
	v_mfma_f32_16x16x32_bf16 v[48:51], v[214:217], v[164:167], v[48:51]
	v_mfma_f32_16x16x32_bf16 v[40:43], v[204:207], v[172:175], v[40:43]
	v_mfma_f32_16x16x32_bf16 v[32:35], v[214:217], v[172:175], v[32:35]
	v_mfma_f32_16x16x32_bf16 v[24:27], v[204:207], v[180:183], v[24:27]
	v_mfma_f32_16x16x32_bf16 v[16:19], v[214:217], v[180:183], v[16:19]
	v_mfma_f32_16x16x32_bf16 v[8:11], v[204:207], v[188:191], v[8:11]
	v_mfma_f32_16x16x32_bf16 v[0:3], v[214:217], v[188:191], v[0:3]
	s_add_i32 s41, 0, 0x18000
	s_barrier
	ds_read_b128 v[144:147], v220 offset:32768
	ds_read_b128 v[148:151], v220 offset:33792
	ds_read_b128 v[152:155], v220 offset:34816
	ds_read_b128 v[156:159], v220 offset:35840
	s_add_u32 s18, s18, 0x80000
	s_addc_u32 s19, s19, 0
	s_mov_b32 m0, s29
	ds_read_b128 v[160:163], v143 offset:32768
	ds_read_b128 v[164:167], v143 offset:33792
	ds_read_b128 v[168:171], v143 offset:34816
	ds_read_b128 v[172:175], v143 offset:35840
	ds_read_b128 v[176:179], v143 offset:36864
	ds_read_b128 v[180:183], v143 offset:37888
	ds_read_b128 v[184:187], v143 offset:38912
	ds_read_b128 v[188:191], v143 offset:39936
	global_load_lds_dwordx4 v132, s[18:19]
	s_mov_b32 m0, s30
	s_nop 0
	global_load_lds_dwordx4 v130, s[18:19]
	s_waitcnt lgkmcnt(8)
	s_waitcnt lgkmcnt(0)
	s_barrier
	v_mfma_f32_16x16x32_bf16 v[124:127], v[144:147], v[160:163], v[124:127]
	v_mfma_f32_16x16x32_bf16 v[116:119], v[152:155], v[160:163], v[116:119]
	v_mfma_f32_16x16x32_bf16 v[108:111], v[144:147], v[168:171], v[108:111]
	v_mfma_f32_16x16x32_bf16 v[100:103], v[152:155], v[168:171], v[100:103]
	v_mfma_f32_16x16x32_bf16 v[92:95], v[144:147], v[176:179], v[92:95]
	v_mfma_f32_16x16x32_bf16 v[84:87], v[152:155], v[176:179], v[84:87]
	v_mfma_f32_16x16x32_bf16 v[76:79], v[144:147], v[184:187], v[76:79]
	v_mfma_f32_16x16x32_bf16 v[68:71], v[152:155], v[184:187], v[68:71]
	v_mfma_f32_16x16x32_bf16 v[124:127], v[148:151], v[164:167], v[124:127]
	v_mfma_f32_16x16x32_bf16 v[116:119], v[156:159], v[164:167], v[116:119]
	v_mfma_f32_16x16x32_bf16 v[108:111], v[148:151], v[172:175], v[108:111]
	v_mfma_f32_16x16x32_bf16 v[100:103], v[156:159], v[172:175], v[100:103]
	v_mfma_f32_16x16x32_bf16 v[92:95], v[148:151], v[180:183], v[92:95]
	v_mfma_f32_16x16x32_bf16 v[84:87], v[156:159], v[180:183], v[84:87]
	v_mfma_f32_16x16x32_bf16 v[76:79], v[148:151], v[188:191], v[76:79]
	v_mfma_f32_16x16x32_bf16 v[68:71], v[156:159], v[188:191], v[68:71]
	s_barrier
	s_add_i32 s18, 0, 0x1c000
	s_add_i32 s19, s41, s26
	s_add_i32 m0, s19, 0xffffff80
	ds_read_b128 v[196:199], v220 offset:49152
	ds_read_b128 v[204:207], v220 offset:50176
	ds_read_b128 v[208:211], v220 offset:51200
	ds_read_b128 v[214:217], v220 offset:52224
	global_load_lds_dwordx4 v192, s[16:17] offset:128
	s_add_i32 m0, s19, 0x1f80
	s_nop 0
	global_load_lds_dwordx4 v128, s[16:17] offset:128
	s_waitcnt lgkmcnt(0)
	s_barrier
	v_mfma_f32_16x16x32_bf16 v[120:123], v[196:199], v[160:163], v[120:123]
	v_mfma_f32_16x16x32_bf16 v[112:115], v[208:211], v[160:163], v[112:115]
	v_mfma_f32_16x16x32_bf16 v[104:107], v[196:199], v[168:171], v[104:107]
	v_mfma_f32_16x16x32_bf16 v[96:99], v[208:211], v[168:171], v[96:99]
	v_mfma_f32_16x16x32_bf16 v[88:91], v[196:199], v[176:179], v[88:91]
	v_mfma_f32_16x16x32_bf16 v[80:83], v[208:211], v[176:179], v[80:83]
	v_mfma_f32_16x16x32_bf16 v[72:75], v[196:199], v[184:187], v[72:75]
	v_mfma_f32_16x16x32_bf16 v[64:67], v[208:211], v[184:187], v[64:67]
	v_mfma_f32_16x16x32_bf16 v[120:123], v[204:207], v[164:167], v[120:123]
	v_mfma_f32_16x16x32_bf16 v[112:115], v[214:217], v[164:167], v[112:115]
	v_mfma_f32_16x16x32_bf16 v[104:107], v[204:207], v[172:175], v[104:107]
	v_mfma_f32_16x16x32_bf16 v[96:99], v[214:217], v[172:175], v[96:99]
	v_mfma_f32_16x16x32_bf16 v[88:91], v[204:207], v[180:183], v[88:91]
	v_mfma_f32_16x16x32_bf16 v[80:83], v[214:217], v[180:183], v[80:83]
	v_mfma_f32_16x16x32_bf16 v[72:75], v[204:207], v[188:191], v[72:75]
	v_mfma_f32_16x16x32_bf16 v[64:67], v[214:217], v[188:191], v[64:67]
	s_mov_b32 m0, s33
	s_barrier
	ds_read_b128 v[160:163], v143 offset:49152
	ds_read_b128 v[164:167], v143 offset:50176
	ds_read_b128 v[168:171], v143 offset:51200
	ds_read_b128 v[172:175], v143 offset:52224
	ds_read_b128 v[176:179], v143 offset:53248
	ds_read_b128 v[180:183], v143 offset:54272
	ds_read_b128 v[184:187], v143 offset:55296
	ds_read_b128 v[188:191], v143 offset:56320
	global_load_lds_dwordx4 v132, s[48:49]
	s_mov_b32 m0, s34
	s_nop 0
	global_load_lds_dwordx4 v130, s[48:49]
	s_waitcnt lgkmcnt(0)
	s_barrier
	v_mfma_f32_16x16x32_bf16 v[60:63], v[144:147], v[160:163], v[60:63]
	v_mfma_f32_16x16x32_bf16 v[52:55], v[152:155], v[160:163], v[52:55]
	v_mfma_f32_16x16x32_bf16 v[44:47], v[144:147], v[168:171], v[44:47]
	v_mfma_f32_16x16x32_bf16 v[36:39], v[152:155], v[168:171], v[36:39]
	v_mfma_f32_16x16x32_bf16 v[28:31], v[144:147], v[176:179], v[28:31]
	v_mfma_f32_16x16x32_bf16 v[20:23], v[152:155], v[176:179], v[20:23]
	v_mfma_f32_16x16x32_bf16 v[12:15], v[144:147], v[184:187], v[12:15]
	v_mfma_f32_16x16x32_bf16 v[4:7], v[152:155], v[184:187], v[4:7]
	v_mfma_f32_16x16x32_bf16 v[60:63], v[148:151], v[164:167], v[60:63]
	v_mfma_f32_16x16x32_bf16 v[52:55], v[156:159], v[164:167], v[52:55]
	v_mfma_f32_16x16x32_bf16 v[44:47], v[148:151], v[172:175], v[44:47]
	v_mfma_f32_16x16x32_bf16 v[36:39], v[156:159], v[172:175], v[36:39]
	v_mfma_f32_16x16x32_bf16 v[28:31], v[148:151], v[180:183], v[28:31]
	v_mfma_f32_16x16x32_bf16 v[20:23], v[156:159], v[180:183], v[20:23]
	v_mfma_f32_16x16x32_bf16 v[12:15], v[148:151], v[188:191], v[12:15]
	v_mfma_f32_16x16x32_bf16 v[4:7], v[156:159], v[188:191], v[4:7]
	s_barrier
	s_add_u32 s16, s16, 0x80080
	s_addc_u32 s17, s17, 0
	s_add_i32 s18, s18, s26
	s_mov_b32 m0, s18
	s_nop 0
	global_load_lds_dwordx4 v192, s[16:17]
	s_add_i32 m0, s18, 0x2000
	s_nop 0
	global_load_lds_dwordx4 v128, s[16:17]
	s_waitcnt vmcnt(6)
	s_barrier
	v_mfma_f32_16x16x32_bf16 v[56:59], v[196:199], v[160:163], v[56:59]
	v_mfma_f32_16x16x32_bf16 v[48:51], v[208:211], v[160:163], v[48:51]
	v_mfma_f32_16x16x32_bf16 v[40:43], v[196:199], v[168:171], v[40:43]
	v_mfma_f32_16x16x32_bf16 v[32:35], v[208:211], v[168:171], v[32:35]
	v_mfma_f32_16x16x32_bf16 v[24:27], v[196:199], v[176:179], v[24:27]
	v_mfma_f32_16x16x32_bf16 v[16:19], v[208:211], v[176:179], v[16:19]
	v_mfma_f32_16x16x32_bf16 v[8:11], v[196:199], v[184:187], v[8:11]
	v_mfma_f32_16x16x32_bf16 v[0:3], v[208:211], v[184:187], v[0:3]
	v_mfma_f32_16x16x32_bf16 v[56:59], v[204:207], v[164:167], v[56:59]
	v_mfma_f32_16x16x32_bf16 v[48:51], v[214:217], v[164:167], v[48:51]
	v_mfma_f32_16x16x32_bf16 v[40:43], v[204:207], v[172:175], v[40:43]
	v_mfma_f32_16x16x32_bf16 v[32:35], v[214:217], v[172:175], v[32:35]
	v_mfma_f32_16x16x32_bf16 v[24:27], v[204:207], v[180:183], v[24:27]
	v_mfma_f32_16x16x32_bf16 v[16:19], v[214:217], v[180:183], v[16:19]
	v_mfma_f32_16x16x32_bf16 v[8:11], v[204:207], v[188:191], v[8:11]
	v_mfma_f32_16x16x32_bf16 v[0:3], v[214:217], v[188:191], v[0:3]
	s_add_i32 s40, s40, 2
	s_add_u32 s14, s14, 0x100
	s_addc_u32 s15, s15, 0
	s_add_u32 s38, s38, 0x100
	s_addc_u32 s39, s39, 0
	s_cmp_gt_u32 s40, 29
	s_barrier
.LBB0_217:
	s_add_u32 s16, s14, 0xfff80080
	s_addc_u32 s17, s15, -1
	s_add_i32 s41, 0, 0x10000
	ds_read_b128 v[144:147], v220 offset:0
	ds_read_b128 v[148:151], v220 offset:1024
	ds_read_b128 v[152:155], v220 offset:2048
	ds_read_b128 v[156:159], v220 offset:3072
	s_cmp_eq_u32 s40, 28
	s_cselect_b32 s19, s7, s17
	s_cselect_b32 s18, s36, s16
	s_cselect_b32 s17, s5, s39
	s_cselect_b32 s16, s37, s38
	s_add_i32 m0, s13, 0xc000
	ds_read_b128 v[160:163], v143
	ds_read_b128 v[164:167], v143 offset:1024
	ds_read_b128 v[168:171], v143 offset:2048
	ds_read_b128 v[172:175], v143 offset:3072
	ds_read_b128 v[176:179], v143 offset:4096
	ds_read_b128 v[180:183], v143 offset:5120
	ds_read_b128 v[184:187], v143 offset:6144
	ds_read_b128 v[188:191], v143 offset:7168
	global_load_lds_dwordx4 v134, s[14:15]
	s_add_i32 m0, s13, 0xe000
	s_nop 0
	global_load_lds_dwordx4 v136, s[14:15]
	s_waitcnt lgkmcnt(8)
	s_waitcnt lgkmcnt(0)
	s_barrier
	v_mfma_f32_16x16x32_bf16 v[124:127], v[144:147], v[160:163], v[124:127]
	v_mfma_f32_16x16x32_bf16 v[116:119], v[152:155], v[160:163], v[116:119]
	v_mfma_f32_16x16x32_bf16 v[108:111], v[144:147], v[168:171], v[108:111]
	v_mfma_f32_16x16x32_bf16 v[100:103], v[152:155], v[168:171], v[100:103]
	v_mfma_f32_16x16x32_bf16 v[92:95], v[144:147], v[176:179], v[92:95]
	v_mfma_f32_16x16x32_bf16 v[84:87], v[152:155], v[176:179], v[84:87]
	v_mfma_f32_16x16x32_bf16 v[76:79], v[144:147], v[184:187], v[76:79]
	v_mfma_f32_16x16x32_bf16 v[68:71], v[152:155], v[184:187], v[68:71]
	v_mfma_f32_16x16x32_bf16 v[124:127], v[148:151], v[164:167], v[124:127]
	v_mfma_f32_16x16x32_bf16 v[116:119], v[156:159], v[164:167], v[116:119]
	v_mfma_f32_16x16x32_bf16 v[108:111], v[148:151], v[172:175], v[108:111]
	v_mfma_f32_16x16x32_bf16 v[100:103], v[156:159], v[172:175], v[100:103]
	v_mfma_f32_16x16x32_bf16 v[92:95], v[148:151], v[180:183], v[92:95]
	v_mfma_f32_16x16x32_bf16 v[84:87], v[156:159], v[180:183], v[84:87]
	v_mfma_f32_16x16x32_bf16 v[76:79], v[148:151], v[188:191], v[76:79]
	v_mfma_f32_16x16x32_bf16 v[68:71], v[156:159], v[188:191], v[68:71]
	s_barrier
	s_add_i32 s44, 0, 0x14000
	s_add_i32 s41, s41, s26
	ds_read_b128 v[196:199], v220 offset:16384
	ds_read_b128 v[204:207], v220 offset:17408
	ds_read_b128 v[208:211], v220 offset:18432
	ds_read_b128 v[214:217], v220 offset:19456
	s_mov_b32 m0, s41
	s_nop 0
	global_load_lds_dwordx4 v192, s[16:17]
	s_add_i32 m0, s41, 0x2000
	s_nop 0
	global_load_lds_dwordx4 v128, s[16:17]
	s_waitcnt lgkmcnt(0)
	s_barrier
	v_mfma_f32_16x16x32_bf16 v[120:123], v[196:199], v[160:163], v[120:123]
	v_mfma_f32_16x16x32_bf16 v[112:115], v[208:211], v[160:163], v[112:115]
	v_mfma_f32_16x16x32_bf16 v[104:107], v[196:199], v[168:171], v[104:107]
	v_mfma_f32_16x16x32_bf16 v[96:99], v[208:211], v[168:171], v[96:99]
	v_mfma_f32_16x16x32_bf16 v[88:91], v[196:199], v[176:179], v[88:91]
	v_mfma_f32_16x16x32_bf16 v[80:83], v[208:211], v[176:179], v[80:83]
	v_mfma_f32_16x16x32_bf16 v[72:75], v[196:199], v[184:187], v[72:75]
	v_mfma_f32_16x16x32_bf16 v[64:67], v[208:211], v[184:187], v[64:67]
	v_mfma_f32_16x16x32_bf16 v[120:123], v[204:207], v[164:167], v[120:123]
	v_mfma_f32_16x16x32_bf16 v[112:115], v[214:217], v[164:167], v[112:115]
	v_mfma_f32_16x16x32_bf16 v[104:107], v[204:207], v[172:175], v[104:107]
	v_mfma_f32_16x16x32_bf16 v[96:99], v[214:217], v[172:175], v[96:99]
	v_mfma_f32_16x16x32_bf16 v[88:91], v[204:207], v[180:183], v[88:91]
	v_mfma_f32_16x16x32_bf16 v[80:83], v[214:217], v[180:183], v[80:83]
	v_mfma_f32_16x16x32_bf16 v[72:75], v[204:207], v[188:191], v[72:75]
	v_mfma_f32_16x16x32_bf16 v[64:67], v[214:217], v[188:191], v[64:67]
	s_mov_b32 m0, s13
	s_add_u32 s48, s18, 0x80
	s_addc_u32 s49, s19, 0
	s_barrier
	ds_read_b128 v[160:163], v143 offset:16384
	ds_read_b128 v[164:167], v143 offset:17408
	ds_read_b128 v[168:171], v143 offset:18432
	ds_read_b128 v[172:175], v143 offset:19456
	ds_read_b128 v[176:179], v143 offset:20480
	ds_read_b128 v[180:183], v143 offset:21504
	ds_read_b128 v[184:187], v143 offset:22528
	ds_read_b128 v[188:191], v143 offset:23552
	global_load_lds_dwordx4 v132, s[18:19]
	s_mov_b32 m0, s28
	s_nop 0
	global_load_lds_dwordx4 v130, s[18:19]
	s_waitcnt lgkmcnt(0)
	s_barrier
	v_mfma_f32_16x16x32_bf16 v[60:63], v[144:147], v[160:163], v[60:63]
	v_mfma_f32_16x16x32_bf16 v[52:55], v[152:155], v[160:163], v[52:55]
	v_mfma_f32_16x16x32_bf16 v[44:47], v[144:147], v[168:171], v[44:47]
	v_mfma_f32_16x16x32_bf16 v[36:39], v[152:155], v[168:171], v[36:39]
	v_mfma_f32_16x16x32_bf16 v[28:31], v[144:147], v[176:179], v[28:31]
	v_mfma_f32_16x16x32_bf16 v[20:23], v[152:155], v[176:179], v[20:23]
	v_mfma_f32_16x16x32_bf16 v[12:15], v[144:147], v[184:187], v[12:15]
	v_mfma_f32_16x16x32_bf16 v[4:7], v[152:155], v[184:187], v[4:7]
	v_mfma_f32_16x16x32_bf16 v[60:63], v[148:151], v[164:167], v[60:63]
	v_mfma_f32_16x16x32_bf16 v[52:55], v[156:159], v[164:167], v[52:55]
	v_mfma_f32_16x16x32_bf16 v[44:47], v[148:151], v[172:175], v[44:47]
	v_mfma_f32_16x16x32_bf16 v[36:39], v[156:159], v[172:175], v[36:39]
	v_mfma_f32_16x16x32_bf16 v[28:31], v[148:151], v[180:183], v[28:31]
	v_mfma_f32_16x16x32_bf16 v[20:23], v[156:159], v[180:183], v[20:23]
	v_mfma_f32_16x16x32_bf16 v[12:15], v[148:151], v[188:191], v[12:15]
	v_mfma_f32_16x16x32_bf16 v[4:7], v[156:159], v[188:191], v[4:7]
	s_barrier
	s_add_u32 s42, s16, 0x80000
	s_addc_u32 s43, s17, 0
	s_add_i32 s41, s44, s26
	s_mov_b32 m0, s41
	s_nop 0
	global_load_lds_dwordx4 v192, s[42:43]
	s_add_i32 m0, s41, 0x2000
	s_nop 0
	global_load_lds_dwordx4 v128, s[42:43]
	s_waitcnt vmcnt(6)
	s_barrier
	v_mfma_f32_16x16x32_bf16 v[56:59], v[196:199], v[160:163], v[56:59]
	v_mfma_f32_16x16x32_bf16 v[48:51], v[208:211], v[160:163], v[48:51]
	v_mfma_f32_16x16x32_bf16 v[40:43], v[196:199], v[168:171], v[40:43]
	v_mfma_f32_16x16x32_bf16 v[32:35], v[208:211], v[168:171], v[32:35]
	v_mfma_f32_16x16x32_bf16 v[24:27], v[196:199], v[176:179], v[24:27]
	v_mfma_f32_16x16x32_bf16 v[16:19], v[208:211], v[176:179], v[16:19]
	v_mfma_f32_16x16x32_bf16 v[8:11], v[196:199], v[184:187], v[8:11]
	v_mfma_f32_16x16x32_bf16 v[0:3], v[208:211], v[184:187], v[0:3]
	v_mfma_f32_16x16x32_bf16 v[56:59], v[204:207], v[164:167], v[56:59]
	v_mfma_f32_16x16x32_bf16 v[48:51], v[214:217], v[164:167], v[48:51]
	v_mfma_f32_16x16x32_bf16 v[40:43], v[204:207], v[172:175], v[40:43]
	v_mfma_f32_16x16x32_bf16 v[32:35], v[214:217], v[172:175], v[32:35]
	v_mfma_f32_16x16x32_bf16 v[24:27], v[204:207], v[180:183], v[24:27]
	v_mfma_f32_16x16x32_bf16 v[16:19], v[214:217], v[180:183], v[16:19]
	v_mfma_f32_16x16x32_bf16 v[8:11], v[204:207], v[188:191], v[8:11]
	v_mfma_f32_16x16x32_bf16 v[0:3], v[214:217], v[188:191], v[0:3]
	s_add_i32 s41, 0, 0x18000
	s_barrier
	ds_read_b128 v[144:147], v220 offset:32768
	ds_read_b128 v[148:151], v220 offset:33792
	ds_read_b128 v[152:155], v220 offset:34816
	ds_read_b128 v[156:159], v220 offset:35840
	s_add_u32 s18, s18, 0x80000
	s_addc_u32 s19, s19, 0
	s_mov_b32 m0, s29
	ds_read_b128 v[160:163], v143 offset:32768
	ds_read_b128 v[164:167], v143 offset:33792
	ds_read_b128 v[168:171], v143 offset:34816
	ds_read_b128 v[172:175], v143 offset:35840
	ds_read_b128 v[176:179], v143 offset:36864
	ds_read_b128 v[180:183], v143 offset:37888
	ds_read_b128 v[184:187], v143 offset:38912
	ds_read_b128 v[188:191], v143 offset:39936
	global_load_lds_dwordx4 v132, s[18:19]
	s_mov_b32 m0, s30
	s_nop 0
	global_load_lds_dwordx4 v130, s[18:19]
	s_waitcnt lgkmcnt(8)
	s_waitcnt lgkmcnt(0)
	s_barrier
	v_mfma_f32_16x16x32_bf16 v[124:127], v[144:147], v[160:163], v[124:127]
	v_mfma_f32_16x16x32_bf16 v[116:119], v[152:155], v[160:163], v[116:119]
	v_mfma_f32_16x16x32_bf16 v[108:111], v[144:147], v[168:171], v[108:111]
	v_mfma_f32_16x16x32_bf16 v[100:103], v[152:155], v[168:171], v[100:103]
	v_mfma_f32_16x16x32_bf16 v[92:95], v[144:147], v[176:179], v[92:95]
	v_mfma_f32_16x16x32_bf16 v[84:87], v[152:155], v[176:179], v[84:87]
	v_mfma_f32_16x16x32_bf16 v[76:79], v[144:147], v[184:187], v[76:79]
	v_mfma_f32_16x16x32_bf16 v[68:71], v[152:155], v[184:187], v[68:71]
	v_mfma_f32_16x16x32_bf16 v[124:127], v[148:151], v[164:167], v[124:127]
	v_mfma_f32_16x16x32_bf16 v[116:119], v[156:159], v[164:167], v[116:119]
	v_mfma_f32_16x16x32_bf16 v[108:111], v[148:151], v[172:175], v[108:111]
	v_mfma_f32_16x16x32_bf16 v[100:103], v[156:159], v[172:175], v[100:103]
	v_mfma_f32_16x16x32_bf16 v[92:95], v[148:151], v[180:183], v[92:95]
	v_mfma_f32_16x16x32_bf16 v[84:87], v[156:159], v[180:183], v[84:87]
	v_mfma_f32_16x16x32_bf16 v[76:79], v[148:151], v[188:191], v[76:79]
	v_mfma_f32_16x16x32_bf16 v[68:71], v[156:159], v[188:191], v[68:71]
	s_barrier
	s_add_i32 s18, 0, 0x1c000
	s_add_i32 s19, s41, s26
	s_add_i32 m0, s19, 0xffffff80
	ds_read_b128 v[196:199], v220 offset:49152
	ds_read_b128 v[204:207], v220 offset:50176
	ds_read_b128 v[208:211], v220 offset:51200
	ds_read_b128 v[214:217], v220 offset:52224
	global_load_lds_dwordx4 v192, s[16:17] offset:128
	s_add_i32 m0, s19, 0x1f80
	s_nop 0
	global_load_lds_dwordx4 v128, s[16:17] offset:128
	s_waitcnt lgkmcnt(0)
	s_barrier
	v_mfma_f32_16x16x32_bf16 v[120:123], v[196:199], v[160:163], v[120:123]
	v_mfma_f32_16x16x32_bf16 v[112:115], v[208:211], v[160:163], v[112:115]
	v_mfma_f32_16x16x32_bf16 v[104:107], v[196:199], v[168:171], v[104:107]
	v_mfma_f32_16x16x32_bf16 v[96:99], v[208:211], v[168:171], v[96:99]
	v_mfma_f32_16x16x32_bf16 v[88:91], v[196:199], v[176:179], v[88:91]
	v_mfma_f32_16x16x32_bf16 v[80:83], v[208:211], v[176:179], v[80:83]
	v_mfma_f32_16x16x32_bf16 v[72:75], v[196:199], v[184:187], v[72:75]
	v_mfma_f32_16x16x32_bf16 v[64:67], v[208:211], v[184:187], v[64:67]
	v_mfma_f32_16x16x32_bf16 v[120:123], v[204:207], v[164:167], v[120:123]
	v_mfma_f32_16x16x32_bf16 v[112:115], v[214:217], v[164:167], v[112:115]
	v_mfma_f32_16x16x32_bf16 v[104:107], v[204:207], v[172:175], v[104:107]
	v_mfma_f32_16x16x32_bf16 v[96:99], v[214:217], v[172:175], v[96:99]
	v_mfma_f32_16x16x32_bf16 v[88:91], v[204:207], v[180:183], v[88:91]
	v_mfma_f32_16x16x32_bf16 v[80:83], v[214:217], v[180:183], v[80:83]
	v_mfma_f32_16x16x32_bf16 v[72:75], v[204:207], v[188:191], v[72:75]
	v_mfma_f32_16x16x32_bf16 v[64:67], v[214:217], v[188:191], v[64:67]
	s_mov_b32 m0, s33
	s_barrier
	ds_read_b128 v[160:163], v143 offset:49152
	ds_read_b128 v[164:167], v143 offset:50176
	ds_read_b128 v[168:171], v143 offset:51200
	ds_read_b128 v[172:175], v143 offset:52224
	ds_read_b128 v[176:179], v143 offset:53248
	ds_read_b128 v[180:183], v143 offset:54272
	ds_read_b128 v[184:187], v143 offset:55296
	ds_read_b128 v[188:191], v143 offset:56320
	global_load_lds_dwordx4 v132, s[48:49]
	s_mov_b32 m0, s34
	s_nop 0
	global_load_lds_dwordx4 v130, s[48:49]
	s_waitcnt lgkmcnt(0)
	s_barrier
	v_mfma_f32_16x16x32_bf16 v[60:63], v[144:147], v[160:163], v[60:63]
	v_mfma_f32_16x16x32_bf16 v[52:55], v[152:155], v[160:163], v[52:55]
	v_mfma_f32_16x16x32_bf16 v[44:47], v[144:147], v[168:171], v[44:47]
	v_mfma_f32_16x16x32_bf16 v[36:39], v[152:155], v[168:171], v[36:39]
	v_mfma_f32_16x16x32_bf16 v[28:31], v[144:147], v[176:179], v[28:31]
	v_mfma_f32_16x16x32_bf16 v[20:23], v[152:155], v[176:179], v[20:23]
	v_mfma_f32_16x16x32_bf16 v[12:15], v[144:147], v[184:187], v[12:15]
	v_mfma_f32_16x16x32_bf16 v[4:7], v[152:155], v[184:187], v[4:7]
	v_mfma_f32_16x16x32_bf16 v[60:63], v[148:151], v[164:167], v[60:63]
	v_mfma_f32_16x16x32_bf16 v[52:55], v[156:159], v[164:167], v[52:55]
	v_mfma_f32_16x16x32_bf16 v[44:47], v[148:151], v[172:175], v[44:47]
	v_mfma_f32_16x16x32_bf16 v[36:39], v[156:159], v[172:175], v[36:39]
	v_mfma_f32_16x16x32_bf16 v[28:31], v[148:151], v[180:183], v[28:31]
	v_mfma_f32_16x16x32_bf16 v[20:23], v[156:159], v[180:183], v[20:23]
	v_mfma_f32_16x16x32_bf16 v[12:15], v[148:151], v[188:191], v[12:15]
	v_mfma_f32_16x16x32_bf16 v[4:7], v[156:159], v[188:191], v[4:7]
	s_barrier
	s_add_u32 s16, s16, 0x80080
	s_addc_u32 s17, s17, 0
	s_add_i32 s18, s18, s26
	s_mov_b32 m0, s18
	s_nop 0
	global_load_lds_dwordx4 v192, s[16:17]
	s_add_i32 m0, s18, 0x2000
	s_nop 0
	global_load_lds_dwordx4 v128, s[16:17]
	s_waitcnt vmcnt(6)
	s_barrier
	v_mfma_f32_16x16x32_bf16 v[56:59], v[196:199], v[160:163], v[56:59]
	v_mfma_f32_16x16x32_bf16 v[48:51], v[208:211], v[160:163], v[48:51]
	v_mfma_f32_16x16x32_bf16 v[40:43], v[196:199], v[168:171], v[40:43]
	v_mfma_f32_16x16x32_bf16 v[32:35], v[208:211], v[168:171], v[32:35]
	v_mfma_f32_16x16x32_bf16 v[24:27], v[196:199], v[176:179], v[24:27]
	v_mfma_f32_16x16x32_bf16 v[16:19], v[208:211], v[176:179], v[16:19]
	v_mfma_f32_16x16x32_bf16 v[8:11], v[196:199], v[184:187], v[8:11]
	v_mfma_f32_16x16x32_bf16 v[0:3], v[208:211], v[184:187], v[0:3]
	v_mfma_f32_16x16x32_bf16 v[56:59], v[204:207], v[164:167], v[56:59]
	v_mfma_f32_16x16x32_bf16 v[48:51], v[214:217], v[164:167], v[48:51]
	v_mfma_f32_16x16x32_bf16 v[40:43], v[204:207], v[172:175], v[40:43]
	v_mfma_f32_16x16x32_bf16 v[32:35], v[214:217], v[172:175], v[32:35]
	v_mfma_f32_16x16x32_bf16 v[24:27], v[204:207], v[180:183], v[24:27]
	v_mfma_f32_16x16x32_bf16 v[16:19], v[214:217], v[180:183], v[16:19]
	v_mfma_f32_16x16x32_bf16 v[8:11], v[204:207], v[188:191], v[8:11]
	v_mfma_f32_16x16x32_bf16 v[0:3], v[214:217], v[188:191], v[0:3]
	s_add_i32 s40, s40, 2
	s_add_u32 s14, s14, 0x100
	s_addc_u32 s15, s15, 0
	s_add_u32 s38, s38, 0x100
	s_addc_u32 s39, s39, 0
	s_cmp_gt_u32 s40, 29
	s_barrier
	s_cbranch_scc0 .LBB0_217
	v_mul_f32_e32 v145, 0xbfb8aa3b, v124
	v_exp_f32_e32 v145, v145
	v_lshl_or_b32 v146, s35, 7, v142
	v_lshl_add_u32 v144, s12, 8, v140
	v_ashrrev_i32_e32 v147, 31, v146
	v_add_f32_e32 v145, 1.0, v145
	v_rcp_f32_e32 v145, v145
	v_mov_b64_e32 v[138:139], s[2:3]
	s_movk_i32 s5, 0x2c00
	v_mad_i64_i32 v[148:149], s[14:15], v144, s5, v[138:139]
	v_mul_f32_e32 v124, v124, v145
	v_mul_f32_e32 v120, v124, v120
	v_mul_f32_e32 v124, 0xbfb8aa3b, v125
	v_exp_f32_e32 v124, v124
	s_and_b64 vcc, exec, s[0:1]
	s_mov_b32 s35, s4
	s_mov_b32 s12, s6
	v_add_f32_e32 v124, 1.0, v124
	v_rcp_f32_e32 v124, v124
	s_mov_b64 s[16:17], s[10:11]
	v_mul_f32_e32 v124, v125, v124
	v_mul_f32_e32 v121, v124, v121
	v_mul_f32_e32 v124, 0xbfb8aa3b, v126
	v_exp_f32_e32 v124, v124
	s_nop 0
	v_add_f32_e32 v124, 1.0, v124
	v_rcp_f32_e32 v124, v124
	s_nop 0
	v_mul_f32_e32 v124, v126, v124
	v_mul_f32_e32 v122, v124, v122
	v_mul_f32_e32 v124, 0xbfb8aa3b, v127
	v_exp_f32_e32 v124, v124
	s_nop 0
	v_add_f32_e32 v124, 1.0, v124
	v_rcp_f32_e32 v124, v124
	s_nop 0
	v_mul_f32_e32 v124, v127, v124
	v_mul_f32_e32 v123, v124, v123
	v_mul_f32_e32 v124, 0xbfb8aa3b, v116
	v_exp_f32_e32 v124, v124
	s_nop 0
	v_add_f32_e32 v124, 1.0, v124
	v_rcp_f32_e32 v124, v124
	s_nop 0
	v_mul_f32_e32 v116, v116, v124
	v_mul_f32_e32 v116, v116, v112
	v_mul_f32_e32 v112, 0xbfb8aa3b, v117
	v_exp_f32_e32 v112, v112
	s_nop 0
	v_add_f32_e32 v112, 1.0, v112
	v_rcp_f32_e32 v112, v112
	s_nop 0
	v_mul_f32_e32 v112, v117, v112
	v_mul_f32_e32 v117, v112, v113
	v_mul_f32_e32 v112, 0xbfb8aa3b, v118
	v_exp_f32_e32 v112, v112
	s_nop 0
	v_add_f32_e32 v112, 1.0, v112
	v_rcp_f32_e32 v112, v112
	s_nop 0
	v_mul_f32_e32 v112, v118, v112
	v_mul_f32_e32 v124, v112, v114
	v_mul_f32_e32 v112, 0xbfb8aa3b, v119
	v_exp_f32_e32 v112, v112
	v_cvt_pk_bf16_f32 v114, v120, v121
	s_nop 0
	v_add_f32_e32 v112, 1.0, v112
	v_rcp_f32_e32 v112, v112
	s_nop 0
	v_mul_f32_e32 v112, v119, v112
	v_mul_f32_e32 v125, v112, v115
	v_lshlrev_b64 v[112:113], 1, v[146:147]
	v_lshl_add_u64 v[118:119], v[148:149], 0, v[112:113]
	v_cvt_pk_bf16_f32 v115, v122, v123
	v_cvt_pk_bf16_f32 v116, v116, v117
	v_cvt_pk_bf16_f32 v117, v124, v125
	global_store_dwordx4 v[118:119], v[114:117], off
	s_nop 1
	v_mul_f32_e32 v116, 0xbfb8aa3b, v108
	v_exp_f32_e32 v116, v116
	v_or_b32_e32 v114, 16, v144
	v_mad_i64_i32 v[114:115], s[14:15], v114, s5, v[138:139]
	v_add_f32_e32 v116, 1.0, v116
	v_rcp_f32_e32 v116, v116
	s_nop 0
	v_mul_f32_e32 v108, v108, v116
	v_mul_f32_e32 v104, v108, v104
	v_mul_f32_e32 v108, 0xbfb8aa3b, v109
	v_exp_f32_e32 v108, v108
	s_nop 0
	v_add_f32_e32 v108, 1.0, v108
	v_rcp_f32_e32 v108, v108
	s_nop 0
	v_mul_f32_e32 v108, v109, v108
	v_mul_f32_e32 v105, v108, v105
	v_mul_f32_e32 v108, 0xbfb8aa3b, v110
	v_exp_f32_e32 v108, v108
	s_nop 0
	v_add_f32_e32 v108, 1.0, v108
	v_rcp_f32_e32 v108, v108
	s_nop 0
	v_mul_f32_e32 v108, v110, v108
	v_mul_f32_e32 v106, v108, v106
	v_mul_f32_e32 v108, 0xbfb8aa3b, v111
	v_exp_f32_e32 v108, v108
	s_nop 0
	v_add_f32_e32 v108, 1.0, v108
	v_rcp_f32_e32 v108, v108
	s_nop 0
	v_mul_f32_e32 v108, v111, v108
	v_mul_f32_e32 v107, v108, v107
	v_mul_f32_e32 v108, 0xbfb8aa3b, v100
	v_exp_f32_e32 v108, v108
	s_nop 0
	v_add_f32_e32 v108, 1.0, v108
	v_rcp_f32_e32 v108, v108
	s_nop 0
	v_mul_f32_e32 v100, v100, v108
	v_mul_f32_e32 v108, v100, v96
	v_mul_f32_e32 v96, 0xbfb8aa3b, v101
	v_exp_f32_e32 v96, v96
	s_nop 0
	v_add_f32_e32 v96, 1.0, v96
	v_rcp_f32_e32 v96, v96
	s_nop 0
	v_mul_f32_e32 v96, v101, v96
	v_mul_f32_e32 v109, v96, v97
	v_mul_f32_e32 v96, 0xbfb8aa3b, v102
	v_exp_f32_e32 v96, v96
	v_lshl_add_u64 v[100:101], v[114:115], 0, v[112:113]
	v_add_f32_e32 v96, 1.0, v96
	v_rcp_f32_e32 v96, v96
	s_nop 0
	v_mul_f32_e32 v96, v102, v96
	v_mul_f32_e32 v102, v96, v98
	v_mul_f32_e32 v96, 0xbfb8aa3b, v103
	v_exp_f32_e32 v96, v96
	s_nop 0
	v_add_f32_e32 v96, 1.0, v96
	v_rcp_f32_e32 v96, v96
	s_nop 0
	v_mul_f32_e32 v96, v103, v96
	v_mul_f32_e32 v99, v96, v99
	v_cvt_pk_bf16_f32 v96, v104, v105
	v_cvt_pk_bf16_f32 v97, v106, v107
	v_cvt_pk_bf16_f32 v98, v108, v109
	v_cvt_pk_bf16_f32 v99, v102, v99
	global_store_dwordx4 v[100:101], v[96:99], off
	s_nop 1
	v_mul_f32_e32 v98, 0xbfb8aa3b, v92
	v_exp_f32_e32 v98, v98
	v_or_b32_e32 v96, 32, v144
	v_mad_i64_i32 v[96:97], s[14:15], v96, s5, v[138:139]
	v_add_f32_e32 v98, 1.0, v98
	v_rcp_f32_e32 v98, v98
	s_nop 0
	v_mul_f32_e32 v92, v92, v98
	v_mul_f32_e32 v88, v92, v88
	v_mul_f32_e32 v92, 0xbfb8aa3b, v93
	v_exp_f32_e32 v92, v92
	s_nop 0
	v_add_f32_e32 v92, 1.0, v92
	v_rcp_f32_e32 v92, v92
	s_nop 0
	v_mul_f32_e32 v92, v93, v92
	v_mul_f32_e32 v89, v92, v89
	v_mul_f32_e32 v92, 0xbfb8aa3b, v94
	v_exp_f32_e32 v92, v92
	s_nop 0
	v_add_f32_e32 v92, 1.0, v92
	v_rcp_f32_e32 v92, v92
	s_nop 0
	v_mul_f32_e32 v92, v94, v92
	v_mul_f32_e32 v90, v92, v90
	v_mul_f32_e32 v92, 0xbfb8aa3b, v95
	v_exp_f32_e32 v92, v92
	s_nop 0
	v_add_f32_e32 v92, 1.0, v92
	v_rcp_f32_e32 v92, v92
	s_nop 0
	v_mul_f32_e32 v92, v95, v92
	v_mul_f32_e32 v91, v92, v91
	v_mul_f32_e32 v92, 0xbfb8aa3b, v84
	v_exp_f32_e32 v92, v92
	s_nop 0
	v_add_f32_e32 v92, 1.0, v92
	v_rcp_f32_e32 v92, v92
	s_nop 0
	v_mul_f32_e32 v84, v84, v92
	v_mul_f32_e32 v92, v84, v80
	v_mul_f32_e32 v80, 0xbfb8aa3b, v85
	v_exp_f32_e32 v80, v80
	s_nop 0
	v_add_f32_e32 v80, 1.0, v80
	v_rcp_f32_e32 v80, v80
	s_nop 0
	v_mul_f32_e32 v80, v85, v80
	v_mul_f32_e32 v93, v80, v81
	v_mul_f32_e32 v80, 0xbfb8aa3b, v86
	v_exp_f32_e32 v80, v80
	v_lshl_add_u64 v[84:85], v[96:97], 0, v[112:113]
	v_add_f32_e32 v80, 1.0, v80
	v_rcp_f32_e32 v80, v80
	s_nop 0
	v_mul_f32_e32 v80, v86, v80
	v_mul_f32_e32 v86, v80, v82
	v_mul_f32_e32 v80, 0xbfb8aa3b, v87
	v_exp_f32_e32 v80, v80
	s_nop 0
	v_add_f32_e32 v80, 1.0, v80
	v_rcp_f32_e32 v80, v80
	s_nop 0
	v_mul_f32_e32 v80, v87, v80
	v_mul_f32_e32 v83, v80, v83
	v_cvt_pk_bf16_f32 v80, v88, v89
	v_cvt_pk_bf16_f32 v81, v90, v91
	v_cvt_pk_bf16_f32 v82, v92, v93
	v_cvt_pk_bf16_f32 v83, v86, v83
	global_store_dwordx4 v[84:85], v[80:83], off
	s_nop 1
	v_mul_f32_e32 v82, 0xbfb8aa3b, v76
	v_exp_f32_e32 v82, v82
	v_or_b32_e32 v80, 48, v144
	v_mad_i64_i32 v[80:81], s[14:15], v80, s5, v[138:139]
	v_add_f32_e32 v82, 1.0, v82
	v_rcp_f32_e32 v82, v82
	s_nop 0
	v_mul_f32_e32 v76, v76, v82
	v_mul_f32_e32 v72, v76, v72
	v_mul_f32_e32 v76, 0xbfb8aa3b, v77
	v_exp_f32_e32 v76, v76
	s_nop 0
	v_add_f32_e32 v76, 1.0, v76
	v_rcp_f32_e32 v76, v76
	s_nop 0
	v_mul_f32_e32 v76, v77, v76
	v_mul_f32_e32 v73, v76, v73
	v_mul_f32_e32 v76, 0xbfb8aa3b, v78
	v_exp_f32_e32 v76, v76
	s_nop 0
	v_add_f32_e32 v76, 1.0, v76
	v_rcp_f32_e32 v76, v76
	s_nop 0
	v_mul_f32_e32 v76, v78, v76
	v_mul_f32_e32 v74, v76, v74
	v_mul_f32_e32 v76, 0xbfb8aa3b, v79
	v_exp_f32_e32 v76, v76
	s_nop 0
	v_add_f32_e32 v76, 1.0, v76
	v_rcp_f32_e32 v76, v76
	s_nop 0
	v_mul_f32_e32 v76, v79, v76
	v_mul_f32_e32 v75, v76, v75
	v_mul_f32_e32 v76, 0xbfb8aa3b, v68
	v_exp_f32_e32 v76, v76
	s_nop 0
	v_add_f32_e32 v76, 1.0, v76
	v_rcp_f32_e32 v76, v76
	s_nop 0
	v_mul_f32_e32 v68, v68, v76
	v_mul_f32_e32 v76, v68, v64
	v_mul_f32_e32 v64, 0xbfb8aa3b, v69
	v_exp_f32_e32 v64, v64
	s_nop 0
	v_add_f32_e32 v64, 1.0, v64
	v_rcp_f32_e32 v64, v64
	s_nop 0
	v_mul_f32_e32 v64, v69, v64
	v_mul_f32_e32 v77, v64, v65
	v_mul_f32_e32 v64, 0xbfb8aa3b, v70
	v_exp_f32_e32 v64, v64
	v_lshl_add_u64 v[68:69], v[80:81], 0, v[112:113]
	v_add_f32_e32 v64, 1.0, v64
	v_rcp_f32_e32 v64, v64
	s_nop 0
	v_mul_f32_e32 v64, v70, v64
	v_mul_f32_e32 v70, v64, v66
	v_mul_f32_e32 v64, 0xbfb8aa3b, v71
	v_exp_f32_e32 v64, v64
	s_nop 0
	v_add_f32_e32 v64, 1.0, v64
	v_rcp_f32_e32 v64, v64
	s_nop 0
	v_mul_f32_e32 v64, v71, v64
	v_mul_f32_e32 v67, v64, v67
	v_cvt_pk_bf16_f32 v64, v72, v73
	v_cvt_pk_bf16_f32 v65, v74, v75
	v_cvt_pk_bf16_f32 v66, v76, v77
	v_cvt_pk_bf16_f32 v67, v70, v67
	global_store_dwordx4 v[68:69], v[64:67], off
	s_nop 1
	v_mul_f32_e32 v66, 0xbfb8aa3b, v60
	v_exp_f32_e32 v66, v66
	v_add_u32_e32 v64, 0x80, v144
	v_mad_i64_i32 v[64:65], s[14:15], v64, s5, v[138:139]
	v_add_f32_e32 v66, 1.0, v66
	v_rcp_f32_e32 v66, v66
	s_nop 0
	v_mul_f32_e32 v60, v60, v66
	v_mul_f32_e32 v56, v60, v56
	v_mul_f32_e32 v60, 0xbfb8aa3b, v61
	v_exp_f32_e32 v60, v60
	s_nop 0
	v_add_f32_e32 v60, 1.0, v60
	v_rcp_f32_e32 v60, v60
	s_nop 0
	v_mul_f32_e32 v60, v61, v60
	v_mul_f32_e32 v57, v60, v57
	v_mul_f32_e32 v60, 0xbfb8aa3b, v62
	v_exp_f32_e32 v60, v60
	s_nop 0
	v_add_f32_e32 v60, 1.0, v60
	v_rcp_f32_e32 v60, v60
	s_nop 0
	v_mul_f32_e32 v60, v62, v60
	v_mul_f32_e32 v58, v60, v58
	v_mul_f32_e32 v60, 0xbfb8aa3b, v63
	v_exp_f32_e32 v60, v60
	s_nop 0
	v_add_f32_e32 v60, 1.0, v60
	v_rcp_f32_e32 v60, v60
	s_nop 0
	v_mul_f32_e32 v60, v63, v60
	v_mul_f32_e32 v59, v60, v59
	v_mul_f32_e32 v60, 0xbfb8aa3b, v52
	v_exp_f32_e32 v60, v60
	s_nop 0
	v_add_f32_e32 v60, 1.0, v60
	v_rcp_f32_e32 v60, v60
	s_nop 0
	v_mul_f32_e32 v52, v52, v60
	v_mul_f32_e32 v60, v52, v48
	v_mul_f32_e32 v48, 0xbfb8aa3b, v53
	v_exp_f32_e32 v48, v48
	s_nop 0
	v_add_f32_e32 v48, 1.0, v48
	v_rcp_f32_e32 v48, v48
	s_nop 0
	v_mul_f32_e32 v48, v53, v48
	v_mul_f32_e32 v61, v48, v49
	v_mul_f32_e32 v48, 0xbfb8aa3b, v54
	v_exp_f32_e32 v48, v48
	v_lshl_add_u64 v[52:53], v[64:65], 0, v[112:113]
	v_add_f32_e32 v48, 1.0, v48
	v_rcp_f32_e32 v48, v48
	s_nop 0
	v_mul_f32_e32 v48, v54, v48
	v_mul_f32_e32 v54, v48, v50
	v_mul_f32_e32 v48, 0xbfb8aa3b, v55
	v_exp_f32_e32 v48, v48
	s_nop 0
	v_add_f32_e32 v48, 1.0, v48
	v_rcp_f32_e32 v48, v48
	s_nop 0
	v_mul_f32_e32 v48, v55, v48
	v_mul_f32_e32 v51, v48, v51
	v_cvt_pk_bf16_f32 v48, v56, v57
	v_cvt_pk_bf16_f32 v49, v58, v59
	v_cvt_pk_bf16_f32 v50, v60, v61
	v_cvt_pk_bf16_f32 v51, v54, v51
	global_store_dwordx4 v[52:53], v[48:51], off
	s_nop 1
	v_mul_f32_e32 v50, 0xbfb8aa3b, v44
	v_exp_f32_e32 v50, v50
	v_add_u32_e32 v48, 0x90, v144
	v_mad_i64_i32 v[48:49], s[14:15], v48, s5, v[138:139]
	v_add_f32_e32 v50, 1.0, v50
	v_rcp_f32_e32 v50, v50
	s_nop 0
	v_mul_f32_e32 v44, v44, v50
	v_mul_f32_e32 v40, v44, v40
	v_mul_f32_e32 v44, 0xbfb8aa3b, v45
	v_exp_f32_e32 v44, v44
	s_nop 0
	v_add_f32_e32 v44, 1.0, v44
	v_rcp_f32_e32 v44, v44
	s_nop 0
	v_mul_f32_e32 v44, v45, v44
	v_mul_f32_e32 v41, v44, v41
	v_mul_f32_e32 v44, 0xbfb8aa3b, v46
	v_exp_f32_e32 v44, v44
	s_nop 0
	v_add_f32_e32 v44, 1.0, v44
	v_rcp_f32_e32 v44, v44
	s_nop 0
	v_mul_f32_e32 v44, v46, v44
	v_mul_f32_e32 v42, v44, v42
	v_mul_f32_e32 v44, 0xbfb8aa3b, v47
	v_exp_f32_e32 v44, v44
	s_nop 0
	v_add_f32_e32 v44, 1.0, v44
	v_rcp_f32_e32 v44, v44
	s_nop 0
	v_mul_f32_e32 v44, v47, v44
	v_mul_f32_e32 v43, v44, v43
	v_mul_f32_e32 v44, 0xbfb8aa3b, v36
	v_exp_f32_e32 v44, v44
	s_nop 0
	v_add_f32_e32 v44, 1.0, v44
	v_rcp_f32_e32 v44, v44
	s_nop 0
	v_mul_f32_e32 v36, v36, v44
	v_mul_f32_e32 v44, v36, v32
	v_mul_f32_e32 v32, 0xbfb8aa3b, v37
	v_exp_f32_e32 v32, v32
	s_nop 0
	v_add_f32_e32 v32, 1.0, v32
	v_rcp_f32_e32 v32, v32
	s_nop 0
	v_mul_f32_e32 v32, v37, v32
	v_mul_f32_e32 v45, v32, v33
	v_mul_f32_e32 v32, 0xbfb8aa3b, v38
	v_exp_f32_e32 v32, v32
	v_lshl_add_u64 v[36:37], v[48:49], 0, v[112:113]
	v_add_f32_e32 v32, 1.0, v32
	v_rcp_f32_e32 v32, v32
	s_nop 0
	v_mul_f32_e32 v32, v38, v32
	v_mul_f32_e32 v38, v32, v34
	v_mul_f32_e32 v32, 0xbfb8aa3b, v39
	v_exp_f32_e32 v32, v32
	s_nop 0
	v_add_f32_e32 v32, 1.0, v32
	v_rcp_f32_e32 v32, v32
	s_nop 0
	v_mul_f32_e32 v32, v39, v32
	v_mul_f32_e32 v35, v32, v35
	v_cvt_pk_bf16_f32 v32, v40, v41
	v_cvt_pk_bf16_f32 v33, v42, v43
	v_cvt_pk_bf16_f32 v34, v44, v45
	v_cvt_pk_bf16_f32 v35, v38, v35
	global_store_dwordx4 v[36:37], v[32:35], off
	s_nop 1
	v_mul_f32_e32 v34, 0xbfb8aa3b, v28
	v_exp_f32_e32 v34, v34
	v_add_u32_e32 v32, 0xa0, v144
	v_mad_i64_i32 v[32:33], s[14:15], v32, s5, v[138:139]
	v_add_f32_e32 v34, 1.0, v34
	v_rcp_f32_e32 v34, v34
	s_nop 0
	v_mul_f32_e32 v28, v28, v34
	v_mul_f32_e32 v24, v28, v24
	v_mul_f32_e32 v28, 0xbfb8aa3b, v29
	v_exp_f32_e32 v28, v28
	s_nop 0
	v_add_f32_e32 v28, 1.0, v28
	v_rcp_f32_e32 v28, v28
	s_nop 0
	v_mul_f32_e32 v28, v29, v28
	v_mul_f32_e32 v25, v28, v25
	v_mul_f32_e32 v28, 0xbfb8aa3b, v30
	v_exp_f32_e32 v28, v28
	s_nop 0
	v_add_f32_e32 v28, 1.0, v28
	v_rcp_f32_e32 v28, v28
	s_nop 0
	v_mul_f32_e32 v28, v30, v28
	v_mul_f32_e32 v26, v28, v26
	v_mul_f32_e32 v28, 0xbfb8aa3b, v31
	v_exp_f32_e32 v28, v28
	s_nop 0
	v_add_f32_e32 v28, 1.0, v28
	v_rcp_f32_e32 v28, v28
	s_nop 0
	v_mul_f32_e32 v28, v31, v28
	v_mul_f32_e32 v27, v28, v27
	v_mul_f32_e32 v28, 0xbfb8aa3b, v20
	v_exp_f32_e32 v28, v28
	s_nop 0
	v_add_f32_e32 v28, 1.0, v28
	v_rcp_f32_e32 v28, v28
	s_nop 0
	v_mul_f32_e32 v20, v20, v28
	v_mul_f32_e32 v28, v20, v16
	v_mul_f32_e32 v16, 0xbfb8aa3b, v21
	v_exp_f32_e32 v16, v16
	s_nop 0
	v_add_f32_e32 v16, 1.0, v16
	v_rcp_f32_e32 v16, v16
	s_nop 0
	v_mul_f32_e32 v16, v21, v16
	v_mul_f32_e32 v29, v16, v17
	v_mul_f32_e32 v16, 0xbfb8aa3b, v22
	v_exp_f32_e32 v16, v16
	v_lshl_add_u64 v[20:21], v[32:33], 0, v[112:113]
	v_add_f32_e32 v16, 1.0, v16
	v_rcp_f32_e32 v16, v16
	s_nop 0
	v_mul_f32_e32 v16, v22, v16
	v_mul_f32_e32 v22, v16, v18
	v_mul_f32_e32 v16, 0xbfb8aa3b, v23
	v_exp_f32_e32 v16, v16
	s_nop 0
	v_add_f32_e32 v16, 1.0, v16
	v_rcp_f32_e32 v16, v16
	s_nop 0
	v_mul_f32_e32 v16, v23, v16
	v_mul_f32_e32 v19, v16, v19
	v_cvt_pk_bf16_f32 v16, v24, v25
	v_cvt_pk_bf16_f32 v17, v26, v27
	v_cvt_pk_bf16_f32 v18, v28, v29
	v_cvt_pk_bf16_f32 v19, v22, v19
	global_store_dwordx4 v[20:21], v[16:19], off
	s_nop 1
	v_mul_f32_e32 v18, 0xbfb8aa3b, v12
	v_exp_f32_e32 v18, v18
	v_add_u32_e32 v16, 0xb0, v144
	v_mad_i64_i32 v[16:17], s[14:15], v16, s5, v[138:139]
	v_add_f32_e32 v18, 1.0, v18
	v_rcp_f32_e32 v18, v18
	s_mov_b64 s[14:15], s[8:9]
	v_mul_f32_e32 v12, v12, v18
	v_mul_f32_e32 v8, v12, v8
	v_mul_f32_e32 v12, 0xbfb8aa3b, v13
	v_exp_f32_e32 v12, v12
	s_nop 0
	v_add_f32_e32 v12, 1.0, v12
	v_rcp_f32_e32 v12, v12
	s_nop 0
	v_mul_f32_e32 v12, v13, v12
	v_mul_f32_e32 v9, v12, v9
	v_mul_f32_e32 v12, 0xbfb8aa3b, v14
	v_exp_f32_e32 v12, v12
	s_nop 0
	v_add_f32_e32 v12, 1.0, v12
	v_rcp_f32_e32 v12, v12
	s_nop 0
	v_mul_f32_e32 v12, v14, v12
	v_mul_f32_e32 v10, v12, v10
	v_mul_f32_e32 v12, 0xbfb8aa3b, v15
	v_exp_f32_e32 v12, v12
	s_nop 0
	v_add_f32_e32 v12, 1.0, v12
	v_rcp_f32_e32 v12, v12
	s_nop 0
	v_mul_f32_e32 v12, v15, v12
	v_mul_f32_e32 v11, v12, v11
	v_mul_f32_e32 v12, 0xbfb8aa3b, v4
	v_exp_f32_e32 v12, v12
	s_nop 0
	v_add_f32_e32 v12, 1.0, v12
	v_rcp_f32_e32 v12, v12
	s_nop 0
	v_mul_f32_e32 v4, v4, v12
	v_mul_f32_e32 v12, v4, v0
	v_mul_f32_e32 v0, 0xbfb8aa3b, v5
	v_exp_f32_e32 v0, v0
	s_nop 0
	v_add_f32_e32 v0, 1.0, v0
	v_rcp_f32_e32 v0, v0
	s_nop 0
	v_mul_f32_e32 v0, v5, v0
	v_mul_f32_e32 v13, v0, v1
	v_mul_f32_e32 v0, 0xbfb8aa3b, v6
	v_exp_f32_e32 v0, v0
	v_lshl_add_u64 v[4:5], v[16:17], 0, v[112:113]
	v_add_f32_e32 v0, 1.0, v0
	v_rcp_f32_e32 v0, v0
	s_nop 0
	v_mul_f32_e32 v0, v6, v0
	v_mul_f32_e32 v6, v0, v2
	v_mul_f32_e32 v0, 0xbfb8aa3b, v7
	v_exp_f32_e32 v0, v0
	s_nop 0
	v_add_f32_e32 v0, 1.0, v0
	v_rcp_f32_e32 v0, v0
	s_nop 0
	v_mul_f32_e32 v0, v7, v0
	v_mul_f32_e32 v3, v0, v3
	v_cvt_pk_bf16_f32 v0, v8, v9
	v_cvt_pk_bf16_f32 v1, v10, v11
	v_cvt_pk_bf16_f32 v2, v12, v13
	v_cvt_pk_bf16_f32 v3, v6, v3
	global_store_dwordx4 v[4:5], v[0:3], off
	s_cbranch_vccz .LBB0_214
	s_waitcnt vmcnt(0)
	v_readlane_b32 s34, v254, 18
	s_cmpk_gt_u32 s21, 0xff
	v_readlane_b32 s35, v254, 19
	v_readlane_b32 s31, v254, 20
	s_cbranch_scc1 .LBB0_221
	s_barrier

.LBB0_245:
	s_add_u32 s10, s10, 0x80
	s_addc_u32 s11, s11, 0
	s_add_u32 s42, s12, 0x100
	s_addc_u32 s43, s13, 0
	s_mov_b32 s12, 0
	s_mov_b64 s[48:49], 0x80
	v_readlane_b32 s52, v254, 14
	v_readlane_b32 s53, v254, 15
	v_readlane_b32 s54, v254, 16
	v_readlane_b32 s55, v254, 17
	v_add_u32_e32 v218, 0x10000, v191
	s_add_i32 s44, s12, 2
	s_add_u32 s14, s10, 0x80
	s_addc_u32 s13, s11, 0
	s_add_i32 s45, 0, 0x10000
	ds_read_b128 v[120:123], v218 offset:0
	ds_read_b128 v[124:127], v218 offset:1024
	ds_read_b128 v[128:131], v218 offset:2048
	ds_read_b128 v[132:135], v218 offset:3072
	s_cmp_eq_u32 s36, s12
	s_cselect_b32 s12, s4, s14
	s_cselect_b32 s13, s5, s13
	s_cselect_b32 s15, s7, s43
	s_cselect_b32 s14, s6, s42
	s_add_i32 m0, s26, 0xc000
	ds_read_b128 v[144:147], v205
	ds_read_b128 v[148:151], v205 offset:1024
	ds_read_b128 v[152:155], v205 offset:2048
	ds_read_b128 v[156:159], v205 offset:3072
	ds_read_b128 v[160:163], v205 offset:4096
	ds_read_b128 v[164:167], v205 offset:5120
	ds_read_b128 v[178:181], v205 offset:6144
	ds_read_b128 v[182:185], v205 offset:7168
	global_load_lds_dwordx4 v174, s[10:11]
	s_add_i32 m0, s26, 0xe000
	s_nop 0
	global_load_lds_dwordx4 v176, s[10:11]
	s_waitcnt lgkmcnt(8)
	s_waitcnt lgkmcnt(0)
	s_barrier
	v_mfma_f32_16x16x32_bf16 v[140:143], v[120:123], v[144:147], 0
	v_mfma_f32_16x16x32_bf16 v[136:139], v[128:131], v[144:147], 0
	v_mfma_f32_16x16x32_bf16 v[108:111], v[120:123], v[152:155], 0
	v_mfma_f32_16x16x32_bf16 v[104:107], v[128:131], v[152:155], 0
	v_mfma_f32_16x16x32_bf16 v[92:95], v[120:123], v[160:163], 0
	v_mfma_f32_16x16x32_bf16 v[88:91], v[128:131], v[160:163], 0
	v_mfma_f32_16x16x32_bf16 v[76:79], v[120:123], v[178:181], 0
	v_mfma_f32_16x16x32_bf16 v[72:75], v[128:131], v[178:181], 0
	v_mfma_f32_16x16x32_bf16 v[140:143], v[124:127], v[148:151], v[140:143]
	v_mfma_f32_16x16x32_bf16 v[136:139], v[132:135], v[148:151], v[136:139]
	v_mfma_f32_16x16x32_bf16 v[108:111], v[124:127], v[156:159], v[108:111]
	v_mfma_f32_16x16x32_bf16 v[104:107], v[132:135], v[156:159], v[104:107]
	v_mfma_f32_16x16x32_bf16 v[92:95], v[124:127], v[164:167], v[92:95]
	v_mfma_f32_16x16x32_bf16 v[88:91], v[132:135], v[164:167], v[88:91]
	v_mfma_f32_16x16x32_bf16 v[76:79], v[124:127], v[182:185], v[76:79]
	v_mfma_f32_16x16x32_bf16 v[72:75], v[132:135], v[182:185], v[72:75]
	s_barrier
	s_add_i32 s46, 0, 0x14000
	s_add_i32 s45, s45, s25
	ds_read_b128 v[186:189], v218 offset:16384
	ds_read_b128 v[196:199], v218 offset:17408
	ds_read_b128 v[206:209], v218 offset:18432
	ds_read_b128 v[214:217], v218 offset:19456
	s_add_u32 s68, s14, 0x80
	s_addc_u32 s69, s15, 0
	s_mov_b32 m0, s45
	s_nop 0
	global_load_lds_dwordx4 v192, s[14:15]
	s_add_i32 m0, s45, 0x2000
	s_nop 0
	global_load_lds_dwordx4 v172, s[14:15]
	s_waitcnt lgkmcnt(0)
	s_barrier
	v_mfma_f32_16x16x32_bf16 v[116:119], v[186:189], v[144:147], 0
	v_mfma_f32_16x16x32_bf16 v[112:115], v[206:209], v[144:147], 0
	v_mfma_f32_16x16x32_bf16 v[100:103], v[186:189], v[152:155], 0
	v_mfma_f32_16x16x32_bf16 v[96:99], v[206:209], v[152:155], 0
	v_mfma_f32_16x16x32_bf16 v[84:87], v[186:189], v[160:163], 0
	v_mfma_f32_16x16x32_bf16 v[80:83], v[206:209], v[160:163], 0
	v_mfma_f32_16x16x32_bf16 v[68:71], v[186:189], v[178:181], 0
	v_mfma_f32_16x16x32_bf16 v[64:67], v[206:209], v[178:181], 0
	v_mfma_f32_16x16x32_bf16 v[116:119], v[196:199], v[148:151], v[116:119]
	v_mfma_f32_16x16x32_bf16 v[112:115], v[214:217], v[148:151], v[112:115]
	v_mfma_f32_16x16x32_bf16 v[100:103], v[196:199], v[156:159], v[100:103]
	v_mfma_f32_16x16x32_bf16 v[96:99], v[214:217], v[156:159], v[96:99]
	v_mfma_f32_16x16x32_bf16 v[84:87], v[196:199], v[164:167], v[84:87]
	v_mfma_f32_16x16x32_bf16 v[80:83], v[214:217], v[164:167], v[80:83]
	v_mfma_f32_16x16x32_bf16 v[68:71], v[196:199], v[182:185], v[68:71]
	v_mfma_f32_16x16x32_bf16 v[64:67], v[214:217], v[182:185], v[64:67]
	s_mov_b32 m0, s26
	s_add_u32 s70, s12, 0x80
	s_addc_u32 s71, s13, 0
	s_barrier
	ds_read_b128 v[144:147], v205 offset:16384
	ds_read_b128 v[148:151], v205 offset:17408
	ds_read_b128 v[152:155], v205 offset:18432
	ds_read_b128 v[156:159], v205 offset:19456
	ds_read_b128 v[160:163], v205 offset:20480
	ds_read_b128 v[164:167], v205 offset:21504
	ds_read_b128 v[178:181], v205 offset:22528
	ds_read_b128 v[182:185], v205 offset:23552
	global_load_lds_dwordx4 v168, s[12:13]
	s_mov_b32 m0, s27
	s_nop 0
	global_load_lds_dwordx4 v170, s[12:13]
	s_waitcnt lgkmcnt(0)
	s_barrier
	v_mfma_f32_16x16x32_bf16 v[60:63], v[120:123], v[144:147], 0
	v_mfma_f32_16x16x32_bf16 v[56:59], v[128:131], v[144:147], 0
	v_mfma_f32_16x16x32_bf16 v[44:47], v[120:123], v[152:155], 0
	v_mfma_f32_16x16x32_bf16 v[40:43], v[128:131], v[152:155], 0
	v_mfma_f32_16x16x32_bf16 v[28:31], v[120:123], v[160:163], 0
	v_mfma_f32_16x16x32_bf16 v[24:27], v[128:131], v[160:163], 0
	v_mfma_f32_16x16x32_bf16 v[12:15], v[120:123], v[178:181], 0
	v_mfma_f32_16x16x32_bf16 v[8:11], v[128:131], v[178:181], 0
	v_mfma_f32_16x16x32_bf16 v[60:63], v[124:127], v[148:151], v[60:63]
	v_mfma_f32_16x16x32_bf16 v[56:59], v[132:135], v[148:151], v[56:59]
	v_mfma_f32_16x16x32_bf16 v[44:47], v[124:127], v[156:159], v[44:47]
	v_mfma_f32_16x16x32_bf16 v[40:43], v[132:135], v[156:159], v[40:43]
	v_mfma_f32_16x16x32_bf16 v[28:31], v[124:127], v[164:167], v[28:31]
	v_mfma_f32_16x16x32_bf16 v[24:27], v[132:135], v[164:167], v[24:27]
	v_mfma_f32_16x16x32_bf16 v[12:15], v[124:127], v[182:185], v[12:15]
	v_mfma_f32_16x16x32_bf16 v[8:11], v[132:135], v[182:185], v[8:11]
	s_barrier
	s_add_u32 s14, s14, s52
	s_addc_u32 s15, s15, 0
	s_add_i32 s45, s46, s25
	s_mov_b32 m0, s45
	s_nop 0
	global_load_lds_dwordx4 v192, s[14:15]
	s_add_i32 m0, s45, 0x2000
	s_nop 0
	global_load_lds_dwordx4 v172, s[14:15]
	s_waitcnt vmcnt(6)
	s_barrier
	v_mfma_f32_16x16x32_bf16 v[52:55], v[186:189], v[144:147], 0
	v_mfma_f32_16x16x32_bf16 v[48:51], v[206:209], v[144:147], 0
	v_mfma_f32_16x16x32_bf16 v[36:39], v[186:189], v[152:155], 0
	v_mfma_f32_16x16x32_bf16 v[32:35], v[206:209], v[152:155], 0
	v_mfma_f32_16x16x32_bf16 v[20:23], v[186:189], v[160:163], 0
	v_mfma_f32_16x16x32_bf16 v[16:19], v[206:209], v[160:163], 0
	v_mfma_f32_16x16x32_bf16 v[4:7], v[186:189], v[178:181], 0
	v_mfma_f32_16x16x32_bf16 v[0:3], v[206:209], v[178:181], 0
	v_mfma_f32_16x16x32_bf16 v[52:55], v[196:199], v[148:151], v[52:55]
	v_mfma_f32_16x16x32_bf16 v[48:51], v[214:217], v[148:151], v[48:51]
	v_mfma_f32_16x16x32_bf16 v[36:39], v[196:199], v[156:159], v[36:39]
	v_mfma_f32_16x16x32_bf16 v[32:35], v[214:217], v[156:159], v[32:35]
	v_mfma_f32_16x16x32_bf16 v[20:23], v[196:199], v[164:167], v[20:23]
	v_mfma_f32_16x16x32_bf16 v[16:19], v[214:217], v[164:167], v[16:19]
	v_mfma_f32_16x16x32_bf16 v[4:7], v[196:199], v[182:185], v[4:7]
	v_mfma_f32_16x16x32_bf16 v[0:3], v[214:217], v[182:185], v[0:3]
	s_add_i32 s14, 0, 0x18000
	s_barrier
	ds_read_b128 v[120:123], v218 offset:32768
	ds_read_b128 v[124:127], v218 offset:33792
	ds_read_b128 v[128:131], v218 offset:34816
	ds_read_b128 v[132:135], v218 offset:35840
	s_add_u32 s12, s12, s52
	s_addc_u32 s13, s13, 0
	s_mov_b32 m0, s28
	ds_read_b128 v[144:147], v205 offset:32768
	ds_read_b128 v[148:151], v205 offset:33792
	ds_read_b128 v[152:155], v205 offset:34816
	ds_read_b128 v[156:159], v205 offset:35840
	ds_read_b128 v[160:163], v205 offset:36864
	ds_read_b128 v[164:167], v205 offset:37888
	ds_read_b128 v[178:181], v205 offset:38912
	ds_read_b128 v[182:185], v205 offset:39936
	global_load_lds_dwordx4 v168, s[12:13]
	s_mov_b32 m0, s29
	s_nop 0
	global_load_lds_dwordx4 v170, s[12:13]
	s_waitcnt lgkmcnt(8)
	s_waitcnt lgkmcnt(0)
	s_barrier
	v_mfma_f32_16x16x32_bf16 v[140:143], v[120:123], v[144:147], v[140:143]
	v_mfma_f32_16x16x32_bf16 v[136:139], v[128:131], v[144:147], v[136:139]
	v_mfma_f32_16x16x32_bf16 v[108:111], v[120:123], v[152:155], v[108:111]
	v_mfma_f32_16x16x32_bf16 v[104:107], v[128:131], v[152:155], v[104:107]
	v_mfma_f32_16x16x32_bf16 v[92:95], v[120:123], v[160:163], v[92:95]
	v_mfma_f32_16x16x32_bf16 v[88:91], v[128:131], v[160:163], v[88:91]
	v_mfma_f32_16x16x32_bf16 v[76:79], v[120:123], v[178:181], v[76:79]
	v_mfma_f32_16x16x32_bf16 v[72:75], v[128:131], v[178:181], v[72:75]
	v_mfma_f32_16x16x32_bf16 v[140:143], v[124:127], v[148:151], v[140:143]
	v_mfma_f32_16x16x32_bf16 v[136:139], v[132:135], v[148:151], v[136:139]
	v_mfma_f32_16x16x32_bf16 v[108:111], v[124:127], v[156:159], v[108:111]
	v_mfma_f32_16x16x32_bf16 v[104:107], v[132:135], v[156:159], v[104:107]
	v_mfma_f32_16x16x32_bf16 v[92:95], v[124:127], v[164:167], v[92:95]
	v_mfma_f32_16x16x32_bf16 v[88:91], v[132:135], v[164:167], v[88:91]
	v_mfma_f32_16x16x32_bf16 v[76:79], v[124:127], v[182:185], v[76:79]
	v_mfma_f32_16x16x32_bf16 v[72:75], v[132:135], v[182:185], v[72:75]
	s_barrier
	s_add_i32 s12, 0, 0x1c000
	s_add_i32 s13, s14, s25
	s_mov_b32 m0, s13
	ds_read_b128 v[186:189], v218 offset:49152
	ds_read_b128 v[196:199], v218 offset:50176
	ds_read_b128 v[206:209], v218 offset:51200
	ds_read_b128 v[214:217], v218 offset:52224
	global_load_lds_dwordx4 v192, s[68:69]
	s_add_i32 m0, s13, 0x2000
	s_nop 0
	global_load_lds_dwordx4 v172, s[68:69]
	s_waitcnt lgkmcnt(0)
	s_barrier
	v_mfma_f32_16x16x32_bf16 v[116:119], v[186:189], v[144:147], v[116:119]
	v_mfma_f32_16x16x32_bf16 v[112:115], v[206:209], v[144:147], v[112:115]
	v_mfma_f32_16x16x32_bf16 v[100:103], v[186:189], v[152:155], v[100:103]
	v_mfma_f32_16x16x32_bf16 v[96:99], v[206:209], v[152:155], v[96:99]
	v_mfma_f32_16x16x32_bf16 v[84:87], v[186:189], v[160:163], v[84:87]
	v_mfma_f32_16x16x32_bf16 v[80:83], v[206:209], v[160:163], v[80:83]
	v_mfma_f32_16x16x32_bf16 v[68:71], v[186:189], v[178:181], v[68:71]
	v_mfma_f32_16x16x32_bf16 v[64:67], v[206:209], v[178:181], v[64:67]
	v_mfma_f32_16x16x32_bf16 v[116:119], v[196:199], v[148:151], v[116:119]
	v_mfma_f32_16x16x32_bf16 v[112:115], v[214:217], v[148:151], v[112:115]
	v_mfma_f32_16x16x32_bf16 v[100:103], v[196:199], v[156:159], v[100:103]
	v_mfma_f32_16x16x32_bf16 v[96:99], v[214:217], v[156:159], v[96:99]
	v_mfma_f32_16x16x32_bf16 v[84:87], v[196:199], v[164:167], v[84:87]
	v_mfma_f32_16x16x32_bf16 v[80:83], v[214:217], v[164:167], v[80:83]
	v_mfma_f32_16x16x32_bf16 v[68:71], v[196:199], v[182:185], v[68:71]
	v_mfma_f32_16x16x32_bf16 v[64:67], v[214:217], v[182:185], v[64:67]
	s_mov_b32 m0, s34
	s_barrier
	ds_read_b128 v[144:147], v205 offset:49152
	ds_read_b128 v[148:151], v205 offset:50176
	ds_read_b128 v[152:155], v205 offset:51200
	ds_read_b128 v[156:159], v205 offset:52224
	ds_read_b128 v[160:163], v205 offset:53248
	ds_read_b128 v[164:167], v205 offset:54272
	ds_read_b128 v[178:181], v205 offset:55296
	ds_read_b128 v[182:185], v205 offset:56320
	global_load_lds_dwordx4 v168, s[70:71]
	s_mov_b32 m0, s35
	s_nop 0
	global_load_lds_dwordx4 v170, s[70:71]
	s_waitcnt lgkmcnt(0)
	s_barrier
	v_mfma_f32_16x16x32_bf16 v[60:63], v[120:123], v[144:147], v[60:63]
	v_mfma_f32_16x16x32_bf16 v[56:59], v[128:131], v[144:147], v[56:59]
	v_mfma_f32_16x16x32_bf16 v[44:47], v[120:123], v[152:155], v[44:47]
	v_mfma_f32_16x16x32_bf16 v[40:43], v[128:131], v[152:155], v[40:43]
	v_mfma_f32_16x16x32_bf16 v[28:31], v[120:123], v[160:163], v[28:31]
	v_mfma_f32_16x16x32_bf16 v[24:27], v[128:131], v[160:163], v[24:27]
	v_mfma_f32_16x16x32_bf16 v[12:15], v[120:123], v[178:181], v[12:15]
	v_mfma_f32_16x16x32_bf16 v[8:11], v[128:131], v[178:181], v[8:11]
	v_mfma_f32_16x16x32_bf16 v[60:63], v[124:127], v[148:151], v[60:63]
	v_mfma_f32_16x16x32_bf16 v[56:59], v[132:135], v[148:151], v[56:59]
	v_mfma_f32_16x16x32_bf16 v[44:47], v[124:127], v[156:159], v[44:47]
	v_mfma_f32_16x16x32_bf16 v[40:43], v[132:135], v[156:159], v[40:43]
	v_mfma_f32_16x16x32_bf16 v[28:31], v[124:127], v[164:167], v[28:31]
	v_mfma_f32_16x16x32_bf16 v[24:27], v[132:135], v[164:167], v[24:27]
	v_mfma_f32_16x16x32_bf16 v[12:15], v[124:127], v[182:185], v[12:15]
	v_mfma_f32_16x16x32_bf16 v[8:11], v[132:135], v[182:185], v[8:11]
	s_barrier
	s_add_i32 s12, s12, s25
	s_add_u32 s68, s68, s52
	s_addc_u32 s69, s69, 0
	s_mov_b32 m0, s12
	s_nop 0
	global_load_lds_dwordx4 v192, s[68:69]
	s_add_i32 m0, s12, 0x2000
	s_nop 0
	global_load_lds_dwordx4 v172, s[68:69]
	s_waitcnt vmcnt(6)
	s_barrier
	v_mfma_f32_16x16x32_bf16 v[52:55], v[186:189], v[144:147], v[52:55]
	v_mfma_f32_16x16x32_bf16 v[48:51], v[206:209], v[144:147], v[48:51]
	v_mfma_f32_16x16x32_bf16 v[36:39], v[186:189], v[152:155], v[36:39]
	v_mfma_f32_16x16x32_bf16 v[32:35], v[206:209], v[152:155], v[32:35]
	v_mfma_f32_16x16x32_bf16 v[20:23], v[186:189], v[160:163], v[20:23]
	v_mfma_f32_16x16x32_bf16 v[16:19], v[206:209], v[160:163], v[16:19]
	v_mfma_f32_16x16x32_bf16 v[4:7], v[186:189], v[178:181], v[4:7]
	v_mfma_f32_16x16x32_bf16 v[0:3], v[206:209], v[178:181], v[0:3]
	v_mfma_f32_16x16x32_bf16 v[52:55], v[196:199], v[148:151], v[52:55]
	v_mfma_f32_16x16x32_bf16 v[48:51], v[214:217], v[148:151], v[48:51]
	v_mfma_f32_16x16x32_bf16 v[36:39], v[196:199], v[156:159], v[36:39]
	v_mfma_f32_16x16x32_bf16 v[32:35], v[214:217], v[156:159], v[32:35]
	v_mfma_f32_16x16x32_bf16 v[20:23], v[196:199], v[164:167], v[20:23]
	v_mfma_f32_16x16x32_bf16 v[16:19], v[214:217], v[164:167], v[16:19]
	v_mfma_f32_16x16x32_bf16 v[4:7], v[196:199], v[182:185], v[4:7]
	v_mfma_f32_16x16x32_bf16 v[0:3], v[214:217], v[182:185], v[0:3]
	s_add_u32 s10, s10, 0x100
	s_addc_u32 s11, s11, 0
	s_add_u32 s42, s42, 0x100
	s_addc_u32 s43, s43, 0
	s_cmp_ge_u32 s44, s33
	s_mov_b32 s12, s44
	s_barrier
.LBB0_246:
	s_add_i32 s44, s12, 2
	s_add_u32 s14, s10, 0x80
	s_addc_u32 s13, s11, 0
	s_add_i32 s45, 0, 0x10000
	ds_read_b128 v[120:123], v218 offset:0
	ds_read_b128 v[124:127], v218 offset:1024
	ds_read_b128 v[128:131], v218 offset:2048
	ds_read_b128 v[132:135], v218 offset:3072
	s_cmp_eq_u32 s36, s12
	s_cselect_b32 s12, s4, s14
	s_cselect_b32 s13, s5, s13
	s_cselect_b32 s15, s7, s43
	s_cselect_b32 s14, s6, s42
	s_add_i32 m0, s26, 0xc000
	ds_read_b128 v[144:147], v205
	ds_read_b128 v[148:151], v205 offset:1024
	ds_read_b128 v[152:155], v205 offset:2048
	ds_read_b128 v[156:159], v205 offset:3072
	ds_read_b128 v[160:163], v205 offset:4096
	ds_read_b128 v[164:167], v205 offset:5120
	ds_read_b128 v[178:181], v205 offset:6144
	ds_read_b128 v[182:185], v205 offset:7168
	global_load_lds_dwordx4 v174, s[10:11]
	s_add_i32 m0, s26, 0xe000
	s_nop 0
	global_load_lds_dwordx4 v176, s[10:11]
	s_waitcnt lgkmcnt(8)
	s_waitcnt lgkmcnt(0)
	s_barrier
	v_mfma_f32_16x16x32_bf16 v[140:143], v[120:123], v[144:147], v[140:143]
	v_mfma_f32_16x16x32_bf16 v[136:139], v[128:131], v[144:147], v[136:139]
	v_mfma_f32_16x16x32_bf16 v[108:111], v[120:123], v[152:155], v[108:111]
	v_mfma_f32_16x16x32_bf16 v[104:107], v[128:131], v[152:155], v[104:107]
	v_mfma_f32_16x16x32_bf16 v[92:95], v[120:123], v[160:163], v[92:95]
	v_mfma_f32_16x16x32_bf16 v[88:91], v[128:131], v[160:163], v[88:91]
	v_mfma_f32_16x16x32_bf16 v[76:79], v[120:123], v[178:181], v[76:79]
	v_mfma_f32_16x16x32_bf16 v[72:75], v[128:131], v[178:181], v[72:75]
	v_mfma_f32_16x16x32_bf16 v[140:143], v[124:127], v[148:151], v[140:143]
	v_mfma_f32_16x16x32_bf16 v[136:139], v[132:135], v[148:151], v[136:139]
	v_mfma_f32_16x16x32_bf16 v[108:111], v[124:127], v[156:159], v[108:111]
	v_mfma_f32_16x16x32_bf16 v[104:107], v[132:135], v[156:159], v[104:107]
	v_mfma_f32_16x16x32_bf16 v[92:95], v[124:127], v[164:167], v[92:95]
	v_mfma_f32_16x16x32_bf16 v[88:91], v[132:135], v[164:167], v[88:91]
	v_mfma_f32_16x16x32_bf16 v[76:79], v[124:127], v[182:185], v[76:79]
	v_mfma_f32_16x16x32_bf16 v[72:75], v[132:135], v[182:185], v[72:75]
	s_barrier
	s_add_i32 s46, 0, 0x14000
	s_add_i32 s45, s45, s25
	ds_read_b128 v[186:189], v218 offset:16384
	ds_read_b128 v[196:199], v218 offset:17408
	ds_read_b128 v[206:209], v218 offset:18432
	ds_read_b128 v[214:217], v218 offset:19456
	s_add_u32 s68, s14, 0x80
	s_addc_u32 s69, s15, 0
	s_mov_b32 m0, s45
	s_nop 0
	global_load_lds_dwordx4 v192, s[14:15]
	s_add_i32 m0, s45, 0x2000
	s_nop 0
	global_load_lds_dwordx4 v172, s[14:15]
	s_waitcnt lgkmcnt(0)
	s_barrier
	v_mfma_f32_16x16x32_bf16 v[116:119], v[186:189], v[144:147], v[116:119]
	v_mfma_f32_16x16x32_bf16 v[112:115], v[206:209], v[144:147], v[112:115]
	v_mfma_f32_16x16x32_bf16 v[100:103], v[186:189], v[152:155], v[100:103]
	v_mfma_f32_16x16x32_bf16 v[96:99], v[206:209], v[152:155], v[96:99]
	v_mfma_f32_16x16x32_bf16 v[84:87], v[186:189], v[160:163], v[84:87]
	v_mfma_f32_16x16x32_bf16 v[80:83], v[206:209], v[160:163], v[80:83]
	v_mfma_f32_16x16x32_bf16 v[68:71], v[186:189], v[178:181], v[68:71]
	v_mfma_f32_16x16x32_bf16 v[64:67], v[206:209], v[178:181], v[64:67]
	v_mfma_f32_16x16x32_bf16 v[116:119], v[196:199], v[148:151], v[116:119]
	v_mfma_f32_16x16x32_bf16 v[112:115], v[214:217], v[148:151], v[112:115]
	v_mfma_f32_16x16x32_bf16 v[100:103], v[196:199], v[156:159], v[100:103]
	v_mfma_f32_16x16x32_bf16 v[96:99], v[214:217], v[156:159], v[96:99]
	v_mfma_f32_16x16x32_bf16 v[84:87], v[196:199], v[164:167], v[84:87]
	v_mfma_f32_16x16x32_bf16 v[80:83], v[214:217], v[164:167], v[80:83]
	v_mfma_f32_16x16x32_bf16 v[68:71], v[196:199], v[182:185], v[68:71]
	v_mfma_f32_16x16x32_bf16 v[64:67], v[214:217], v[182:185], v[64:67]
	s_mov_b32 m0, s26
	s_add_u32 s70, s12, 0x80
	s_addc_u32 s71, s13, 0
	s_barrier
	ds_read_b128 v[144:147], v205 offset:16384
	ds_read_b128 v[148:151], v205 offset:17408
	ds_read_b128 v[152:155], v205 offset:18432
	ds_read_b128 v[156:159], v205 offset:19456
	ds_read_b128 v[160:163], v205 offset:20480
	ds_read_b128 v[164:167], v205 offset:21504
	ds_read_b128 v[178:181], v205 offset:22528
	ds_read_b128 v[182:185], v205 offset:23552
	global_load_lds_dwordx4 v168, s[12:13]
	s_mov_b32 m0, s27
	s_nop 0
	global_load_lds_dwordx4 v170, s[12:13]
	s_waitcnt lgkmcnt(0)
	s_barrier
	v_mfma_f32_16x16x32_bf16 v[60:63], v[120:123], v[144:147], v[60:63]
	v_mfma_f32_16x16x32_bf16 v[56:59], v[128:131], v[144:147], v[56:59]
	v_mfma_f32_16x16x32_bf16 v[44:47], v[120:123], v[152:155], v[44:47]
	v_mfma_f32_16x16x32_bf16 v[40:43], v[128:131], v[152:155], v[40:43]
	v_mfma_f32_16x16x32_bf16 v[28:31], v[120:123], v[160:163], v[28:31]
	v_mfma_f32_16x16x32_bf16 v[24:27], v[128:131], v[160:163], v[24:27]
	v_mfma_f32_16x16x32_bf16 v[12:15], v[120:123], v[178:181], v[12:15]
	v_mfma_f32_16x16x32_bf16 v[8:11], v[128:131], v[178:181], v[8:11]
	v_mfma_f32_16x16x32_bf16 v[60:63], v[124:127], v[148:151], v[60:63]
	v_mfma_f32_16x16x32_bf16 v[56:59], v[132:135], v[148:151], v[56:59]
	v_mfma_f32_16x16x32_bf16 v[44:47], v[124:127], v[156:159], v[44:47]
	v_mfma_f32_16x16x32_bf16 v[40:43], v[132:135], v[156:159], v[40:43]
	v_mfma_f32_16x16x32_bf16 v[28:31], v[124:127], v[164:167], v[28:31]
	v_mfma_f32_16x16x32_bf16 v[24:27], v[132:135], v[164:167], v[24:27]
	v_mfma_f32_16x16x32_bf16 v[12:15], v[124:127], v[182:185], v[12:15]
	v_mfma_f32_16x16x32_bf16 v[8:11], v[132:135], v[182:185], v[8:11]
	s_barrier
	s_add_u32 s14, s14, s52
	s_addc_u32 s15, s15, 0
	s_add_i32 s45, s46, s25
	s_mov_b32 m0, s45
	s_nop 0
	global_load_lds_dwordx4 v192, s[14:15]
	s_add_i32 m0, s45, 0x2000
	s_nop 0
	global_load_lds_dwordx4 v172, s[14:15]
	s_waitcnt vmcnt(6)
	s_barrier
	v_mfma_f32_16x16x32_bf16 v[52:55], v[186:189], v[144:147], v[52:55]
	v_mfma_f32_16x16x32_bf16 v[48:51], v[206:209], v[144:147], v[48:51]
	v_mfma_f32_16x16x32_bf16 v[36:39], v[186:189], v[152:155], v[36:39]
	v_mfma_f32_16x16x32_bf16 v[32:35], v[206:209], v[152:155], v[32:35]
	v_mfma_f32_16x16x32_bf16 v[20:23], v[186:189], v[160:163], v[20:23]
	v_mfma_f32_16x16x32_bf16 v[16:19], v[206:209], v[160:163], v[16:19]
	v_mfma_f32_16x16x32_bf16 v[4:7], v[186:189], v[178:181], v[4:7]
	v_mfma_f32_16x16x32_bf16 v[0:3], v[206:209], v[178:181], v[0:3]
	v_mfma_f32_16x16x32_bf16 v[52:55], v[196:199], v[148:151], v[52:55]
	v_mfma_f32_16x16x32_bf16 v[48:51], v[214:217], v[148:151], v[48:51]
	v_mfma_f32_16x16x32_bf16 v[36:39], v[196:199], v[156:159], v[36:39]
	v_mfma_f32_16x16x32_bf16 v[32:35], v[214:217], v[156:159], v[32:35]
	v_mfma_f32_16x16x32_bf16 v[20:23], v[196:199], v[164:167], v[20:23]
	v_mfma_f32_16x16x32_bf16 v[16:19], v[214:217], v[164:167], v[16:19]
	v_mfma_f32_16x16x32_bf16 v[4:7], v[196:199], v[182:185], v[4:7]
	v_mfma_f32_16x16x32_bf16 v[0:3], v[214:217], v[182:185], v[0:3]
	s_add_i32 s14, 0, 0x18000
	s_barrier
	ds_read_b128 v[120:123], v218 offset:32768
	ds_read_b128 v[124:127], v218 offset:33792
	ds_read_b128 v[128:131], v218 offset:34816
	ds_read_b128 v[132:135], v218 offset:35840
	s_add_u32 s12, s12, s52
	s_addc_u32 s13, s13, 0
	s_mov_b32 m0, s28
	ds_read_b128 v[144:147], v205 offset:32768
	ds_read_b128 v[148:151], v205 offset:33792
	ds_read_b128 v[152:155], v205 offset:34816
	ds_read_b128 v[156:159], v205 offset:35840
	ds_read_b128 v[160:163], v205 offset:36864
	ds_read_b128 v[164:167], v205 offset:37888
	ds_read_b128 v[178:181], v205 offset:38912
	ds_read_b128 v[182:185], v205 offset:39936
	global_load_lds_dwordx4 v168, s[12:13]
	s_mov_b32 m0, s29
	s_nop 0
	global_load_lds_dwordx4 v170, s[12:13]
	s_waitcnt lgkmcnt(8)
	s_waitcnt lgkmcnt(0)
	s_barrier
	v_mfma_f32_16x16x32_bf16 v[140:143], v[120:123], v[144:147], v[140:143]
	v_mfma_f32_16x16x32_bf16 v[136:139], v[128:131], v[144:147], v[136:139]
	v_mfma_f32_16x16x32_bf16 v[108:111], v[120:123], v[152:155], v[108:111]
	v_mfma_f32_16x16x32_bf16 v[104:107], v[128:131], v[152:155], v[104:107]
	v_mfma_f32_16x16x32_bf16 v[92:95], v[120:123], v[160:163], v[92:95]
	v_mfma_f32_16x16x32_bf16 v[88:91], v[128:131], v[160:163], v[88:91]
	v_mfma_f32_16x16x32_bf16 v[76:79], v[120:123], v[178:181], v[76:79]
	v_mfma_f32_16x16x32_bf16 v[72:75], v[128:131], v[178:181], v[72:75]
	v_mfma_f32_16x16x32_bf16 v[140:143], v[124:127], v[148:151], v[140:143]
	v_mfma_f32_16x16x32_bf16 v[136:139], v[132:135], v[148:151], v[136:139]
	v_mfma_f32_16x16x32_bf16 v[108:111], v[124:127], v[156:159], v[108:111]
	v_mfma_f32_16x16x32_bf16 v[104:107], v[132:135], v[156:159], v[104:107]
	v_mfma_f32_16x16x32_bf16 v[92:95], v[124:127], v[164:167], v[92:95]
	v_mfma_f32_16x16x32_bf16 v[88:91], v[132:135], v[164:167], v[88:91]
	v_mfma_f32_16x16x32_bf16 v[76:79], v[124:127], v[182:185], v[76:79]
	v_mfma_f32_16x16x32_bf16 v[72:75], v[132:135], v[182:185], v[72:75]
	s_barrier
	s_add_i32 s12, 0, 0x1c000
	s_add_i32 s13, s14, s25
	s_mov_b32 m0, s13
	ds_read_b128 v[186:189], v218 offset:49152
	ds_read_b128 v[196:199], v218 offset:50176
	ds_read_b128 v[206:209], v218 offset:51200
	ds_read_b128 v[214:217], v218 offset:52224
	global_load_lds_dwordx4 v192, s[68:69]
	s_add_i32 m0, s13, 0x2000
	s_nop 0
	global_load_lds_dwordx4 v172, s[68:69]
	s_waitcnt lgkmcnt(0)
	s_barrier
	v_mfma_f32_16x16x32_bf16 v[116:119], v[186:189], v[144:147], v[116:119]
	v_mfma_f32_16x16x32_bf16 v[112:115], v[206:209], v[144:147], v[112:115]
	v_mfma_f32_16x16x32_bf16 v[100:103], v[186:189], v[152:155], v[100:103]
	v_mfma_f32_16x16x32_bf16 v[96:99], v[206:209], v[152:155], v[96:99]
	v_mfma_f32_16x16x32_bf16 v[84:87], v[186:189], v[160:163], v[84:87]
	v_mfma_f32_16x16x32_bf16 v[80:83], v[206:209], v[160:163], v[80:83]
	v_mfma_f32_16x16x32_bf16 v[68:71], v[186:189], v[178:181], v[68:71]
	v_mfma_f32_16x16x32_bf16 v[64:67], v[206:209], v[178:181], v[64:67]
	v_mfma_f32_16x16x32_bf16 v[116:119], v[196:199], v[148:151], v[116:119]
	v_mfma_f32_16x16x32_bf16 v[112:115], v[214:217], v[148:151], v[112:115]
	v_mfma_f32_16x16x32_bf16 v[100:103], v[196:199], v[156:159], v[100:103]
	v_mfma_f32_16x16x32_bf16 v[96:99], v[214:217], v[156:159], v[96:99]
	v_mfma_f32_16x16x32_bf16 v[84:87], v[196:199], v[164:167], v[84:87]
	v_mfma_f32_16x16x32_bf16 v[80:83], v[214:217], v[164:167], v[80:83]
	v_mfma_f32_16x16x32_bf16 v[68:71], v[196:199], v[182:185], v[68:71]
	v_mfma_f32_16x16x32_bf16 v[64:67], v[214:217], v[182:185], v[64:67]
	s_mov_b32 m0, s34
	s_barrier
	ds_read_b128 v[144:147], v205 offset:49152
	ds_read_b128 v[148:151], v205 offset:50176
	ds_read_b128 v[152:155], v205 offset:51200
	ds_read_b128 v[156:159], v205 offset:52224
	ds_read_b128 v[160:163], v205 offset:53248
	ds_read_b128 v[164:167], v205 offset:54272
	ds_read_b128 v[178:181], v205 offset:55296
	ds_read_b128 v[182:185], v205 offset:56320
	global_load_lds_dwordx4 v168, s[70:71]
	s_mov_b32 m0, s35
	s_nop 0
	global_load_lds_dwordx4 v170, s[70:71]
	s_waitcnt lgkmcnt(0)
	s_barrier
	v_mfma_f32_16x16x32_bf16 v[60:63], v[120:123], v[144:147], v[60:63]
	v_mfma_f32_16x16x32_bf16 v[56:59], v[128:131], v[144:147], v[56:59]
	v_mfma_f32_16x16x32_bf16 v[44:47], v[120:123], v[152:155], v[44:47]
	v_mfma_f32_16x16x32_bf16 v[40:43], v[128:131], v[152:155], v[40:43]
	v_mfma_f32_16x16x32_bf16 v[28:31], v[120:123], v[160:163], v[28:31]
	v_mfma_f32_16x16x32_bf16 v[24:27], v[128:131], v[160:163], v[24:27]
	v_mfma_f32_16x16x32_bf16 v[12:15], v[120:123], v[178:181], v[12:15]
	v_mfma_f32_16x16x32_bf16 v[8:11], v[128:131], v[178:181], v[8:11]
	v_mfma_f32_16x16x32_bf16 v[60:63], v[124:127], v[148:151], v[60:63]
	v_mfma_f32_16x16x32_bf16 v[56:59], v[132:135], v[148:151], v[56:59]
	v_mfma_f32_16x16x32_bf16 v[44:47], v[124:127], v[156:159], v[44:47]
	v_mfma_f32_16x16x32_bf16 v[40:43], v[132:135], v[156:159], v[40:43]
	v_mfma_f32_16x16x32_bf16 v[28:31], v[124:127], v[164:167], v[28:31]
	v_mfma_f32_16x16x32_bf16 v[24:27], v[132:135], v[164:167], v[24:27]
	v_mfma_f32_16x16x32_bf16 v[12:15], v[124:127], v[182:185], v[12:15]
	v_mfma_f32_16x16x32_bf16 v[8:11], v[132:135], v[182:185], v[8:11]
	s_barrier
	s_add_i32 s12, s12, s25
	s_add_u32 s68, s68, s52
	s_addc_u32 s69, s69, 0
	s_mov_b32 m0, s12
	s_nop 0
	global_load_lds_dwordx4 v192, s[68:69]
	s_add_i32 m0, s12, 0x2000
	s_nop 0
	global_load_lds_dwordx4 v172, s[68:69]
	s_waitcnt vmcnt(6)
	s_barrier
	v_mfma_f32_16x16x32_bf16 v[52:55], v[186:189], v[144:147], v[52:55]
	v_mfma_f32_16x16x32_bf16 v[48:51], v[206:209], v[144:147], v[48:51]
	v_mfma_f32_16x16x32_bf16 v[36:39], v[186:189], v[152:155], v[36:39]
	v_mfma_f32_16x16x32_bf16 v[32:35], v[206:209], v[152:155], v[32:35]
	v_mfma_f32_16x16x32_bf16 v[20:23], v[186:189], v[160:163], v[20:23]
	v_mfma_f32_16x16x32_bf16 v[16:19], v[206:209], v[160:163], v[16:19]
	v_mfma_f32_16x16x32_bf16 v[4:7], v[186:189], v[178:181], v[4:7]
	v_mfma_f32_16x16x32_bf16 v[0:3], v[206:209], v[178:181], v[0:3]
	v_mfma_f32_16x16x32_bf16 v[52:55], v[196:199], v[148:151], v[52:55]
	v_mfma_f32_16x16x32_bf16 v[48:51], v[214:217], v[148:151], v[48:51]
	v_mfma_f32_16x16x32_bf16 v[36:39], v[196:199], v[156:159], v[36:39]
	v_mfma_f32_16x16x32_bf16 v[32:35], v[214:217], v[156:159], v[32:35]
	v_mfma_f32_16x16x32_bf16 v[20:23], v[196:199], v[164:167], v[20:23]
	v_mfma_f32_16x16x32_bf16 v[16:19], v[214:217], v[164:167], v[16:19]
	v_mfma_f32_16x16x32_bf16 v[4:7], v[196:199], v[182:185], v[4:7]
	v_mfma_f32_16x16x32_bf16 v[0:3], v[214:217], v[182:185], v[0:3]
	s_add_u32 s10, s10, 0x100
	s_addc_u32 s11, s11, 0
	s_add_u32 s42, s42, 0x100
	s_addc_u32 s43, s43, 0
	s_cmp_ge_u32 s44, s33
	s_mov_b32 s12, s44
	s_barrier
	s_cbranch_scc0 .LBB0_246
	v_lshl_or_b32 v144, s41, 8, v204
	s_ashr_i32 s10, s40, 4
	s_mul_hi_i32 s11, s10, 0xc000
	s_mul_i32 s10, s10, 0xc000
	v_ashrrev_i32_e32 v145, 31, v144
	v_lshl_add_u32 v146, s40, 8, v190
	s_add_u32 s10, s30, s10
	v_lshlrev_b64 v[178:179], 1, v[144:145]
	v_ashrrev_i32_e32 v147, 31, v146
	s_addc_u32 s11, s31, s11
	v_lshl_add_u64 v[180:181], s[2:3], 0, v[178:179]
	v_lshlrev_b64 v[182:183], 12, v[146:147]
	v_lshl_add_u64 v[124:125], v[144:145], 2, s[10:11]
	v_lshl_add_u64 v[144:145], v[180:181], 0, v[182:183]
	global_load_dwordx4 v[128:131], v[124:125], off offset:16
	global_load_dwordx4 v[132:135], v[124:125], off
	global_load_dwordx4 v[120:123], v[124:125], off offset:528
	s_nop 0
	global_load_dwordx4 v[124:127], v[124:125], off offset:512
	s_nop 0
	global_load_dwordx4 v[196:199], v[144:145], off
	global_load_dwordx4 v[206:209], v[144:145], off offset:256
	v_or_b32_e32 v144, 16, v146
	v_ashrrev_i32_e32 v145, 31, v144
	v_lshlrev_b64 v[188:189], 12, v[144:145]
	v_lshl_add_u64 v[144:145], v[180:181], 0, v[188:189]
	global_load_dwordx4 v[164:167], v[144:145], off
	global_load_dwordx4 v[160:163], v[144:145], off offset:256
	v_or_b32_e32 v144, 32, v146
	v_ashrrev_i32_e32 v145, 31, v144
	v_lshlrev_b64 v[186:187], 12, v[144:145]
	v_lshl_add_u64 v[144:145], v[180:181], 0, v[186:187]
	global_load_dwordx4 v[156:159], v[144:145], off
	global_load_dwordx4 v[152:155], v[144:145], off offset:256
	v_or_b32_e32 v144, 48, v146
	v_ashrrev_i32_e32 v145, 31, v144
	v_lshlrev_b64 v[184:185], 12, v[144:145]
	v_lshl_add_u64 v[144:145], v[180:181], 0, v[184:185]
	global_load_dwordx4 v[148:151], v[144:145], off
	s_nop 0
	global_load_dwordx4 v[144:147], v[144:145], off offset:256
	s_mov_b64 s[10:11], 0x80000
	s_and_b64 vcc, exec, s[0:1]
	s_mov_b32 s41, s38
	s_mov_b32 s40, s39
	s_mov_b64 s[12:13], s[6:7]
	v_readlane_b32 s14, v254, 21
	s_movk_i32 s15, 0x2000
	s_waitcnt vmcnt(0)
	v_lshlrev_b32_e32 v210, 16, v196
	v_and_b32_e32 v211, 0xffff0000, v196
	v_lshlrev_b32_e32 v196, 16, v197
	v_and_b32_e32 v197, 0xffff0000, v197
	v_lshlrev_b32_e32 v214, 16, v198
	v_and_b32_e32 v215, 0xffff0000, v198
	v_lshlrev_b32_e32 v198, 16, v199
	v_and_b32_e32 v199, 0xffff0000, v199
	v_pk_fma_f32 v[140:141], v[140:141], v[132:133], v[210:211]
	v_pk_fma_f32 v[142:143], v[142:143], v[134:135], v[196:197]
	v_pk_fma_f32 v[196:197], v[138:139], v[130:131], v[198:199]
	v_pk_fma_f32 v[138:139], v[136:137], v[128:129], v[214:215]
	v_cvt_pk_bf16_f32 v136, v140, v141
	v_lshl_add_u64 v[140:141], s[8:9], 0, v[182:183]
	v_cvt_pk_bf16_f32 v137, v142, v143
	v_cvt_pk_bf16_f32 v138, v138, v139
	v_cvt_pk_bf16_f32 v139, v196, v197
	v_lshl_add_u64 v[140:141], v[140:141], 0, v[178:179]
	global_store_dwordx4 v[140:141], v[136:139], off
	v_lshlrev_b32_e32 v142, 16, v208
	v_and_b32_e32 v143, 0xffff0000, v208
	v_lshlrev_b32_e32 v136, 16, v206
	v_and_b32_e32 v137, 0xffff0000, v206
	v_lshlrev_b32_e32 v138, 16, v207
	v_and_b32_e32 v139, 0xffff0000, v207
	v_lshlrev_b32_e32 v196, 16, v209
	v_and_b32_e32 v197, 0xffff0000, v209
	v_pk_fma_f32 v[118:119], v[118:119], v[126:127], v[138:139]
	v_pk_fma_f32 v[116:117], v[116:117], v[124:125], v[136:137]
	v_pk_fma_f32 v[136:137], v[114:115], v[122:123], v[196:197]
	v_pk_fma_f32 v[114:115], v[112:113], v[120:121], v[142:143]
	v_cvt_pk_bf16_f32 v112, v116, v117
	v_cvt_pk_bf16_f32 v113, v118, v119
	v_lshlrev_b32_e32 v116, 16, v166
	v_cvt_pk_bf16_f32 v114, v114, v115
	v_cvt_pk_bf16_f32 v115, v136, v137
	global_store_dwordx4 v[140:141], v[112:115], off offset:256
	v_and_b32_e32 v117, 0xffff0000, v166
	v_lshlrev_b32_e32 v118, 16, v167
	v_lshlrev_b32_e32 v112, 16, v164
	v_and_b32_e32 v113, 0xffff0000, v164
	v_and_b32_e32 v119, 0xffff0000, v167
	v_pk_fma_f32 v[108:109], v[108:109], v[132:133], v[112:113]
	v_lshlrev_b32_e32 v114, 16, v165
	v_and_b32_e32 v115, 0xffff0000, v165
	v_pk_fma_f32 v[112:113], v[106:107], v[130:131], v[118:119]
	v_pk_fma_f32 v[106:107], v[104:105], v[128:129], v[116:117]
	v_cvt_pk_bf16_f32 v104, v108, v109
	v_lshl_add_u64 v[108:109], s[8:9], 0, v[188:189]
	v_pk_fma_f32 v[110:111], v[110:111], v[134:135], v[114:115]
	v_lshl_add_u64 v[108:109], v[108:109], 0, v[178:179]
	v_cvt_pk_bf16_f32 v105, v110, v111
	v_cvt_pk_bf16_f32 v106, v106, v107
	v_cvt_pk_bf16_f32 v107, v112, v113
	global_store_dwordx4 v[108:109], v[104:107], off
	v_lshlrev_b32_e32 v110, 16, v162
	v_and_b32_e32 v111, 0xffff0000, v162
	v_lshlrev_b32_e32 v104, 16, v160
	v_and_b32_e32 v105, 0xffff0000, v160
	v_lshlrev_b32_e32 v106, 16, v161
	v_and_b32_e32 v107, 0xffff0000, v161
	v_lshlrev_b32_e32 v112, 16, v163
	v_and_b32_e32 v113, 0xffff0000, v163
	v_pk_fma_f32 v[102:103], v[102:103], v[126:127], v[106:107]
	v_pk_fma_f32 v[100:101], v[100:101], v[124:125], v[104:105]
	v_pk_fma_f32 v[104:105], v[98:99], v[122:123], v[112:113]
	v_pk_fma_f32 v[98:99], v[96:97], v[120:121], v[110:111]
	v_cvt_pk_bf16_f32 v96, v100, v101
	v_cvt_pk_bf16_f32 v97, v102, v103
	v_lshlrev_b32_e32 v100, 16, v158
	v_cvt_pk_bf16_f32 v98, v98, v99
	v_cvt_pk_bf16_f32 v99, v104, v105
	global_store_dwordx4 v[108:109], v[96:99], off offset:256
	v_and_b32_e32 v101, 0xffff0000, v158
	v_lshlrev_b32_e32 v102, 16, v159
	v_lshlrev_b32_e32 v96, 16, v156
	v_and_b32_e32 v97, 0xffff0000, v156
	v_and_b32_e32 v103, 0xffff0000, v159
	v_pk_fma_f32 v[92:93], v[92:93], v[132:133], v[96:97]
	v_lshlrev_b32_e32 v98, 16, v157
	v_and_b32_e32 v99, 0xffff0000, v157
	v_pk_fma_f32 v[96:97], v[90:91], v[130:131], v[102:103]
	v_pk_fma_f32 v[90:91], v[88:89], v[128:129], v[100:101]
	v_cvt_pk_bf16_f32 v88, v92, v93
	v_lshl_add_u64 v[92:93], s[8:9], 0, v[186:187]
	v_pk_fma_f32 v[94:95], v[94:95], v[134:135], v[98:99]
	v_lshl_add_u64 v[92:93], v[92:93], 0, v[178:179]
	v_cvt_pk_bf16_f32 v89, v94, v95
	v_cvt_pk_bf16_f32 v90, v90, v91
	v_cvt_pk_bf16_f32 v91, v96, v97
	global_store_dwordx4 v[92:93], v[88:91], off
	v_lshlrev_b32_e32 v94, 16, v154
	v_and_b32_e32 v95, 0xffff0000, v154
	v_lshlrev_b32_e32 v88, 16, v152
	v_and_b32_e32 v89, 0xffff0000, v152
	v_lshlrev_b32_e32 v90, 16, v153
	v_and_b32_e32 v91, 0xffff0000, v153
	v_lshlrev_b32_e32 v96, 16, v155
	v_and_b32_e32 v97, 0xffff0000, v155
	v_pk_fma_f32 v[86:87], v[86:87], v[126:127], v[90:91]
	v_pk_fma_f32 v[84:85], v[84:85], v[124:125], v[88:89]
	v_pk_fma_f32 v[88:89], v[82:83], v[122:123], v[96:97]
	v_pk_fma_f32 v[82:83], v[80:81], v[120:121], v[94:95]
	v_cvt_pk_bf16_f32 v80, v84, v85
	v_cvt_pk_bf16_f32 v81, v86, v87
	v_lshlrev_b32_e32 v84, 16, v150
	v_cvt_pk_bf16_f32 v82, v82, v83
	v_cvt_pk_bf16_f32 v83, v88, v89
	global_store_dwordx4 v[92:93], v[80:83], off offset:256
	v_and_b32_e32 v85, 0xffff0000, v150
	v_lshlrev_b32_e32 v86, 16, v151
	v_lshlrev_b32_e32 v80, 16, v148
	v_and_b32_e32 v81, 0xffff0000, v148
	v_and_b32_e32 v87, 0xffff0000, v151
	v_pk_fma_f32 v[76:77], v[76:77], v[132:133], v[80:81]
	v_lshlrev_b32_e32 v82, 16, v149
	v_and_b32_e32 v83, 0xffff0000, v149
	v_pk_fma_f32 v[80:81], v[74:75], v[130:131], v[86:87]
	v_pk_fma_f32 v[74:75], v[72:73], v[128:129], v[84:85]
	v_cvt_pk_bf16_f32 v72, v76, v77
	v_lshl_add_u64 v[76:77], s[8:9], 0, v[184:185]
	v_pk_fma_f32 v[78:79], v[78:79], v[134:135], v[82:83]
	v_lshl_add_u64 v[76:77], v[76:77], 0, v[178:179]
	v_cvt_pk_bf16_f32 v73, v78, v79
	v_cvt_pk_bf16_f32 v74, v74, v75
	v_cvt_pk_bf16_f32 v75, v80, v81
	global_store_dwordx4 v[76:77], v[72:75], off
	v_lshlrev_b32_e32 v78, 16, v146
	v_and_b32_e32 v79, 0xffff0000, v146
	v_lshlrev_b32_e32 v72, 16, v144
	v_and_b32_e32 v73, 0xffff0000, v144
	v_lshlrev_b32_e32 v74, 16, v145
	v_and_b32_e32 v75, 0xffff0000, v145
	v_lshlrev_b32_e32 v80, 16, v147
	v_and_b32_e32 v81, 0xffff0000, v147
	v_pk_fma_f32 v[70:71], v[70:71], v[126:127], v[74:75]
	v_pk_fma_f32 v[68:69], v[68:69], v[124:125], v[72:73]
	v_pk_fma_f32 v[72:73], v[66:67], v[122:123], v[80:81]
	v_pk_fma_f32 v[66:67], v[64:65], v[120:121], v[78:79]
	v_cvt_pk_bf16_f32 v64, v68, v69
	v_cvt_pk_bf16_f32 v65, v70, v71
	v_lshl_add_u64 v[98:99], v[182:183], 0, s[10:11]
	v_cvt_pk_bf16_f32 v66, v66, v67
	v_cvt_pk_bf16_f32 v67, v72, v73
	global_store_dwordx4 v[76:77], v[64:67], off offset:256
	s_mov_b64 s[10:11], 0x90000
	v_lshl_add_u64 v[100:101], v[182:183], 0, s[10:11]
	v_lshl_add_u64 v[64:65], v[180:181], 0, v[98:99]
	global_load_dwordx4 v[74:77], v[64:65], off
	global_load_dwordx4 v[78:81], v[64:65], off offset:256
	v_lshl_add_u64 v[64:65], v[180:181], 0, v[100:101]
	global_load_dwordx4 v[82:85], v[64:65], off
	global_load_dwordx4 v[86:89], v[64:65], off offset:256
	s_mov_b64 s[10:11], 0xa0000
	v_lshl_add_u64 v[102:103], v[182:183], 0, s[10:11]
	v_lshl_add_u64 v[64:65], v[180:181], 0, v[102:103]
	global_load_dwordx4 v[90:93], v[64:65], off
	global_load_dwordx4 v[94:97], v[64:65], off offset:256
	s_mov_b64 s[10:11], 0xb0000
	v_lshl_add_u64 v[72:73], v[182:183], 0, s[10:11]
	v_lshl_add_u64 v[64:65], v[180:181], 0, v[72:73]
	global_load_dwordx4 v[68:71], v[64:65], off
	s_nop 0
	global_load_dwordx4 v[64:67], v[64:65], off offset:256
	s_mov_b64 s[10:11], s[4:5]
	s_waitcnt vmcnt(0)
	v_lshlrev_b32_e32 v104, 16, v74
	v_and_b32_e32 v105, 0xffff0000, v74
	v_lshlrev_b32_e32 v74, 16, v75
	v_and_b32_e32 v75, 0xffff0000, v75
	v_lshlrev_b32_e32 v106, 16, v76
	v_and_b32_e32 v107, 0xffff0000, v76
	v_lshlrev_b32_e32 v76, 16, v77
	v_and_b32_e32 v77, 0xffff0000, v77
	v_pk_fma_f32 v[60:61], v[60:61], v[132:133], v[104:105]
	v_pk_fma_f32 v[62:63], v[62:63], v[134:135], v[74:75]
	v_pk_fma_f32 v[74:75], v[58:59], v[130:131], v[76:77]
	v_pk_fma_f32 v[58:59], v[56:57], v[128:129], v[106:107]
	v_cvt_pk_bf16_f32 v56, v60, v61
	v_lshl_add_u64 v[60:61], s[8:9], 0, v[98:99]
	v_cvt_pk_bf16_f32 v57, v62, v63
	v_cvt_pk_bf16_f32 v58, v58, v59
	v_cvt_pk_bf16_f32 v59, v74, v75
	v_lshl_add_u64 v[60:61], v[60:61], 0, v[178:179]
	global_store_dwordx4 v[60:61], v[56:59], off
	v_lshlrev_b32_e32 v62, 16, v80
	v_and_b32_e32 v63, 0xffff0000, v80
	v_lshlrev_b32_e32 v56, 16, v78
	v_and_b32_e32 v57, 0xffff0000, v78
	v_lshlrev_b32_e32 v58, 16, v79
	v_and_b32_e32 v59, 0xffff0000, v79
	v_lshlrev_b32_e32 v74, 16, v81
	v_and_b32_e32 v75, 0xffff0000, v81
	v_pk_fma_f32 v[54:55], v[54:55], v[126:127], v[58:59]
	v_pk_fma_f32 v[52:53], v[52:53], v[124:125], v[56:57]
	v_pk_fma_f32 v[56:57], v[50:51], v[122:123], v[74:75]
	v_pk_fma_f32 v[50:51], v[48:49], v[120:121], v[62:63]
	v_cvt_pk_bf16_f32 v48, v52, v53
	v_cvt_pk_bf16_f32 v49, v54, v55
	v_lshlrev_b32_e32 v52, 16, v84
	v_cvt_pk_bf16_f32 v50, v50, v51
	v_cvt_pk_bf16_f32 v51, v56, v57
	global_store_dwordx4 v[60:61], v[48:51], off offset:256
	v_and_b32_e32 v53, 0xffff0000, v84
	v_lshlrev_b32_e32 v54, 16, v85
	v_lshlrev_b32_e32 v48, 16, v82
	v_and_b32_e32 v49, 0xffff0000, v82
	v_and_b32_e32 v55, 0xffff0000, v85
	v_pk_fma_f32 v[44:45], v[44:45], v[132:133], v[48:49]
	v_lshlrev_b32_e32 v50, 16, v83
	v_and_b32_e32 v51, 0xffff0000, v83
	v_pk_fma_f32 v[48:49], v[42:43], v[130:131], v[54:55]
	v_pk_fma_f32 v[42:43], v[40:41], v[128:129], v[52:53]
	v_cvt_pk_bf16_f32 v40, v44, v45
	v_lshl_add_u64 v[44:45], s[8:9], 0, v[100:101]
	v_pk_fma_f32 v[46:47], v[46:47], v[134:135], v[50:51]
	v_lshl_add_u64 v[44:45], v[44:45], 0, v[178:179]
	v_cvt_pk_bf16_f32 v41, v46, v47
	v_cvt_pk_bf16_f32 v42, v42, v43
	v_cvt_pk_bf16_f32 v43, v48, v49
	global_store_dwordx4 v[44:45], v[40:43], off
	v_lshlrev_b32_e32 v46, 16, v88
	v_and_b32_e32 v47, 0xffff0000, v88
	v_lshlrev_b32_e32 v40, 16, v86
	v_and_b32_e32 v41, 0xffff0000, v86
	v_lshlrev_b32_e32 v42, 16, v87
	v_and_b32_e32 v43, 0xffff0000, v87
	v_lshlrev_b32_e32 v48, 16, v89
	v_and_b32_e32 v49, 0xffff0000, v89
	v_pk_fma_f32 v[38:39], v[38:39], v[126:127], v[42:43]
	v_pk_fma_f32 v[36:37], v[36:37], v[124:125], v[40:41]
	v_pk_fma_f32 v[40:41], v[34:35], v[122:123], v[48:49]
	v_pk_fma_f32 v[34:35], v[32:33], v[120:121], v[46:47]
	v_cvt_pk_bf16_f32 v32, v36, v37
	v_cvt_pk_bf16_f32 v33, v38, v39
	v_lshlrev_b32_e32 v36, 16, v92
	v_cvt_pk_bf16_f32 v34, v34, v35
	v_cvt_pk_bf16_f32 v35, v40, v41
	global_store_dwordx4 v[44:45], v[32:35], off offset:256
	v_and_b32_e32 v37, 0xffff0000, v92
	v_lshlrev_b32_e32 v38, 16, v93
	v_lshlrev_b32_e32 v32, 16, v90
	v_and_b32_e32 v33, 0xffff0000, v90
	v_and_b32_e32 v39, 0xffff0000, v93
	v_pk_fma_f32 v[28:29], v[28:29], v[132:133], v[32:33]
	v_lshlrev_b32_e32 v34, 16, v91
	v_and_b32_e32 v35, 0xffff0000, v91
	v_pk_fma_f32 v[32:33], v[26:27], v[130:131], v[38:39]
	v_pk_fma_f32 v[26:27], v[24:25], v[128:129], v[36:37]
	v_cvt_pk_bf16_f32 v24, v28, v29
	v_lshl_add_u64 v[28:29], s[8:9], 0, v[102:103]
	v_pk_fma_f32 v[30:31], v[30:31], v[134:135], v[34:35]
	v_lshl_add_u64 v[28:29], v[28:29], 0, v[178:179]
	v_cvt_pk_bf16_f32 v25, v30, v31
	v_cvt_pk_bf16_f32 v26, v26, v27
	v_cvt_pk_bf16_f32 v27, v32, v33
	global_store_dwordx4 v[28:29], v[24:27], off
	v_lshlrev_b32_e32 v30, 16, v96
	v_and_b32_e32 v31, 0xffff0000, v96
	v_lshlrev_b32_e32 v24, 16, v94
	v_and_b32_e32 v25, 0xffff0000, v94
	v_lshlrev_b32_e32 v26, 16, v95
	v_and_b32_e32 v27, 0xffff0000, v95
	v_lshlrev_b32_e32 v32, 16, v97
	v_and_b32_e32 v33, 0xffff0000, v97
	v_pk_fma_f32 v[22:23], v[22:23], v[126:127], v[26:27]
	v_pk_fma_f32 v[20:21], v[20:21], v[124:125], v[24:25]
	v_pk_fma_f32 v[24:25], v[18:19], v[122:123], v[32:33]
	v_pk_fma_f32 v[18:19], v[16:17], v[120:121], v[30:31]
	v_cvt_pk_bf16_f32 v16, v20, v21
	v_cvt_pk_bf16_f32 v17, v22, v23
	v_lshlrev_b32_e32 v20, 16, v70
	v_cvt_pk_bf16_f32 v18, v18, v19
	v_cvt_pk_bf16_f32 v19, v24, v25
	global_store_dwordx4 v[28:29], v[16:19], off offset:256
	v_and_b32_e32 v21, 0xffff0000, v70
	v_lshlrev_b32_e32 v22, 16, v71
	v_lshlrev_b32_e32 v16, 16, v68
	v_and_b32_e32 v17, 0xffff0000, v68
	v_and_b32_e32 v23, 0xffff0000, v71
	v_pk_fma_f32 v[12:13], v[12:13], v[132:133], v[16:17]
	v_lshlrev_b32_e32 v18, 16, v69
	v_and_b32_e32 v19, 0xffff0000, v69
	v_pk_fma_f32 v[16:17], v[10:11], v[130:131], v[22:23]
	v_pk_fma_f32 v[10:11], v[8:9], v[128:129], v[20:21]
	v_cvt_pk_bf16_f32 v8, v12, v13
	v_lshl_add_u64 v[12:13], s[8:9], 0, v[72:73]
	v_pk_fma_f32 v[14:15], v[14:15], v[134:135], v[18:19]
	v_lshl_add_u64 v[12:13], v[12:13], 0, v[178:179]
	v_cvt_pk_bf16_f32 v9, v14, v15
	v_cvt_pk_bf16_f32 v10, v10, v11
	v_cvt_pk_bf16_f32 v11, v16, v17
	global_store_dwordx4 v[12:13], v[8:11], off
	v_lshlrev_b32_e32 v14, 16, v66
	v_and_b32_e32 v15, 0xffff0000, v66
	v_lshlrev_b32_e32 v8, 16, v64
	v_and_b32_e32 v9, 0xffff0000, v64
	v_lshlrev_b32_e32 v16, 16, v67
	v_and_b32_e32 v17, 0xffff0000, v67
	v_lshlrev_b32_e32 v10, 16, v65
	v_and_b32_e32 v11, 0xffff0000, v65
	v_pk_fma_f32 v[4:5], v[4:5], v[124:125], v[8:9]
	v_pk_fma_f32 v[8:9], v[2:3], v[122:123], v[16:17]
	v_pk_fma_f32 v[2:3], v[0:1], v[120:121], v[14:15]
	v_pk_fma_f32 v[6:7], v[6:7], v[126:127], v[10:11]
	v_cvt_pk_bf16_f32 v0, v4, v5
	s_nop 0
	v_cvt_pk_bf16_f32 v1, v6, v7
	v_cvt_pk_bf16_f32 v2, v2, v3
	v_cvt_pk_bf16_f32 v3, v8, v9
	global_store_dwordx4 v[12:13], v[0:3], off offset:256
	s_cbranch_vccz .LBB0_235
	s_waitcnt vmcnt(0)
	s_cmpk_gt_u32 s16, 0xff
	s_cbranch_scc1 .LBB0_250
	s_barrier

.LBB0_271:
	s_add_u32 s39, s10, 0x100
	s_addc_u32 s40, s11, 0
	s_mov_b32 s41, -2
	s_mov_b64 s[44:45], 0x80
	v_add_u32_e32 v220, 0x10000, v187
	s_add_u32 s10, s8, 0x100
	s_addc_u32 s11, s9, 0
	s_add_i32 s42, 0, 0x10000
	ds_read_b128 v[108:111], v220 offset:0
	ds_read_b128 v[112:115], v220 offset:1024
	ds_read_b128 v[116:119], v220 offset:2048
	ds_read_b128 v[120:123], v220 offset:3072
	s_cmpk_eq_i32 s41, 0x54
	s_cselect_b32 s15, s5, s11
	s_cselect_b32 s14, s4, s10
	s_cselect_b32 s13, s7, s40
	s_cselect_b32 s12, s6, s39
	s_add_i32 m0, s25, 0xc000
	ds_read_b128 v[144:147], v189
	ds_read_b128 v[148:151], v189 offset:1024
	ds_read_b128 v[152:155], v189 offset:2048
	ds_read_b128 v[156:159], v189 offset:3072
	ds_read_b128 v[160:163], v189 offset:4096
	ds_read_b128 v[174:177], v189 offset:5120
	ds_read_b128 v[178:181], v189 offset:6144
	ds_read_b128 v[182:185], v189 offset:7168
	global_load_lds_dwordx4 v170, s[8:9]
	s_add_i32 m0, s25, 0xe000
	s_nop 0
	global_load_lds_dwordx4 v172, s[8:9]
	s_waitcnt lgkmcnt(8)
	s_waitcnt lgkmcnt(0)
	s_barrier
	v_mfma_f32_16x16x32_bf16 v[140:143], v[108:111], v[144:147], 0
	v_mfma_f32_16x16x32_bf16 v[136:139], v[116:119], v[144:147], 0
	v_mfma_f32_16x16x32_bf16 v[132:135], v[108:111], v[152:155], 0
	v_mfma_f32_16x16x32_bf16 v[104:107], v[116:119], v[152:155], 0
	v_mfma_f32_16x16x32_bf16 v[96:99], v[108:111], v[160:163], 0
	v_mfma_f32_16x16x32_bf16 v[88:91], v[116:119], v[160:163], 0
	v_mfma_f32_16x16x32_bf16 v[80:83], v[108:111], v[178:181], 0
	v_mfma_f32_16x16x32_bf16 v[72:75], v[116:119], v[178:181], 0
	v_mfma_f32_16x16x32_bf16 v[140:143], v[112:115], v[148:151], v[140:143]
	v_mfma_f32_16x16x32_bf16 v[136:139], v[120:123], v[148:151], v[136:139]
	v_mfma_f32_16x16x32_bf16 v[132:135], v[112:115], v[156:159], v[132:135]
	v_mfma_f32_16x16x32_bf16 v[104:107], v[120:123], v[156:159], v[104:107]
	v_mfma_f32_16x16x32_bf16 v[96:99], v[112:115], v[174:177], v[96:99]
	v_mfma_f32_16x16x32_bf16 v[88:91], v[120:123], v[174:177], v[88:91]
	v_mfma_f32_16x16x32_bf16 v[80:83], v[112:115], v[182:185], v[80:83]
	v_mfma_f32_16x16x32_bf16 v[72:75], v[120:123], v[182:185], v[72:75]
	s_barrier
	s_add_i32 s43, 0, 0x14000
	s_add_i32 s8, s42, s19
	ds_read_b128 v[196:199], v220 offset:16384
	ds_read_b128 v[204:207], v220 offset:17408
	ds_read_b128 v[208:211], v220 offset:18432
	ds_read_b128 v[214:217], v220 offset:19456
	s_mov_b32 m0, s8
	s_nop 0
	global_load_lds_dwordx4 v192, s[12:13]
	s_add_i32 m0, s8, 0x2000
	s_nop 0
	global_load_lds_dwordx4 v168, s[12:13]
	s_waitcnt lgkmcnt(0)
	s_barrier
	v_mfma_f32_16x16x32_bf16 v[128:131], v[196:199], v[144:147], 0
	v_mfma_f32_16x16x32_bf16 v[124:127], v[208:211], v[144:147], 0
	v_mfma_f32_16x16x32_bf16 v[100:103], v[196:199], v[152:155], 0
	v_mfma_f32_16x16x32_bf16 v[92:95], v[208:211], v[152:155], 0
	v_mfma_f32_16x16x32_bf16 v[84:87], v[196:199], v[160:163], 0
	v_mfma_f32_16x16x32_bf16 v[76:79], v[208:211], v[160:163], 0
	v_mfma_f32_16x16x32_bf16 v[68:71], v[196:199], v[178:181], 0
	v_mfma_f32_16x16x32_bf16 v[64:67], v[208:211], v[178:181], 0
	v_mfma_f32_16x16x32_bf16 v[128:131], v[204:207], v[148:151], v[128:131]
	v_mfma_f32_16x16x32_bf16 v[124:127], v[214:217], v[148:151], v[124:127]
	v_mfma_f32_16x16x32_bf16 v[100:103], v[204:207], v[156:159], v[100:103]
	v_mfma_f32_16x16x32_bf16 v[92:95], v[214:217], v[156:159], v[92:95]
	v_mfma_f32_16x16x32_bf16 v[84:87], v[204:207], v[174:177], v[84:87]
	v_mfma_f32_16x16x32_bf16 v[76:79], v[214:217], v[174:177], v[76:79]
	v_mfma_f32_16x16x32_bf16 v[68:71], v[204:207], v[182:185], v[68:71]
	v_mfma_f32_16x16x32_bf16 v[64:67], v[214:217], v[182:185], v[64:67]
	s_mov_b32 m0, s25
	s_add_u32 s44, s14, 0x80
	s_addc_u32 s45, s15, 0
	s_barrier
	ds_read_b128 v[144:147], v189 offset:16384
	ds_read_b128 v[148:151], v189 offset:17408
	ds_read_b128 v[152:155], v189 offset:18432
	ds_read_b128 v[156:159], v189 offset:19456
	ds_read_b128 v[160:163], v189 offset:20480
	ds_read_b128 v[174:177], v189 offset:21504
	ds_read_b128 v[178:181], v189 offset:22528
	ds_read_b128 v[182:185], v189 offset:23552
	global_load_lds_dwordx4 v164, s[14:15]
	s_mov_b32 m0, s26
	s_nop 0
	global_load_lds_dwordx4 v166, s[14:15]
	s_waitcnt lgkmcnt(0)
	s_barrier
	v_mfma_f32_16x16x32_bf16 v[60:63], v[108:111], v[144:147], 0
	v_mfma_f32_16x16x32_bf16 v[56:59], v[116:119], v[144:147], 0
	v_mfma_f32_16x16x32_bf16 v[48:51], v[108:111], v[152:155], 0
	v_mfma_f32_16x16x32_bf16 v[40:43], v[116:119], v[152:155], 0
	v_mfma_f32_16x16x32_bf16 v[32:35], v[108:111], v[160:163], 0
	v_mfma_f32_16x16x32_bf16 v[24:27], v[116:119], v[160:163], 0
	v_mfma_f32_16x16x32_bf16 v[16:19], v[108:111], v[178:181], 0
	v_mfma_f32_16x16x32_bf16 v[8:11], v[116:119], v[178:181], 0
	v_mfma_f32_16x16x32_bf16 v[60:63], v[112:115], v[148:151], v[60:63]
	v_mfma_f32_16x16x32_bf16 v[56:59], v[120:123], v[148:151], v[56:59]
	v_mfma_f32_16x16x32_bf16 v[48:51], v[112:115], v[156:159], v[48:51]
	v_mfma_f32_16x16x32_bf16 v[40:43], v[120:123], v[156:159], v[40:43]
	v_mfma_f32_16x16x32_bf16 v[32:35], v[112:115], v[174:177], v[32:35]
	v_mfma_f32_16x16x32_bf16 v[24:27], v[120:123], v[174:177], v[24:27]
	v_mfma_f32_16x16x32_bf16 v[16:19], v[112:115], v[182:185], v[16:19]
	v_mfma_f32_16x16x32_bf16 v[8:11], v[120:123], v[182:185], v[8:11]
	s_barrier
	s_add_u32 s8, s12, 0x160000
	s_addc_u32 s9, s13, 0
	s_add_i32 s42, s43, s19
	s_mov_b32 m0, s42
	s_nop 0
	global_load_lds_dwordx4 v192, s[8:9]
	s_add_i32 m0, s42, 0x2000
	s_nop 0
	global_load_lds_dwordx4 v168, s[8:9]
	s_waitcnt vmcnt(6)
	s_barrier
	v_mfma_f32_16x16x32_bf16 v[52:55], v[196:199], v[144:147], 0
	v_mfma_f32_16x16x32_bf16 v[44:47], v[208:211], v[144:147], 0
	v_mfma_f32_16x16x32_bf16 v[36:39], v[196:199], v[152:155], 0
	v_mfma_f32_16x16x32_bf16 v[28:31], v[208:211], v[152:155], 0
	v_mfma_f32_16x16x32_bf16 v[20:23], v[196:199], v[160:163], 0
	v_mfma_f32_16x16x32_bf16 v[12:15], v[208:211], v[160:163], 0
	v_mfma_f32_16x16x32_bf16 v[4:7], v[196:199], v[178:181], 0
	v_mfma_f32_16x16x32_bf16 v[0:3], v[208:211], v[178:181], 0
	v_mfma_f32_16x16x32_bf16 v[52:55], v[204:207], v[148:151], v[52:55]
	v_mfma_f32_16x16x32_bf16 v[44:47], v[214:217], v[148:151], v[44:47]
	v_mfma_f32_16x16x32_bf16 v[36:39], v[204:207], v[156:159], v[36:39]
	v_mfma_f32_16x16x32_bf16 v[28:31], v[214:217], v[156:159], v[28:31]
	v_mfma_f32_16x16x32_bf16 v[20:23], v[204:207], v[174:177], v[20:23]
	v_mfma_f32_16x16x32_bf16 v[12:15], v[214:217], v[174:177], v[12:15]
	v_mfma_f32_16x16x32_bf16 v[4:7], v[204:207], v[182:185], v[4:7]
	v_mfma_f32_16x16x32_bf16 v[0:3], v[214:217], v[182:185], v[0:3]
	s_add_i32 s42, 0, 0x18000
	s_barrier
	ds_read_b128 v[108:111], v220 offset:32768
	ds_read_b128 v[112:115], v220 offset:33792
	ds_read_b128 v[116:119], v220 offset:34816
	ds_read_b128 v[120:123], v220 offset:35840
	s_add_u32 s8, s14, 0x160000
	s_addc_u32 s9, s15, 0
	s_mov_b32 m0, s27
	ds_read_b128 v[144:147], v189 offset:32768
	ds_read_b128 v[148:151], v189 offset:33792
	ds_read_b128 v[152:155], v189 offset:34816
	ds_read_b128 v[156:159], v189 offset:35840
	ds_read_b128 v[160:163], v189 offset:36864
	ds_read_b128 v[174:177], v189 offset:37888
	ds_read_b128 v[178:181], v189 offset:38912
	ds_read_b128 v[182:185], v189 offset:39936
	global_load_lds_dwordx4 v164, s[8:9]
	s_mov_b32 m0, s28
	s_nop 0
	global_load_lds_dwordx4 v166, s[8:9]
	s_waitcnt lgkmcnt(8)
	s_waitcnt lgkmcnt(0)
	s_barrier
	v_mfma_f32_16x16x32_bf16 v[140:143], v[108:111], v[144:147], v[140:143]
	v_mfma_f32_16x16x32_bf16 v[136:139], v[116:119], v[144:147], v[136:139]
	v_mfma_f32_16x16x32_bf16 v[132:135], v[108:111], v[152:155], v[132:135]
	v_mfma_f32_16x16x32_bf16 v[104:107], v[116:119], v[152:155], v[104:107]
	v_mfma_f32_16x16x32_bf16 v[96:99], v[108:111], v[160:163], v[96:99]
	v_mfma_f32_16x16x32_bf16 v[88:91], v[116:119], v[160:163], v[88:91]
	v_mfma_f32_16x16x32_bf16 v[80:83], v[108:111], v[178:181], v[80:83]
	v_mfma_f32_16x16x32_bf16 v[72:75], v[116:119], v[178:181], v[72:75]
	v_mfma_f32_16x16x32_bf16 v[140:143], v[112:115], v[148:151], v[140:143]
	v_mfma_f32_16x16x32_bf16 v[136:139], v[120:123], v[148:151], v[136:139]
	v_mfma_f32_16x16x32_bf16 v[132:135], v[112:115], v[156:159], v[132:135]
	v_mfma_f32_16x16x32_bf16 v[104:107], v[120:123], v[156:159], v[104:107]
	v_mfma_f32_16x16x32_bf16 v[96:99], v[112:115], v[174:177], v[96:99]
	v_mfma_f32_16x16x32_bf16 v[88:91], v[120:123], v[174:177], v[88:91]
	v_mfma_f32_16x16x32_bf16 v[80:83], v[112:115], v[182:185], v[80:83]
	v_mfma_f32_16x16x32_bf16 v[72:75], v[120:123], v[182:185], v[72:75]
	s_barrier
	s_add_i32 s14, 0, 0x1c000
	s_add_i32 s8, s42, s19
	s_add_i32 m0, s8, 0xffffff80
	ds_read_b128 v[196:199], v220 offset:49152
	ds_read_b128 v[204:207], v220 offset:50176
	ds_read_b128 v[208:211], v220 offset:51200
	ds_read_b128 v[214:217], v220 offset:52224
	global_load_lds_dwordx4 v192, s[12:13] offset:128
	s_add_i32 m0, s8, 0x1f80
	s_nop 0
	global_load_lds_dwordx4 v168, s[12:13] offset:128
	s_waitcnt lgkmcnt(0)
	s_barrier
	v_mfma_f32_16x16x32_bf16 v[128:131], v[196:199], v[144:147], v[128:131]
	v_mfma_f32_16x16x32_bf16 v[124:127], v[208:211], v[144:147], v[124:127]
	v_mfma_f32_16x16x32_bf16 v[100:103], v[196:199], v[152:155], v[100:103]
	v_mfma_f32_16x16x32_bf16 v[92:95], v[208:211], v[152:155], v[92:95]
	v_mfma_f32_16x16x32_bf16 v[84:87], v[196:199], v[160:163], v[84:87]
	v_mfma_f32_16x16x32_bf16 v[76:79], v[208:211], v[160:163], v[76:79]
	v_mfma_f32_16x16x32_bf16 v[68:71], v[196:199], v[178:181], v[68:71]
	v_mfma_f32_16x16x32_bf16 v[64:67], v[208:211], v[178:181], v[64:67]
	v_mfma_f32_16x16x32_bf16 v[128:131], v[204:207], v[148:151], v[128:131]
	v_mfma_f32_16x16x32_bf16 v[124:127], v[214:217], v[148:151], v[124:127]
	v_mfma_f32_16x16x32_bf16 v[100:103], v[204:207], v[156:159], v[100:103]
	v_mfma_f32_16x16x32_bf16 v[92:95], v[214:217], v[156:159], v[92:95]
	v_mfma_f32_16x16x32_bf16 v[84:87], v[204:207], v[174:177], v[84:87]
	v_mfma_f32_16x16x32_bf16 v[76:79], v[214:217], v[174:177], v[76:79]
	v_mfma_f32_16x16x32_bf16 v[68:71], v[204:207], v[182:185], v[68:71]
	v_mfma_f32_16x16x32_bf16 v[64:67], v[214:217], v[182:185], v[64:67]
	s_mov_b32 m0, s31
	s_barrier
	ds_read_b128 v[144:147], v189 offset:49152
	ds_read_b128 v[148:151], v189 offset:50176
	ds_read_b128 v[152:155], v189 offset:51200
	ds_read_b128 v[156:159], v189 offset:52224
	ds_read_b128 v[160:163], v189 offset:53248
	ds_read_b128 v[174:177], v189 offset:54272
	ds_read_b128 v[178:181], v189 offset:55296
	ds_read_b128 v[182:185], v189 offset:56320
	global_load_lds_dwordx4 v164, s[44:45]
	s_mov_b32 m0, s33
	s_nop 0
	global_load_lds_dwordx4 v166, s[44:45]
	s_waitcnt lgkmcnt(0)
	s_barrier
	v_mfma_f32_16x16x32_bf16 v[60:63], v[108:111], v[144:147], v[60:63]
	v_mfma_f32_16x16x32_bf16 v[56:59], v[116:119], v[144:147], v[56:59]
	v_mfma_f32_16x16x32_bf16 v[48:51], v[108:111], v[152:155], v[48:51]
	v_mfma_f32_16x16x32_bf16 v[40:43], v[116:119], v[152:155], v[40:43]
	v_mfma_f32_16x16x32_bf16 v[32:35], v[108:111], v[160:163], v[32:35]
	v_mfma_f32_16x16x32_bf16 v[24:27], v[116:119], v[160:163], v[24:27]
	v_mfma_f32_16x16x32_bf16 v[16:19], v[108:111], v[178:181], v[16:19]
	v_mfma_f32_16x16x32_bf16 v[8:11], v[116:119], v[178:181], v[8:11]
	v_mfma_f32_16x16x32_bf16 v[60:63], v[112:115], v[148:151], v[60:63]
	v_mfma_f32_16x16x32_bf16 v[56:59], v[120:123], v[148:151], v[56:59]
	v_mfma_f32_16x16x32_bf16 v[48:51], v[112:115], v[156:159], v[48:51]
	v_mfma_f32_16x16x32_bf16 v[40:43], v[120:123], v[156:159], v[40:43]
	v_mfma_f32_16x16x32_bf16 v[32:35], v[112:115], v[174:177], v[32:35]
	v_mfma_f32_16x16x32_bf16 v[24:27], v[120:123], v[174:177], v[24:27]
	v_mfma_f32_16x16x32_bf16 v[16:19], v[112:115], v[182:185], v[16:19]
	v_mfma_f32_16x16x32_bf16 v[8:11], v[120:123], v[182:185], v[8:11]
	s_barrier
	s_add_u32 s8, s12, 0x160080
	s_addc_u32 s9, s13, 0
	s_add_i32 s12, s14, s19
	s_mov_b32 m0, s12
	s_nop 0
	global_load_lds_dwordx4 v192, s[8:9]
	s_add_i32 m0, s12, 0x2000
	s_nop 0
	global_load_lds_dwordx4 v168, s[8:9]
	s_waitcnt vmcnt(6)
	s_barrier
	v_mfma_f32_16x16x32_bf16 v[52:55], v[196:199], v[144:147], v[52:55]
	v_mfma_f32_16x16x32_bf16 v[44:47], v[208:211], v[144:147], v[44:47]
	v_mfma_f32_16x16x32_bf16 v[36:39], v[196:199], v[152:155], v[36:39]
	v_mfma_f32_16x16x32_bf16 v[28:31], v[208:211], v[152:155], v[28:31]
	v_mfma_f32_16x16x32_bf16 v[20:23], v[196:199], v[160:163], v[20:23]
	v_mfma_f32_16x16x32_bf16 v[12:15], v[208:211], v[160:163], v[12:15]
	v_mfma_f32_16x16x32_bf16 v[4:7], v[196:199], v[178:181], v[4:7]
	v_mfma_f32_16x16x32_bf16 v[0:3], v[208:211], v[178:181], v[0:3]
	v_mfma_f32_16x16x32_bf16 v[52:55], v[204:207], v[148:151], v[52:55]
	v_mfma_f32_16x16x32_bf16 v[44:47], v[214:217], v[148:151], v[44:47]
	v_mfma_f32_16x16x32_bf16 v[36:39], v[204:207], v[156:159], v[36:39]
	v_mfma_f32_16x16x32_bf16 v[28:31], v[214:217], v[156:159], v[28:31]
	v_mfma_f32_16x16x32_bf16 v[20:23], v[204:207], v[174:177], v[20:23]
	v_mfma_f32_16x16x32_bf16 v[12:15], v[214:217], v[174:177], v[12:15]
	v_mfma_f32_16x16x32_bf16 v[4:7], v[204:207], v[182:185], v[4:7]
	v_mfma_f32_16x16x32_bf16 v[0:3], v[214:217], v[182:185], v[0:3]
	s_add_i32 s41, s41, 2
	s_add_u32 s39, s39, 0x100
	s_addc_u32 s40, s40, 0
	s_cmpk_gt_u32 s41, 0x55
	s_mov_b64 s[8:9], s[10:11]
	s_barrier
.LBB0_272:
	s_add_u32 s10, s8, 0x100
	s_addc_u32 s11, s9, 0
	s_add_i32 s42, 0, 0x10000
	ds_read_b128 v[108:111], v220 offset:0
	ds_read_b128 v[112:115], v220 offset:1024
	ds_read_b128 v[116:119], v220 offset:2048
	ds_read_b128 v[120:123], v220 offset:3072
	s_cmpk_eq_i32 s41, 0x54
	s_cselect_b32 s15, s5, s11
	s_cselect_b32 s14, s4, s10
	s_cselect_b32 s13, s7, s40
	s_cselect_b32 s12, s6, s39
	s_add_i32 m0, s25, 0xc000
	ds_read_b128 v[144:147], v189
	ds_read_b128 v[148:151], v189 offset:1024
	ds_read_b128 v[152:155], v189 offset:2048
	ds_read_b128 v[156:159], v189 offset:3072
	ds_read_b128 v[160:163], v189 offset:4096
	ds_read_b128 v[174:177], v189 offset:5120
	ds_read_b128 v[178:181], v189 offset:6144
	ds_read_b128 v[182:185], v189 offset:7168
	global_load_lds_dwordx4 v170, s[8:9]
	s_add_i32 m0, s25, 0xe000
	s_nop 0
	global_load_lds_dwordx4 v172, s[8:9]
	s_waitcnt lgkmcnt(8)
	s_waitcnt lgkmcnt(0)
	s_barrier
	v_mfma_f32_16x16x32_bf16 v[140:143], v[108:111], v[144:147], v[140:143]
	v_mfma_f32_16x16x32_bf16 v[136:139], v[116:119], v[144:147], v[136:139]
	v_mfma_f32_16x16x32_bf16 v[132:135], v[108:111], v[152:155], v[132:135]
	v_mfma_f32_16x16x32_bf16 v[104:107], v[116:119], v[152:155], v[104:107]
	v_mfma_f32_16x16x32_bf16 v[96:99], v[108:111], v[160:163], v[96:99]
	v_mfma_f32_16x16x32_bf16 v[88:91], v[116:119], v[160:163], v[88:91]
	v_mfma_f32_16x16x32_bf16 v[80:83], v[108:111], v[178:181], v[80:83]
	v_mfma_f32_16x16x32_bf16 v[72:75], v[116:119], v[178:181], v[72:75]
	v_mfma_f32_16x16x32_bf16 v[140:143], v[112:115], v[148:151], v[140:143]
	v_mfma_f32_16x16x32_bf16 v[136:139], v[120:123], v[148:151], v[136:139]
	v_mfma_f32_16x16x32_bf16 v[132:135], v[112:115], v[156:159], v[132:135]
	v_mfma_f32_16x16x32_bf16 v[104:107], v[120:123], v[156:159], v[104:107]
	v_mfma_f32_16x16x32_bf16 v[96:99], v[112:115], v[174:177], v[96:99]
	v_mfma_f32_16x16x32_bf16 v[88:91], v[120:123], v[174:177], v[88:91]
	v_mfma_f32_16x16x32_bf16 v[80:83], v[112:115], v[182:185], v[80:83]
	v_mfma_f32_16x16x32_bf16 v[72:75], v[120:123], v[182:185], v[72:75]
	s_barrier
	s_add_i32 s43, 0, 0x14000
	s_add_i32 s8, s42, s19
	ds_read_b128 v[196:199], v220 offset:16384
	ds_read_b128 v[204:207], v220 offset:17408
	ds_read_b128 v[208:211], v220 offset:18432
	ds_read_b128 v[214:217], v220 offset:19456
	s_mov_b32 m0, s8
	s_nop 0
	global_load_lds_dwordx4 v192, s[12:13]
	s_add_i32 m0, s8, 0x2000
	s_nop 0
	global_load_lds_dwordx4 v168, s[12:13]
	s_waitcnt lgkmcnt(0)
	s_barrier
	v_mfma_f32_16x16x32_bf16 v[128:131], v[196:199], v[144:147], v[128:131]
	v_mfma_f32_16x16x32_bf16 v[124:127], v[208:211], v[144:147], v[124:127]
	v_mfma_f32_16x16x32_bf16 v[100:103], v[196:199], v[152:155], v[100:103]
	v_mfma_f32_16x16x32_bf16 v[92:95], v[208:211], v[152:155], v[92:95]
	v_mfma_f32_16x16x32_bf16 v[84:87], v[196:199], v[160:163], v[84:87]
	v_mfma_f32_16x16x32_bf16 v[76:79], v[208:211], v[160:163], v[76:79]
	v_mfma_f32_16x16x32_bf16 v[68:71], v[196:199], v[178:181], v[68:71]
	v_mfma_f32_16x16x32_bf16 v[64:67], v[208:211], v[178:181], v[64:67]
	v_mfma_f32_16x16x32_bf16 v[128:131], v[204:207], v[148:151], v[128:131]
	v_mfma_f32_16x16x32_bf16 v[124:127], v[214:217], v[148:151], v[124:127]
	v_mfma_f32_16x16x32_bf16 v[100:103], v[204:207], v[156:159], v[100:103]
	v_mfma_f32_16x16x32_bf16 v[92:95], v[214:217], v[156:159], v[92:95]
	v_mfma_f32_16x16x32_bf16 v[84:87], v[204:207], v[174:177], v[84:87]
	v_mfma_f32_16x16x32_bf16 v[76:79], v[214:217], v[174:177], v[76:79]
	v_mfma_f32_16x16x32_bf16 v[68:71], v[204:207], v[182:185], v[68:71]
	v_mfma_f32_16x16x32_bf16 v[64:67], v[214:217], v[182:185], v[64:67]
	s_mov_b32 m0, s25
	s_add_u32 s44, s14, 0x80
	s_addc_u32 s45, s15, 0
	s_barrier
	ds_read_b128 v[144:147], v189 offset:16384
	ds_read_b128 v[148:151], v189 offset:17408
	ds_read_b128 v[152:155], v189 offset:18432
	ds_read_b128 v[156:159], v189 offset:19456
	ds_read_b128 v[160:163], v189 offset:20480
	ds_read_b128 v[174:177], v189 offset:21504
	ds_read_b128 v[178:181], v189 offset:22528
	ds_read_b128 v[182:185], v189 offset:23552
	global_load_lds_dwordx4 v164, s[14:15]
	s_mov_b32 m0, s26
	s_nop 0
	global_load_lds_dwordx4 v166, s[14:15]
	s_waitcnt lgkmcnt(0)
	s_barrier
	v_mfma_f32_16x16x32_bf16 v[60:63], v[108:111], v[144:147], v[60:63]
	v_mfma_f32_16x16x32_bf16 v[56:59], v[116:119], v[144:147], v[56:59]
	v_mfma_f32_16x16x32_bf16 v[48:51], v[108:111], v[152:155], v[48:51]
	v_mfma_f32_16x16x32_bf16 v[40:43], v[116:119], v[152:155], v[40:43]
	v_mfma_f32_16x16x32_bf16 v[32:35], v[108:111], v[160:163], v[32:35]
	v_mfma_f32_16x16x32_bf16 v[24:27], v[116:119], v[160:163], v[24:27]
	v_mfma_f32_16x16x32_bf16 v[16:19], v[108:111], v[178:181], v[16:19]
	v_mfma_f32_16x16x32_bf16 v[8:11], v[116:119], v[178:181], v[8:11]
	v_mfma_f32_16x16x32_bf16 v[60:63], v[112:115], v[148:151], v[60:63]
	v_mfma_f32_16x16x32_bf16 v[56:59], v[120:123], v[148:151], v[56:59]
	v_mfma_f32_16x16x32_bf16 v[48:51], v[112:115], v[156:159], v[48:51]
	v_mfma_f32_16x16x32_bf16 v[40:43], v[120:123], v[156:159], v[40:43]
	v_mfma_f32_16x16x32_bf16 v[32:35], v[112:115], v[174:177], v[32:35]
	v_mfma_f32_16x16x32_bf16 v[24:27], v[120:123], v[174:177], v[24:27]
	v_mfma_f32_16x16x32_bf16 v[16:19], v[112:115], v[182:185], v[16:19]
	v_mfma_f32_16x16x32_bf16 v[8:11], v[120:123], v[182:185], v[8:11]
	s_barrier
	s_add_u32 s8, s12, 0x160000
	s_addc_u32 s9, s13, 0
	s_add_i32 s42, s43, s19
	s_mov_b32 m0, s42
	s_nop 0
	global_load_lds_dwordx4 v192, s[8:9]
	s_add_i32 m0, s42, 0x2000
	s_nop 0
	global_load_lds_dwordx4 v168, s[8:9]
	s_waitcnt vmcnt(6)
	s_barrier
	v_mfma_f32_16x16x32_bf16 v[52:55], v[196:199], v[144:147], v[52:55]
	v_mfma_f32_16x16x32_bf16 v[44:47], v[208:211], v[144:147], v[44:47]
	v_mfma_f32_16x16x32_bf16 v[36:39], v[196:199], v[152:155], v[36:39]
	v_mfma_f32_16x16x32_bf16 v[28:31], v[208:211], v[152:155], v[28:31]
	v_mfma_f32_16x16x32_bf16 v[20:23], v[196:199], v[160:163], v[20:23]
	v_mfma_f32_16x16x32_bf16 v[12:15], v[208:211], v[160:163], v[12:15]
	v_mfma_f32_16x16x32_bf16 v[4:7], v[196:199], v[178:181], v[4:7]
	v_mfma_f32_16x16x32_bf16 v[0:3], v[208:211], v[178:181], v[0:3]
	v_mfma_f32_16x16x32_bf16 v[52:55], v[204:207], v[148:151], v[52:55]
	v_mfma_f32_16x16x32_bf16 v[44:47], v[214:217], v[148:151], v[44:47]
	v_mfma_f32_16x16x32_bf16 v[36:39], v[204:207], v[156:159], v[36:39]
	v_mfma_f32_16x16x32_bf16 v[28:31], v[214:217], v[156:159], v[28:31]
	v_mfma_f32_16x16x32_bf16 v[20:23], v[204:207], v[174:177], v[20:23]
	v_mfma_f32_16x16x32_bf16 v[12:15], v[214:217], v[174:177], v[12:15]
	v_mfma_f32_16x16x32_bf16 v[4:7], v[204:207], v[182:185], v[4:7]
	v_mfma_f32_16x16x32_bf16 v[0:3], v[214:217], v[182:185], v[0:3]
	s_add_i32 s42, 0, 0x18000
	s_barrier
	ds_read_b128 v[108:111], v220 offset:32768
	ds_read_b128 v[112:115], v220 offset:33792
	ds_read_b128 v[116:119], v220 offset:34816
	ds_read_b128 v[120:123], v220 offset:35840
	s_add_u32 s8, s14, 0x160000
	s_addc_u32 s9, s15, 0
	s_mov_b32 m0, s27
	ds_read_b128 v[144:147], v189 offset:32768
	ds_read_b128 v[148:151], v189 offset:33792
	ds_read_b128 v[152:155], v189 offset:34816
	ds_read_b128 v[156:159], v189 offset:35840
	ds_read_b128 v[160:163], v189 offset:36864
	ds_read_b128 v[174:177], v189 offset:37888
	ds_read_b128 v[178:181], v189 offset:38912
	ds_read_b128 v[182:185], v189 offset:39936
	global_load_lds_dwordx4 v164, s[8:9]
	s_mov_b32 m0, s28
	s_nop 0
	global_load_lds_dwordx4 v166, s[8:9]
	s_waitcnt lgkmcnt(8)
	s_waitcnt lgkmcnt(0)
	s_barrier
	v_mfma_f32_16x16x32_bf16 v[140:143], v[108:111], v[144:147], v[140:143]
	v_mfma_f32_16x16x32_bf16 v[136:139], v[116:119], v[144:147], v[136:139]
	v_mfma_f32_16x16x32_bf16 v[132:135], v[108:111], v[152:155], v[132:135]
	v_mfma_f32_16x16x32_bf16 v[104:107], v[116:119], v[152:155], v[104:107]
	v_mfma_f32_16x16x32_bf16 v[96:99], v[108:111], v[160:163], v[96:99]
	v_mfma_f32_16x16x32_bf16 v[88:91], v[116:119], v[160:163], v[88:91]
	v_mfma_f32_16x16x32_bf16 v[80:83], v[108:111], v[178:181], v[80:83]
	v_mfma_f32_16x16x32_bf16 v[72:75], v[116:119], v[178:181], v[72:75]
	v_mfma_f32_16x16x32_bf16 v[140:143], v[112:115], v[148:151], v[140:143]
	v_mfma_f32_16x16x32_bf16 v[136:139], v[120:123], v[148:151], v[136:139]
	v_mfma_f32_16x16x32_bf16 v[132:135], v[112:115], v[156:159], v[132:135]
	v_mfma_f32_16x16x32_bf16 v[104:107], v[120:123], v[156:159], v[104:107]
	v_mfma_f32_16x16x32_bf16 v[96:99], v[112:115], v[174:177], v[96:99]
	v_mfma_f32_16x16x32_bf16 v[88:91], v[120:123], v[174:177], v[88:91]
	v_mfma_f32_16x16x32_bf16 v[80:83], v[112:115], v[182:185], v[80:83]
	v_mfma_f32_16x16x32_bf16 v[72:75], v[120:123], v[182:185], v[72:75]
	s_barrier
	s_add_i32 s14, 0, 0x1c000
	s_add_i32 s8, s42, s19
	s_add_i32 m0, s8, 0xffffff80
	ds_read_b128 v[196:199], v220 offset:49152
	ds_read_b128 v[204:207], v220 offset:50176
	ds_read_b128 v[208:211], v220 offset:51200
	ds_read_b128 v[214:217], v220 offset:52224
	global_load_lds_dwordx4 v192, s[12:13] offset:128
	s_add_i32 m0, s8, 0x1f80
	s_nop 0
	global_load_lds_dwordx4 v168, s[12:13] offset:128
	s_waitcnt lgkmcnt(0)
	s_barrier
	v_mfma_f32_16x16x32_bf16 v[128:131], v[196:199], v[144:147], v[128:131]
	v_mfma_f32_16x16x32_bf16 v[124:127], v[208:211], v[144:147], v[124:127]
	v_mfma_f32_16x16x32_bf16 v[100:103], v[196:199], v[152:155], v[100:103]
	v_mfma_f32_16x16x32_bf16 v[92:95], v[208:211], v[152:155], v[92:95]
	v_mfma_f32_16x16x32_bf16 v[84:87], v[196:199], v[160:163], v[84:87]
	v_mfma_f32_16x16x32_bf16 v[76:79], v[208:211], v[160:163], v[76:79]
	v_mfma_f32_16x16x32_bf16 v[68:71], v[196:199], v[178:181], v[68:71]
	v_mfma_f32_16x16x32_bf16 v[64:67], v[208:211], v[178:181], v[64:67]
	v_mfma_f32_16x16x32_bf16 v[128:131], v[204:207], v[148:151], v[128:131]
	v_mfma_f32_16x16x32_bf16 v[124:127], v[214:217], v[148:151], v[124:127]
	v_mfma_f32_16x16x32_bf16 v[100:103], v[204:207], v[156:159], v[100:103]
	v_mfma_f32_16x16x32_bf16 v[92:95], v[214:217], v[156:159], v[92:95]
	v_mfma_f32_16x16x32_bf16 v[84:87], v[204:207], v[174:177], v[84:87]
	v_mfma_f32_16x16x32_bf16 v[76:79], v[214:217], v[174:177], v[76:79]
	v_mfma_f32_16x16x32_bf16 v[68:71], v[204:207], v[182:185], v[68:71]
	v_mfma_f32_16x16x32_bf16 v[64:67], v[214:217], v[182:185], v[64:67]
	s_mov_b32 m0, s31
	s_barrier
	ds_read_b128 v[144:147], v189 offset:49152
	ds_read_b128 v[148:151], v189 offset:50176
	ds_read_b128 v[152:155], v189 offset:51200
	ds_read_b128 v[156:159], v189 offset:52224
	ds_read_b128 v[160:163], v189 offset:53248
	ds_read_b128 v[174:177], v189 offset:54272
	ds_read_b128 v[178:181], v189 offset:55296
	ds_read_b128 v[182:185], v189 offset:56320
	global_load_lds_dwordx4 v164, s[44:45]
	s_mov_b32 m0, s33
	s_nop 0
	global_load_lds_dwordx4 v166, s[44:45]
	s_waitcnt lgkmcnt(0)
	s_barrier
	v_mfma_f32_16x16x32_bf16 v[60:63], v[108:111], v[144:147], v[60:63]
	v_mfma_f32_16x16x32_bf16 v[56:59], v[116:119], v[144:147], v[56:59]
	v_mfma_f32_16x16x32_bf16 v[48:51], v[108:111], v[152:155], v[48:51]
	v_mfma_f32_16x16x32_bf16 v[40:43], v[116:119], v[152:155], v[40:43]
	v_mfma_f32_16x16x32_bf16 v[32:35], v[108:111], v[160:163], v[32:35]
	v_mfma_f32_16x16x32_bf16 v[24:27], v[116:119], v[160:163], v[24:27]
	v_mfma_f32_16x16x32_bf16 v[16:19], v[108:111], v[178:181], v[16:19]
	v_mfma_f32_16x16x32_bf16 v[8:11], v[116:119], v[178:181], v[8:11]
	v_mfma_f32_16x16x32_bf16 v[60:63], v[112:115], v[148:151], v[60:63]
	v_mfma_f32_16x16x32_bf16 v[56:59], v[120:123], v[148:151], v[56:59]
	v_mfma_f32_16x16x32_bf16 v[48:51], v[112:115], v[156:159], v[48:51]
	v_mfma_f32_16x16x32_bf16 v[40:43], v[120:123], v[156:159], v[40:43]
	v_mfma_f32_16x16x32_bf16 v[32:35], v[112:115], v[174:177], v[32:35]
	v_mfma_f32_16x16x32_bf16 v[24:27], v[120:123], v[174:177], v[24:27]
	v_mfma_f32_16x16x32_bf16 v[16:19], v[112:115], v[182:185], v[16:19]
	v_mfma_f32_16x16x32_bf16 v[8:11], v[120:123], v[182:185], v[8:11]
	s_barrier
	s_add_u32 s8, s12, 0x160080
	s_addc_u32 s9, s13, 0
	s_add_i32 s12, s14, s19
	s_mov_b32 m0, s12
	s_nop 0
	global_load_lds_dwordx4 v192, s[8:9]
	s_add_i32 m0, s12, 0x2000
	s_nop 0
	global_load_lds_dwordx4 v168, s[8:9]
	s_waitcnt vmcnt(6)
	s_barrier
	v_mfma_f32_16x16x32_bf16 v[52:55], v[196:199], v[144:147], v[52:55]
	v_mfma_f32_16x16x32_bf16 v[44:47], v[208:211], v[144:147], v[44:47]
	v_mfma_f32_16x16x32_bf16 v[36:39], v[196:199], v[152:155], v[36:39]
	v_mfma_f32_16x16x32_bf16 v[28:31], v[208:211], v[152:155], v[28:31]
	v_mfma_f32_16x16x32_bf16 v[20:23], v[196:199], v[160:163], v[20:23]
	v_mfma_f32_16x16x32_bf16 v[12:15], v[208:211], v[160:163], v[12:15]
	v_mfma_f32_16x16x32_bf16 v[4:7], v[196:199], v[178:181], v[4:7]
	v_mfma_f32_16x16x32_bf16 v[0:3], v[208:211], v[178:181], v[0:3]
	v_mfma_f32_16x16x32_bf16 v[52:55], v[204:207], v[148:151], v[52:55]
	v_mfma_f32_16x16x32_bf16 v[44:47], v[214:217], v[148:151], v[44:47]
	v_mfma_f32_16x16x32_bf16 v[36:39], v[204:207], v[156:159], v[36:39]
	v_mfma_f32_16x16x32_bf16 v[28:31], v[214:217], v[156:159], v[28:31]
	v_mfma_f32_16x16x32_bf16 v[20:23], v[204:207], v[174:177], v[20:23]
	v_mfma_f32_16x16x32_bf16 v[12:15], v[214:217], v[174:177], v[12:15]
	v_mfma_f32_16x16x32_bf16 v[4:7], v[204:207], v[182:185], v[4:7]
	v_mfma_f32_16x16x32_bf16 v[0:3], v[214:217], v[182:185], v[0:3]
	s_add_i32 s41, s41, 2
	s_add_u32 s39, s39, 0x100
	s_addc_u32 s40, s40, 0
	s_cmpk_gt_u32 s41, 0x55
	s_mov_b64 s[8:9], s[10:11]
	s_barrier
	s_cbranch_scc0 .LBB0_272
	s_ashr_i32 s8, s37, 4
	v_lshl_or_b32 v144, s38, 8, v188
	s_mul_hi_i32 s9, s8, 0xc000
	s_mul_i32 s8, s8, 0xc000
	v_lshl_add_u32 v178, s37, 8, v186
	s_add_u32 s8, s29, s8
	v_ashrrev_i32_e32 v145, 31, v144
	v_ashrrev_i32_e32 v179, 31, v178
	s_addc_u32 s9, s30, s9
	v_lshlrev_b64 v[174:175], 2, v[144:145]
	v_lshl_add_u64 v[176:177], v[144:145], 1, s[2:3]
	v_lshlrev_b64 v[144:145], 12, v[178:179]
	v_lshl_add_u64 v[112:113], s[8:9], 0, v[174:175]
	v_lshl_add_u64 v[144:145], v[176:177], 0, v[144:145]
	global_load_dwordx4 v[116:119], v[112:113], off offset:16
	global_load_dwordx4 v[120:123], v[112:113], off
	global_load_dwordx4 v[108:111], v[112:113], off offset:528
	s_nop 0
	global_load_dwordx4 v[112:115], v[112:113], off offset:512
	s_nop 0
	global_load_dwordx4 v[196:199], v[144:145], off
	global_load_dwordx4 v[204:207], v[144:145], off offset:256
	v_or_b32_e32 v184, 16, v178
	v_ashrrev_i32_e32 v185, 31, v184
	v_lshlrev_b64 v[144:145], 12, v[184:185]
	v_lshl_add_u64 v[144:145], v[176:177], 0, v[144:145]
	global_load_dwordx4 v[208:211], v[144:145], off
	global_load_dwordx4 v[160:163], v[144:145], off offset:256
	v_or_b32_e32 v182, 32, v178
	v_ashrrev_i32_e32 v183, 31, v182
	v_lshlrev_b64 v[144:145], 12, v[182:183]
	v_lshl_add_u64 v[144:145], v[176:177], 0, v[144:145]
	global_load_dwordx4 v[156:159], v[144:145], off
	global_load_dwordx4 v[152:155], v[144:145], off offset:256
	v_or_b32_e32 v180, 48, v178
	v_ashrrev_i32_e32 v181, 31, v180
	v_lshlrev_b64 v[144:145], 12, v[180:181]
	v_lshl_add_u64 v[144:145], v[176:177], 0, v[144:145]
	global_load_dwordx4 v[148:151], v[144:145], off
	s_nop 0
	global_load_dwordx4 v[144:147], v[144:145], off offset:256
	v_readlane_b32 s52, v254, 39
	v_readlane_b32 s66, v254, 53
	v_readlane_b32 s67, v254, 54
	s_and_b64 vcc, exec, s[0:1]
	s_mov_b32 s38, s35
	s_mov_b32 s37, s36
	s_mov_b64 s[10:11], s[6:7]
	s_mov_b64 s[8:9], s[4:5]
	v_readlane_b32 s14, v254, 21
	s_movk_i32 s15, 0x2000
	v_readlane_b32 s53, v254, 40
	v_readlane_b32 s54, v254, 41
	v_readlane_b32 s55, v254, 42
	v_readlane_b32 s56, v254, 43
	v_readlane_b32 s57, v254, 44
	v_readlane_b32 s58, v254, 45
	v_readlane_b32 s59, v254, 46
	v_readlane_b32 s60, v254, 47
	v_readlane_b32 s61, v254, 48
	v_readlane_b32 s62, v254, 49
	v_readlane_b32 s63, v254, 50
	v_readlane_b32 s64, v254, 51
	v_readlane_b32 s65, v254, 52
	s_waitcnt vmcnt(0)
	v_lshlrev_b32_e32 v190, 16, v196
	v_and_b32_e32 v191, 0xffff0000, v196
	v_pk_fma_f32 v[140:141], v[140:141], v[120:121], v[190:191]
	v_lshlrev_b64 v[190:191], 13, v[178:179]
	v_lshlrev_b32_e32 v196, 16, v197
	v_and_b32_e32 v197, 0xffff0000, v197
	v_lshl_add_u64 v[190:191], s[66:67], 0, v[190:191]
	v_pk_fma_f32 v[142:143], v[142:143], v[122:123], v[196:197]
	v_lshl_add_u64 v[190:191], v[190:191], 0, v[174:175]
	global_store_dwordx4 v[190:191], v[140:143], off
	v_lshlrev_b32_e32 v214, 16, v198
	v_and_b32_e32 v215, 0xffff0000, v198
	v_lshlrev_b32_e32 v140, 16, v206
	v_and_b32_e32 v141, 0xffff0000, v206
	v_lshlrev_b32_e32 v142, 16, v207
	v_and_b32_e32 v143, 0xffff0000, v207
	v_pk_fma_f32 v[126:127], v[126:127], v[110:111], v[142:143]
	v_pk_fma_f32 v[124:125], v[124:125], v[108:109], v[140:141]
	global_store_dwordx4 v[190:191], v[124:127], off offset:528
	v_lshlrev_b32_e32 v198, 16, v199
	v_and_b32_e32 v199, 0xffff0000, v199
	v_lshlrev_b32_e32 v124, 16, v208
	v_and_b32_e32 v125, 0xffff0000, v208
	v_pk_fma_f32 v[124:125], v[132:133], v[120:121], v[124:125]
	v_lshlrev_b64 v[132:133], 13, v[184:185]
	v_lshlrev_b32_e32 v126, 16, v209
	v_and_b32_e32 v127, 0xffff0000, v209
	v_lshl_add_u64 v[132:133], s[66:67], 0, v[132:133]
	v_pk_fma_f32 v[126:127], v[134:135], v[122:123], v[126:127]
	v_lshl_add_u64 v[132:133], v[132:133], 0, v[174:175]
	v_pk_fma_f32 v[138:139], v[138:139], v[118:119], v[198:199]
	v_pk_fma_f32 v[136:137], v[136:137], v[116:117], v[214:215]
	global_store_dwordx4 v[132:133], v[124:127], off
	global_store_dwordx4 v[190:191], v[136:139], off offset:16
	s_nop 0
	v_lshlrev_b32_e32 v124, 16, v162
	v_and_b32_e32 v125, 0xffff0000, v162
	v_lshlrev_b32_e32 v126, 16, v163
	v_and_b32_e32 v127, 0xffff0000, v163
	v_lshlrev_b32_e32 v136, 16, v204
	v_and_b32_e32 v137, 0xffff0000, v204
	v_lshlrev_b32_e32 v138, 16, v205
	v_and_b32_e32 v139, 0xffff0000, v205
	v_pk_fma_f32 v[94:95], v[94:95], v[110:111], v[126:127]
	v_pk_fma_f32 v[92:93], v[92:93], v[108:109], v[124:125]
	v_pk_fma_f32 v[130:131], v[130:131], v[114:115], v[138:139]
	v_pk_fma_f32 v[128:129], v[128:129], v[112:113], v[136:137]
	global_store_dwordx4 v[132:133], v[92:95], off offset:528
	global_store_dwordx4 v[190:191], v[128:131], off offset:512
	s_nop 0
	v_lshlrev_b32_e32 v92, 16, v156
	v_and_b32_e32 v93, 0xffff0000, v156
	v_lshlrev_b32_e32 v128, 16, v210
	v_and_b32_e32 v129, 0xffff0000, v210
	v_lshlrev_b32_e32 v130, 16, v211
	v_and_b32_e32 v131, 0xffff0000, v211
	v_pk_fma_f32 v[92:93], v[96:97], v[120:121], v[92:93]
	v_lshlrev_b64 v[96:97], 13, v[182:183]
	v_pk_fma_f32 v[106:107], v[106:107], v[118:119], v[130:131]
	v_pk_fma_f32 v[104:105], v[104:105], v[116:117], v[128:129]
	v_lshlrev_b32_e32 v94, 16, v157
	v_and_b32_e32 v95, 0xffff0000, v157
	v_lshl_add_u64 v[96:97], s[66:67], 0, v[96:97]
	global_store_dwordx4 v[132:133], v[104:107], off offset:16
	v_pk_fma_f32 v[94:95], v[98:99], v[122:123], v[94:95]
	v_lshl_add_u64 v[96:97], v[96:97], 0, v[174:175]
	v_lshlrev_b32_e32 v104, 16, v160
	v_and_b32_e32 v105, 0xffff0000, v160
	v_lshlrev_b32_e32 v106, 16, v161
	v_and_b32_e32 v107, 0xffff0000, v161
	v_pk_fma_f32 v[102:103], v[102:103], v[114:115], v[106:107]
	v_pk_fma_f32 v[100:101], v[100:101], v[112:113], v[104:105]
	global_store_dwordx4 v[96:97], v[92:95], off
	global_store_dwordx4 v[132:133], v[100:103], off offset:512
	v_add_u32_e32 v98, 0x90, v178
	v_lshlrev_b32_e32 v92, 16, v154
	v_and_b32_e32 v93, 0xffff0000, v154
	v_lshlrev_b32_e32 v94, 16, v155
	v_and_b32_e32 v95, 0xffff0000, v155
	v_lshlrev_b32_e32 v100, 16, v158
	v_and_b32_e32 v101, 0xffff0000, v158
	v_lshlrev_b32_e32 v102, 16, v159
	v_and_b32_e32 v103, 0xffff0000, v159
	v_pk_fma_f32 v[78:79], v[78:79], v[110:111], v[94:95]
	v_pk_fma_f32 v[76:77], v[76:77], v[108:109], v[92:93]
	v_pk_fma_f32 v[90:91], v[90:91], v[118:119], v[102:103]
	v_pk_fma_f32 v[88:89], v[88:89], v[116:117], v[100:101]
	global_store_dwordx4 v[96:97], v[76:79], off offset:528
	global_store_dwordx4 v[96:97], v[88:91], off offset:16
	v_ashrrev_i32_e32 v99, 31, v98
	v_lshlrev_b32_e32 v76, 16, v148
	v_and_b32_e32 v77, 0xffff0000, v148
	v_lshlrev_b32_e32 v88, 16, v152
	v_and_b32_e32 v89, 0xffff0000, v152
	v_lshlrev_b32_e32 v90, 16, v153
	v_and_b32_e32 v91, 0xffff0000, v153
	v_pk_fma_f32 v[76:77], v[80:81], v[120:121], v[76:77]
	v_lshlrev_b64 v[80:81], 13, v[180:181]
	v_pk_fma_f32 v[86:87], v[86:87], v[114:115], v[90:91]
	v_pk_fma_f32 v[84:85], v[84:85], v[112:113], v[88:89]
	v_lshlrev_b32_e32 v78, 16, v149
	v_and_b32_e32 v79, 0xffff0000, v149
	v_lshl_add_u64 v[80:81], s[66:67], 0, v[80:81]
	global_store_dwordx4 v[96:97], v[84:87], off offset:512
	v_pk_fma_f32 v[78:79], v[82:83], v[122:123], v[78:79]
	v_lshl_add_u64 v[80:81], v[80:81], 0, v[174:175]
	v_lshlrev_b32_e32 v84, 16, v150
	v_and_b32_e32 v85, 0xffff0000, v150
	v_lshlrev_b32_e32 v86, 16, v151
	v_and_b32_e32 v87, 0xffff0000, v151
	global_store_dwordx4 v[80:81], v[76:79], off
	v_pk_fma_f32 v[74:75], v[74:75], v[118:119], v[86:87]
	v_pk_fma_f32 v[72:73], v[72:73], v[116:117], v[84:85]
	v_lshlrev_b32_e32 v76, 16, v146
	v_and_b32_e32 v77, 0xffff0000, v146
	v_lshlrev_b32_e32 v78, 16, v147
	v_and_b32_e32 v79, 0xffff0000, v147
	v_add_u32_e32 v96, 0x80, v178
	global_store_dwordx4 v[80:81], v[72:75], off offset:16
	v_pk_fma_f32 v[66:67], v[66:67], v[110:111], v[78:79]
	v_pk_fma_f32 v[64:65], v[64:65], v[108:109], v[76:77]
	v_lshlrev_b32_e32 v72, 16, v144
	v_and_b32_e32 v73, 0xffff0000, v144
	v_lshlrev_b32_e32 v74, 16, v145
	v_and_b32_e32 v75, 0xffff0000, v145
	v_ashrrev_i32_e32 v97, 31, v96
	v_pk_fma_f32 v[70:71], v[70:71], v[114:115], v[74:75]
	v_pk_fma_f32 v[68:69], v[68:69], v[112:113], v[72:73]
	global_store_dwordx4 v[80:81], v[64:67], off offset:528
	global_store_dwordx4 v[80:81], v[68:71], off offset:512
	v_add_u32_e32 v100, 0xa0, v178
	v_lshlrev_b64 v[64:65], 12, v[96:97]
	v_lshl_add_u64 v[64:65], v[176:177], 0, v[64:65]
	global_load_dwordx4 v[68:71], v[64:65], off
	global_load_dwordx4 v[72:75], v[64:65], off offset:256
	v_lshlrev_b64 v[64:65], 12, v[98:99]
	v_lshl_add_u64 v[64:65], v[176:177], 0, v[64:65]
	global_load_dwordx4 v[76:79], v[64:65], off
	global_load_dwordx4 v[80:83], v[64:65], off offset:256
	v_ashrrev_i32_e32 v101, 31, v100
	v_lshlrev_b64 v[64:65], 12, v[100:101]
	v_lshl_add_u64 v[64:65], v[176:177], 0, v[64:65]
	global_load_dwordx4 v[84:87], v[64:65], off
	global_load_dwordx4 v[88:91], v[64:65], off offset:256
	v_add_u32_e32 v102, 0xb0, v178
	v_ashrrev_i32_e32 v103, 31, v102
	v_lshlrev_b64 v[64:65], 12, v[102:103]
	v_lshl_add_u64 v[64:65], v[176:177], 0, v[64:65]
	global_load_dwordx4 v[92:95], v[64:65], off
	s_nop 0
	global_load_dwordx4 v[64:67], v[64:65], off offset:256
	s_waitcnt vmcnt(0)
	v_lshlrev_b32_e32 v104, 16, v68
	v_and_b32_e32 v105, 0xffff0000, v68
	v_lshlrev_b32_e32 v68, 16, v69
	v_and_b32_e32 v69, 0xffff0000, v69
	v_pk_fma_f32 v[62:63], v[62:63], v[122:123], v[68:69]
	v_lshlrev_b64 v[68:69], 13, v[96:97]
	v_lshl_add_u64 v[68:69], s[66:67], 0, v[68:69]
	v_pk_fma_f32 v[60:61], v[60:61], v[120:121], v[104:105]
	v_lshl_add_u64 v[68:69], v[68:69], 0, v[174:175]
	global_store_dwordx4 v[68:69], v[60:63], off
	v_lshlrev_b32_e32 v106, 16, v70
	v_and_b32_e32 v107, 0xffff0000, v70
	v_lshlrev_b32_e32 v60, 16, v74
	v_and_b32_e32 v61, 0xffff0000, v74
	v_lshlrev_b32_e32 v62, 16, v75
	v_and_b32_e32 v63, 0xffff0000, v75
	v_pk_fma_f32 v[46:47], v[46:47], v[110:111], v[62:63]
	v_pk_fma_f32 v[44:45], v[44:45], v[108:109], v[60:61]
	global_store_dwordx4 v[68:69], v[44:47], off offset:528
	v_lshlrev_b32_e32 v70, 16, v71
	v_and_b32_e32 v71, 0xffff0000, v71
	v_lshlrev_b32_e32 v44, 16, v76
	v_and_b32_e32 v45, 0xffff0000, v76
	v_pk_fma_f32 v[44:45], v[48:49], v[120:121], v[44:45]
	v_lshlrev_b64 v[48:49], 13, v[98:99]
	v_lshlrev_b32_e32 v46, 16, v77
	v_and_b32_e32 v47, 0xffff0000, v77
	v_lshl_add_u64 v[48:49], s[66:67], 0, v[48:49]
	v_pk_fma_f32 v[58:59], v[58:59], v[118:119], v[70:71]
	v_pk_fma_f32 v[56:57], v[56:57], v[116:117], v[106:107]
	v_pk_fma_f32 v[46:47], v[50:51], v[122:123], v[46:47]
	v_lshl_add_u64 v[48:49], v[48:49], 0, v[174:175]
	global_store_dwordx4 v[68:69], v[56:59], off offset:16
	global_store_dwordx4 v[48:49], v[44:47], off
	s_nop 0
	v_lshlrev_b32_e32 v56, 16, v72
	v_and_b32_e32 v57, 0xffff0000, v72
	v_lshlrev_b32_e32 v58, 16, v73
	v_and_b32_e32 v59, 0xffff0000, v73
	v_lshlrev_b32_e32 v44, 16, v82
	v_and_b32_e32 v45, 0xffff0000, v82
	v_lshlrev_b32_e32 v46, 16, v83
	v_and_b32_e32 v47, 0xffff0000, v83
	v_pk_fma_f32 v[54:55], v[54:55], v[114:115], v[58:59]
	v_pk_fma_f32 v[52:53], v[52:53], v[112:113], v[56:57]
	v_pk_fma_f32 v[30:31], v[30:31], v[110:111], v[46:47]
	v_pk_fma_f32 v[28:29], v[28:29], v[108:109], v[44:45]
	global_store_dwordx4 v[68:69], v[52:55], off offset:512
	global_store_dwordx4 v[48:49], v[28:31], off offset:528
	s_nop 0
	v_lshlrev_b32_e32 v52, 16, v78
	v_and_b32_e32 v53, 0xffff0000, v78
	v_lshlrev_b32_e32 v54, 16, v79
	v_and_b32_e32 v55, 0xffff0000, v79
	v_lshlrev_b32_e32 v28, 16, v84
	v_and_b32_e32 v29, 0xffff0000, v84
	v_pk_fma_f32 v[42:43], v[42:43], v[118:119], v[54:55]
	v_pk_fma_f32 v[40:41], v[40:41], v[116:117], v[52:53]
	v_pk_fma_f32 v[28:29], v[32:33], v[120:121], v[28:29]
	v_lshlrev_b64 v[32:33], 13, v[100:101]
	global_store_dwordx4 v[48:49], v[40:43], off offset:16
	v_lshlrev_b32_e32 v30, 16, v85
	v_and_b32_e32 v31, 0xffff0000, v85
	v_lshlrev_b32_e32 v40, 16, v80
	v_and_b32_e32 v41, 0xffff0000, v80
	v_lshlrev_b32_e32 v42, 16, v81
	v_and_b32_e32 v43, 0xffff0000, v81
	v_lshl_add_u64 v[32:33], s[66:67], 0, v[32:33]
	v_pk_fma_f32 v[38:39], v[38:39], v[114:115], v[42:43]
	v_pk_fma_f32 v[36:37], v[36:37], v[112:113], v[40:41]
	v_pk_fma_f32 v[30:31], v[34:35], v[122:123], v[30:31]
	v_lshl_add_u64 v[32:33], v[32:33], 0, v[174:175]
	global_store_dwordx4 v[48:49], v[36:39], off offset:512
	global_store_dwordx4 v[32:33], v[28:31], off
	s_nop 0
	v_lshlrev_b32_e32 v36, 16, v86
	v_and_b32_e32 v37, 0xffff0000, v86
	v_lshlrev_b32_e32 v38, 16, v87
	v_and_b32_e32 v39, 0xffff0000, v87
	v_lshlrev_b32_e32 v28, 16, v90
	v_and_b32_e32 v29, 0xffff0000, v90
	v_lshlrev_b32_e32 v30, 16, v91
	v_and_b32_e32 v31, 0xffff0000, v91
	v_pk_fma_f32 v[26:27], v[26:27], v[118:119], v[38:39]
	v_pk_fma_f32 v[24:25], v[24:25], v[116:117], v[36:37]
	v_pk_fma_f32 v[14:15], v[14:15], v[110:111], v[30:31]
	v_pk_fma_f32 v[12:13], v[12:13], v[108:109], v[28:29]
	global_store_dwordx4 v[32:33], v[24:27], off offset:16
	global_store_dwordx4 v[32:33], v[12:15], off offset:528
	s_nop 0
	v_lshlrev_b32_e32 v24, 16, v88
	v_and_b32_e32 v25, 0xffff0000, v88
	v_lshlrev_b32_e32 v26, 16, v89
	v_and_b32_e32 v27, 0xffff0000, v89
	v_lshlrev_b32_e32 v12, 16, v92
	v_and_b32_e32 v13, 0xffff0000, v92
	v_pk_fma_f32 v[22:23], v[22:23], v[114:115], v[26:27]
	v_pk_fma_f32 v[20:21], v[20:21], v[112:113], v[24:25]
	v_pk_fma_f32 v[12:13], v[16:17], v[120:121], v[12:13]
	v_lshlrev_b64 v[16:17], 13, v[102:103]
	global_store_dwordx4 v[32:33], v[20:23], off offset:512
	v_lshlrev_b32_e32 v14, 16, v93
	v_and_b32_e32 v15, 0xffff0000, v93
	v_lshlrev_b32_e32 v20, 16, v94
	v_and_b32_e32 v21, 0xffff0000, v94
	v_lshlrev_b32_e32 v22, 16, v95
	v_and_b32_e32 v23, 0xffff0000, v95
	v_lshl_add_u64 v[16:17], s[66:67], 0, v[16:17]
	v_pk_fma_f32 v[14:15], v[18:19], v[122:123], v[14:15]
	v_lshl_add_u64 v[16:17], v[16:17], 0, v[174:175]
	v_pk_fma_f32 v[10:11], v[10:11], v[118:119], v[22:23]
	v_pk_fma_f32 v[8:9], v[8:9], v[116:117], v[20:21]
	global_store_dwordx4 v[16:17], v[12:15], off
	global_store_dwordx4 v[16:17], v[8:11], off offset:16
	s_nop 0
	v_lshlrev_b32_e32 v12, 16, v66
	v_lshlrev_b32_e32 v8, 16, v64
	v_and_b32_e32 v9, 0xffff0000, v64
	v_lshlrev_b32_e32 v10, 16, v65
	v_and_b32_e32 v11, 0xffff0000, v65
	v_and_b32_e32 v13, 0xffff0000, v66
	v_lshlrev_b32_e32 v14, 16, v67
	v_and_b32_e32 v15, 0xffff0000, v67
	v_pk_fma_f32 v[6:7], v[6:7], v[114:115], v[10:11]
	v_pk_fma_f32 v[4:5], v[4:5], v[112:113], v[8:9]
	v_pk_fma_f32 v[2:3], v[2:3], v[110:111], v[14:15]
	v_pk_fma_f32 v[0:1], v[0:1], v[108:109], v[12:13]
	global_store_dwordx4 v[16:17], v[4:7], off offset:512
	global_store_dwordx4 v[16:17], v[0:3], off offset:528
	s_cbranch_vccz .LBB0_261
	s_waitcnt vmcnt(0)
	s_cmpk_gt_u32 s16, 0xff
	s_cbranch_scc1 .LBB0_276
	s_barrier

.LBB0_293:
	v_mov_b64_e32 v[0:1], 0x400
	s_ashr_i32 s7, s6, 31
	v_cmp_lt_i64_e32 vcc, s[8:9], v[0:1]
	s_lshl_b64 s[8:9], s[6:7], 20
	s_add_u32 s8, s20, s8
	s_addc_u32 s9, s21, s9
	s_and_b64 s[10:11], vcc, exec
	s_cselect_b32 s7, s9, s15
	s_cselect_b32 s38, s8, s14
	s_ashr_i32 s5, s4, 31
	s_lshl_b64 s[10:11], s[4:5], 20
	s_add_u32 s10, s22, s10
	s_addc_u32 s11, s23, s11
	s_and_b64 s[18:19], vcc, exec
	s_cselect_b32 s5, s11, s17
	s_cselect_b32 s39, s10, s16
	s_add_u32 s14, s14, 0x80080
	s_addc_u32 s15, s15, 0
	s_add_u32 s40, s16, 0x100
	s_addc_u32 s41, s17, 0
	s_mov_b32 s42, -2
	s_mov_b64 s[48:49], 0x80
	v_add_u32_e32 v220, 0x10000, v159
	s_add_u32 s16, s14, 0xfff80080
	s_addc_u32 s17, s15, -1
	s_add_i32 s43, 0, 0x10000
	ds_read_b128 v[64:67], v220 offset:0
	ds_read_b128 v[68:71], v220 offset:1024
	ds_read_b128 v[72:75], v220 offset:2048
	ds_read_b128 v[76:79], v220 offset:3072
	s_cmp_eq_u32 s42, 28
	s_cselect_b32 s19, s7, s17
	s_cselect_b32 s18, s38, s16
	s_cselect_b32 s17, s5, s41
	s_cselect_b32 s16, s39, s40
	s_add_i32 m0, s13, 0xc000
	ds_read_b128 v[154:157], v161
	ds_read_b128 v[162:165], v161 offset:1024
	ds_read_b128 v[166:169], v161 offset:2048
	ds_read_b128 v[170:173], v161 offset:3072
	ds_read_b128 v[174:177], v161 offset:4096
	ds_read_b128 v[178:181], v161 offset:5120
	ds_read_b128 v[182:185], v161 offset:6144
	ds_read_b128 v[186:189], v161 offset:7168
	global_load_lds_dwordx4 v150, s[14:15]
	s_add_i32 m0, s13, 0xe000
	s_nop 0
	global_load_lds_dwordx4 v152, s[14:15]
	s_waitcnt lgkmcnt(8)
	s_waitcnt lgkmcnt(0)
	s_barrier
	v_mfma_f32_16x16x32_bf16 v[140:143], v[64:67], v[154:157], 0
	v_mfma_f32_16x16x32_bf16 v[136:139], v[72:75], v[154:157], 0
	v_mfma_f32_16x16x32_bf16 v[132:135], v[64:67], v[166:169], 0
	v_mfma_f32_16x16x32_bf16 v[128:131], v[72:75], v[166:169], 0
	v_mfma_f32_16x16x32_bf16 v[108:111], v[64:67], v[174:177], 0
	v_mfma_f32_16x16x32_bf16 v[104:107], v[72:75], v[174:177], 0
	v_mfma_f32_16x16x32_bf16 v[100:103], v[64:67], v[182:185], 0
	v_mfma_f32_16x16x32_bf16 v[96:99], v[72:75], v[182:185], 0
	v_mfma_f32_16x16x32_bf16 v[140:143], v[68:71], v[162:165], v[140:143]
	v_mfma_f32_16x16x32_bf16 v[136:139], v[76:79], v[162:165], v[136:139]
	v_mfma_f32_16x16x32_bf16 v[132:135], v[68:71], v[170:173], v[132:135]
	v_mfma_f32_16x16x32_bf16 v[128:131], v[76:79], v[170:173], v[128:131]
	v_mfma_f32_16x16x32_bf16 v[108:111], v[68:71], v[178:181], v[108:111]
	v_mfma_f32_16x16x32_bf16 v[104:107], v[76:79], v[178:181], v[104:107]
	v_mfma_f32_16x16x32_bf16 v[100:103], v[68:71], v[186:189], v[100:103]
	v_mfma_f32_16x16x32_bf16 v[96:99], v[76:79], v[186:189], v[96:99]
	s_barrier
	s_add_i32 s46, 0, 0x14000
	s_add_i32 s43, s43, s27
	ds_read_b128 v[196:199], v220 offset:16384
	ds_read_b128 v[204:207], v220 offset:17408
	ds_read_b128 v[208:211], v220 offset:18432
	ds_read_b128 v[214:217], v220 offset:19456
	s_mov_b32 m0, s43
	s_nop 0
	global_load_lds_dwordx4 v192, s[16:17]
	s_add_i32 m0, s43, 0x2000
	s_nop 0
	global_load_lds_dwordx4 v148, s[16:17]
	s_waitcnt lgkmcnt(0)
	s_barrier
	v_mfma_f32_16x16x32_bf16 v[124:127], v[196:199], v[154:157], 0
	v_mfma_f32_16x16x32_bf16 v[120:123], v[208:211], v[154:157], 0
	v_mfma_f32_16x16x32_bf16 v[116:119], v[196:199], v[166:169], 0
	v_mfma_f32_16x16x32_bf16 v[112:115], v[208:211], v[166:169], 0
	v_mfma_f32_16x16x32_bf16 v[92:95], v[196:199], v[174:177], 0
	v_mfma_f32_16x16x32_bf16 v[88:91], v[208:211], v[174:177], 0
	v_mfma_f32_16x16x32_bf16 v[84:87], v[196:199], v[182:185], 0
	v_mfma_f32_16x16x32_bf16 v[80:83], v[208:211], v[182:185], 0
	v_mfma_f32_16x16x32_bf16 v[124:127], v[204:207], v[162:165], v[124:127]
	v_mfma_f32_16x16x32_bf16 v[120:123], v[214:217], v[162:165], v[120:123]
	v_mfma_f32_16x16x32_bf16 v[116:119], v[204:207], v[170:173], v[116:119]
	v_mfma_f32_16x16x32_bf16 v[112:115], v[214:217], v[170:173], v[112:115]
	v_mfma_f32_16x16x32_bf16 v[92:95], v[204:207], v[178:181], v[92:95]
	v_mfma_f32_16x16x32_bf16 v[88:91], v[214:217], v[178:181], v[88:91]
	v_mfma_f32_16x16x32_bf16 v[84:87], v[204:207], v[186:189], v[84:87]
	v_mfma_f32_16x16x32_bf16 v[80:83], v[214:217], v[186:189], v[80:83]
	s_mov_b32 m0, s13
	s_add_u32 s48, s18, 0x80
	s_addc_u32 s49, s19, 0
	s_barrier
	ds_read_b128 v[154:157], v161 offset:16384
	ds_read_b128 v[162:165], v161 offset:17408
	ds_read_b128 v[166:169], v161 offset:18432
	ds_read_b128 v[170:173], v161 offset:19456
	ds_read_b128 v[174:177], v161 offset:20480
	ds_read_b128 v[178:181], v161 offset:21504
	ds_read_b128 v[182:185], v161 offset:22528
	ds_read_b128 v[186:189], v161 offset:23552
	global_load_lds_dwordx4 v144, s[18:19]
	s_mov_b32 m0, s28
	s_nop 0
	global_load_lds_dwordx4 v146, s[18:19]
	s_waitcnt lgkmcnt(0)
	s_barrier
	v_mfma_f32_16x16x32_bf16 v[60:63], v[64:67], v[154:157], 0
	v_mfma_f32_16x16x32_bf16 v[56:59], v[72:75], v[154:157], 0
	v_mfma_f32_16x16x32_bf16 v[52:55], v[64:67], v[166:169], 0
	v_mfma_f32_16x16x32_bf16 v[48:51], v[72:75], v[166:169], 0
	v_mfma_f32_16x16x32_bf16 v[28:31], v[64:67], v[174:177], 0
	v_mfma_f32_16x16x32_bf16 v[24:27], v[72:75], v[174:177], 0
	v_mfma_f32_16x16x32_bf16 v[20:23], v[64:67], v[182:185], 0
	v_mfma_f32_16x16x32_bf16 v[16:19], v[72:75], v[182:185], 0
	v_mfma_f32_16x16x32_bf16 v[60:63], v[68:71], v[162:165], v[60:63]
	v_mfma_f32_16x16x32_bf16 v[56:59], v[76:79], v[162:165], v[56:59]
	v_mfma_f32_16x16x32_bf16 v[52:55], v[68:71], v[170:173], v[52:55]
	v_mfma_f32_16x16x32_bf16 v[48:51], v[76:79], v[170:173], v[48:51]
	v_mfma_f32_16x16x32_bf16 v[28:31], v[68:71], v[178:181], v[28:31]
	v_mfma_f32_16x16x32_bf16 v[24:27], v[76:79], v[178:181], v[24:27]
	v_mfma_f32_16x16x32_bf16 v[20:23], v[68:71], v[186:189], v[20:23]
	v_mfma_f32_16x16x32_bf16 v[16:19], v[76:79], v[186:189], v[16:19]
	s_barrier
	s_add_u32 s44, s16, 0x80000
	s_addc_u32 s45, s17, 0
	s_add_i32 s43, s46, s27
	s_mov_b32 m0, s43
	s_nop 0
	global_load_lds_dwordx4 v192, s[44:45]
	s_add_i32 m0, s43, 0x2000
	s_nop 0
	global_load_lds_dwordx4 v148, s[44:45]
	s_waitcnt vmcnt(6)
	s_barrier
	v_mfma_f32_16x16x32_bf16 v[44:47], v[196:199], v[154:157], 0
	v_mfma_f32_16x16x32_bf16 v[40:43], v[208:211], v[154:157], 0
	v_mfma_f32_16x16x32_bf16 v[36:39], v[196:199], v[166:169], 0
	v_mfma_f32_16x16x32_bf16 v[32:35], v[208:211], v[166:169], 0
	v_mfma_f32_16x16x32_bf16 v[12:15], v[196:199], v[174:177], 0
	v_mfma_f32_16x16x32_bf16 v[8:11], v[208:211], v[174:177], 0
	v_mfma_f32_16x16x32_bf16 v[4:7], v[196:199], v[182:185], 0
	v_mfma_f32_16x16x32_bf16 v[0:3], v[208:211], v[182:185], 0
	v_mfma_f32_16x16x32_bf16 v[44:47], v[204:207], v[162:165], v[44:47]
	v_mfma_f32_16x16x32_bf16 v[40:43], v[214:217], v[162:165], v[40:43]
	v_mfma_f32_16x16x32_bf16 v[36:39], v[204:207], v[170:173], v[36:39]
	v_mfma_f32_16x16x32_bf16 v[32:35], v[214:217], v[170:173], v[32:35]
	v_mfma_f32_16x16x32_bf16 v[12:15], v[204:207], v[178:181], v[12:15]
	v_mfma_f32_16x16x32_bf16 v[8:11], v[214:217], v[178:181], v[8:11]
	v_mfma_f32_16x16x32_bf16 v[4:7], v[204:207], v[186:189], v[4:7]
	v_mfma_f32_16x16x32_bf16 v[0:3], v[214:217], v[186:189], v[0:3]
	s_add_i32 s43, 0, 0x18000
	s_barrier
	ds_read_b128 v[64:67], v220 offset:32768
	ds_read_b128 v[68:71], v220 offset:33792
	ds_read_b128 v[72:75], v220 offset:34816
	ds_read_b128 v[76:79], v220 offset:35840
	s_add_u32 s18, s18, 0x80000
	s_addc_u32 s19, s19, 0
	s_mov_b32 m0, s29
	ds_read_b128 v[154:157], v161 offset:32768
	ds_read_b128 v[162:165], v161 offset:33792
	ds_read_b128 v[166:169], v161 offset:34816
	ds_read_b128 v[170:173], v161 offset:35840
	ds_read_b128 v[174:177], v161 offset:36864
	ds_read_b128 v[178:181], v161 offset:37888
	ds_read_b128 v[182:185], v161 offset:38912
	ds_read_b128 v[186:189], v161 offset:39936
	global_load_lds_dwordx4 v144, s[18:19]
	s_mov_b32 m0, s30
	s_nop 0
	global_load_lds_dwordx4 v146, s[18:19]
	s_waitcnt lgkmcnt(8)
	s_waitcnt lgkmcnt(0)
	s_barrier
	v_mfma_f32_16x16x32_bf16 v[140:143], v[64:67], v[154:157], v[140:143]
	v_mfma_f32_16x16x32_bf16 v[136:139], v[72:75], v[154:157], v[136:139]
	v_mfma_f32_16x16x32_bf16 v[132:135], v[64:67], v[166:169], v[132:135]
	v_mfma_f32_16x16x32_bf16 v[128:131], v[72:75], v[166:169], v[128:131]
	v_mfma_f32_16x16x32_bf16 v[108:111], v[64:67], v[174:177], v[108:111]
	v_mfma_f32_16x16x32_bf16 v[104:107], v[72:75], v[174:177], v[104:107]
	v_mfma_f32_16x16x32_bf16 v[100:103], v[64:67], v[182:185], v[100:103]
	v_mfma_f32_16x16x32_bf16 v[96:99], v[72:75], v[182:185], v[96:99]
	v_mfma_f32_16x16x32_bf16 v[140:143], v[68:71], v[162:165], v[140:143]
	v_mfma_f32_16x16x32_bf16 v[136:139], v[76:79], v[162:165], v[136:139]
	v_mfma_f32_16x16x32_bf16 v[132:135], v[68:71], v[170:173], v[132:135]
	v_mfma_f32_16x16x32_bf16 v[128:131], v[76:79], v[170:173], v[128:131]
	v_mfma_f32_16x16x32_bf16 v[108:111], v[68:71], v[178:181], v[108:111]
	v_mfma_f32_16x16x32_bf16 v[104:107], v[76:79], v[178:181], v[104:107]
	v_mfma_f32_16x16x32_bf16 v[100:103], v[68:71], v[186:189], v[100:103]
	v_mfma_f32_16x16x32_bf16 v[96:99], v[76:79], v[186:189], v[96:99]
	s_barrier
	s_add_i32 s18, 0, 0x1c000
	s_add_i32 s19, s43, s27
	s_add_i32 m0, s19, 0xffffff80
	ds_read_b128 v[196:199], v220 offset:49152
	ds_read_b128 v[204:207], v220 offset:50176
	ds_read_b128 v[208:211], v220 offset:51200
	ds_read_b128 v[214:217], v220 offset:52224
	global_load_lds_dwordx4 v192, s[16:17] offset:128
	s_add_i32 m0, s19, 0x1f80
	s_nop 0
	global_load_lds_dwordx4 v148, s[16:17] offset:128
	s_waitcnt lgkmcnt(0)
	s_barrier
	v_mfma_f32_16x16x32_bf16 v[124:127], v[196:199], v[154:157], v[124:127]
	v_mfma_f32_16x16x32_bf16 v[120:123], v[208:211], v[154:157], v[120:123]
	v_mfma_f32_16x16x32_bf16 v[116:119], v[196:199], v[166:169], v[116:119]
	v_mfma_f32_16x16x32_bf16 v[112:115], v[208:211], v[166:169], v[112:115]
	v_mfma_f32_16x16x32_bf16 v[92:95], v[196:199], v[174:177], v[92:95]
	v_mfma_f32_16x16x32_bf16 v[88:91], v[208:211], v[174:177], v[88:91]
	v_mfma_f32_16x16x32_bf16 v[84:87], v[196:199], v[182:185], v[84:87]
	v_mfma_f32_16x16x32_bf16 v[80:83], v[208:211], v[182:185], v[80:83]
	v_mfma_f32_16x16x32_bf16 v[124:127], v[204:207], v[162:165], v[124:127]
	v_mfma_f32_16x16x32_bf16 v[120:123], v[214:217], v[162:165], v[120:123]
	v_mfma_f32_16x16x32_bf16 v[116:119], v[204:207], v[170:173], v[116:119]
	v_mfma_f32_16x16x32_bf16 v[112:115], v[214:217], v[170:173], v[112:115]
	v_mfma_f32_16x16x32_bf16 v[92:95], v[204:207], v[178:181], v[92:95]
	v_mfma_f32_16x16x32_bf16 v[88:91], v[214:217], v[178:181], v[88:91]
	v_mfma_f32_16x16x32_bf16 v[84:87], v[204:207], v[186:189], v[84:87]
	v_mfma_f32_16x16x32_bf16 v[80:83], v[214:217], v[186:189], v[80:83]
	s_mov_b32 m0, s34
	s_barrier
	ds_read_b128 v[154:157], v161 offset:49152
	ds_read_b128 v[162:165], v161 offset:50176
	ds_read_b128 v[166:169], v161 offset:51200
	ds_read_b128 v[170:173], v161 offset:52224
	ds_read_b128 v[174:177], v161 offset:53248
	ds_read_b128 v[178:181], v161 offset:54272
	ds_read_b128 v[182:185], v161 offset:55296
	ds_read_b128 v[186:189], v161 offset:56320
	global_load_lds_dwordx4 v144, s[48:49]
	s_mov_b32 m0, s35
	s_nop 0
	global_load_lds_dwordx4 v146, s[48:49]
	s_waitcnt lgkmcnt(0)
	s_barrier
	v_mfma_f32_16x16x32_bf16 v[60:63], v[64:67], v[154:157], v[60:63]
	v_mfma_f32_16x16x32_bf16 v[56:59], v[72:75], v[154:157], v[56:59]
	v_mfma_f32_16x16x32_bf16 v[52:55], v[64:67], v[166:169], v[52:55]
	v_mfma_f32_16x16x32_bf16 v[48:51], v[72:75], v[166:169], v[48:51]
	v_mfma_f32_16x16x32_bf16 v[28:31], v[64:67], v[174:177], v[28:31]
	v_mfma_f32_16x16x32_bf16 v[24:27], v[72:75], v[174:177], v[24:27]
	v_mfma_f32_16x16x32_bf16 v[20:23], v[64:67], v[182:185], v[20:23]
	v_mfma_f32_16x16x32_bf16 v[16:19], v[72:75], v[182:185], v[16:19]
	v_mfma_f32_16x16x32_bf16 v[60:63], v[68:71], v[162:165], v[60:63]
	v_mfma_f32_16x16x32_bf16 v[56:59], v[76:79], v[162:165], v[56:59]
	v_mfma_f32_16x16x32_bf16 v[52:55], v[68:71], v[170:173], v[52:55]
	v_mfma_f32_16x16x32_bf16 v[48:51], v[76:79], v[170:173], v[48:51]
	v_mfma_f32_16x16x32_bf16 v[28:31], v[68:71], v[178:181], v[28:31]
	v_mfma_f32_16x16x32_bf16 v[24:27], v[76:79], v[178:181], v[24:27]
	v_mfma_f32_16x16x32_bf16 v[20:23], v[68:71], v[186:189], v[20:23]
	v_mfma_f32_16x16x32_bf16 v[16:19], v[76:79], v[186:189], v[16:19]
	s_barrier
	s_add_u32 s16, s16, 0x80080
	s_addc_u32 s17, s17, 0
	s_add_i32 s18, s18, s27
	s_mov_b32 m0, s18
	s_nop 0
	global_load_lds_dwordx4 v192, s[16:17]
	s_add_i32 m0, s18, 0x2000
	s_nop 0
	global_load_lds_dwordx4 v148, s[16:17]
	s_waitcnt vmcnt(6)
	s_barrier
	v_mfma_f32_16x16x32_bf16 v[44:47], v[196:199], v[154:157], v[44:47]
	v_mfma_f32_16x16x32_bf16 v[40:43], v[208:211], v[154:157], v[40:43]
	v_mfma_f32_16x16x32_bf16 v[36:39], v[196:199], v[166:169], v[36:39]
	v_mfma_f32_16x16x32_bf16 v[32:35], v[208:211], v[166:169], v[32:35]
	v_mfma_f32_16x16x32_bf16 v[12:15], v[196:199], v[174:177], v[12:15]
	v_mfma_f32_16x16x32_bf16 v[8:11], v[208:211], v[174:177], v[8:11]
	v_mfma_f32_16x16x32_bf16 v[4:7], v[196:199], v[182:185], v[4:7]
	v_mfma_f32_16x16x32_bf16 v[0:3], v[208:211], v[182:185], v[0:3]
	v_mfma_f32_16x16x32_bf16 v[44:47], v[204:207], v[162:165], v[44:47]
	v_mfma_f32_16x16x32_bf16 v[40:43], v[214:217], v[162:165], v[40:43]
	v_mfma_f32_16x16x32_bf16 v[36:39], v[204:207], v[170:173], v[36:39]
	v_mfma_f32_16x16x32_bf16 v[32:35], v[214:217], v[170:173], v[32:35]
	v_mfma_f32_16x16x32_bf16 v[12:15], v[204:207], v[178:181], v[12:15]
	v_mfma_f32_16x16x32_bf16 v[8:11], v[214:217], v[178:181], v[8:11]
	v_mfma_f32_16x16x32_bf16 v[4:7], v[204:207], v[186:189], v[4:7]
	v_mfma_f32_16x16x32_bf16 v[0:3], v[214:217], v[186:189], v[0:3]
	s_add_i32 s42, s42, 2
	s_add_u32 s14, s14, 0x100
	s_addc_u32 s15, s15, 0
	s_add_u32 s40, s40, 0x100
	s_addc_u32 s41, s41, 0
	s_cmp_gt_u32 s42, 29
	s_barrier
.LBB0_294:
	s_add_u32 s16, s14, 0xfff80080
	s_addc_u32 s17, s15, -1
	s_add_i32 s43, 0, 0x10000
	ds_read_b128 v[64:67], v220 offset:0
	ds_read_b128 v[68:71], v220 offset:1024
	ds_read_b128 v[72:75], v220 offset:2048
	ds_read_b128 v[76:79], v220 offset:3072
	s_cmp_eq_u32 s42, 28
	s_cselect_b32 s19, s7, s17
	s_cselect_b32 s18, s38, s16
	s_cselect_b32 s17, s5, s41
	s_cselect_b32 s16, s39, s40
	s_add_i32 m0, s13, 0xc000
	ds_read_b128 v[154:157], v161
	ds_read_b128 v[162:165], v161 offset:1024
	ds_read_b128 v[166:169], v161 offset:2048
	ds_read_b128 v[170:173], v161 offset:3072
	ds_read_b128 v[174:177], v161 offset:4096
	ds_read_b128 v[178:181], v161 offset:5120
	ds_read_b128 v[182:185], v161 offset:6144
	ds_read_b128 v[186:189], v161 offset:7168
	global_load_lds_dwordx4 v150, s[14:15]
	s_add_i32 m0, s13, 0xe000
	s_nop 0
	global_load_lds_dwordx4 v152, s[14:15]
	s_waitcnt lgkmcnt(8)
	s_waitcnt lgkmcnt(0)
	s_barrier
	v_mfma_f32_16x16x32_bf16 v[140:143], v[64:67], v[154:157], v[140:143]
	v_mfma_f32_16x16x32_bf16 v[136:139], v[72:75], v[154:157], v[136:139]
	v_mfma_f32_16x16x32_bf16 v[132:135], v[64:67], v[166:169], v[132:135]
	v_mfma_f32_16x16x32_bf16 v[128:131], v[72:75], v[166:169], v[128:131]
	v_mfma_f32_16x16x32_bf16 v[108:111], v[64:67], v[174:177], v[108:111]
	v_mfma_f32_16x16x32_bf16 v[104:107], v[72:75], v[174:177], v[104:107]
	v_mfma_f32_16x16x32_bf16 v[100:103], v[64:67], v[182:185], v[100:103]
	v_mfma_f32_16x16x32_bf16 v[96:99], v[72:75], v[182:185], v[96:99]
	v_mfma_f32_16x16x32_bf16 v[140:143], v[68:71], v[162:165], v[140:143]
	v_mfma_f32_16x16x32_bf16 v[136:139], v[76:79], v[162:165], v[136:139]
	v_mfma_f32_16x16x32_bf16 v[132:135], v[68:71], v[170:173], v[132:135]
	v_mfma_f32_16x16x32_bf16 v[128:131], v[76:79], v[170:173], v[128:131]
	v_mfma_f32_16x16x32_bf16 v[108:111], v[68:71], v[178:181], v[108:111]
	v_mfma_f32_16x16x32_bf16 v[104:107], v[76:79], v[178:181], v[104:107]
	v_mfma_f32_16x16x32_bf16 v[100:103], v[68:71], v[186:189], v[100:103]
	v_mfma_f32_16x16x32_bf16 v[96:99], v[76:79], v[186:189], v[96:99]
	s_barrier
	s_add_i32 s46, 0, 0x14000
	s_add_i32 s43, s43, s27
	ds_read_b128 v[196:199], v220 offset:16384
	ds_read_b128 v[204:207], v220 offset:17408
	ds_read_b128 v[208:211], v220 offset:18432
	ds_read_b128 v[214:217], v220 offset:19456
	s_mov_b32 m0, s43
	s_nop 0
	global_load_lds_dwordx4 v192, s[16:17]
	s_add_i32 m0, s43, 0x2000
	s_nop 0
	global_load_lds_dwordx4 v148, s[16:17]
	s_waitcnt lgkmcnt(0)
	s_barrier
	v_mfma_f32_16x16x32_bf16 v[124:127], v[196:199], v[154:157], v[124:127]
	v_mfma_f32_16x16x32_bf16 v[120:123], v[208:211], v[154:157], v[120:123]
	v_mfma_f32_16x16x32_bf16 v[116:119], v[196:199], v[166:169], v[116:119]
	v_mfma_f32_16x16x32_bf16 v[112:115], v[208:211], v[166:169], v[112:115]
	v_mfma_f32_16x16x32_bf16 v[92:95], v[196:199], v[174:177], v[92:95]
	v_mfma_f32_16x16x32_bf16 v[88:91], v[208:211], v[174:177], v[88:91]
	v_mfma_f32_16x16x32_bf16 v[84:87], v[196:199], v[182:185], v[84:87]
	v_mfma_f32_16x16x32_bf16 v[80:83], v[208:211], v[182:185], v[80:83]
	v_mfma_f32_16x16x32_bf16 v[124:127], v[204:207], v[162:165], v[124:127]
	v_mfma_f32_16x16x32_bf16 v[120:123], v[214:217], v[162:165], v[120:123]
	v_mfma_f32_16x16x32_bf16 v[116:119], v[204:207], v[170:173], v[116:119]
	v_mfma_f32_16x16x32_bf16 v[112:115], v[214:217], v[170:173], v[112:115]
	v_mfma_f32_16x16x32_bf16 v[92:95], v[204:207], v[178:181], v[92:95]
	v_mfma_f32_16x16x32_bf16 v[88:91], v[214:217], v[178:181], v[88:91]
	v_mfma_f32_16x16x32_bf16 v[84:87], v[204:207], v[186:189], v[84:87]
	v_mfma_f32_16x16x32_bf16 v[80:83], v[214:217], v[186:189], v[80:83]
	s_mov_b32 m0, s13
	s_add_u32 s48, s18, 0x80
	s_addc_u32 s49, s19, 0
	s_barrier
	ds_read_b128 v[154:157], v161 offset:16384
	ds_read_b128 v[162:165], v161 offset:17408
	ds_read_b128 v[166:169], v161 offset:18432
	ds_read_b128 v[170:173], v161 offset:19456
	ds_read_b128 v[174:177], v161 offset:20480
	ds_read_b128 v[178:181], v161 offset:21504
	ds_read_b128 v[182:185], v161 offset:22528
	ds_read_b128 v[186:189], v161 offset:23552
	global_load_lds_dwordx4 v144, s[18:19]
	s_mov_b32 m0, s28
	s_nop 0
	global_load_lds_dwordx4 v146, s[18:19]
	s_waitcnt lgkmcnt(0)
	s_barrier
	v_mfma_f32_16x16x32_bf16 v[60:63], v[64:67], v[154:157], v[60:63]
	v_mfma_f32_16x16x32_bf16 v[56:59], v[72:75], v[154:157], v[56:59]
	v_mfma_f32_16x16x32_bf16 v[52:55], v[64:67], v[166:169], v[52:55]
	v_mfma_f32_16x16x32_bf16 v[48:51], v[72:75], v[166:169], v[48:51]
	v_mfma_f32_16x16x32_bf16 v[28:31], v[64:67], v[174:177], v[28:31]
	v_mfma_f32_16x16x32_bf16 v[24:27], v[72:75], v[174:177], v[24:27]
	v_mfma_f32_16x16x32_bf16 v[20:23], v[64:67], v[182:185], v[20:23]
	v_mfma_f32_16x16x32_bf16 v[16:19], v[72:75], v[182:185], v[16:19]
	v_mfma_f32_16x16x32_bf16 v[60:63], v[68:71], v[162:165], v[60:63]
	v_mfma_f32_16x16x32_bf16 v[56:59], v[76:79], v[162:165], v[56:59]
	v_mfma_f32_16x16x32_bf16 v[52:55], v[68:71], v[170:173], v[52:55]
	v_mfma_f32_16x16x32_bf16 v[48:51], v[76:79], v[170:173], v[48:51]
	v_mfma_f32_16x16x32_bf16 v[28:31], v[68:71], v[178:181], v[28:31]
	v_mfma_f32_16x16x32_bf16 v[24:27], v[76:79], v[178:181], v[24:27]
	v_mfma_f32_16x16x32_bf16 v[20:23], v[68:71], v[186:189], v[20:23]
	v_mfma_f32_16x16x32_bf16 v[16:19], v[76:79], v[186:189], v[16:19]
	s_barrier
	s_add_u32 s44, s16, 0x80000
	s_addc_u32 s45, s17, 0
	s_add_i32 s43, s46, s27
	s_mov_b32 m0, s43
	s_nop 0
	global_load_lds_dwordx4 v192, s[44:45]
	s_add_i32 m0, s43, 0x2000
	s_nop 0
	global_load_lds_dwordx4 v148, s[44:45]
	s_waitcnt vmcnt(6)
	s_barrier
	v_mfma_f32_16x16x32_bf16 v[44:47], v[196:199], v[154:157], v[44:47]
	v_mfma_f32_16x16x32_bf16 v[40:43], v[208:211], v[154:157], v[40:43]
	v_mfma_f32_16x16x32_bf16 v[36:39], v[196:199], v[166:169], v[36:39]
	v_mfma_f32_16x16x32_bf16 v[32:35], v[208:211], v[166:169], v[32:35]
	v_mfma_f32_16x16x32_bf16 v[12:15], v[196:199], v[174:177], v[12:15]
	v_mfma_f32_16x16x32_bf16 v[8:11], v[208:211], v[174:177], v[8:11]
	v_mfma_f32_16x16x32_bf16 v[4:7], v[196:199], v[182:185], v[4:7]
	v_mfma_f32_16x16x32_bf16 v[0:3], v[208:211], v[182:185], v[0:3]
	v_mfma_f32_16x16x32_bf16 v[44:47], v[204:207], v[162:165], v[44:47]
	v_mfma_f32_16x16x32_bf16 v[40:43], v[214:217], v[162:165], v[40:43]
	v_mfma_f32_16x16x32_bf16 v[36:39], v[204:207], v[170:173], v[36:39]
	v_mfma_f32_16x16x32_bf16 v[32:35], v[214:217], v[170:173], v[32:35]
	v_mfma_f32_16x16x32_bf16 v[12:15], v[204:207], v[178:181], v[12:15]
	v_mfma_f32_16x16x32_bf16 v[8:11], v[214:217], v[178:181], v[8:11]
	v_mfma_f32_16x16x32_bf16 v[4:7], v[204:207], v[186:189], v[4:7]
	v_mfma_f32_16x16x32_bf16 v[0:3], v[214:217], v[186:189], v[0:3]
	s_add_i32 s43, 0, 0x18000
	s_barrier
	ds_read_b128 v[64:67], v220 offset:32768
	ds_read_b128 v[68:71], v220 offset:33792
	ds_read_b128 v[72:75], v220 offset:34816
	ds_read_b128 v[76:79], v220 offset:35840
	s_add_u32 s18, s18, 0x80000
	s_addc_u32 s19, s19, 0
	s_mov_b32 m0, s29
	ds_read_b128 v[154:157], v161 offset:32768
	ds_read_b128 v[162:165], v161 offset:33792
	ds_read_b128 v[166:169], v161 offset:34816
	ds_read_b128 v[170:173], v161 offset:35840
	ds_read_b128 v[174:177], v161 offset:36864
	ds_read_b128 v[178:181], v161 offset:37888
	ds_read_b128 v[182:185], v161 offset:38912
	ds_read_b128 v[186:189], v161 offset:39936
	global_load_lds_dwordx4 v144, s[18:19]
	s_mov_b32 m0, s30
	s_nop 0
	global_load_lds_dwordx4 v146, s[18:19]
	s_waitcnt lgkmcnt(8)
	s_waitcnt lgkmcnt(0)
	s_barrier
	v_mfma_f32_16x16x32_bf16 v[140:143], v[64:67], v[154:157], v[140:143]
	v_mfma_f32_16x16x32_bf16 v[136:139], v[72:75], v[154:157], v[136:139]
	v_mfma_f32_16x16x32_bf16 v[132:135], v[64:67], v[166:169], v[132:135]
	v_mfma_f32_16x16x32_bf16 v[128:131], v[72:75], v[166:169], v[128:131]
	v_mfma_f32_16x16x32_bf16 v[108:111], v[64:67], v[174:177], v[108:111]
	v_mfma_f32_16x16x32_bf16 v[104:107], v[72:75], v[174:177], v[104:107]
	v_mfma_f32_16x16x32_bf16 v[100:103], v[64:67], v[182:185], v[100:103]
	v_mfma_f32_16x16x32_bf16 v[96:99], v[72:75], v[182:185], v[96:99]
	v_mfma_f32_16x16x32_bf16 v[140:143], v[68:71], v[162:165], v[140:143]
	v_mfma_f32_16x16x32_bf16 v[136:139], v[76:79], v[162:165], v[136:139]
	v_mfma_f32_16x16x32_bf16 v[132:135], v[68:71], v[170:173], v[132:135]
	v_mfma_f32_16x16x32_bf16 v[128:131], v[76:79], v[170:173], v[128:131]
	v_mfma_f32_16x16x32_bf16 v[108:111], v[68:71], v[178:181], v[108:111]
	v_mfma_f32_16x16x32_bf16 v[104:107], v[76:79], v[178:181], v[104:107]
	v_mfma_f32_16x16x32_bf16 v[100:103], v[68:71], v[186:189], v[100:103]
	v_mfma_f32_16x16x32_bf16 v[96:99], v[76:79], v[186:189], v[96:99]
	s_barrier
	s_add_i32 s18, 0, 0x1c000
	s_add_i32 s19, s43, s27
	s_add_i32 m0, s19, 0xffffff80
	ds_read_b128 v[196:199], v220 offset:49152
	ds_read_b128 v[204:207], v220 offset:50176
	ds_read_b128 v[208:211], v220 offset:51200
	ds_read_b128 v[214:217], v220 offset:52224
	global_load_lds_dwordx4 v192, s[16:17] offset:128
	s_add_i32 m0, s19, 0x1f80
	s_nop 0
	global_load_lds_dwordx4 v148, s[16:17] offset:128
	s_waitcnt lgkmcnt(0)
	s_barrier
	v_mfma_f32_16x16x32_bf16 v[124:127], v[196:199], v[154:157], v[124:127]
	v_mfma_f32_16x16x32_bf16 v[120:123], v[208:211], v[154:157], v[120:123]
	v_mfma_f32_16x16x32_bf16 v[116:119], v[196:199], v[166:169], v[116:119]
	v_mfma_f32_16x16x32_bf16 v[112:115], v[208:211], v[166:169], v[112:115]
	v_mfma_f32_16x16x32_bf16 v[92:95], v[196:199], v[174:177], v[92:95]
	v_mfma_f32_16x16x32_bf16 v[88:91], v[208:211], v[174:177], v[88:91]
	v_mfma_f32_16x16x32_bf16 v[84:87], v[196:199], v[182:185], v[84:87]
	v_mfma_f32_16x16x32_bf16 v[80:83], v[208:211], v[182:185], v[80:83]
	v_mfma_f32_16x16x32_bf16 v[124:127], v[204:207], v[162:165], v[124:127]
	v_mfma_f32_16x16x32_bf16 v[120:123], v[214:217], v[162:165], v[120:123]
	v_mfma_f32_16x16x32_bf16 v[116:119], v[204:207], v[170:173], v[116:119]
	v_mfma_f32_16x16x32_bf16 v[112:115], v[214:217], v[170:173], v[112:115]
	v_mfma_f32_16x16x32_bf16 v[92:95], v[204:207], v[178:181], v[92:95]
	v_mfma_f32_16x16x32_bf16 v[88:91], v[214:217], v[178:181], v[88:91]
	v_mfma_f32_16x16x32_bf16 v[84:87], v[204:207], v[186:189], v[84:87]
	v_mfma_f32_16x16x32_bf16 v[80:83], v[214:217], v[186:189], v[80:83]
	s_mov_b32 m0, s34
	s_barrier
	ds_read_b128 v[154:157], v161 offset:49152
	ds_read_b128 v[162:165], v161 offset:50176
	ds_read_b128 v[166:169], v161 offset:51200
	ds_read_b128 v[170:173], v161 offset:52224
	ds_read_b128 v[174:177], v161 offset:53248
	ds_read_b128 v[178:181], v161 offset:54272
	ds_read_b128 v[182:185], v161 offset:55296
	ds_read_b128 v[186:189], v161 offset:56320
	global_load_lds_dwordx4 v144, s[48:49]
	s_mov_b32 m0, s35
	s_nop 0
	global_load_lds_dwordx4 v146, s[48:49]
	s_waitcnt lgkmcnt(0)
	s_barrier
	v_mfma_f32_16x16x32_bf16 v[60:63], v[64:67], v[154:157], v[60:63]
	v_mfma_f32_16x16x32_bf16 v[56:59], v[72:75], v[154:157], v[56:59]
	v_mfma_f32_16x16x32_bf16 v[52:55], v[64:67], v[166:169], v[52:55]
	v_mfma_f32_16x16x32_bf16 v[48:51], v[72:75], v[166:169], v[48:51]
	v_mfma_f32_16x16x32_bf16 v[28:31], v[64:67], v[174:177], v[28:31]
	v_mfma_f32_16x16x32_bf16 v[24:27], v[72:75], v[174:177], v[24:27]
	v_mfma_f32_16x16x32_bf16 v[20:23], v[64:67], v[182:185], v[20:23]
	v_mfma_f32_16x16x32_bf16 v[16:19], v[72:75], v[182:185], v[16:19]
	v_mfma_f32_16x16x32_bf16 v[60:63], v[68:71], v[162:165], v[60:63]
	v_mfma_f32_16x16x32_bf16 v[56:59], v[76:79], v[162:165], v[56:59]
	v_mfma_f32_16x16x32_bf16 v[52:55], v[68:71], v[170:173], v[52:55]
	v_mfma_f32_16x16x32_bf16 v[48:51], v[76:79], v[170:173], v[48:51]
	v_mfma_f32_16x16x32_bf16 v[28:31], v[68:71], v[178:181], v[28:31]
	v_mfma_f32_16x16x32_bf16 v[24:27], v[76:79], v[178:181], v[24:27]
	v_mfma_f32_16x16x32_bf16 v[20:23], v[68:71], v[186:189], v[20:23]
	v_mfma_f32_16x16x32_bf16 v[16:19], v[76:79], v[186:189], v[16:19]
	s_barrier
	s_add_u32 s16, s16, 0x80080
	s_addc_u32 s17, s17, 0
	s_add_i32 s18, s18, s27
	s_mov_b32 m0, s18
	s_nop 0
	global_load_lds_dwordx4 v192, s[16:17]
	s_add_i32 m0, s18, 0x2000
	s_nop 0
	global_load_lds_dwordx4 v148, s[16:17]
	s_waitcnt vmcnt(6)
	s_barrier
	v_mfma_f32_16x16x32_bf16 v[44:47], v[196:199], v[154:157], v[44:47]
	v_mfma_f32_16x16x32_bf16 v[40:43], v[208:211], v[154:157], v[40:43]
	v_mfma_f32_16x16x32_bf16 v[36:39], v[196:199], v[166:169], v[36:39]
	v_mfma_f32_16x16x32_bf16 v[32:35], v[208:211], v[166:169], v[32:35]
	v_mfma_f32_16x16x32_bf16 v[12:15], v[196:199], v[174:177], v[12:15]
	v_mfma_f32_16x16x32_bf16 v[8:11], v[208:211], v[174:177], v[8:11]
	v_mfma_f32_16x16x32_bf16 v[4:7], v[196:199], v[182:185], v[4:7]
	v_mfma_f32_16x16x32_bf16 v[0:3], v[208:211], v[182:185], v[0:3]
	v_mfma_f32_16x16x32_bf16 v[44:47], v[204:207], v[162:165], v[44:47]
	v_mfma_f32_16x16x32_bf16 v[40:43], v[214:217], v[162:165], v[40:43]
	v_mfma_f32_16x16x32_bf16 v[36:39], v[204:207], v[170:173], v[36:39]
	v_mfma_f32_16x16x32_bf16 v[32:35], v[214:217], v[170:173], v[32:35]
	v_mfma_f32_16x16x32_bf16 v[12:15], v[204:207], v[178:181], v[12:15]
	v_mfma_f32_16x16x32_bf16 v[8:11], v[214:217], v[178:181], v[8:11]
	v_mfma_f32_16x16x32_bf16 v[4:7], v[204:207], v[186:189], v[4:7]
	v_mfma_f32_16x16x32_bf16 v[0:3], v[214:217], v[186:189], v[0:3]
	s_add_i32 s42, s42, 2
	s_add_u32 s14, s14, 0x100
	s_addc_u32 s15, s15, 0
	s_add_u32 s40, s40, 0x100
	s_addc_u32 s41, s41, 0
	s_cmp_gt_u32 s42, 29
	s_barrier
	s_cbranch_scc0 .LBB0_294
	s_ashr_i32 s5, s12, 4
	v_lshl_or_b32 v190, s37, 8, v160
	s_mul_hi_i32 s7, s5, 0xc000
	s_mul_i32 s5, s5, 0xc000
	s_add_u32 s14, s31, s5
	v_ashrrev_i32_e32 v191, 31, v190
	v_lshl_add_u32 v154, s12, 8, v158
	v_readlane_b32 s52, v254, 23
	s_addc_u32 s15, s33, s7
	v_lshlrev_b64 v[156:157], 2, v[190:191]
	v_readlane_b32 s53, v254, 24
	v_ashrrev_i32_e32 v155, 31, v154
	v_lshl_add_u64 v[68:69], s[14:15], 0, v[156:157]
	v_lshl_add_u64 v[156:157], s[52:53], 0, v[156:157]
	v_lshlrev_b64 v[162:163], 13, v[154:155]
	v_lshl_add_u64 v[174:175], v[156:157], 0, v[162:163]
	global_load_dwordx4 v[72:75], v[68:69], off offset:16
	global_load_dwordx4 v[76:79], v[68:69], off
	global_load_dwordx4 v[64:67], v[68:69], off offset:528
	s_nop 0
	global_load_dwordx4 v[68:71], v[68:69], off offset:512
	s_nop 0
	global_load_dwordx4 v[162:165], v[174:175], off offset:16
	global_load_dwordx4 v[166:169], v[174:175], off
	global_load_dwordx4 v[170:173], v[174:175], off offset:528
	s_nop 0
	global_load_dwordx4 v[174:177], v[174:175], off offset:512
	v_or_b32_e32 v204, 16, v154
	v_ashrrev_i32_e32 v205, 31, v204
	v_lshlrev_b64 v[178:179], 13, v[204:205]
	v_lshl_add_u64 v[196:197], v[156:157], 0, v[178:179]
	global_load_dwordx4 v[178:181], v[196:197], off offset:16
	global_load_dwordx4 v[182:185], v[196:197], off
	global_load_dwordx4 v[186:189], v[196:197], off offset:528
	s_nop 0
	global_load_dwordx4 v[196:199], v[196:197], off offset:512
	v_lshlrev_b64 v[206:207], 12, v[154:155]
	s_and_b64 vcc, exec, s[0:1]
	s_mov_b32 s37, s4
	s_mov_b32 s12, s6
	s_mov_b64 s[16:17], s[10:11]
	s_mov_b64 s[14:15], s[8:9]
	s_mov_b32 s11, 0xc000
	v_readlane_b32 s54, v254, 25
	v_readlane_b32 s55, v254, 26
	v_readlane_b32 s56, v254, 27
	v_readlane_b32 s57, v254, 28
	v_readlane_b32 s58, v254, 29
	v_readlane_b32 s59, v254, 30
	v_readlane_b32 s60, v254, 31
	v_readlane_b32 s61, v254, 32
	v_readlane_b32 s62, v254, 33
	v_readlane_b32 s63, v254, 34
	v_readlane_b32 s64, v254, 35
	v_readlane_b32 s65, v254, 36
	v_readlane_b32 s66, v254, 37
	v_readlane_b32 s67, v254, 38
	s_waitcnt vmcnt(0)
	v_pk_fma_f32 v[136:137], v[136:137], v[72:73], v[162:163]
	v_pk_fma_f32 v[142:143], v[142:143], v[78:79], v[168:169]
	v_pk_fma_f32 v[140:141], v[140:141], v[76:77], v[166:167]
	v_pk_fma_f32 v[164:165], v[138:139], v[74:75], v[164:165]
	v_cvt_pk_bf16_f32 v138, v140, v141
	v_cvt_pk_bf16_f32 v139, v142, v143
	v_cvt_pk_bf16_f32 v140, v136, v137
	v_lshl_add_u64 v[142:143], s[2:3], 0, v[206:207]
	v_lshlrev_b64 v[136:137], 1, v[190:191]
	v_lshl_add_u64 v[142:143], v[142:143], 0, v[136:137]
	v_pk_fma_f32 v[124:125], v[124:125], v[68:69], v[174:175]
	v_cvt_pk_bf16_f32 v141, v164, v165
	global_store_dwordx4 v[142:143], v[138:141], off
	v_pk_fma_f32 v[126:127], v[126:127], v[70:71], v[176:177]
	v_pk_fma_f32 v[128:129], v[128:129], v[72:73], v[178:179]
	v_pk_fma_f32 v[138:139], v[122:123], v[66:67], v[172:173]
	v_pk_fma_f32 v[122:123], v[120:121], v[64:65], v[170:171]
	v_cvt_pk_bf16_f32 v120, v124, v125
	v_cvt_pk_bf16_f32 v121, v126, v127
	v_lshlrev_b64 v[124:125], 12, v[204:205]
	v_cvt_pk_bf16_f32 v122, v122, v123
	v_cvt_pk_bf16_f32 v123, v138, v139
	global_store_dwordx4 v[142:143], v[120:123], off offset:256
	v_lshl_add_u64 v[124:125], s[2:3], 0, v[124:125]
	v_lshl_add_u64 v[124:125], v[124:125], 0, v[136:137]
	v_pk_fma_f32 v[120:121], v[132:133], v[76:77], v[182:183]
	v_pk_fma_f32 v[122:123], v[134:135], v[78:79], v[184:185]
	v_cvt_pk_bf16_f32 v120, v120, v121
	v_or_b32_e32 v142, 32, v154
	v_cvt_pk_bf16_f32 v121, v122, v123
	v_pk_fma_f32 v[126:127], v[130:131], v[74:75], v[180:181]
	v_cvt_pk_bf16_f32 v122, v128, v129
	v_pk_fma_f32 v[118:119], v[118:119], v[70:71], v[198:199]
	v_cvt_pk_bf16_f32 v123, v126, v127
	global_store_dwordx4 v[124:125], v[120:123], off
	v_pk_fma_f32 v[116:117], v[116:117], v[68:69], v[196:197]
	v_ashrrev_i32_e32 v143, 31, v142
	v_pk_fma_f32 v[120:121], v[114:115], v[66:67], v[188:189]
	v_pk_fma_f32 v[114:115], v[112:113], v[64:65], v[186:187]
	v_cvt_pk_bf16_f32 v112, v116, v117
	v_cvt_pk_bf16_f32 v113, v118, v119
	v_or_b32_e32 v166, 48, v154
	v_cvt_pk_bf16_f32 v114, v114, v115
	v_cvt_pk_bf16_f32 v115, v120, v121
	global_store_dwordx4 v[124:125], v[112:115], off offset:256
	v_ashrrev_i32_e32 v167, 31, v166
	v_lshlrev_b64 v[128:129], 13, v[166:167]
	v_lshlrev_b64 v[112:113], 13, v[142:143]
	v_lshl_add_u64 v[124:125], v[156:157], 0, v[112:113]
	global_load_dwordx4 v[112:115], v[124:125], off offset:16
	global_load_dwordx4 v[116:119], v[124:125], off
	global_load_dwordx4 v[120:123], v[124:125], off offset:528
	s_nop 0
	global_load_dwordx4 v[124:127], v[124:125], off offset:512
	v_lshl_add_u64 v[162:163], v[156:157], 0, v[128:129]
	global_load_dwordx4 v[128:131], v[162:163], off offset:16
	global_load_dwordx4 v[132:135], v[162:163], off
	global_load_dwordx4 v[138:141], v[162:163], off offset:528
	s_nop 0
	global_load_dwordx4 v[162:165], v[162:163], off offset:512
	v_lshlrev_b64 v[142:143], 12, v[142:143]
	s_waitcnt vmcnt(0)
	v_pk_fma_f32 v[114:115], v[106:107], v[74:75], v[114:115]
	v_pk_fma_f32 v[108:109], v[108:109], v[76:77], v[116:117]
	v_pk_fma_f32 v[106:107], v[104:105], v[72:73], v[112:113]
	v_cvt_pk_bf16_f32 v104, v108, v109
	v_lshl_add_u64 v[108:109], s[2:3], 0, v[142:143]
	v_pk_fma_f32 v[110:111], v[110:111], v[78:79], v[118:119]
	v_lshl_add_u64 v[108:109], v[108:109], 0, v[136:137]
	v_cvt_pk_bf16_f32 v105, v110, v111
	v_pk_fma_f32 v[92:93], v[92:93], v[68:69], v[124:125]
	v_cvt_pk_bf16_f32 v106, v106, v107
	v_cvt_pk_bf16_f32 v107, v114, v115
	global_store_dwordx4 v[108:109], v[104:107], off
	v_pk_fma_f32 v[94:95], v[94:95], v[70:71], v[126:127]
	v_add_u32_e32 v112, 0x80, v154
	v_pk_fma_f32 v[104:105], v[90:91], v[66:67], v[122:123]
	v_pk_fma_f32 v[90:91], v[88:89], v[64:65], v[120:121]
	v_cvt_pk_bf16_f32 v88, v92, v93
	v_cvt_pk_bf16_f32 v89, v94, v95
	v_lshlrev_b64 v[92:93], 12, v[166:167]
	v_cvt_pk_bf16_f32 v90, v90, v91
	v_cvt_pk_bf16_f32 v91, v104, v105
	global_store_dwordx4 v[108:109], v[88:91], off offset:256
	v_lshl_add_u64 v[92:93], s[2:3], 0, v[92:93]
	v_lshl_add_u64 v[92:93], v[92:93], 0, v[136:137]
	v_pk_fma_f32 v[88:89], v[100:101], v[76:77], v[132:133]
	v_pk_fma_f32 v[90:91], v[102:103], v[78:79], v[134:135]
	v_cvt_pk_bf16_f32 v88, v88, v89
	v_pk_fma_f32 v[94:95], v[98:99], v[74:75], v[130:131]
	v_cvt_pk_bf16_f32 v89, v90, v91
	v_pk_fma_f32 v[96:97], v[96:97], v[72:73], v[128:129]
	v_pk_fma_f32 v[86:87], v[86:87], v[70:71], v[164:165]
	v_cvt_pk_bf16_f32 v90, v96, v97
	v_cvt_pk_bf16_f32 v91, v94, v95
	global_store_dwordx4 v[92:93], v[88:91], off
	v_pk_fma_f32 v[84:85], v[84:85], v[68:69], v[162:163]
	v_ashrrev_i32_e32 v113, 31, v112
	v_pk_fma_f32 v[88:89], v[82:83], v[66:67], v[140:141]
	v_pk_fma_f32 v[82:83], v[80:81], v[64:65], v[138:139]
	v_cvt_pk_bf16_f32 v80, v84, v85
	v_cvt_pk_bf16_f32 v81, v86, v87
	v_add_u32_e32 v114, 0x90, v154
	v_cvt_pk_bf16_f32 v82, v82, v83
	v_cvt_pk_bf16_f32 v83, v88, v89
	global_store_dwordx4 v[92:93], v[80:83], off offset:256
	v_ashrrev_i32_e32 v115, 31, v114
	v_lshlrev_b64 v[96:97], 13, v[114:115]
	v_lshlrev_b64 v[80:81], 13, v[112:113]
	v_lshl_add_u64 v[92:93], v[156:157], 0, v[80:81]
	global_load_dwordx4 v[80:83], v[92:93], off offset:16
	global_load_dwordx4 v[84:87], v[92:93], off
	global_load_dwordx4 v[88:91], v[92:93], off offset:528
	s_nop 0
	global_load_dwordx4 v[92:95], v[92:93], off offset:512
	v_lshl_add_u64 v[108:109], v[156:157], 0, v[96:97]
	global_load_dwordx4 v[96:99], v[108:109], off offset:16
	global_load_dwordx4 v[100:103], v[108:109], off
	global_load_dwordx4 v[104:107], v[108:109], off offset:528
	s_nop 0
	global_load_dwordx4 v[108:111], v[108:109], off offset:512
	v_lshlrev_b64 v[112:113], 12, v[112:113]
	s_waitcnt vmcnt(0)
	v_pk_fma_f32 v[82:83], v[58:59], v[74:75], v[82:83]
	v_pk_fma_f32 v[60:61], v[60:61], v[76:77], v[84:85]
	v_pk_fma_f32 v[58:59], v[56:57], v[72:73], v[80:81]
	v_cvt_pk_bf16_f32 v56, v60, v61
	v_lshl_add_u64 v[60:61], s[2:3], 0, v[112:113]
	v_pk_fma_f32 v[62:63], v[62:63], v[78:79], v[86:87]
	v_lshl_add_u64 v[60:61], v[60:61], 0, v[136:137]
	v_cvt_pk_bf16_f32 v57, v62, v63
	v_pk_fma_f32 v[44:45], v[44:45], v[68:69], v[92:93]
	v_cvt_pk_bf16_f32 v58, v58, v59
	v_cvt_pk_bf16_f32 v59, v82, v83
	global_store_dwordx4 v[60:61], v[56:59], off
	v_pk_fma_f32 v[46:47], v[46:47], v[70:71], v[94:95]
	v_add_u32_e32 v80, 0xa0, v154
	v_pk_fma_f32 v[56:57], v[42:43], v[66:67], v[90:91]
	v_pk_fma_f32 v[42:43], v[40:41], v[64:65], v[88:89]
	v_cvt_pk_bf16_f32 v40, v44, v45
	v_cvt_pk_bf16_f32 v41, v46, v47
	v_lshlrev_b64 v[44:45], 12, v[114:115]
	v_cvt_pk_bf16_f32 v42, v42, v43
	v_cvt_pk_bf16_f32 v43, v56, v57
	global_store_dwordx4 v[60:61], v[40:43], off offset:256
	v_lshl_add_u64 v[44:45], s[2:3], 0, v[44:45]
	v_lshl_add_u64 v[44:45], v[44:45], 0, v[136:137]
	v_pk_fma_f32 v[40:41], v[52:53], v[76:77], v[100:101]
	v_pk_fma_f32 v[42:43], v[54:55], v[78:79], v[102:103]
	v_cvt_pk_bf16_f32 v40, v40, v41
	v_pk_fma_f32 v[46:47], v[50:51], v[74:75], v[98:99]
	v_cvt_pk_bf16_f32 v41, v42, v43
	v_pk_fma_f32 v[48:49], v[48:49], v[72:73], v[96:97]
	v_pk_fma_f32 v[38:39], v[38:39], v[70:71], v[110:111]
	v_cvt_pk_bf16_f32 v42, v48, v49
	v_cvt_pk_bf16_f32 v43, v46, v47
	global_store_dwordx4 v[44:45], v[40:43], off
	v_pk_fma_f32 v[36:37], v[36:37], v[68:69], v[108:109]
	v_ashrrev_i32_e32 v81, 31, v80
	v_pk_fma_f32 v[40:41], v[34:35], v[66:67], v[106:107]
	v_pk_fma_f32 v[34:35], v[32:33], v[64:65], v[104:105]
	v_cvt_pk_bf16_f32 v32, v36, v37
	v_cvt_pk_bf16_f32 v33, v38, v39
	v_add_u32_e32 v82, 0xb0, v154
	v_cvt_pk_bf16_f32 v34, v34, v35
	v_cvt_pk_bf16_f32 v35, v40, v41
	global_store_dwordx4 v[44:45], v[32:35], off offset:256
	v_ashrrev_i32_e32 v83, 31, v82
	v_lshlrev_b64 v[48:49], 13, v[82:83]
	v_lshlrev_b64 v[32:33], 13, v[80:81]
	v_lshl_add_u64 v[44:45], v[156:157], 0, v[32:33]
	global_load_dwordx4 v[32:35], v[44:45], off offset:16
	global_load_dwordx4 v[36:39], v[44:45], off
	global_load_dwordx4 v[40:43], v[44:45], off offset:528
	s_nop 0
	global_load_dwordx4 v[44:47], v[44:45], off offset:512
	v_lshl_add_u64 v[60:61], v[156:157], 0, v[48:49]
	global_load_dwordx4 v[48:51], v[60:61], off offset:16
	global_load_dwordx4 v[52:55], v[60:61], off
	global_load_dwordx4 v[56:59], v[60:61], off offset:528
	s_nop 0
	global_load_dwordx4 v[60:63], v[60:61], off offset:512
	v_lshlrev_b64 v[80:81], 12, v[80:81]
	s_waitcnt vmcnt(0)
	v_pk_fma_f32 v[34:35], v[26:27], v[74:75], v[34:35]
	v_pk_fma_f32 v[28:29], v[28:29], v[76:77], v[36:37]
	v_pk_fma_f32 v[26:27], v[24:25], v[72:73], v[32:33]
	v_cvt_pk_bf16_f32 v24, v28, v29
	v_lshl_add_u64 v[28:29], s[2:3], 0, v[80:81]
	v_pk_fma_f32 v[30:31], v[30:31], v[78:79], v[38:39]
	v_lshl_add_u64 v[28:29], v[28:29], 0, v[136:137]
	v_cvt_pk_bf16_f32 v25, v30, v31
	v_pk_fma_f32 v[12:13], v[12:13], v[68:69], v[44:45]
	v_cvt_pk_bf16_f32 v26, v26, v27
	v_cvt_pk_bf16_f32 v27, v34, v35
	global_store_dwordx4 v[28:29], v[24:27], off
	v_pk_fma_f32 v[14:15], v[14:15], v[70:71], v[46:47]
	v_pk_fma_f32 v[16:17], v[16:17], v[72:73], v[48:49]
	v_pk_fma_f32 v[24:25], v[10:11], v[66:67], v[42:43]
	v_pk_fma_f32 v[10:11], v[8:9], v[64:65], v[40:41]
	v_cvt_pk_bf16_f32 v8, v12, v13
	v_cvt_pk_bf16_f32 v9, v14, v15
	v_lshlrev_b64 v[12:13], 12, v[82:83]
	v_cvt_pk_bf16_f32 v10, v10, v11
	v_cvt_pk_bf16_f32 v11, v24, v25
	global_store_dwordx4 v[28:29], v[8:11], off offset:256
	v_lshl_add_u64 v[12:13], s[2:3], 0, v[12:13]
	v_lshl_add_u64 v[12:13], v[12:13], 0, v[136:137]
	v_pk_fma_f32 v[8:9], v[20:21], v[76:77], v[52:53]
	v_pk_fma_f32 v[10:11], v[22:23], v[78:79], v[54:55]
	v_cvt_pk_bf16_f32 v8, v8, v9
	v_pk_fma_f32 v[14:15], v[18:19], v[74:75], v[50:51]
	v_cvt_pk_bf16_f32 v9, v10, v11
	v_cvt_pk_bf16_f32 v10, v16, v17
	v_pk_fma_f32 v[6:7], v[6:7], v[70:71], v[62:63]
	v_cvt_pk_bf16_f32 v11, v14, v15
	global_store_dwordx4 v[12:13], v[8:11], off
	v_pk_fma_f32 v[4:5], v[4:5], v[68:69], v[60:61]
	s_nop 0
	v_pk_fma_f32 v[8:9], v[2:3], v[66:67], v[58:59]
	v_pk_fma_f32 v[2:3], v[0:1], v[64:65], v[56:57]
	v_cvt_pk_bf16_f32 v0, v4, v5
	v_cvt_pk_bf16_f32 v1, v6, v7
	s_nop 0
	v_cvt_pk_bf16_f32 v2, v2, v3
	v_cvt_pk_bf16_f32 v3, v8, v9
	global_store_dwordx4 v[12:13], v[0:3], off offset:256
	s_cbranch_vccz .LBB0_287
	s_waitcnt vmcnt(0)
	s_cmpk_gt_u32 s25, 0xff
	s_cbranch_scc1 .LBB0_298
	s_barrier

.LBB0_414:
	s_ashr_i32 s9, s8, 31
	v_cmp_lt_i64_e32 vcc, s[10:11], v[202:203]
	s_lshl_b64 s[10:11], s[8:9], 20
	s_add_u32 s10, s24, s10
	s_addc_u32 s11, s25, s11
	s_and_b64 s[12:13], vcc, exec
	s_cselect_b32 s9, s11, s17
	s_cselect_b32 s38, s10, s16
	s_ashr_i32 s7, s6, 31
	s_lshl_b64 s[12:13], s[6:7], 20
	s_add_u32 s12, s26, s12
	s_addc_u32 s13, s27, s13
	s_and_b64 s[20:21], vcc, exec
	s_cselect_b32 s7, s13, s19
	s_cselect_b32 s39, s12, s18
	s_add_u32 s16, s16, 0x80080
	s_addc_u32 s17, s17, 0
	s_add_u32 s40, s18, 0x100
	s_addc_u32 s41, s19, 0
	s_mov_b32 s42, -2
	s_mov_b64 s[48:49], 0x80
	v_add_u32_e32 v196, 0x10000, v143
	s_add_u32 s18, s16, 0xfff80080
	s_addc_u32 s19, s17, -1
	s_add_i32 s43, 0, 0x10000
	ds_read_b128 v[146:149], v196 offset:0
	ds_read_b128 v[150:153], v196 offset:1024
	ds_read_b128 v[154:157], v196 offset:2048
	ds_read_b128 v[158:161], v196 offset:3072
	s_cmp_eq_u32 s42, 28
	s_cselect_b32 s21, s9, s19
	s_cselect_b32 s20, s38, s18
	s_cselect_b32 s19, s7, s41
	s_cselect_b32 s18, s39, s40
	s_add_i32 m0, s30, 0xc000
	ds_read_b128 v[162:165], v145
	ds_read_b128 v[166:169], v145 offset:1024
	ds_read_b128 v[170:173], v145 offset:2048
	ds_read_b128 v[174:177], v145 offset:3072
	ds_read_b128 v[178:181], v145 offset:4096
	ds_read_b128 v[182:185], v145 offset:5120
	ds_read_b128 v[186:189], v145 offset:6144
	ds_read_b128 v[204:207], v145 offset:7168
	global_load_lds_dwordx4 v136, s[16:17]
	s_add_i32 m0, s30, 0xe000
	s_nop 0
	global_load_lds_dwordx4 v138, s[16:17]
	s_waitcnt lgkmcnt(8)
	s_waitcnt lgkmcnt(0)
	s_barrier
	v_mfma_f32_16x16x32_bf16 v[124:127], v[146:149], v[162:165], 0
	v_mfma_f32_16x16x32_bf16 v[120:123], v[154:157], v[162:165], 0
	v_mfma_f32_16x16x32_bf16 v[116:119], v[146:149], v[170:173], 0
	v_mfma_f32_16x16x32_bf16 v[108:111], v[154:157], v[170:173], 0
	v_mfma_f32_16x16x32_bf16 v[100:103], v[146:149], v[178:181], 0
	v_mfma_f32_16x16x32_bf16 v[92:95], v[154:157], v[178:181], 0
	v_mfma_f32_16x16x32_bf16 v[84:87], v[146:149], v[186:189], 0
	v_mfma_f32_16x16x32_bf16 v[76:79], v[154:157], v[186:189], 0
	v_mfma_f32_16x16x32_bf16 v[124:127], v[150:153], v[166:169], v[124:127]
	v_mfma_f32_16x16x32_bf16 v[120:123], v[158:161], v[166:169], v[120:123]
	v_mfma_f32_16x16x32_bf16 v[116:119], v[150:153], v[174:177], v[116:119]
	v_mfma_f32_16x16x32_bf16 v[108:111], v[158:161], v[174:177], v[108:111]
	v_mfma_f32_16x16x32_bf16 v[100:103], v[150:153], v[182:185], v[100:103]
	v_mfma_f32_16x16x32_bf16 v[92:95], v[158:161], v[182:185], v[92:95]
	v_mfma_f32_16x16x32_bf16 v[84:87], v[150:153], v[204:207], v[84:87]
	v_mfma_f32_16x16x32_bf16 v[76:79], v[158:161], v[204:207], v[76:79]
	s_barrier
	s_add_i32 s46, 0, 0x14000
	s_add_i32 s43, s43, s28
	ds_read_b128 v[208:211], v196 offset:16384
	ds_read_b128 v[214:217], v196 offset:17408
	ds_read_b128 v[218:221], v196 offset:18432
	ds_read_b128 v[222:225], v196 offset:19456
	s_mov_b32 m0, s43
	s_nop 0
	global_load_lds_dwordx4 v192, s[18:19]
	s_add_i32 m0, s43, 0x2000
	s_nop 0
	global_load_lds_dwordx4 v128, s[18:19]
	s_waitcnt lgkmcnt(0)
	s_barrier
	v_mfma_f32_16x16x32_bf16 v[112:115], v[208:211], v[162:165], 0
	v_mfma_f32_16x16x32_bf16 v[104:107], v[218:221], v[162:165], 0
	v_mfma_f32_16x16x32_bf16 v[96:99], v[208:211], v[170:173], 0
	v_mfma_f32_16x16x32_bf16 v[88:91], v[218:221], v[170:173], 0
	v_mfma_f32_16x16x32_bf16 v[80:83], v[208:211], v[178:181], 0
	v_mfma_f32_16x16x32_bf16 v[72:75], v[218:221], v[178:181], 0
	v_mfma_f32_16x16x32_bf16 v[68:71], v[208:211], v[186:189], 0
	v_mfma_f32_16x16x32_bf16 v[64:67], v[218:221], v[186:189], 0
	v_mfma_f32_16x16x32_bf16 v[112:115], v[214:217], v[166:169], v[112:115]
	v_mfma_f32_16x16x32_bf16 v[104:107], v[222:225], v[166:169], v[104:107]
	v_mfma_f32_16x16x32_bf16 v[96:99], v[214:217], v[174:177], v[96:99]
	v_mfma_f32_16x16x32_bf16 v[88:91], v[222:225], v[174:177], v[88:91]
	v_mfma_f32_16x16x32_bf16 v[80:83], v[214:217], v[182:185], v[80:83]
	v_mfma_f32_16x16x32_bf16 v[72:75], v[222:225], v[182:185], v[72:75]
	v_mfma_f32_16x16x32_bf16 v[68:71], v[214:217], v[204:207], v[68:71]
	v_mfma_f32_16x16x32_bf16 v[64:67], v[222:225], v[204:207], v[64:67]
	s_mov_b32 m0, s30
	s_add_u32 s48, s20, 0x80
	s_addc_u32 s49, s21, 0
	s_barrier
	ds_read_b128 v[162:165], v145 offset:16384
	ds_read_b128 v[166:169], v145 offset:17408
	ds_read_b128 v[170:173], v145 offset:18432
	ds_read_b128 v[174:177], v145 offset:19456
	ds_read_b128 v[178:181], v145 offset:20480
	ds_read_b128 v[182:185], v145 offset:21504
	ds_read_b128 v[186:189], v145 offset:22528
	ds_read_b128 v[204:207], v145 offset:23552
	global_load_lds_dwordx4 v132, s[20:21]
	s_mov_b32 m0, s31
	s_nop 0
	global_load_lds_dwordx4 v130, s[20:21]
	s_waitcnt lgkmcnt(0)
	s_barrier
	v_mfma_f32_16x16x32_bf16 v[60:63], v[146:149], v[162:165], 0
	v_mfma_f32_16x16x32_bf16 v[56:59], v[154:157], v[162:165], 0
	v_mfma_f32_16x16x32_bf16 v[52:55], v[146:149], v[170:173], 0
	v_mfma_f32_16x16x32_bf16 v[44:47], v[154:157], v[170:173], 0
	v_mfma_f32_16x16x32_bf16 v[36:39], v[146:149], v[178:181], 0
	v_mfma_f32_16x16x32_bf16 v[28:31], v[154:157], v[178:181], 0
	v_mfma_f32_16x16x32_bf16 v[20:23], v[146:149], v[186:189], 0
	v_mfma_f32_16x16x32_bf16 v[12:15], v[154:157], v[186:189], 0
	v_mfma_f32_16x16x32_bf16 v[60:63], v[150:153], v[166:169], v[60:63]
	v_mfma_f32_16x16x32_bf16 v[56:59], v[158:161], v[166:169], v[56:59]
	v_mfma_f32_16x16x32_bf16 v[52:55], v[150:153], v[174:177], v[52:55]
	v_mfma_f32_16x16x32_bf16 v[44:47], v[158:161], v[174:177], v[44:47]
	v_mfma_f32_16x16x32_bf16 v[36:39], v[150:153], v[182:185], v[36:39]
	v_mfma_f32_16x16x32_bf16 v[28:31], v[158:161], v[182:185], v[28:31]
	v_mfma_f32_16x16x32_bf16 v[20:23], v[150:153], v[204:207], v[20:23]
	v_mfma_f32_16x16x32_bf16 v[12:15], v[158:161], v[204:207], v[12:15]
	s_barrier
	s_add_u32 s44, s18, 0x80000
	s_addc_u32 s45, s19, 0
	s_add_i32 s43, s46, s28
	s_mov_b32 m0, s43
	s_nop 0
	global_load_lds_dwordx4 v192, s[44:45]
	s_add_i32 m0, s43, 0x2000
	s_nop 0
	global_load_lds_dwordx4 v128, s[44:45]
	s_waitcnt vmcnt(6)
	s_barrier
	v_mfma_f32_16x16x32_bf16 v[48:51], v[208:211], v[162:165], 0
	v_mfma_f32_16x16x32_bf16 v[40:43], v[218:221], v[162:165], 0
	v_mfma_f32_16x16x32_bf16 v[32:35], v[208:211], v[170:173], 0
	v_mfma_f32_16x16x32_bf16 v[24:27], v[218:221], v[170:173], 0
	v_mfma_f32_16x16x32_bf16 v[16:19], v[208:211], v[178:181], 0
	v_mfma_f32_16x16x32_bf16 v[8:11], v[218:221], v[178:181], 0
	v_mfma_f32_16x16x32_bf16 v[4:7], v[208:211], v[186:189], 0
	v_mfma_f32_16x16x32_bf16 v[0:3], v[218:221], v[186:189], 0
	v_mfma_f32_16x16x32_bf16 v[48:51], v[214:217], v[166:169], v[48:51]
	v_mfma_f32_16x16x32_bf16 v[40:43], v[222:225], v[166:169], v[40:43]
	v_mfma_f32_16x16x32_bf16 v[32:35], v[214:217], v[174:177], v[32:35]
	v_mfma_f32_16x16x32_bf16 v[24:27], v[222:225], v[174:177], v[24:27]
	v_mfma_f32_16x16x32_bf16 v[16:19], v[214:217], v[182:185], v[16:19]
	v_mfma_f32_16x16x32_bf16 v[8:11], v[222:225], v[182:185], v[8:11]
	v_mfma_f32_16x16x32_bf16 v[4:7], v[214:217], v[204:207], v[4:7]
	v_mfma_f32_16x16x32_bf16 v[0:3], v[222:225], v[204:207], v[0:3]
	s_add_i32 s43, 0, 0x18000
	s_barrier
	ds_read_b128 v[146:149], v196 offset:32768
	ds_read_b128 v[150:153], v196 offset:33792
	ds_read_b128 v[154:157], v196 offset:34816
	ds_read_b128 v[158:161], v196 offset:35840
	s_add_u32 s20, s20, 0x80000
	s_addc_u32 s21, s21, 0
	s_mov_b32 m0, s33
	ds_read_b128 v[162:165], v145 offset:32768
	ds_read_b128 v[166:169], v145 offset:33792
	ds_read_b128 v[170:173], v145 offset:34816
	ds_read_b128 v[174:177], v145 offset:35840
	ds_read_b128 v[178:181], v145 offset:36864
	ds_read_b128 v[182:185], v145 offset:37888
	ds_read_b128 v[186:189], v145 offset:38912
	ds_read_b128 v[204:207], v145 offset:39936
	global_load_lds_dwordx4 v132, s[20:21]
	s_mov_b32 m0, s34
	s_nop 0
	global_load_lds_dwordx4 v130, s[20:21]
	s_waitcnt lgkmcnt(8)
	s_waitcnt lgkmcnt(0)
	s_barrier
	v_mfma_f32_16x16x32_bf16 v[124:127], v[146:149], v[162:165], v[124:127]
	v_mfma_f32_16x16x32_bf16 v[120:123], v[154:157], v[162:165], v[120:123]
	v_mfma_f32_16x16x32_bf16 v[116:119], v[146:149], v[170:173], v[116:119]
	v_mfma_f32_16x16x32_bf16 v[108:111], v[154:157], v[170:173], v[108:111]
	v_mfma_f32_16x16x32_bf16 v[100:103], v[146:149], v[178:181], v[100:103]
	v_mfma_f32_16x16x32_bf16 v[92:95], v[154:157], v[178:181], v[92:95]
	v_mfma_f32_16x16x32_bf16 v[84:87], v[146:149], v[186:189], v[84:87]
	v_mfma_f32_16x16x32_bf16 v[76:79], v[154:157], v[186:189], v[76:79]
	v_mfma_f32_16x16x32_bf16 v[124:127], v[150:153], v[166:169], v[124:127]
	v_mfma_f32_16x16x32_bf16 v[120:123], v[158:161], v[166:169], v[120:123]
	v_mfma_f32_16x16x32_bf16 v[116:119], v[150:153], v[174:177], v[116:119]
	v_mfma_f32_16x16x32_bf16 v[108:111], v[158:161], v[174:177], v[108:111]
	v_mfma_f32_16x16x32_bf16 v[100:103], v[150:153], v[182:185], v[100:103]
	v_mfma_f32_16x16x32_bf16 v[92:95], v[158:161], v[182:185], v[92:95]
	v_mfma_f32_16x16x32_bf16 v[84:87], v[150:153], v[204:207], v[84:87]
	v_mfma_f32_16x16x32_bf16 v[76:79], v[158:161], v[204:207], v[76:79]
	s_barrier
	s_add_i32 s20, 0, 0x1c000
	s_add_i32 s21, s43, s28
	s_add_i32 m0, s21, 0xffffff80
	ds_read_b128 v[208:211], v196 offset:49152
	ds_read_b128 v[214:217], v196 offset:50176
	ds_read_b128 v[218:221], v196 offset:51200
	ds_read_b128 v[222:225], v196 offset:52224
	global_load_lds_dwordx4 v192, s[18:19] offset:128
	s_add_i32 m0, s21, 0x1f80
	s_nop 0
	global_load_lds_dwordx4 v128, s[18:19] offset:128
	s_waitcnt lgkmcnt(0)
	s_barrier
	v_mfma_f32_16x16x32_bf16 v[112:115], v[208:211], v[162:165], v[112:115]
	v_mfma_f32_16x16x32_bf16 v[104:107], v[218:221], v[162:165], v[104:107]
	v_mfma_f32_16x16x32_bf16 v[96:99], v[208:211], v[170:173], v[96:99]
	v_mfma_f32_16x16x32_bf16 v[88:91], v[218:221], v[170:173], v[88:91]
	v_mfma_f32_16x16x32_bf16 v[80:83], v[208:211], v[178:181], v[80:83]
	v_mfma_f32_16x16x32_bf16 v[72:75], v[218:221], v[178:181], v[72:75]
	v_mfma_f32_16x16x32_bf16 v[68:71], v[208:211], v[186:189], v[68:71]
	v_mfma_f32_16x16x32_bf16 v[64:67], v[218:221], v[186:189], v[64:67]
	v_mfma_f32_16x16x32_bf16 v[112:115], v[214:217], v[166:169], v[112:115]
	v_mfma_f32_16x16x32_bf16 v[104:107], v[222:225], v[166:169], v[104:107]
	v_mfma_f32_16x16x32_bf16 v[96:99], v[214:217], v[174:177], v[96:99]
	v_mfma_f32_16x16x32_bf16 v[88:91], v[222:225], v[174:177], v[88:91]
	v_mfma_f32_16x16x32_bf16 v[80:83], v[214:217], v[182:185], v[80:83]
	v_mfma_f32_16x16x32_bf16 v[72:75], v[222:225], v[182:185], v[72:75]
	v_mfma_f32_16x16x32_bf16 v[68:71], v[214:217], v[204:207], v[68:71]
	v_mfma_f32_16x16x32_bf16 v[64:67], v[222:225], v[204:207], v[64:67]
	s_mov_b32 m0, s35
	s_barrier
	ds_read_b128 v[162:165], v145 offset:49152
	ds_read_b128 v[166:169], v145 offset:50176
	ds_read_b128 v[170:173], v145 offset:51200
	ds_read_b128 v[174:177], v145 offset:52224
	ds_read_b128 v[178:181], v145 offset:53248
	ds_read_b128 v[182:185], v145 offset:54272
	ds_read_b128 v[186:189], v145 offset:55296
	ds_read_b128 v[204:207], v145 offset:56320
	global_load_lds_dwordx4 v132, s[48:49]
	s_mov_b32 m0, s36
	s_nop 0
	global_load_lds_dwordx4 v130, s[48:49]
	s_waitcnt lgkmcnt(0)
	s_barrier
	v_mfma_f32_16x16x32_bf16 v[60:63], v[146:149], v[162:165], v[60:63]
	v_mfma_f32_16x16x32_bf16 v[56:59], v[154:157], v[162:165], v[56:59]
	v_mfma_f32_16x16x32_bf16 v[52:55], v[146:149], v[170:173], v[52:55]
	v_mfma_f32_16x16x32_bf16 v[44:47], v[154:157], v[170:173], v[44:47]
	v_mfma_f32_16x16x32_bf16 v[36:39], v[146:149], v[178:181], v[36:39]
	v_mfma_f32_16x16x32_bf16 v[28:31], v[154:157], v[178:181], v[28:31]
	v_mfma_f32_16x16x32_bf16 v[20:23], v[146:149], v[186:189], v[20:23]
	v_mfma_f32_16x16x32_bf16 v[12:15], v[154:157], v[186:189], v[12:15]
	v_mfma_f32_16x16x32_bf16 v[60:63], v[150:153], v[166:169], v[60:63]
	v_mfma_f32_16x16x32_bf16 v[56:59], v[158:161], v[166:169], v[56:59]
	v_mfma_f32_16x16x32_bf16 v[52:55], v[150:153], v[174:177], v[52:55]
	v_mfma_f32_16x16x32_bf16 v[44:47], v[158:161], v[174:177], v[44:47]
	v_mfma_f32_16x16x32_bf16 v[36:39], v[150:153], v[182:185], v[36:39]
	v_mfma_f32_16x16x32_bf16 v[28:31], v[158:161], v[182:185], v[28:31]
	v_mfma_f32_16x16x32_bf16 v[20:23], v[150:153], v[204:207], v[20:23]
	v_mfma_f32_16x16x32_bf16 v[12:15], v[158:161], v[204:207], v[12:15]
	s_barrier
	s_add_u32 s18, s18, 0x80080
	s_addc_u32 s19, s19, 0
	s_add_i32 s20, s20, s28
	s_mov_b32 m0, s20
	s_nop 0
	global_load_lds_dwordx4 v192, s[18:19]
	s_add_i32 m0, s20, 0x2000
	s_nop 0
	global_load_lds_dwordx4 v128, s[18:19]
	s_waitcnt vmcnt(6)
	s_barrier
	v_mfma_f32_16x16x32_bf16 v[48:51], v[208:211], v[162:165], v[48:51]
	v_mfma_f32_16x16x32_bf16 v[40:43], v[218:221], v[162:165], v[40:43]
	v_mfma_f32_16x16x32_bf16 v[32:35], v[208:211], v[170:173], v[32:35]
	v_mfma_f32_16x16x32_bf16 v[24:27], v[218:221], v[170:173], v[24:27]
	v_mfma_f32_16x16x32_bf16 v[16:19], v[208:211], v[178:181], v[16:19]
	v_mfma_f32_16x16x32_bf16 v[8:11], v[218:221], v[178:181], v[8:11]
	v_mfma_f32_16x16x32_bf16 v[4:7], v[208:211], v[186:189], v[4:7]
	v_mfma_f32_16x16x32_bf16 v[0:3], v[218:221], v[186:189], v[0:3]
	v_mfma_f32_16x16x32_bf16 v[48:51], v[214:217], v[166:169], v[48:51]
	v_mfma_f32_16x16x32_bf16 v[40:43], v[222:225], v[166:169], v[40:43]
	v_mfma_f32_16x16x32_bf16 v[32:35], v[214:217], v[174:177], v[32:35]
	v_mfma_f32_16x16x32_bf16 v[24:27], v[222:225], v[174:177], v[24:27]
	v_mfma_f32_16x16x32_bf16 v[16:19], v[214:217], v[182:185], v[16:19]
	v_mfma_f32_16x16x32_bf16 v[8:11], v[222:225], v[182:185], v[8:11]
	v_mfma_f32_16x16x32_bf16 v[4:7], v[214:217], v[204:207], v[4:7]
	v_mfma_f32_16x16x32_bf16 v[0:3], v[222:225], v[204:207], v[0:3]
	s_add_i32 s42, s42, 2
	s_add_u32 s16, s16, 0x100
	s_addc_u32 s17, s17, 0
	s_add_u32 s40, s40, 0x100
	s_addc_u32 s41, s41, 0
	s_cmp_gt_u32 s42, 29
	s_barrier
.LBB0_415:
	s_add_u32 s18, s16, 0xfff80080
	s_addc_u32 s19, s17, -1
	s_add_i32 s43, 0, 0x10000
	ds_read_b128 v[146:149], v196 offset:0
	ds_read_b128 v[150:153], v196 offset:1024
	ds_read_b128 v[154:157], v196 offset:2048
	ds_read_b128 v[158:161], v196 offset:3072
	s_cmp_eq_u32 s42, 28
	s_cselect_b32 s21, s9, s19
	s_cselect_b32 s20, s38, s18
	s_cselect_b32 s19, s7, s41
	s_cselect_b32 s18, s39, s40
	s_add_i32 m0, s30, 0xc000
	ds_read_b128 v[162:165], v145
	ds_read_b128 v[166:169], v145 offset:1024
	ds_read_b128 v[170:173], v145 offset:2048
	ds_read_b128 v[174:177], v145 offset:3072
	ds_read_b128 v[178:181], v145 offset:4096
	ds_read_b128 v[182:185], v145 offset:5120
	ds_read_b128 v[186:189], v145 offset:6144
	ds_read_b128 v[204:207], v145 offset:7168
	global_load_lds_dwordx4 v136, s[16:17]
	s_add_i32 m0, s30, 0xe000
	s_nop 0
	global_load_lds_dwordx4 v138, s[16:17]
	s_waitcnt lgkmcnt(8)
	s_waitcnt lgkmcnt(0)
	s_barrier
	v_mfma_f32_16x16x32_bf16 v[124:127], v[146:149], v[162:165], v[124:127]
	v_mfma_f32_16x16x32_bf16 v[120:123], v[154:157], v[162:165], v[120:123]
	v_mfma_f32_16x16x32_bf16 v[116:119], v[146:149], v[170:173], v[116:119]
	v_mfma_f32_16x16x32_bf16 v[108:111], v[154:157], v[170:173], v[108:111]
	v_mfma_f32_16x16x32_bf16 v[100:103], v[146:149], v[178:181], v[100:103]
	v_mfma_f32_16x16x32_bf16 v[92:95], v[154:157], v[178:181], v[92:95]
	v_mfma_f32_16x16x32_bf16 v[84:87], v[146:149], v[186:189], v[84:87]
	v_mfma_f32_16x16x32_bf16 v[76:79], v[154:157], v[186:189], v[76:79]
	v_mfma_f32_16x16x32_bf16 v[124:127], v[150:153], v[166:169], v[124:127]
	v_mfma_f32_16x16x32_bf16 v[120:123], v[158:161], v[166:169], v[120:123]
	v_mfma_f32_16x16x32_bf16 v[116:119], v[150:153], v[174:177], v[116:119]
	v_mfma_f32_16x16x32_bf16 v[108:111], v[158:161], v[174:177], v[108:111]
	v_mfma_f32_16x16x32_bf16 v[100:103], v[150:153], v[182:185], v[100:103]
	v_mfma_f32_16x16x32_bf16 v[92:95], v[158:161], v[182:185], v[92:95]
	v_mfma_f32_16x16x32_bf16 v[84:87], v[150:153], v[204:207], v[84:87]
	v_mfma_f32_16x16x32_bf16 v[76:79], v[158:161], v[204:207], v[76:79]
	s_barrier
	s_add_i32 s46, 0, 0x14000
	s_add_i32 s43, s43, s28
	ds_read_b128 v[208:211], v196 offset:16384
	ds_read_b128 v[214:217], v196 offset:17408
	ds_read_b128 v[218:221], v196 offset:18432
	ds_read_b128 v[222:225], v196 offset:19456
	s_mov_b32 m0, s43
	s_nop 0
	global_load_lds_dwordx4 v192, s[18:19]
	s_add_i32 m0, s43, 0x2000
	s_nop 0
	global_load_lds_dwordx4 v128, s[18:19]
	s_waitcnt lgkmcnt(0)
	s_barrier
	v_mfma_f32_16x16x32_bf16 v[112:115], v[208:211], v[162:165], v[112:115]
	v_mfma_f32_16x16x32_bf16 v[104:107], v[218:221], v[162:165], v[104:107]
	v_mfma_f32_16x16x32_bf16 v[96:99], v[208:211], v[170:173], v[96:99]
	v_mfma_f32_16x16x32_bf16 v[88:91], v[218:221], v[170:173], v[88:91]
	v_mfma_f32_16x16x32_bf16 v[80:83], v[208:211], v[178:181], v[80:83]
	v_mfma_f32_16x16x32_bf16 v[72:75], v[218:221], v[178:181], v[72:75]
	v_mfma_f32_16x16x32_bf16 v[68:71], v[208:211], v[186:189], v[68:71]
	v_mfma_f32_16x16x32_bf16 v[64:67], v[218:221], v[186:189], v[64:67]
	v_mfma_f32_16x16x32_bf16 v[112:115], v[214:217], v[166:169], v[112:115]
	v_mfma_f32_16x16x32_bf16 v[104:107], v[222:225], v[166:169], v[104:107]
	v_mfma_f32_16x16x32_bf16 v[96:99], v[214:217], v[174:177], v[96:99]
	v_mfma_f32_16x16x32_bf16 v[88:91], v[222:225], v[174:177], v[88:91]
	v_mfma_f32_16x16x32_bf16 v[80:83], v[214:217], v[182:185], v[80:83]
	v_mfma_f32_16x16x32_bf16 v[72:75], v[222:225], v[182:185], v[72:75]
	v_mfma_f32_16x16x32_bf16 v[68:71], v[214:217], v[204:207], v[68:71]
	v_mfma_f32_16x16x32_bf16 v[64:67], v[222:225], v[204:207], v[64:67]
	s_mov_b32 m0, s30
	s_add_u32 s48, s20, 0x80
	s_addc_u32 s49, s21, 0
	s_barrier
	ds_read_b128 v[162:165], v145 offset:16384
	ds_read_b128 v[166:169], v145 offset:17408
	ds_read_b128 v[170:173], v145 offset:18432
	ds_read_b128 v[174:177], v145 offset:19456
	ds_read_b128 v[178:181], v145 offset:20480
	ds_read_b128 v[182:185], v145 offset:21504
	ds_read_b128 v[186:189], v145 offset:22528
	ds_read_b128 v[204:207], v145 offset:23552
	global_load_lds_dwordx4 v132, s[20:21]
	s_mov_b32 m0, s31
	s_nop 0
	global_load_lds_dwordx4 v130, s[20:21]
	s_waitcnt lgkmcnt(0)
	s_barrier
	v_mfma_f32_16x16x32_bf16 v[60:63], v[146:149], v[162:165], v[60:63]
	v_mfma_f32_16x16x32_bf16 v[56:59], v[154:157], v[162:165], v[56:59]
	v_mfma_f32_16x16x32_bf16 v[52:55], v[146:149], v[170:173], v[52:55]
	v_mfma_f32_16x16x32_bf16 v[44:47], v[154:157], v[170:173], v[44:47]
	v_mfma_f32_16x16x32_bf16 v[36:39], v[146:149], v[178:181], v[36:39]
	v_mfma_f32_16x16x32_bf16 v[28:31], v[154:157], v[178:181], v[28:31]
	v_mfma_f32_16x16x32_bf16 v[20:23], v[146:149], v[186:189], v[20:23]
	v_mfma_f32_16x16x32_bf16 v[12:15], v[154:157], v[186:189], v[12:15]
	v_mfma_f32_16x16x32_bf16 v[60:63], v[150:153], v[166:169], v[60:63]
	v_mfma_f32_16x16x32_bf16 v[56:59], v[158:161], v[166:169], v[56:59]
	v_mfma_f32_16x16x32_bf16 v[52:55], v[150:153], v[174:177], v[52:55]
	v_mfma_f32_16x16x32_bf16 v[44:47], v[158:161], v[174:177], v[44:47]
	v_mfma_f32_16x16x32_bf16 v[36:39], v[150:153], v[182:185], v[36:39]
	v_mfma_f32_16x16x32_bf16 v[28:31], v[158:161], v[182:185], v[28:31]
	v_mfma_f32_16x16x32_bf16 v[20:23], v[150:153], v[204:207], v[20:23]
	v_mfma_f32_16x16x32_bf16 v[12:15], v[158:161], v[204:207], v[12:15]
	s_barrier
	s_add_u32 s44, s18, 0x80000
	s_addc_u32 s45, s19, 0
	s_add_i32 s43, s46, s28
	s_mov_b32 m0, s43
	s_nop 0
	global_load_lds_dwordx4 v192, s[44:45]
	s_add_i32 m0, s43, 0x2000
	s_nop 0
	global_load_lds_dwordx4 v128, s[44:45]
	s_waitcnt vmcnt(6)
	s_barrier
	v_mfma_f32_16x16x32_bf16 v[48:51], v[208:211], v[162:165], v[48:51]
	v_mfma_f32_16x16x32_bf16 v[40:43], v[218:221], v[162:165], v[40:43]
	v_mfma_f32_16x16x32_bf16 v[32:35], v[208:211], v[170:173], v[32:35]
	v_mfma_f32_16x16x32_bf16 v[24:27], v[218:221], v[170:173], v[24:27]
	v_mfma_f32_16x16x32_bf16 v[16:19], v[208:211], v[178:181], v[16:19]
	v_mfma_f32_16x16x32_bf16 v[8:11], v[218:221], v[178:181], v[8:11]
	v_mfma_f32_16x16x32_bf16 v[4:7], v[208:211], v[186:189], v[4:7]
	v_mfma_f32_16x16x32_bf16 v[0:3], v[218:221], v[186:189], v[0:3]
	v_mfma_f32_16x16x32_bf16 v[48:51], v[214:217], v[166:169], v[48:51]
	v_mfma_f32_16x16x32_bf16 v[40:43], v[222:225], v[166:169], v[40:43]
	v_mfma_f32_16x16x32_bf16 v[32:35], v[214:217], v[174:177], v[32:35]
	v_mfma_f32_16x16x32_bf16 v[24:27], v[222:225], v[174:177], v[24:27]
	v_mfma_f32_16x16x32_bf16 v[16:19], v[214:217], v[182:185], v[16:19]
	v_mfma_f32_16x16x32_bf16 v[8:11], v[222:225], v[182:185], v[8:11]
	v_mfma_f32_16x16x32_bf16 v[4:7], v[214:217], v[204:207], v[4:7]
	v_mfma_f32_16x16x32_bf16 v[0:3], v[222:225], v[204:207], v[0:3]
	s_add_i32 s43, 0, 0x18000
	s_barrier
	ds_read_b128 v[146:149], v196 offset:32768
	ds_read_b128 v[150:153], v196 offset:33792
	ds_read_b128 v[154:157], v196 offset:34816
	ds_read_b128 v[158:161], v196 offset:35840
	s_add_u32 s20, s20, 0x80000
	s_addc_u32 s21, s21, 0
	s_mov_b32 m0, s33
	ds_read_b128 v[162:165], v145 offset:32768
	ds_read_b128 v[166:169], v145 offset:33792
	ds_read_b128 v[170:173], v145 offset:34816
	ds_read_b128 v[174:177], v145 offset:35840
	ds_read_b128 v[178:181], v145 offset:36864
	ds_read_b128 v[182:185], v145 offset:37888
	ds_read_b128 v[186:189], v145 offset:38912
	ds_read_b128 v[204:207], v145 offset:39936
	global_load_lds_dwordx4 v132, s[20:21]
	s_mov_b32 m0, s34
	s_nop 0
	global_load_lds_dwordx4 v130, s[20:21]
	s_waitcnt lgkmcnt(8)
	s_waitcnt lgkmcnt(0)
	s_barrier
	v_mfma_f32_16x16x32_bf16 v[124:127], v[146:149], v[162:165], v[124:127]
	v_mfma_f32_16x16x32_bf16 v[120:123], v[154:157], v[162:165], v[120:123]
	v_mfma_f32_16x16x32_bf16 v[116:119], v[146:149], v[170:173], v[116:119]
	v_mfma_f32_16x16x32_bf16 v[108:111], v[154:157], v[170:173], v[108:111]
	v_mfma_f32_16x16x32_bf16 v[100:103], v[146:149], v[178:181], v[100:103]
	v_mfma_f32_16x16x32_bf16 v[92:95], v[154:157], v[178:181], v[92:95]
	v_mfma_f32_16x16x32_bf16 v[84:87], v[146:149], v[186:189], v[84:87]
	v_mfma_f32_16x16x32_bf16 v[76:79], v[154:157], v[186:189], v[76:79]
	v_mfma_f32_16x16x32_bf16 v[124:127], v[150:153], v[166:169], v[124:127]
	v_mfma_f32_16x16x32_bf16 v[120:123], v[158:161], v[166:169], v[120:123]
	v_mfma_f32_16x16x32_bf16 v[116:119], v[150:153], v[174:177], v[116:119]
	v_mfma_f32_16x16x32_bf16 v[108:111], v[158:161], v[174:177], v[108:111]
	v_mfma_f32_16x16x32_bf16 v[100:103], v[150:153], v[182:185], v[100:103]
	v_mfma_f32_16x16x32_bf16 v[92:95], v[158:161], v[182:185], v[92:95]
	v_mfma_f32_16x16x32_bf16 v[84:87], v[150:153], v[204:207], v[84:87]
	v_mfma_f32_16x16x32_bf16 v[76:79], v[158:161], v[204:207], v[76:79]
	s_barrier
	s_add_i32 s20, 0, 0x1c000
	s_add_i32 s21, s43, s28
	s_add_i32 m0, s21, 0xffffff80
	ds_read_b128 v[208:211], v196 offset:49152
	ds_read_b128 v[214:217], v196 offset:50176
	ds_read_b128 v[218:221], v196 offset:51200
	ds_read_b128 v[222:225], v196 offset:52224
	global_load_lds_dwordx4 v192, s[18:19] offset:128
	s_add_i32 m0, s21, 0x1f80
	s_nop 0
	global_load_lds_dwordx4 v128, s[18:19] offset:128
	s_waitcnt lgkmcnt(0)
	s_barrier
	v_mfma_f32_16x16x32_bf16 v[112:115], v[208:211], v[162:165], v[112:115]
	v_mfma_f32_16x16x32_bf16 v[104:107], v[218:221], v[162:165], v[104:107]
	v_mfma_f32_16x16x32_bf16 v[96:99], v[208:211], v[170:173], v[96:99]
	v_mfma_f32_16x16x32_bf16 v[88:91], v[218:221], v[170:173], v[88:91]
	v_mfma_f32_16x16x32_bf16 v[80:83], v[208:211], v[178:181], v[80:83]
	v_mfma_f32_16x16x32_bf16 v[72:75], v[218:221], v[178:181], v[72:75]
	v_mfma_f32_16x16x32_bf16 v[68:71], v[208:211], v[186:189], v[68:71]
	v_mfma_f32_16x16x32_bf16 v[64:67], v[218:221], v[186:189], v[64:67]
	v_mfma_f32_16x16x32_bf16 v[112:115], v[214:217], v[166:169], v[112:115]
	v_mfma_f32_16x16x32_bf16 v[104:107], v[222:225], v[166:169], v[104:107]
	v_mfma_f32_16x16x32_bf16 v[96:99], v[214:217], v[174:177], v[96:99]
	v_mfma_f32_16x16x32_bf16 v[88:91], v[222:225], v[174:177], v[88:91]
	v_mfma_f32_16x16x32_bf16 v[80:83], v[214:217], v[182:185], v[80:83]
	v_mfma_f32_16x16x32_bf16 v[72:75], v[222:225], v[182:185], v[72:75]
	v_mfma_f32_16x16x32_bf16 v[68:71], v[214:217], v[204:207], v[68:71]
	v_mfma_f32_16x16x32_bf16 v[64:67], v[222:225], v[204:207], v[64:67]
	s_mov_b32 m0, s35
	s_barrier
	ds_read_b128 v[162:165], v145 offset:49152
	ds_read_b128 v[166:169], v145 offset:50176
	ds_read_b128 v[170:173], v145 offset:51200
	ds_read_b128 v[174:177], v145 offset:52224
	ds_read_b128 v[178:181], v145 offset:53248
	ds_read_b128 v[182:185], v145 offset:54272
	ds_read_b128 v[186:189], v145 offset:55296
	ds_read_b128 v[204:207], v145 offset:56320
	global_load_lds_dwordx4 v132, s[48:49]
	s_mov_b32 m0, s36
	s_nop 0
	global_load_lds_dwordx4 v130, s[48:49]
	s_waitcnt lgkmcnt(0)
	s_barrier
	v_mfma_f32_16x16x32_bf16 v[60:63], v[146:149], v[162:165], v[60:63]
	v_mfma_f32_16x16x32_bf16 v[56:59], v[154:157], v[162:165], v[56:59]
	v_mfma_f32_16x16x32_bf16 v[52:55], v[146:149], v[170:173], v[52:55]
	v_mfma_f32_16x16x32_bf16 v[44:47], v[154:157], v[170:173], v[44:47]
	v_mfma_f32_16x16x32_bf16 v[36:39], v[146:149], v[178:181], v[36:39]
	v_mfma_f32_16x16x32_bf16 v[28:31], v[154:157], v[178:181], v[28:31]
	v_mfma_f32_16x16x32_bf16 v[20:23], v[146:149], v[186:189], v[20:23]
	v_mfma_f32_16x16x32_bf16 v[12:15], v[154:157], v[186:189], v[12:15]
	v_mfma_f32_16x16x32_bf16 v[60:63], v[150:153], v[166:169], v[60:63]
	v_mfma_f32_16x16x32_bf16 v[56:59], v[158:161], v[166:169], v[56:59]
	v_mfma_f32_16x16x32_bf16 v[52:55], v[150:153], v[174:177], v[52:55]
	v_mfma_f32_16x16x32_bf16 v[44:47], v[158:161], v[174:177], v[44:47]
	v_mfma_f32_16x16x32_bf16 v[36:39], v[150:153], v[182:185], v[36:39]
	v_mfma_f32_16x16x32_bf16 v[28:31], v[158:161], v[182:185], v[28:31]
	v_mfma_f32_16x16x32_bf16 v[20:23], v[150:153], v[204:207], v[20:23]
	v_mfma_f32_16x16x32_bf16 v[12:15], v[158:161], v[204:207], v[12:15]
	s_barrier
	s_add_u32 s18, s18, 0x80080
	s_addc_u32 s19, s19, 0
	s_add_i32 s20, s20, s28
	s_mov_b32 m0, s20
	s_nop 0
	global_load_lds_dwordx4 v192, s[18:19]
	s_add_i32 m0, s20, 0x2000
	s_nop 0
	global_load_lds_dwordx4 v128, s[18:19]
	s_waitcnt vmcnt(6)
	s_barrier
	v_mfma_f32_16x16x32_bf16 v[48:51], v[208:211], v[162:165], v[48:51]
	v_mfma_f32_16x16x32_bf16 v[40:43], v[218:221], v[162:165], v[40:43]
	v_mfma_f32_16x16x32_bf16 v[32:35], v[208:211], v[170:173], v[32:35]
	v_mfma_f32_16x16x32_bf16 v[24:27], v[218:221], v[170:173], v[24:27]
	v_mfma_f32_16x16x32_bf16 v[16:19], v[208:211], v[178:181], v[16:19]
	v_mfma_f32_16x16x32_bf16 v[8:11], v[218:221], v[178:181], v[8:11]
	v_mfma_f32_16x16x32_bf16 v[4:7], v[208:211], v[186:189], v[4:7]
	v_mfma_f32_16x16x32_bf16 v[0:3], v[218:221], v[186:189], v[0:3]
	v_mfma_f32_16x16x32_bf16 v[48:51], v[214:217], v[166:169], v[48:51]
	v_mfma_f32_16x16x32_bf16 v[40:43], v[222:225], v[166:169], v[40:43]
	v_mfma_f32_16x16x32_bf16 v[32:35], v[214:217], v[174:177], v[32:35]
	v_mfma_f32_16x16x32_bf16 v[24:27], v[222:225], v[174:177], v[24:27]
	v_mfma_f32_16x16x32_bf16 v[16:19], v[214:217], v[182:185], v[16:19]
	v_mfma_f32_16x16x32_bf16 v[8:11], v[222:225], v[182:185], v[8:11]
	v_mfma_f32_16x16x32_bf16 v[4:7], v[214:217], v[204:207], v[4:7]
	v_mfma_f32_16x16x32_bf16 v[0:3], v[222:225], v[204:207], v[0:3]
	s_add_i32 s42, s42, 2
	s_add_u32 s16, s16, 0x100
	s_addc_u32 s17, s17, 0
	s_add_u32 s40, s40, 0x100
	s_addc_u32 s41, s41, 0
	s_cmp_gt_u32 s42, 29
	s_barrier
	s_cbranch_scc0 .LBB0_415
	s_mul_hi_i32 s9, s15, 0x2aaaaaab
	v_lshl_add_u32 v153, s14, 8, v142
	s_lshr_b32 s14, s9, 31
	s_lshr_b32 s9, s9, 2
	s_add_i32 s9, s9, s14
	s_lshl_b32 s7, s15, 8
	s_mul_i32 s16, s9, 0x1800
	v_readlane_b32 s40, v254, 14
	v_readlane_b32 s41, v254, 15
	s_sub_i32 s40, s7, s16
	s_mov_b64 s[20:21], s[40:41]
	v_readlane_b32 s42, v254, 16
	v_readlane_b32 s43, v254, 17
	v_writelane_b32 v254, s20, 14
	s_mov_b64 s[14:15], -1
	s_cmpk_gt_i32 s40, 0xfff
	v_writelane_b32 v254, s21, 15
	v_writelane_b32 v254, s22, 16
	v_writelane_b32 v254, s23, 17
	v_or_b32_e32 v152, 16, v153
	v_or_b32_e32 v151, 32, v153
	v_or_b32_e32 v150, 48, v153
	v_add_u32_e32 v149, 0x80, v153
	v_add_u32_e32 v148, 0x90, v153
	v_add_u32_e32 v147, 0xa0, v153
	v_add_u32_e32 v146, 0xb0, v153
	s_cbranch_scc0 .LBB0_418
	v_mov_b32_e32 v156, v193
	v_mov_b32_e32 v157, v193
	s_ashr_i32 s17, s16, 31
	v_mov_b64_e32 v[140:141], s[2:3]
	s_mov_b32 s9, 0x9000
	v_cvt_pk_fp8_f32 v156, v124, v125
	v_cvt_pk_fp8_f32 v157, v120, v121
	s_lshl_b64 s[14:15], s[16:17], 1
	v_mad_i64_i32 v[154:155], s[16:17], v153, s9, v[140:141]
	s_add_u32 s14, s14, 0x2000
	v_readlane_b32 s16, v254, 14
	s_addc_u32 s15, s15, 0
	v_readlane_b32 s17, v254, 15
	v_lshl_add_u64 v[154:155], v[154:155], 0, s[14:15]
	s_mov_b64 s[20:21], s[16:17]
	v_cvt_pk_fp8_f32 v156, v126, v127 op_sel:[0,0,1]
	v_cvt_pk_fp8_f32 v157, v122, v123 op_sel:[0,0,1]
	v_lshl_add_u64 v[154:155], v[154:155], 0, s[20:21]
	v_lshl_add_u64 v[154:155], v[154:155], 0, s[4:5]
	v_lshl_add_u64 v[154:155], v[154:155], 0, v[134:135]
	global_store_dwordx2 v[154:155], v[156:157], off offset:-4096
	v_mov_b32_e32 v156, v193
	v_mov_b32_e32 v157, v193
	v_cvt_pk_fp8_f32 v156, v112, v113
	v_cvt_pk_fp8_f32 v157, v104, v105
	v_readlane_b32 s18, v254, 16
	v_readlane_b32 s19, v254, 17
	v_cvt_pk_fp8_f32 v156, v114, v115 op_sel:[0,0,1]
	v_cvt_pk_fp8_f32 v157, v106, v107 op_sel:[0,0,1]
	global_store_dwordx2 v[154:155], v[156:157], off offset:-3968
	v_mov_b32_e32 v156, v193
	v_mov_b32_e32 v157, v193
	v_cvt_pk_fp8_f32 v156, v116, v117
	v_cvt_pk_fp8_f32 v157, v108, v109
	v_mad_i64_i32 v[154:155], s[16:17], v152, s9, v[140:141]
	v_lshl_add_u64 v[154:155], v[154:155], 0, s[14:15]
	v_cvt_pk_fp8_f32 v156, v118, v119 op_sel:[0,0,1]
	v_cvt_pk_fp8_f32 v157, v110, v111 op_sel:[0,0,1]
	v_lshl_add_u64 v[154:155], v[154:155], 0, s[20:21]
	v_lshl_add_u64 v[154:155], v[154:155], 0, s[4:5]
	v_lshl_add_u64 v[154:155], v[154:155], 0, v[134:135]
	global_store_dwordx2 v[154:155], v[156:157], off offset:-4096
	v_mov_b32_e32 v156, v193
	v_mov_b32_e32 v157, v193
	v_cvt_pk_fp8_f32 v156, v96, v97
	v_cvt_pk_fp8_f32 v157, v88, v89
	v_cvt_pk_fp8_f32 v156, v98, v99 op_sel:[0,0,1]
	v_cvt_pk_fp8_f32 v157, v90, v91 op_sel:[0,0,1]
	global_store_dwordx2 v[154:155], v[156:157], off offset:-3968
	v_mov_b32_e32 v156, v193
	v_mov_b32_e32 v157, v193
	v_cvt_pk_fp8_f32 v156, v100, v101
	v_cvt_pk_fp8_f32 v157, v92, v93
	v_mad_i64_i32 v[154:155], s[16:17], v151, s9, v[140:141]
	v_lshl_add_u64 v[154:155], v[154:155], 0, s[14:15]
	v_cvt_pk_fp8_f32 v156, v102, v103 op_sel:[0,0,1]
	v_cvt_pk_fp8_f32 v157, v94, v95 op_sel:[0,0,1]
	v_lshl_add_u64 v[154:155], v[154:155], 0, s[20:21]
	v_lshl_add_u64 v[154:155], v[154:155], 0, s[4:5]
	v_lshl_add_u64 v[154:155], v[154:155], 0, v[134:135]
	global_store_dwordx2 v[154:155], v[156:157], off offset:-4096
	v_mov_b32_e32 v156, v193
	v_mov_b32_e32 v157, v193
	v_cvt_pk_fp8_f32 v156, v80, v81
	v_cvt_pk_fp8_f32 v157, v72, v73
	v_cvt_pk_fp8_f32 v156, v82, v83 op_sel:[0,0,1]
	v_cvt_pk_fp8_f32 v157, v74, v75 op_sel:[0,0,1]
	global_store_dwordx2 v[154:155], v[156:157], off offset:-3968
	v_mov_b32_e32 v156, v193
	v_mov_b32_e32 v157, v193
	v_cvt_pk_fp8_f32 v156, v84, v85
	v_cvt_pk_fp8_f32 v157, v76, v77
	v_mad_i64_i32 v[154:155], s[16:17], v150, s9, v[140:141]
	v_lshl_add_u64 v[154:155], v[154:155], 0, s[14:15]
	v_cvt_pk_fp8_f32 v156, v86, v87 op_sel:[0,0,1]
	v_cvt_pk_fp8_f32 v157, v78, v79 op_sel:[0,0,1]
	v_lshl_add_u64 v[154:155], v[154:155], 0, s[20:21]
	v_lshl_add_u64 v[154:155], v[154:155], 0, s[4:5]
	v_lshl_add_u64 v[154:155], v[154:155], 0, v[134:135]
	global_store_dwordx2 v[154:155], v[156:157], off offset:-4096
	v_mov_b32_e32 v156, v193
	v_mov_b32_e32 v157, v193
	v_cvt_pk_fp8_f32 v156, v68, v69
	v_cvt_pk_fp8_f32 v157, v64, v65
	v_cvt_pk_fp8_f32 v156, v70, v71 op_sel:[0,0,1]
	v_cvt_pk_fp8_f32 v157, v66, v67 op_sel:[0,0,1]
	global_store_dwordx2 v[154:155], v[156:157], off offset:-3968
	v_mov_b32_e32 v156, v193
	v_mov_b32_e32 v157, v193
	v_cvt_pk_fp8_f32 v156, v60, v61
	v_cvt_pk_fp8_f32 v157, v56, v57
	v_mad_i64_i32 v[154:155], s[16:17], v149, s9, v[140:141]
	v_lshl_add_u64 v[154:155], v[154:155], 0, s[14:15]
	v_cvt_pk_fp8_f32 v156, v62, v63 op_sel:[0,0,1]
	v_cvt_pk_fp8_f32 v157, v58, v59 op_sel:[0,0,1]
	v_lshl_add_u64 v[154:155], v[154:155], 0, s[20:21]
	v_lshl_add_u64 v[154:155], v[154:155], 0, s[4:5]
	v_lshl_add_u64 v[154:155], v[154:155], 0, v[134:135]
	global_store_dwordx2 v[154:155], v[156:157], off offset:-4096
	v_mov_b32_e32 v156, v193
	v_mov_b32_e32 v157, v193
	v_cvt_pk_fp8_f32 v156, v48, v49
	v_cvt_pk_fp8_f32 v157, v40, v41
	v_cvt_pk_fp8_f32 v156, v50, v51 op_sel:[0,0,1]
	v_cvt_pk_fp8_f32 v157, v42, v43 op_sel:[0,0,1]
	global_store_dwordx2 v[154:155], v[156:157], off offset:-3968
	v_mov_b32_e32 v156, v193
	v_mov_b32_e32 v157, v193
	v_cvt_pk_fp8_f32 v156, v52, v53
	v_cvt_pk_fp8_f32 v157, v44, v45
	v_mad_i64_i32 v[154:155], s[16:17], v148, s9, v[140:141]
	v_lshl_add_u64 v[154:155], v[154:155], 0, s[14:15]
	v_cvt_pk_fp8_f32 v156, v54, v55 op_sel:[0,0,1]
	v_cvt_pk_fp8_f32 v157, v46, v47 op_sel:[0,0,1]
	v_lshl_add_u64 v[154:155], v[154:155], 0, s[20:21]
	v_lshl_add_u64 v[154:155], v[154:155], 0, s[4:5]
	v_lshl_add_u64 v[154:155], v[154:155], 0, v[134:135]
	global_store_dwordx2 v[154:155], v[156:157], off offset:-4096
	v_mov_b32_e32 v156, v193
	v_mov_b32_e32 v157, v193
	v_cvt_pk_fp8_f32 v156, v32, v33
	v_cvt_pk_fp8_f32 v157, v24, v25
	v_cvt_pk_fp8_f32 v156, v34, v35 op_sel:[0,0,1]
	v_cvt_pk_fp8_f32 v157, v26, v27 op_sel:[0,0,1]
	global_store_dwordx2 v[154:155], v[156:157], off offset:-3968
	v_mov_b32_e32 v156, v193
	v_mov_b32_e32 v157, v193
	v_cvt_pk_fp8_f32 v156, v36, v37
	v_cvt_pk_fp8_f32 v157, v28, v29
	v_mad_i64_i32 v[154:155], s[16:17], v147, s9, v[140:141]
	v_lshl_add_u64 v[154:155], v[154:155], 0, s[14:15]
	v_cvt_pk_fp8_f32 v156, v38, v39 op_sel:[0,0,1]
	v_cvt_pk_fp8_f32 v157, v30, v31 op_sel:[0,0,1]
	v_lshl_add_u64 v[154:155], v[154:155], 0, s[20:21]
	v_lshl_add_u64 v[154:155], v[154:155], 0, s[4:5]
	v_lshl_add_u64 v[154:155], v[154:155], 0, v[134:135]
	global_store_dwordx2 v[154:155], v[156:157], off offset:-4096
	v_mov_b32_e32 v156, v193
	v_mov_b32_e32 v157, v193
	v_cvt_pk_fp8_f32 v156, v16, v17
	v_cvt_pk_fp8_f32 v157, v8, v9
	v_mad_i64_i32 v[140:141], s[16:17], v146, s9, v[140:141]
	v_cvt_pk_fp8_f32 v156, v18, v19 op_sel:[0,0,1]
	v_cvt_pk_fp8_f32 v157, v10, v11 op_sel:[0,0,1]
	v_lshl_add_u64 v[140:141], v[140:141], 0, s[14:15]
	v_lshl_add_u64 v[140:141], v[140:141], 0, s[20:21]
	v_lshl_add_u64 v[140:141], v[140:141], 0, s[4:5]
	global_store_dwordx2 v[154:155], v[156:157], off offset:-3968
	v_mov_b32_e32 v154, v193
	v_mov_b32_e32 v155, v193
	v_cvt_pk_fp8_f32 v154, v20, v21
	v_cvt_pk_fp8_f32 v155, v12, v13
	v_lshl_add_u64 v[140:141], v[140:141], 0, v[134:135]
	s_mov_b64 s[14:15], 0
	v_cvt_pk_fp8_f32 v154, v22, v23 op_sel:[0,0,1]
	v_cvt_pk_fp8_f32 v155, v14, v15 op_sel:[0,0,1]
	global_store_dwordx2 v[140:141], v[154:155], off offset:-4096
	v_mov_b32_e32 v154, v193
	v_mov_b32_e32 v155, v193
	v_cvt_pk_fp8_f32 v154, v4, v5
	v_cvt_pk_fp8_f32 v155, v0, v1
	v_cvt_pk_fp8_f32 v154, v6, v7 op_sel:[0,0,1]
	v_cvt_pk_fp8_f32 v155, v2, v3 op_sel:[0,0,1]
	global_store_dwordx2 v[140:141], v[154:155], off offset:-3968
